# speedup vs baseline: 1.0133x; 1.0002x over previous
; #define STAGE(P,BASE,LD,br,kt) do{long _g=(long)(br)*(LD)+(long)(kt)*BK; \
;     _Pragma("unroll") for(int _i=0;_i<2;++_i){int _b=tid*16+_i*8192;int _r,_c;stage_rc(_b,_r,_c); \
;       __builtin_amdgcn_global_load_lds((const unsigned*)((BASE)+_g+(long)_r*(LD)+_c), \
;         (unsigned*)((char*)(P)+_b),16,0,0);}}while(0)
; #define STAGE(P,BASE,LD,br,kt) do{long _g=(long)(br)*(LD)+(long)(kt)*BK; \
;     _Pragma("unroll") for(int _i=0;_i<2;++_i){int _b=tid*16+_i*8192;int _r,_c;stage_rc(_b,_r,_c); \
;       __builtin_amdgcn_global_load_lds((const unsigned*)((BASE)+_g+(long)_r*(LD)+_c), \
;         (unsigned*)((char*)(P)+_b),16,0,0);}}while(0)
; #define LDA(dst,b,h) _Pragma("unroll") for(int m=0;m<4;++m) _Pragma("unroll") for(int k=0;k<2;++k) \
;     dst[m][k]=*reinterpret_cast<const bf16x8*>((char*)SA(b,h)+lds_byte(wr*64+m*16+fr,k*32+fq*8))
; #define LDB(dst,b,h) _Pragma("unroll") for(int n=0;n<2;++n) _Pragma("unroll") for(int k=0;k<2;++k) \
;     dst[n][k]=*reinterpret_cast<const bf16x8*>((char*)SB(b,h)+lds_byte(wc*32+n*16+fr,k*32+fq*8))
; #define MMA(ai,bj,At_,Bt_) do{__builtin_amdgcn_s_setprio(1); \
;     _Pragma("unroll") for(int m=0;m<4;++m) _Pragma("unroll") for(int n=0;n<2;++n) _Pragma("unroll") for(int k=0;k<2;++k) \
;       acc[ai][bj][m][n]=__builtin_amdgcn_mfma_f32_16x16x32_bf16(Bt_[n][k],At_[m][k],acc[ai][bj][m][n],0,0,0); \
;     __builtin_amdgcn_s_setprio(0);}while(0)
; #define WAIT_L(n) asm volatile("s_waitcnt lgkmcnt(" #n ")":::"memory")
; #define BAR __builtin_amdgcn_s_barrier()
; #define SCHED __builtin_amdgcn_sched_barrier(0)
; DEVINL void gemm8_mainloop(const u16* A, long lda, const u16* Bt, long ldb, int K, int brow, int bcol, f32x4 (&acc)[2][2][4][2], char* smem, int tid) {
;     ...
;   for(int t=0;t<nt-2;t+=2){
;     LDB(B0,0,0); SCHED; LDA(At,0,0); STAGE(SA(1,1),A,lda,brow+HALF,t+1);
;     WAIT_L(8); BAR; WAIT_L(0); MMA(0,0,At,B0); BAR; SCHED;
;     LDB(B1,0,1); STAGE(SB(0,0),Bt,ldb,bcol,t+2);
;     BAR; WAIT_L(0); MMA(0,1,At,B1); BAR;
;     LDA(At,0,1); STAGE(SA(0,0),A,lda,brow,t+2);
;     BAR; WAIT_L(0); MMA(1,0,At,B0); BAR; SCHED;
.LBB0_269:
	ds_read_b128 v[170:173], v161
	ds_read_b128 v[180:183], v161 offset:1024
	ds_read_b128 v[184:187], v161 offset:2048
	ds_read_b128 v[188:191], v161 offset:3072
	v_add_u32_e32 v178, 0xc000, v128
	v_lshl_add_u64 v[244:245], s[94:95], 0, v[148:149]
	v_readfirstlane_b32 s3, v178
	v_add_u32_e32 v179, 0xe000, v128
	v_add_u32_e32 v174, s41, v160
	v_add_u32_e32 v175, s45, v160
	v_add_u32_e32 v177, s47, v160
	v_lshl_add_u64 v[162:163], v[244:245], 0, s[12:13]
	s_mov_b32 m0, s3
	v_lshl_add_u64 v[246:247], s[94:95], 0, v[150:151]
	v_readfirstlane_b32 s3, v179
	ds_read_b128 v[192:195], v131
	ds_read_b128 v[196:199], v131 offset:1024
	ds_read_b128 v[200:203], v174
	ds_read_b128 v[204:207], v174 offset:1024
	ds_read_b128 v[208:211], v175
	ds_read_b128 v[212:215], v175 offset:1024
	ds_read_b128 v[216:219], v177
	ds_read_b128 v[220:223], v177 offset:1024
	global_load_lds_dwordx4 v[162:163], off
	v_lshl_add_u64 v[162:163], v[246:247], 0, s[12:13]
	s_mov_b32 m0, s3
	s_nop 0
	global_load_lds_dwordx4 v[162:163], off
	s_waitcnt lgkmcnt(8)
	s_barrier
	s_waitcnt lgkmcnt(0)
	v_mfma_f32_16x16x32_bf16 v[124:127], v[170:173], v[192:195], v[124:127]
	v_mfma_f32_16x16x32_bf16 v[120:123], v[184:187], v[192:195], v[120:123]
	v_mfma_f32_16x16x32_bf16 v[116:119], v[170:173], v[200:203], v[116:119]
	v_mfma_f32_16x16x32_bf16 v[112:115], v[184:187], v[200:203], v[112:115]
	v_mfma_f32_16x16x32_bf16 v[108:111], v[170:173], v[208:211], v[108:111]
	v_mfma_f32_16x16x32_bf16 v[104:107], v[184:187], v[208:211], v[104:107]
	v_mfma_f32_16x16x32_bf16 v[100:103], v[170:173], v[216:219], v[100:103]
	v_mfma_f32_16x16x32_bf16 v[96:99], v[184:187], v[216:219], v[96:99]
	v_mfma_f32_16x16x32_bf16 v[124:127], v[180:183], v[196:199], v[124:127]
	v_mfma_f32_16x16x32_bf16 v[120:123], v[188:191], v[196:199], v[120:123]
	v_mfma_f32_16x16x32_bf16 v[116:119], v[180:183], v[204:207], v[116:119]
	v_mfma_f32_16x16x32_bf16 v[112:115], v[188:191], v[204:207], v[112:115]
	v_mfma_f32_16x16x32_bf16 v[108:111], v[180:183], v[212:215], v[108:111]
	v_mfma_f32_16x16x32_bf16 v[104:107], v[188:191], v[212:215], v[104:107]
	v_mfma_f32_16x16x32_bf16 v[100:103], v[180:183], v[220:223], v[100:103]
	v_mfma_f32_16x16x32_bf16 v[96:99], v[188:191], v[220:223], v[96:99]
	s_barrier
	v_add_u32_e32 v162, s31, v153
	v_lshl_add_u64 v[248:249], s[94:95], 0, v[144:145]
	v_readfirstlane_b32 s3, v162
	v_add_u32_e32 v163, 0x2000, v162
	v_lshl_add_u64 v[240:241], v[248:249], 0, s[14:15]
	s_mov_b32 m0, s3
	v_lshl_add_u64 v[250:251], s[94:95], 0, v[146:147]
	v_readfirstlane_b32 s3, v163
	ds_read_b128 v[224:227], v158
	ds_read_b128 v[228:231], v158 offset:1024
	ds_read_b128 v[232:235], v158 offset:2048
	ds_read_b128 v[236:239], v158 offset:3072
	global_load_lds_dwordx4 v[240:241], off
	v_lshl_add_u64 v[240:241], v[250:251], 0, s[14:15]
	s_mov_b32 m0, s3
	s_nop 0
	global_load_lds_dwordx4 v[240:241], off
	s_barrier
	s_waitcnt lgkmcnt(0)
	v_mfma_f32_16x16x32_bf16 v[92:95], v[224:227], v[192:195], v[92:95]
	v_mfma_f32_16x16x32_bf16 v[88:91], v[232:235], v[192:195], v[88:91]
	v_mfma_f32_16x16x32_bf16 v[84:87], v[224:227], v[200:203], v[84:87]
	v_mfma_f32_16x16x32_bf16 v[80:83], v[232:235], v[200:203], v[80:83]
	v_mfma_f32_16x16x32_bf16 v[76:79], v[224:227], v[208:211], v[76:79]
	v_mfma_f32_16x16x32_bf16 v[72:75], v[232:235], v[208:211], v[72:75]
	v_mfma_f32_16x16x32_bf16 v[68:71], v[224:227], v[216:219], v[68:71]
	v_mfma_f32_16x16x32_bf16 v[64:67], v[232:235], v[216:219], v[64:67]
	v_mfma_f32_16x16x32_bf16 v[92:95], v[228:231], v[196:199], v[92:95]
	v_mfma_f32_16x16x32_bf16 v[88:91], v[236:239], v[196:199], v[88:91]
	v_mfma_f32_16x16x32_bf16 v[84:87], v[228:231], v[204:207], v[84:87]
	v_mfma_f32_16x16x32_bf16 v[80:83], v[236:239], v[204:207], v[80:83]
	v_mfma_f32_16x16x32_bf16 v[76:79], v[228:231], v[212:215], v[76:79]
	v_mfma_f32_16x16x32_bf16 v[72:75], v[236:239], v[212:215], v[72:75]
	v_mfma_f32_16x16x32_bf16 v[68:71], v[228:231], v[220:223], v[68:71]
	v_mfma_f32_16x16x32_bf16 v[64:67], v[236:239], v[220:223], v[64:67]
	v_readfirstlane_b32 s3, v128
	v_add_u32_e32 v169, 0x2000, v128
	v_lshl_add_u64 v[240:241], v[244:245], 0, s[16:17]
	s_mov_b32 m0, s3
	v_readfirstlane_b32 s3, v169
	s_barrier
	ds_read_b128 v[192:195], v131 offset:16384
	ds_read_b128 v[196:199], v131 offset:17408
	ds_read_b128 v[200:203], v174 offset:16384
	ds_read_b128 v[204:207], v174 offset:17408
	ds_read_b128 v[208:211], v175 offset:16384
	ds_read_b128 v[212:215], v175 offset:17408
	ds_read_b128 v[216:219], v177 offset:16384
	ds_read_b128 v[220:223], v177 offset:17408
	global_load_lds_dwordx4 v[240:241], off
	v_lshl_add_u64 v[240:241], v[246:247], 0, s[16:17]
	s_mov_b32 m0, s3
	s_nop 0
	global_load_lds_dwordx4 v[240:241], off
	s_barrier
	s_waitcnt lgkmcnt(0)
	v_mfma_f32_16x16x32_bf16 v[60:63], v[170:173], v[192:195], v[60:63]
	v_mfma_f32_16x16x32_bf16 v[56:59], v[184:187], v[192:195], v[56:59]
	v_mfma_f32_16x16x32_bf16 v[52:55], v[170:173], v[200:203], v[52:55]
	v_mfma_f32_16x16x32_bf16 v[48:51], v[184:187], v[200:203], v[48:51]
	v_mfma_f32_16x16x32_bf16 v[44:47], v[170:173], v[208:211], v[44:47]
	v_mfma_f32_16x16x32_bf16 v[40:43], v[184:187], v[208:211], v[40:43]
	v_mfma_f32_16x16x32_bf16 v[36:39], v[170:173], v[216:219], v[36:39]
	v_mfma_f32_16x16x32_bf16 v[32:35], v[184:187], v[216:219], v[32:35]
	v_mfma_f32_16x16x32_bf16 v[60:63], v[180:183], v[196:199], v[60:63]
	v_mfma_f32_16x16x32_bf16 v[56:59], v[188:191], v[196:199], v[56:59]
	v_mfma_f32_16x16x32_bf16 v[52:55], v[180:183], v[204:207], v[52:55]
	v_mfma_f32_16x16x32_bf16 v[48:51], v[188:191], v[204:207], v[48:51]
	v_mfma_f32_16x16x32_bf16 v[44:47], v[180:183], v[212:215], v[44:47]
	v_mfma_f32_16x16x32_bf16 v[40:43], v[188:191], v[212:215], v[40:43]
	v_mfma_f32_16x16x32_bf16 v[36:39], v[180:183], v[220:223], v[36:39]
	v_mfma_f32_16x16x32_bf16 v[32:35], v[188:191], v[220:223], v[32:35]
	s_barrier
; #define STAGE(P,BASE,LD,br,kt) do{long _g=(long)(br)*(LD)+(long)(kt)*BK; \
;     _Pragma("unroll") for(int _i=0;_i<2;++_i){int _b=tid*16+_i*8192;int _r,_c;stage_rc(_b,_r,_c); \
;       __builtin_amdgcn_global_load_lds((const unsigned*)((BASE)+_g+(long)_r*(LD)+_c), \
;         (unsigned*)((char*)(P)+_b),16,0,0);}}while(0)
; #define STAGE(P,BASE,LD,br,kt) do{long _g=(long)(br)*(LD)+(long)(kt)*BK; \
;     _Pragma("unroll") for(int _i=0;_i<2;++_i){int _b=tid*16+_i*8192;int _r,_c;stage_rc(_b,_r,_c); \
;       __builtin_amdgcn_global_load_lds((const unsigned*)((BASE)+_g+(long)_r*(LD)+_c), \
;         (unsigned*)((char*)(P)+_b),16,0,0);}}while(0)
; #define LDA(dst,b,h) _Pragma("unroll") for(int m=0;m<4;++m) _Pragma("unroll") for(int k=0;k<2;++k) \
;     dst[m][k]=*reinterpret_cast<const bf16x8*>((char*)SA(b,h)+lds_byte(wr*64+m*16+fr,k*32+fq*8))
; #define LDB(dst,b,h) _Pragma("unroll") for(int n=0;n<2;++n) _Pragma("unroll") for(int k=0;k<2;++k) \
;     dst[n][k]=*reinterpret_cast<const bf16x8*>((char*)SB(b,h)+lds_byte(wc*32+n*16+fr,k*32+fq*8))
; #define MMA(ai,bj,At_,Bt_) do{__builtin_amdgcn_s_setprio(1); \
;     _Pragma("unroll") for(int m=0;m<4;++m) _Pragma("unroll") for(int n=0;n<2;++n) _Pragma("unroll") for(int k=0;k<2;++k) \
;       acc[ai][bj][m][n]=__builtin_amdgcn_mfma_f32_16x16x32_bf16(Bt_[n][k],At_[m][k],acc[ai][bj][m][n],0,0,0); \
;     __builtin_amdgcn_s_setprio(0);}while(0)
; #define WAIT_V(n) asm volatile("s_waitcnt vmcnt(" #n ")":::"memory")
; #define WAIT_L(n) asm volatile("s_waitcnt lgkmcnt(" #n ")":::"memory")
; #define BAR __builtin_amdgcn_s_barrier()
; #define SCHED __builtin_amdgcn_sched_barrier(0)
; DEVINL void gemm8_mainloop(const u16* A, long lda, const u16* Bt, long ldb, int K, int brow, int bcol, f32x4 (&acc)[2][2][4][2], char* smem, int tid) {
;     ...
;     STAGE(SB(0,1),Bt,ldb,bcol+HALF,t+2);
;     WAIT_V(6); BAR; MMA(1,1,At,B1); BAR;
;     LDB(B0,1,0); SCHED; LDA(At,1,0); STAGE(SA(0,1),A,lda,brow+HALF,t+2);
;     WAIT_L(8); BAR; WAIT_L(0); MMA(0,0,At,B0); BAR; SCHED;
;     LDB(B1,1,1); STAGE(SB(1,0),Bt,ldb,bcol,t+3);
;     BAR; WAIT_L(0); MMA(0,1,At,B1); BAR;
;     LDA(At,1,1); STAGE(SA(1,0),A,lda,brow,t+3);
	v_add_u32_e32 v170, s33, v153
	v_add_u32_e32 v171, 0x2000, v170
	v_readfirstlane_b32 s3, v170
	v_lshl_add_u64 v[172:173], v[248:249], 0, s[18:19]
	s_mov_b32 m0, s3
	v_readfirstlane_b32 s3, v171
	global_load_lds_dwordx4 v[172:173], off
	v_lshl_add_u64 v[172:173], v[250:251], 0, s[18:19]
	s_mov_b32 m0, s3
	s_nop 0
	global_load_lds_dwordx4 v[172:173], off
	s_waitcnt vmcnt(6)
	s_barrier
	v_mfma_f32_16x16x32_bf16 v[28:31], v[224:227], v[192:195], v[28:31]
	v_mfma_f32_16x16x32_bf16 v[24:27], v[232:235], v[192:195], v[24:27]
	v_mfma_f32_16x16x32_bf16 v[20:23], v[224:227], v[200:203], v[20:23]
	v_mfma_f32_16x16x32_bf16 v[16:19], v[232:235], v[200:203], v[16:19]
	v_mfma_f32_16x16x32_bf16 v[12:15], v[224:227], v[208:211], v[12:15]
	v_mfma_f32_16x16x32_bf16 v[8:11], v[232:235], v[208:211], v[8:11]
	v_mfma_f32_16x16x32_bf16 v[4:7], v[224:227], v[216:219], v[4:7]
	v_mfma_f32_16x16x32_bf16 v[0:3], v[232:235], v[216:219], v[0:3]
	v_mfma_f32_16x16x32_bf16 v[28:31], v[228:231], v[196:199], v[28:31]
	v_mfma_f32_16x16x32_bf16 v[24:27], v[236:239], v[196:199], v[24:27]
	v_mfma_f32_16x16x32_bf16 v[20:23], v[228:231], v[204:207], v[20:23]
	v_mfma_f32_16x16x32_bf16 v[16:19], v[236:239], v[204:207], v[16:19]
	v_mfma_f32_16x16x32_bf16 v[12:15], v[228:231], v[212:215], v[12:15]
	v_mfma_f32_16x16x32_bf16 v[8:11], v[236:239], v[212:215], v[8:11]
	v_mfma_f32_16x16x32_bf16 v[4:7], v[228:231], v[220:223], v[4:7]
	v_mfma_f32_16x16x32_bf16 v[0:3], v[236:239], v[220:223], v[0:3]
	s_barrier
	ds_read_b128 v[180:183], v154
	ds_read_b128 v[184:187], v154 offset:1024
	ds_read_b128 v[188:191], v154 offset:2048
	ds_read_b128 v[192:195], v154 offset:3072
	v_add_u32_e32 v172, 0x4000, v128
	v_add_u32_e32 v173, 0x6000, v128
	v_readfirstlane_b32 s3, v172
	v_lshl_add_u64 v[228:229], v[244:245], 0, s[20:21]
	s_mov_b32 m0, s3
	v_readfirstlane_b32 s3, v173
	ds_read_b128 v[196:199], v131 offset:32768
	ds_read_b128 v[200:203], v131 offset:33792
	ds_read_b128 v[204:207], v174 offset:32768
	ds_read_b128 v[208:211], v174 offset:33792
	ds_read_b128 v[212:215], v175 offset:32768
	ds_read_b128 v[216:219], v175 offset:33792
	ds_read_b128 v[220:223], v177 offset:32768
	ds_read_b128 v[224:227], v177 offset:33792
	global_load_lds_dwordx4 v[228:229], off
	v_lshl_add_u64 v[228:229], v[246:247], 0, s[20:21]
	s_mov_b32 m0, s3
	s_nop 0
	global_load_lds_dwordx4 v[228:229], off
	s_waitcnt lgkmcnt(8)
	s_barrier
	s_waitcnt lgkmcnt(0)
	v_mfma_f32_16x16x32_bf16 v[124:127], v[180:183], v[196:199], v[124:127]
	v_mfma_f32_16x16x32_bf16 v[120:123], v[188:191], v[196:199], v[120:123]
	v_mfma_f32_16x16x32_bf16 v[116:119], v[180:183], v[204:207], v[116:119]
	v_mfma_f32_16x16x32_bf16 v[112:115], v[188:191], v[204:207], v[112:115]
	v_mfma_f32_16x16x32_bf16 v[108:111], v[180:183], v[212:215], v[108:111]
	v_mfma_f32_16x16x32_bf16 v[104:107], v[188:191], v[212:215], v[104:107]
	v_mfma_f32_16x16x32_bf16 v[100:103], v[180:183], v[220:223], v[100:103]
	v_mfma_f32_16x16x32_bf16 v[96:99], v[188:191], v[220:223], v[96:99]
	v_mfma_f32_16x16x32_bf16 v[124:127], v[184:187], v[200:203], v[124:127]
	v_mfma_f32_16x16x32_bf16 v[120:123], v[192:195], v[200:203], v[120:123]
	v_mfma_f32_16x16x32_bf16 v[116:119], v[184:187], v[208:211], v[116:119]
	v_mfma_f32_16x16x32_bf16 v[112:115], v[192:195], v[208:211], v[112:115]
	v_mfma_f32_16x16x32_bf16 v[108:111], v[184:187], v[216:219], v[108:111]
	v_mfma_f32_16x16x32_bf16 v[104:107], v[192:195], v[216:219], v[104:107]
	v_mfma_f32_16x16x32_bf16 v[100:103], v[184:187], v[224:227], v[100:103]
	v_mfma_f32_16x16x32_bf16 v[96:99], v[192:195], v[224:227], v[96:99]
	s_barrier
	v_readfirstlane_b32 s3, v155
	v_add_u32_e32 v165, 0x2000, v155
	v_lshl_add_u64 v[252:253], v[248:249], 0, s[22:23]
	s_mov_b32 m0, s3
	v_readfirstlane_b32 s3, v165
	ds_read_b128 v[228:231], v152
	ds_read_b128 v[232:235], v152 offset:1024
	ds_read_b128 v[236:239], v152 offset:2048
	ds_read_b128 v[240:243], v152 offset:3072
	global_load_lds_dwordx4 v[252:253], off
	v_lshl_add_u64 v[252:253], v[250:251], 0, s[22:23]
	s_mov_b32 m0, s3
	s_nop 0
	global_load_lds_dwordx4 v[252:253], off
	s_barrier
	s_waitcnt lgkmcnt(0)
	v_mfma_f32_16x16x32_bf16 v[92:95], v[228:231], v[196:199], v[92:95]
	v_mfma_f32_16x16x32_bf16 v[88:91], v[236:239], v[196:199], v[88:91]
	v_mfma_f32_16x16x32_bf16 v[84:87], v[228:231], v[204:207], v[84:87]
	v_mfma_f32_16x16x32_bf16 v[80:83], v[236:239], v[204:207], v[80:83]
	v_mfma_f32_16x16x32_bf16 v[76:79], v[228:231], v[212:215], v[76:79]
	v_mfma_f32_16x16x32_bf16 v[72:75], v[236:239], v[212:215], v[72:75]
	v_mfma_f32_16x16x32_bf16 v[68:71], v[228:231], v[220:223], v[68:71]
	v_mfma_f32_16x16x32_bf16 v[64:67], v[236:239], v[220:223], v[64:67]
	v_mfma_f32_16x16x32_bf16 v[92:95], v[232:235], v[200:203], v[92:95]
	v_mfma_f32_16x16x32_bf16 v[88:91], v[240:243], v[200:203], v[88:91]
	v_mfma_f32_16x16x32_bf16 v[84:87], v[232:235], v[208:211], v[84:87]
	v_mfma_f32_16x16x32_bf16 v[80:83], v[240:243], v[208:211], v[80:83]
	v_mfma_f32_16x16x32_bf16 v[76:79], v[232:235], v[216:219], v[76:79]
	v_mfma_f32_16x16x32_bf16 v[72:75], v[240:243], v[216:219], v[72:75]
	v_mfma_f32_16x16x32_bf16 v[68:71], v[232:235], v[224:227], v[68:71]
	v_mfma_f32_16x16x32_bf16 v[64:67], v[240:243], v[224:227], v[64:67]
	v_readfirstlane_b32 s3, v156
	v_lshl_add_u64 v[244:245], v[244:245], 0, s[24:25]
	s_mov_b32 m0, s3
	v_readfirstlane_b32 s3, v157
	s_barrier
	ds_read_b128 v[196:199], v131 offset:49152
	ds_read_b128 v[200:203], v131 offset:50176
	ds_read_b128 v[204:207], v174 offset:49152
	ds_read_b128 v[208:211], v174 offset:50176
	ds_read_b128 v[212:215], v175 offset:49152
	ds_read_b128 v[216:219], v175 offset:50176
	ds_read_b128 v[220:223], v177 offset:49152
	ds_read_b128 v[224:227], v177 offset:50176
	global_load_lds_dwordx4 v[244:245], off
	v_lshl_add_u64 v[244:245], v[246:247], 0, s[24:25]
	s_mov_b32 m0, s3
	s_nop 0
	global_load_lds_dwordx4 v[244:245], off
	s_barrier
; #define STAGE(P,BASE,LD,br,kt) do{long _g=(long)(br)*(LD)+(long)(kt)*BK; \
;     _Pragma("unroll") for(int _i=0;_i<2;++_i){int _b=tid*16+_i*8192;int _r,_c;stage_rc(_b,_r,_c); \
;       __builtin_amdgcn_global_load_lds((const unsigned*)((BASE)+_g+(long)_r*(LD)+_c), \
;         (unsigned*)((char*)(P)+_b),16,0,0);}}while(0)
; #define STAGE(P,BASE,LD,br,kt) do{long _g=(long)(br)*(LD)+(long)(kt)*BK; \
;     _Pragma("unroll") for(int _i=0;_i<2;++_i){int _b=tid*16+_i*8192;int _r,_c;stage_rc(_b,_r,_c); \
;       __builtin_amdgcn_global_load_lds((const unsigned*)((BASE)+_g+(long)_r*(LD)+_c), \
;         (unsigned*)((char*)(P)+_b),16,0,0);}}while(0)
; #define LDA(dst,b,h) _Pragma("unroll") for(int m=0;m<4;++m) _Pragma("unroll") for(int k=0;k<2;++k) \
;     dst[m][k]=*reinterpret_cast<const bf16x8*>((char*)SA(b,h)+lds_byte(wr*64+m*16+fr,k*32+fq*8))
; #define LDB(dst,b,h) _Pragma("unroll") for(int n=0;n<2;++n) _Pragma("unroll") for(int k=0;k<2;++k) \
;     dst[n][k]=*reinterpret_cast<const bf16x8*>((char*)SB(b,h)+lds_byte(wc*32+n*16+fr,k*32+fq*8))
; #define MMA(ai,bj,At_,Bt_) do{__builtin_amdgcn_s_setprio(1); \
;     _Pragma("unroll") for(int m=0;m<4;++m) _Pragma("unroll") for(int n=0;n<2;++n) _Pragma("unroll") for(int k=0;k<2;++k) \
;       acc[ai][bj][m][n]=__builtin_amdgcn_mfma_f32_16x16x32_bf16(Bt_[n][k],At_[m][k],acc[ai][bj][m][n],0,0,0); \
;     __builtin_amdgcn_s_setprio(0);}while(0)
; #define WAIT_V(n) asm volatile("s_waitcnt vmcnt(" #n ")":::"memory")
; #define WAIT_L(n) asm volatile("s_waitcnt lgkmcnt(" #n ")":::"memory")
; #define BAR __builtin_amdgcn_s_barrier()
; #define SCHED __builtin_amdgcn_sched_barrier(0)
; DEVINL void gemm8_mainloop(const u16* A, long lda, const u16* Bt, long ldb, int K, int brow, int bcol, f32x4 (&acc)[2][2][4][2], char* smem, int tid) {
;     ...
;     BAR; WAIT_L(0); MMA(1,0,At,B0); BAR; SCHED;
;     STAGE(SB(1,1),Bt,ldb,bcol+HALF,t+3);
;     WAIT_V(6); BAR; MMA(1,1,At,B1); BAR;
;   }
;   { LDB(B0,0,0); LDA(At,0,0); STAGE(SA(1,1),A,lda,brow+HALF,nt-1);
;     BAR; WAIT_L(0); MMA(0,0,At,B0); BAR;
;     LDB(B1,0,1); BAR; WAIT_L(0); MMA(0,1,At,B1); BAR;
	s_waitcnt lgkmcnt(0)
	v_mfma_f32_16x16x32_bf16 v[60:63], v[180:183], v[196:199], v[60:63]
	v_mfma_f32_16x16x32_bf16 v[56:59], v[188:191], v[196:199], v[56:59]
	v_mfma_f32_16x16x32_bf16 v[52:55], v[180:183], v[204:207], v[52:55]
	v_mfma_f32_16x16x32_bf16 v[48:51], v[188:191], v[204:207], v[48:51]
	v_mfma_f32_16x16x32_bf16 v[44:47], v[180:183], v[212:215], v[44:47]
	v_mfma_f32_16x16x32_bf16 v[40:43], v[188:191], v[212:215], v[40:43]
	v_mfma_f32_16x16x32_bf16 v[36:39], v[180:183], v[220:223], v[36:39]
	v_mfma_f32_16x16x32_bf16 v[32:35], v[188:191], v[220:223], v[32:35]
	v_mfma_f32_16x16x32_bf16 v[60:63], v[184:187], v[200:203], v[60:63]
	v_mfma_f32_16x16x32_bf16 v[56:59], v[192:195], v[200:203], v[56:59]
	v_mfma_f32_16x16x32_bf16 v[52:55], v[184:187], v[208:211], v[52:55]
	v_mfma_f32_16x16x32_bf16 v[48:51], v[192:195], v[208:211], v[48:51]
	v_mfma_f32_16x16x32_bf16 v[44:47], v[184:187], v[216:219], v[44:47]
	v_mfma_f32_16x16x32_bf16 v[40:43], v[192:195], v[216:219], v[40:43]
	v_mfma_f32_16x16x32_bf16 v[36:39], v[184:187], v[224:227], v[36:39]
	v_mfma_f32_16x16x32_bf16 v[32:35], v[192:195], v[224:227], v[32:35]
	s_barrier
	v_readfirstlane_b32 s3, v159
	v_add_u32_e32 v165, 0x2000, v159
	v_lshl_add_u64 v[180:181], v[248:249], 0, s[26:27]
	s_mov_b32 m0, s3
	v_readfirstlane_b32 s3, v165
	global_load_lds_dwordx4 v[180:181], off
	v_lshl_add_u64 v[180:181], v[250:251], 0, s[26:27]
	s_mov_b32 m0, s3
	s_nop 0
	global_load_lds_dwordx4 v[180:181], off
	s_waitcnt vmcnt(6)
	s_barrier
	v_mfma_f32_16x16x32_bf16 v[28:31], v[228:231], v[196:199], v[28:31]
	v_mfma_f32_16x16x32_bf16 v[24:27], v[236:239], v[196:199], v[24:27]
	v_mfma_f32_16x16x32_bf16 v[20:23], v[228:231], v[204:207], v[20:23]
	v_mfma_f32_16x16x32_bf16 v[16:19], v[236:239], v[204:207], v[16:19]
	v_mfma_f32_16x16x32_bf16 v[12:15], v[228:231], v[212:215], v[12:15]
	v_mfma_f32_16x16x32_bf16 v[8:11], v[236:239], v[212:215], v[8:11]
	v_mfma_f32_16x16x32_bf16 v[4:7], v[228:231], v[220:223], v[4:7]
	v_mfma_f32_16x16x32_bf16 v[0:3], v[236:239], v[220:223], v[0:3]
	v_mfma_f32_16x16x32_bf16 v[28:31], v[232:235], v[200:203], v[28:31]
	v_mfma_f32_16x16x32_bf16 v[24:27], v[240:243], v[200:203], v[24:27]
	v_mfma_f32_16x16x32_bf16 v[20:23], v[232:235], v[208:211], v[20:23]
	v_mfma_f32_16x16x32_bf16 v[16:19], v[240:243], v[208:211], v[16:19]
	v_mfma_f32_16x16x32_bf16 v[12:15], v[232:235], v[216:219], v[12:15]
	v_mfma_f32_16x16x32_bf16 v[8:11], v[240:243], v[216:219], v[8:11]
	v_mfma_f32_16x16x32_bf16 v[4:7], v[232:235], v[224:227], v[4:7]
	v_mfma_f32_16x16x32_bf16 v[0:3], v[240:243], v[224:227], v[0:3]
	s_add_i32 s2, s2, 2
	v_lshl_add_u64 v[144:145], v[144:145], 0, s[14:15]
	v_lshl_add_u64 v[146:147], v[146:147], 0, s[14:15]
	v_lshl_add_u64 v[148:149], v[148:149], 0, s[14:15]
	s_cmp_lt_u32 s2, 28
	v_lshl_add_u64 v[150:151], v[150:151], 0, s[14:15]
	s_barrier
	s_cbranch_scc1 .LBB0_269
	s_or_b32 s2, s40, 0x80
	s_ashr_i32 s3, s2, 31
	s_lshl_b64 s[2:3], s[2:3], 12
	s_add_u32 s2, s90, s2
	s_addc_u32 s3, s91, s3
	v_lshl_add_u64 v[156:157], v[136:137], 1, s[2:3]
	v_lshl_add_u64 v[140:141], v[140:141], 1, v[156:157]
	v_readfirstlane_b32 s41, v178
	v_lshl_add_u64 v[140:141], v[140:141], 0, s[28:29]
	s_mov_b32 m0, s41
	ds_read_b128 v[144:147], v161
	ds_read_b128 v[148:151], v161 offset:1024
	ds_read_b128 v[180:183], v161 offset:2048
	ds_read_b128 v[184:187], v161 offset:3072
	ds_read_b128 v[188:191], v131
	ds_read_b128 v[192:195], v131 offset:1024
	ds_read_b128 v[196:199], v174
	ds_read_b128 v[200:203], v174 offset:1024
	ds_read_b128 v[204:207], v175
	ds_read_b128 v[208:211], v175 offset:1024
	ds_read_b128 v[212:215], v177
	ds_read_b128 v[216:219], v177 offset:1024
	global_load_lds_dwordx4 v[140:141], off
	v_lshl_add_u64 v[140:141], v[138:139], 1, s[2:3]
	v_lshl_add_u64 v[140:141], v[142:143], 1, v[140:141]
	v_readfirstlane_b32 s2, v179
	v_lshl_add_u64 v[140:141], v[140:141], 0, s[28:29]
	s_mov_b32 m0, s2
	s_nop 0
	global_load_lds_dwordx4 v[140:141], off
	s_barrier
	s_waitcnt lgkmcnt(0)
	v_mfma_f32_16x16x32_bf16 v[124:127], v[144:147], v[188:191], v[124:127]
	v_mfma_f32_16x16x32_bf16 v[120:123], v[180:183], v[188:191], v[120:123]
	v_mfma_f32_16x16x32_bf16 v[108:111], v[144:147], v[204:207], v[108:111]
	v_mfma_f32_16x16x32_bf16 v[104:107], v[180:183], v[204:207], v[104:107]
	v_mfma_f32_16x16x32_bf16 v[124:127], v[148:151], v[192:195], v[124:127]
	v_mfma_f32_16x16x32_bf16 v[120:123], v[184:187], v[192:195], v[120:123]
	v_mfma_f32_16x16x32_bf16 v[116:119], v[144:147], v[196:199], v[116:119]
	v_mfma_f32_16x16x32_bf16 v[112:115], v[180:183], v[196:199], v[112:115]
	v_mfma_f32_16x16x32_bf16 v[108:111], v[148:151], v[208:211], v[108:111]
	v_mfma_f32_16x16x32_bf16 v[104:107], v[184:187], v[208:211], v[104:107]
	v_mfma_f32_16x16x32_bf16 v[100:103], v[144:147], v[212:215], v[100:103]
	v_mfma_f32_16x16x32_bf16 v[96:99], v[180:183], v[212:215], v[96:99]
	v_mfma_f32_16x16x32_bf16 v[140:143], v[148:151], v[200:203], v[116:119]
	v_mfma_f32_16x16x32_bf16 v[220:223], v[184:187], v[200:203], v[112:115]
	v_mfma_f32_16x16x32_bf16 v[224:227], v[148:151], v[216:219], v[100:103]
	v_mfma_f32_16x16x32_bf16 v[228:231], v[184:187], v[216:219], v[96:99]
	s_barrier
	s_nop 1
	s_nop 0
	ds_read_b128 v[96:99], v158
	ds_read_b128 v[100:103], v158 offset:1024
	ds_read_b128 v[112:115], v158 offset:2048
	ds_read_b128 v[116:119], v158 offset:3072
	s_barrier
; #define LDA(dst,b,h) _Pragma("unroll") for(int m=0;m<4;++m) _Pragma("unroll") for(int k=0;k<2;++k) \
;     dst[m][k]=*reinterpret_cast<const bf16x8*>((char*)SA(b,h)+lds_byte(wr*64+m*16+fr,k*32+fq*8))
; #define LDB(dst,b,h) _Pragma("unroll") for(int n=0;n<2;++n) _Pragma("unroll") for(int k=0;k<2;++k) \
;     dst[n][k]=*reinterpret_cast<const bf16x8*>((char*)SB(b,h)+lds_byte(wc*32+n*16+fr,k*32+fq*8))
; #define MMA(ai,bj,At_,Bt_) do{__builtin_amdgcn_s_setprio(1); \
;     _Pragma("unroll") for(int m=0;m<4;++m) _Pragma("unroll") for(int n=0;n<2;++n) _Pragma("unroll") for(int k=0;k<2;++k) \
;       acc[ai][bj][m][n]=__builtin_amdgcn_mfma_f32_16x16x32_bf16(Bt_[n][k],At_[m][k],acc[ai][bj][m][n],0,0,0); \
;     __builtin_amdgcn_s_setprio(0);}while(0)
; #define WAIT_V(n) asm volatile("s_waitcnt vmcnt(" #n ")":::"memory")
; #define WAIT_L(n) asm volatile("s_waitcnt lgkmcnt(" #n ")":::"memory")
; #define BAR __builtin_amdgcn_s_barrier()
; DEVINL void gemm8_mainloop(const u16* A, long lda, const u16* Bt, long ldb, int K, int brow, int bcol, f32x4 (&acc)[2][2][4][2], char* smem, int tid) {
;     ...
;     LDB(B1,0,1); BAR; WAIT_L(0); MMA(0,1,At,B1); BAR;
;     LDA(At,0,1); WAIT_V(4); BAR; WAIT_L(0); MMA(1,0,At,B0); MMA(1,1,At,B1); BAR; }
;   { LDB(B0,1,0); LDA(At,1,0); WAIT_V(2); BAR; WAIT_L(0); MMA(0,0,At,B0); BAR;
	s_waitcnt lgkmcnt(0)
	v_mfma_f32_16x16x32_bf16 v[92:95], v[96:99], v[188:191], v[92:95]
	v_mfma_f32_16x16x32_bf16 v[88:91], v[112:115], v[188:191], v[88:91]
	v_mfma_f32_16x16x32_bf16 v[76:79], v[96:99], v[204:207], v[76:79]
	v_mfma_f32_16x16x32_bf16 v[72:75], v[112:115], v[204:207], v[72:75]
	v_mfma_f32_16x16x32_bf16 v[92:95], v[100:103], v[192:195], v[92:95]
	v_mfma_f32_16x16x32_bf16 v[88:91], v[116:119], v[192:195], v[88:91]
	v_mfma_f32_16x16x32_bf16 v[84:87], v[96:99], v[196:199], v[84:87]
	v_mfma_f32_16x16x32_bf16 v[80:83], v[112:115], v[196:199], v[80:83]
	v_mfma_f32_16x16x32_bf16 v[76:79], v[100:103], v[208:211], v[76:79]
	v_mfma_f32_16x16x32_bf16 v[72:75], v[116:119], v[208:211], v[72:75]
	v_mfma_f32_16x16x32_bf16 v[68:71], v[96:99], v[212:215], v[68:71]
	v_mfma_f32_16x16x32_bf16 v[64:67], v[112:115], v[212:215], v[64:67]
	v_mfma_f32_16x16x32_bf16 v[156:159], v[100:103], v[200:203], v[84:87]
	v_mfma_f32_16x16x32_bf16 v[188:191], v[116:119], v[200:203], v[80:83]
	v_mfma_f32_16x16x32_bf16 v[192:195], v[100:103], v[216:219], v[68:71]
	v_mfma_f32_16x16x32_bf16 v[196:199], v[116:119], v[216:219], v[64:67]
	s_barrier
	s_nop 1
	s_nop 0
	ds_read_b128 v[64:67], v131 offset:16384
	ds_read_b128 v[68:71], v131 offset:17408
	ds_read_b128 v[80:83], v174 offset:16384
	ds_read_b128 v[84:87], v174 offset:17408
	ds_read_b128 v[200:203], v175 offset:16384
	ds_read_b128 v[204:207], v175 offset:17408
	ds_read_b128 v[208:211], v177 offset:16384
	ds_read_b128 v[212:215], v177 offset:17408
	s_waitcnt vmcnt(4)
	s_barrier
	s_waitcnt lgkmcnt(0)
	v_mfma_f32_16x16x32_bf16 v[60:63], v[144:147], v[64:67], v[60:63]
	v_mfma_f32_16x16x32_bf16 v[52:55], v[144:147], v[80:83], v[52:55]
	v_mfma_f32_16x16x32_bf16 v[44:47], v[144:147], v[200:203], v[44:47]
	v_mfma_f32_16x16x32_bf16 v[40:43], v[180:183], v[200:203], v[40:43]
	v_mfma_f32_16x16x32_bf16 v[60:63], v[148:151], v[68:71], v[60:63]
	v_mfma_f32_16x16x32_bf16 v[56:59], v[180:183], v[64:67], v[56:59]
	v_mfma_f32_16x16x32_bf16 v[52:55], v[148:151], v[84:87], v[52:55]
	v_mfma_f32_16x16x32_bf16 v[48:51], v[180:183], v[80:83], v[48:51]
	v_mfma_f32_16x16x32_bf16 v[44:47], v[148:151], v[204:207], v[44:47]
	v_mfma_f32_16x16x32_bf16 v[40:43], v[184:187], v[204:207], v[40:43]
	v_mfma_f32_16x16x32_bf16 v[36:39], v[144:147], v[208:211], v[36:39]
	v_mfma_f32_16x16x32_bf16 v[32:35], v[180:183], v[208:211], v[32:35]
	v_mfma_f32_16x16x32_bf16 v[216:219], v[184:187], v[68:71], v[56:59]
	v_mfma_f32_16x16x32_bf16 v[232:235], v[184:187], v[84:87], v[48:51]
	v_mfma_f32_16x16x32_bf16 v[144:147], v[148:151], v[212:215], v[36:39]
	v_mfma_f32_16x16x32_bf16 v[148:151], v[184:187], v[212:215], v[32:35]
	v_mfma_f32_16x16x32_bf16 v[28:31], v[96:99], v[64:67], v[28:31]
	v_mfma_f32_16x16x32_bf16 v[20:23], v[96:99], v[80:83], v[20:23]
	v_mfma_f32_16x16x32_bf16 v[12:15], v[96:99], v[200:203], v[12:15]
	v_mfma_f32_16x16x32_bf16 v[4:7], v[96:99], v[208:211], v[4:7]
	v_mfma_f32_16x16x32_bf16 v[28:31], v[100:103], v[68:71], v[28:31]
	v_mfma_f32_16x16x32_bf16 v[24:27], v[112:115], v[64:67], v[24:27]
	v_mfma_f32_16x16x32_bf16 v[20:23], v[100:103], v[84:87], v[20:23]
	v_mfma_f32_16x16x32_bf16 v[16:19], v[112:115], v[80:83], v[16:19]
	v_mfma_f32_16x16x32_bf16 v[12:15], v[100:103], v[204:207], v[12:15]
	v_mfma_f32_16x16x32_bf16 v[8:11], v[112:115], v[200:203], v[8:11]
	v_mfma_f32_16x16x32_bf16 v[4:7], v[100:103], v[212:215], v[4:7]
	v_mfma_f32_16x16x32_bf16 v[0:3], v[112:115], v[208:211], v[0:3]
	v_mfma_f32_16x16x32_bf16 v[178:181], v[116:119], v[68:71], v[24:27]
	v_mfma_f32_16x16x32_bf16 v[182:185], v[116:119], v[84:87], v[16:19]
	v_mfma_f32_16x16x32_bf16 v[200:203], v[116:119], v[204:207], v[8:11]
	v_mfma_f32_16x16x32_bf16 v[204:207], v[116:119], v[212:215], v[0:3]
	s_barrier
	s_nop 1
	s_nop 0
	ds_read_b128 v[0:3], v154
	ds_read_b128 v[8:11], v154 offset:1024
	ds_read_b128 v[208:211], v154 offset:2048
	ds_read_b128 v[212:215], v154 offset:3072
	ds_read_b128 v[16:19], v131 offset:32768
	ds_read_b128 v[24:27], v131 offset:33792
	ds_read_b128 v[32:35], v174 offset:32768
	ds_read_b128 v[36:39], v174 offset:33792
	ds_read_b128 v[48:51], v175 offset:32768
	ds_read_b128 v[56:59], v175 offset:33792
	ds_read_b128 v[236:239], v177 offset:32768
	ds_read_b128 v[240:243], v177 offset:33792
	s_waitcnt vmcnt(2)
	s_barrier
; #define LDA(dst,b,h) _Pragma("unroll") for(int m=0;m<4;++m) _Pragma("unroll") for(int k=0;k<2;++k) \
;     dst[m][k]=*reinterpret_cast<const bf16x8*>((char*)SA(b,h)+lds_byte(wr*64+m*16+fr,k*32+fq*8))
; #define LDB(dst,b,h) _Pragma("unroll") for(int n=0;n<2;++n) _Pragma("unroll") for(int k=0;k<2;++k) \
;     dst[n][k]=*reinterpret_cast<const bf16x8*>((char*)SB(b,h)+lds_byte(wc*32+n*16+fr,k*32+fq*8))
; #define MMA(ai,bj,At_,Bt_) do{__builtin_amdgcn_s_setprio(1); \
;     _Pragma("unroll") for(int m=0;m<4;++m) _Pragma("unroll") for(int n=0;n<2;++n) _Pragma("unroll") for(int k=0;k<2;++k) \
;       acc[ai][bj][m][n]=__builtin_amdgcn_mfma_f32_16x16x32_bf16(Bt_[n][k],At_[m][k],acc[ai][bj][m][n],0,0,0); \
;     __builtin_amdgcn_s_setprio(0);}while(0)
; #define WAIT_V(n) asm volatile("s_waitcnt vmcnt(" #n ")":::"memory")
; #define WAIT_L(n) asm volatile("s_waitcnt lgkmcnt(" #n ")":::"memory")
; #define BAR __builtin_amdgcn_s_barrier()
; DEVINL void gemm8_mainloop(const u16* A, long lda, const u16* Bt, long ldb, int K, int brow, int bcol, f32x4 (&acc)[2][2][4][2], char* smem, int tid) {
;     ...
;   { LDB(B0,1,0); LDA(At,1,0); WAIT_V(2); BAR; WAIT_L(0); MMA(0,0,At,B0); BAR;
;     LDB(B1,1,1); WAIT_V(0); BAR; WAIT_L(0); MMA(0,1,At,B1); BAR;
;     LDA(At,1,1); BAR; WAIT_L(0); MMA(1,0,At,B0); MMA(1,1,At,B1); BAR; }
;   if(wr==0)BAR;
	s_waitcnt lgkmcnt(0)
	v_mfma_f32_16x16x32_bf16 v[64:67], v[0:3], v[16:19], v[124:127]
	v_mfma_f32_16x16x32_bf16 v[116:119], v[8:11], v[24:27], v[64:67]
	v_mfma_f32_16x16x32_bf16 v[64:67], v[208:211], v[16:19], v[120:123]
	v_mfma_f32_16x16x32_bf16 v[112:115], v[212:215], v[24:27], v[64:67]
	v_mfma_f32_16x16x32_bf16 v[64:67], v[0:3], v[32:35], v[140:143]
	v_mfma_f32_16x16x32_bf16 v[100:103], v[8:11], v[36:39], v[64:67]
	v_mfma_f32_16x16x32_bf16 v[64:67], v[208:211], v[32:35], v[220:223]
	v_mfma_f32_16x16x32_bf16 v[96:99], v[212:215], v[36:39], v[64:67]
	v_mfma_f32_16x16x32_bf16 v[64:67], v[0:3], v[48:51], v[108:111]
	v_mfma_f32_16x16x32_bf16 v[84:87], v[8:11], v[56:59], v[64:67]
	v_mfma_f32_16x16x32_bf16 v[64:67], v[208:211], v[48:51], v[104:107]
	v_mfma_f32_16x16x32_bf16 v[80:83], v[212:215], v[56:59], v[64:67]
	v_mfma_f32_16x16x32_bf16 v[64:67], v[0:3], v[236:239], v[224:227]
	v_mfma_f32_16x16x32_bf16 v[68:71], v[8:11], v[240:243], v[64:67]
	v_mfma_f32_16x16x32_bf16 v[64:67], v[208:211], v[236:239], v[228:231]
	v_mfma_f32_16x16x32_bf16 v[64:67], v[212:215], v[240:243], v[64:67]
	s_barrier
	ds_read_b128 v[140:143], v152
	ds_read_b128 v[220:223], v152 offset:1024
	ds_read_b128 v[224:227], v152 offset:2048
	ds_read_b128 v[152:155], v152 offset:3072
	s_waitcnt vmcnt(0)
	s_barrier
	s_waitcnt lgkmcnt(0)
	v_mfma_f32_16x16x32_bf16 v[92:95], v[140:143], v[16:19], v[92:95]
	v_mfma_f32_16x16x32_bf16 v[16:19], v[224:227], v[16:19], v[88:91]
	v_mfma_f32_16x16x32_bf16 v[120:123], v[152:155], v[24:27], v[16:19]
	v_mfma_f32_16x16x32_bf16 v[16:19], v[140:143], v[32:35], v[156:159]
	v_mfma_f32_16x16x32_bf16 v[104:107], v[220:223], v[36:39], v[16:19]
	v_mfma_f32_16x16x32_bf16 v[16:19], v[224:227], v[32:35], v[188:191]
	v_mfma_f32_16x16x32_bf16 v[108:111], v[152:155], v[36:39], v[16:19]
	v_mfma_f32_16x16x32_bf16 v[16:19], v[140:143], v[48:51], v[76:79]
	v_mfma_f32_16x16x32_bf16 v[124:127], v[220:223], v[24:27], v[92:95]
	v_mfma_f32_16x16x32_bf16 v[92:95], v[220:223], v[56:59], v[16:19]
	v_mfma_f32_16x16x32_bf16 v[16:19], v[224:227], v[48:51], v[72:75]
	v_mfma_f32_16x16x32_bf16 v[88:91], v[152:155], v[56:59], v[16:19]
	v_mfma_f32_16x16x32_bf16 v[16:19], v[140:143], v[236:239], v[192:195]
	v_mfma_f32_16x16x32_bf16 v[72:75], v[220:223], v[240:243], v[16:19]
	v_mfma_f32_16x16x32_bf16 v[16:19], v[224:227], v[236:239], v[196:199]
	v_mfma_f32_16x16x32_bf16 v[76:79], v[152:155], v[240:243], v[16:19]
	s_barrier
	ds_read_b128 v[156:159], v131 offset:49152
	ds_read_b128 v[186:189], v131 offset:50176
	ds_read_b128 v[190:193], v174 offset:49152
	ds_read_b128 v[194:197], v174 offset:50176
	ds_read_b128 v[228:231], v175 offset:49152
	ds_read_b128 v[236:239], v175 offset:50176
	ds_read_b128 v[240:243], v177 offset:49152
	ds_read_b128 v[244:247], v177 offset:50176
	s_barrier
	s_waitcnt lgkmcnt(0)
	v_mfma_f32_16x16x32_bf16 v[16:19], v[0:3], v[156:159], v[60:63]
	v_mfma_f32_16x16x32_bf16 v[56:59], v[8:11], v[186:189], v[16:19]
	v_mfma_f32_16x16x32_bf16 v[16:19], v[208:211], v[156:159], v[216:219]
	v_mfma_f32_16x16x32_bf16 v[48:51], v[212:215], v[186:189], v[16:19]
	v_mfma_f32_16x16x32_bf16 v[16:19], v[0:3], v[190:193], v[52:55]
	v_mfma_f32_16x16x32_bf16 v[36:39], v[8:11], v[194:197], v[16:19]
	v_mfma_f32_16x16x32_bf16 v[16:19], v[208:211], v[190:193], v[232:235]
	v_mfma_f32_16x16x32_bf16 v[32:35], v[212:215], v[194:197], v[16:19]
	v_mfma_f32_16x16x32_bf16 v[16:19], v[0:3], v[228:231], v[44:47]
	v_mfma_f32_16x16x32_bf16 v[0:3], v[0:3], v[240:243], v[144:147]
	v_mfma_f32_16x16x32_bf16 v[24:27], v[8:11], v[236:239], v[16:19]
	v_mfma_f32_16x16x32_bf16 v[16:19], v[208:211], v[228:231], v[40:43]
	v_mfma_f32_16x16x32_bf16 v[8:11], v[8:11], v[244:247], v[0:3]
	v_mfma_f32_16x16x32_bf16 v[0:3], v[208:211], v[240:243], v[148:151]
	v_mfma_f32_16x16x32_bf16 v[16:19], v[212:215], v[236:239], v[16:19]
	v_mfma_f32_16x16x32_bf16 v[0:3], v[212:215], v[244:247], v[0:3]
	v_mfma_f32_16x16x32_bf16 v[28:31], v[140:143], v[156:159], v[28:31]
	v_mfma_f32_16x16x32_bf16 v[60:63], v[220:223], v[186:189], v[28:31]
	v_mfma_f32_16x16x32_bf16 v[28:31], v[224:227], v[156:159], v[178:181]
	v_mfma_f32_16x16x32_bf16 v[20:23], v[140:143], v[190:193], v[20:23]
	v_mfma_f32_16x16x32_bf16 v[12:15], v[140:143], v[228:231], v[12:15]
	v_mfma_f32_16x16x32_bf16 v[52:55], v[152:155], v[186:189], v[28:31]
	v_mfma_f32_16x16x32_bf16 v[40:43], v[220:223], v[194:197], v[20:23]
	v_mfma_f32_16x16x32_bf16 v[20:23], v[224:227], v[190:193], v[182:185]
	v_mfma_f32_16x16x32_bf16 v[28:31], v[220:223], v[236:239], v[12:15]
	v_mfma_f32_16x16x32_bf16 v[12:15], v[224:227], v[228:231], v[200:203]
	v_mfma_f32_16x16x32_bf16 v[4:7], v[140:143], v[240:243], v[4:7]
	v_mfma_f32_16x16x32_bf16 v[44:47], v[152:155], v[194:197], v[20:23]
	v_mfma_f32_16x16x32_bf16 v[20:23], v[152:155], v[236:239], v[12:15]
	v_mfma_f32_16x16x32_bf16 v[12:15], v[220:223], v[244:247], v[4:7]
	v_mfma_f32_16x16x32_bf16 v[4:7], v[224:227], v[240:243], v[204:207]
	v_mfma_f32_16x16x32_bf16 v[4:7], v[152:155], v[244:247], v[4:7]
	s_setprio 0
	s_cmpk_gt_u32 s44, 0xff
	s_barrier
	s_cbranch_scc1 .LBB0_272
	s_barrier

; #define STAGE(P,BASE,LD,br,kt) do{long _g=(long)(br)*(LD)+(long)(kt)*BK; \
;     _Pragma("unroll") for(int _i=0;_i<2;++_i){int _b=tid*16+_i*8192;int _r,_c;stage_rc(_b,_r,_c); \
;       __builtin_amdgcn_global_load_lds((const unsigned*)((BASE)+_g+(long)_r*(LD)+_c), \
;         (unsigned*)((char*)(P)+_b),16,0,0);}}while(0)
; #define STAGE(P,BASE,LD,br,kt) do{long _g=(long)(br)*(LD)+(long)(kt)*BK; \
;     _Pragma("unroll") for(int _i=0;_i<2;++_i){int _b=tid*16+_i*8192;int _r,_c;stage_rc(_b,_r,_c); \
;       __builtin_amdgcn_global_load_lds((const unsigned*)((BASE)+_g+(long)_r*(LD)+_c), \
;         (unsigned*)((char*)(P)+_b),16,0,0);}}while(0)
; #define LDA(dst,b,h) _Pragma("unroll") for(int m=0;m<4;++m) _Pragma("unroll") for(int k=0;k<2;++k) \
;     dst[m][k]=*reinterpret_cast<const bf16x8*>((char*)SA(b,h)+lds_byte(wr*64+m*16+fr,k*32+fq*8))
; #define LDB(dst,b,h) _Pragma("unroll") for(int n=0;n<2;++n) _Pragma("unroll") for(int k=0;k<2;++k) \
;     dst[n][k]=*reinterpret_cast<const bf16x8*>((char*)SB(b,h)+lds_byte(wc*32+n*16+fr,k*32+fq*8))
; #define MMA(ai,bj,At_,Bt_) do{__builtin_amdgcn_s_setprio(1); \
;     _Pragma("unroll") for(int m=0;m<4;++m) _Pragma("unroll") for(int n=0;n<2;++n) _Pragma("unroll") for(int k=0;k<2;++k) \
;       acc[ai][bj][m][n]=__builtin_amdgcn_mfma_f32_16x16x32_bf16(Bt_[n][k],At_[m][k],acc[ai][bj][m][n],0,0,0); \
;     __builtin_amdgcn_s_setprio(0);}while(0)
; #define WAIT_L(n) asm volatile("s_waitcnt lgkmcnt(" #n ")":::"memory")
; #define BAR __builtin_amdgcn_s_barrier()
; #define SCHED __builtin_amdgcn_sched_barrier(0)
; DEVINL void gemm8_mainloop(const u16* A, long lda, const u16* Bt, long ldb, int K, int brow, int bcol, f32x4 (&acc)[2][2][4][2], char* smem, int tid) {
;     ...
;   for(int t=0;t<nt-2;t+=2){
;     LDB(B0,0,0); SCHED; LDA(At,0,0); STAGE(SA(1,1),A,lda,brow+HALF,t+1);
;     WAIT_L(8); BAR; WAIT_L(0); MMA(0,0,At,B0); BAR; SCHED;
;     LDB(B1,0,1); STAGE(SB(0,0),Bt,ldb,bcol,t+2);
;     BAR; WAIT_L(0); MMA(0,1,At,B1); BAR;
;     LDA(At,0,1); STAGE(SA(0,0),A,lda,brow,t+2);
.LBB0_849:
	ds_read_b128 v[178:181], v163
	ds_read_b128 v[182:185], v163 offset:1024
	ds_read_b128 v[186:189], v163 offset:2048
	ds_read_b128 v[190:193], v163 offset:3072
	v_add_u32_e32 v174, 0xc000, v152
	v_lshl_add_u64 v[242:243], s[94:95], 0, v[146:147]
	v_readfirstlane_b32 s27, v174
	v_add_u32_e32 v175, 0xe000, v152
	v_add_u32_e32 v171, s0, v162
	v_add_u32_e32 v172, s1, v162
	v_add_u32_e32 v173, s29, v162
	v_lshl_add_u64 v[164:165], v[242:243], 0, s[4:5]
	s_mov_b32 m0, s27
	v_lshl_add_u64 v[244:245], s[94:95], 0, v[148:149]
	v_readfirstlane_b32 s27, v175
	ds_read_b128 v[166:169], v153
	ds_read_b128 v[194:197], v153 offset:1024
	ds_read_b128 v[198:201], v171
	ds_read_b128 v[202:205], v171 offset:1024
	ds_read_b128 v[206:209], v172
	ds_read_b128 v[210:213], v172 offset:1024
	ds_read_b128 v[214:217], v173
	ds_read_b128 v[218:221], v173 offset:1024
	global_load_lds_dwordx4 v[164:165], off
	v_lshl_add_u64 v[164:165], v[244:245], 0, s[4:5]
	s_mov_b32 m0, s27
	s_nop 0
	global_load_lds_dwordx4 v[164:165], off
	s_waitcnt lgkmcnt(8)
	s_barrier
	s_waitcnt lgkmcnt(0)
	v_mfma_f32_16x16x32_bf16 v[124:127], v[178:181], v[166:169], v[124:127]
	v_mfma_f32_16x16x32_bf16 v[120:123], v[186:189], v[166:169], v[120:123]
	v_mfma_f32_16x16x32_bf16 v[116:119], v[178:181], v[198:201], v[116:119]
	v_mfma_f32_16x16x32_bf16 v[112:115], v[186:189], v[198:201], v[112:115]
	v_mfma_f32_16x16x32_bf16 v[108:111], v[178:181], v[206:209], v[108:111]
	v_mfma_f32_16x16x32_bf16 v[104:107], v[186:189], v[206:209], v[104:107]
	v_mfma_f32_16x16x32_bf16 v[100:103], v[178:181], v[214:217], v[100:103]
	v_mfma_f32_16x16x32_bf16 v[96:99], v[186:189], v[214:217], v[96:99]
	v_mfma_f32_16x16x32_bf16 v[124:127], v[182:185], v[194:197], v[124:127]
	v_mfma_f32_16x16x32_bf16 v[120:123], v[190:193], v[194:197], v[120:123]
	v_mfma_f32_16x16x32_bf16 v[116:119], v[182:185], v[202:205], v[116:119]
	v_mfma_f32_16x16x32_bf16 v[112:115], v[190:193], v[202:205], v[112:115]
	v_mfma_f32_16x16x32_bf16 v[108:111], v[182:185], v[210:213], v[108:111]
	v_mfma_f32_16x16x32_bf16 v[104:107], v[190:193], v[210:213], v[104:107]
	v_mfma_f32_16x16x32_bf16 v[100:103], v[182:185], v[218:221], v[100:103]
	v_mfma_f32_16x16x32_bf16 v[96:99], v[190:193], v[218:221], v[96:99]
	s_barrier
	v_add_u32_e32 v164, s33, v154
	v_lshl_add_u64 v[246:247], s[94:95], 0, v[142:143]
	v_readfirstlane_b32 s27, v164
	v_add_u32_e32 v165, 0x2000, v164
	v_lshl_add_u64 v[238:239], v[246:247], 0, s[6:7]
	s_mov_b32 m0, s27
	v_lshl_add_u64 v[248:249], s[94:95], 0, v[144:145]
	v_readfirstlane_b32 s27, v165
	ds_read_b128 v[222:225], v160
	ds_read_b128 v[226:229], v160 offset:1024
	ds_read_b128 v[230:233], v160 offset:2048
	ds_read_b128 v[234:237], v160 offset:3072
	global_load_lds_dwordx4 v[238:239], off
	v_lshl_add_u64 v[238:239], v[248:249], 0, s[6:7]
	s_mov_b32 m0, s27
	s_nop 0
	global_load_lds_dwordx4 v[238:239], off
	s_barrier
	s_waitcnt lgkmcnt(0)
	v_mfma_f32_16x16x32_bf16 v[92:95], v[222:225], v[166:169], v[92:95]
	v_mfma_f32_16x16x32_bf16 v[88:91], v[230:233], v[166:169], v[88:91]
	v_mfma_f32_16x16x32_bf16 v[84:87], v[222:225], v[198:201], v[84:87]
	v_mfma_f32_16x16x32_bf16 v[80:83], v[230:233], v[198:201], v[80:83]
	v_mfma_f32_16x16x32_bf16 v[76:79], v[222:225], v[206:209], v[76:79]
	v_mfma_f32_16x16x32_bf16 v[72:75], v[230:233], v[206:209], v[72:75]
	v_mfma_f32_16x16x32_bf16 v[68:71], v[222:225], v[214:217], v[68:71]
	v_mfma_f32_16x16x32_bf16 v[64:67], v[230:233], v[214:217], v[64:67]
	v_mfma_f32_16x16x32_bf16 v[92:95], v[226:229], v[194:197], v[92:95]
	v_mfma_f32_16x16x32_bf16 v[88:91], v[234:237], v[194:197], v[88:91]
	v_mfma_f32_16x16x32_bf16 v[84:87], v[226:229], v[202:205], v[84:87]
	v_mfma_f32_16x16x32_bf16 v[80:83], v[234:237], v[202:205], v[80:83]
	v_mfma_f32_16x16x32_bf16 v[76:79], v[226:229], v[210:213], v[76:79]
	v_mfma_f32_16x16x32_bf16 v[72:75], v[234:237], v[210:213], v[72:75]
	v_mfma_f32_16x16x32_bf16 v[68:71], v[226:229], v[218:221], v[68:71]
	v_mfma_f32_16x16x32_bf16 v[64:67], v[234:237], v[218:221], v[64:67]
	v_readfirstlane_b32 s27, v152
	v_lshl_add_u64 v[166:167], v[242:243], 0, s[8:9]
	s_mov_b32 m0, s27
	s_barrier
	ds_read_b128 v[194:197], v153 offset:16384
	ds_read_b128 v[198:201], v153 offset:17408
	ds_read_b128 v[202:205], v171 offset:16384
	ds_read_b128 v[206:209], v171 offset:17408
	ds_read_b128 v[210:213], v172 offset:16384
	ds_read_b128 v[214:217], v172 offset:17408
	ds_read_b128 v[218:221], v173 offset:16384
	ds_read_b128 v[238:241], v173 offset:17408
	global_load_lds_dwordx4 v[166:167], off
	v_add_u32_e32 v166, 0x2000, v152
	v_lshl_add_u64 v[168:169], v[244:245], 0, s[8:9]
	v_readfirstlane_b32 s27, v166
	s_mov_b32 m0, s27
	s_nop 0
	global_load_lds_dwordx4 v[168:169], off
	s_barrier
	s_waitcnt lgkmcnt(0)
	v_mfma_f32_16x16x32_bf16 v[60:63], v[178:181], v[194:197], v[60:63]
	v_mfma_f32_16x16x32_bf16 v[56:59], v[186:189], v[194:197], v[56:59]
	v_mfma_f32_16x16x32_bf16 v[52:55], v[178:181], v[202:205], v[52:55]
	v_mfma_f32_16x16x32_bf16 v[48:51], v[186:189], v[202:205], v[48:51]
	v_mfma_f32_16x16x32_bf16 v[44:47], v[178:181], v[210:213], v[44:47]
	v_mfma_f32_16x16x32_bf16 v[40:43], v[186:189], v[210:213], v[40:43]
	v_mfma_f32_16x16x32_bf16 v[36:39], v[178:181], v[218:221], v[36:39]
	v_mfma_f32_16x16x32_bf16 v[32:35], v[186:189], v[218:221], v[32:35]
	v_mfma_f32_16x16x32_bf16 v[60:63], v[182:185], v[198:201], v[60:63]
	v_mfma_f32_16x16x32_bf16 v[56:59], v[190:193], v[198:201], v[56:59]
	v_mfma_f32_16x16x32_bf16 v[52:55], v[182:185], v[206:209], v[52:55]
	v_mfma_f32_16x16x32_bf16 v[48:51], v[190:193], v[206:209], v[48:51]
	v_mfma_f32_16x16x32_bf16 v[44:47], v[182:185], v[214:217], v[44:47]
	v_mfma_f32_16x16x32_bf16 v[40:43], v[190:193], v[214:217], v[40:43]
	v_mfma_f32_16x16x32_bf16 v[36:39], v[182:185], v[238:241], v[36:39]
	v_mfma_f32_16x16x32_bf16 v[32:35], v[190:193], v[238:241], v[32:35]
	s_barrier
; #define STAGE(P,BASE,LD,br,kt) do{long _g=(long)(br)*(LD)+(long)(kt)*BK; \
;     _Pragma("unroll") for(int _i=0;_i<2;++_i){int _b=tid*16+_i*8192;int _r,_c;stage_rc(_b,_r,_c); \
;       __builtin_amdgcn_global_load_lds((const unsigned*)((BASE)+_g+(long)_r*(LD)+_c), \
;         (unsigned*)((char*)(P)+_b),16,0,0);}}while(0)
; #define STAGE(P,BASE,LD,br,kt) do{long _g=(long)(br)*(LD)+(long)(kt)*BK; \
;     _Pragma("unroll") for(int _i=0;_i<2;++_i){int _b=tid*16+_i*8192;int _r,_c;stage_rc(_b,_r,_c); \
;       __builtin_amdgcn_global_load_lds((const unsigned*)((BASE)+_g+(long)_r*(LD)+_c), \
;         (unsigned*)((char*)(P)+_b),16,0,0);}}while(0)
; #define LDA(dst,b,h) _Pragma("unroll") for(int m=0;m<4;++m) _Pragma("unroll") for(int k=0;k<2;++k) \
;     dst[m][k]=*reinterpret_cast<const bf16x8*>((char*)SA(b,h)+lds_byte(wr*64+m*16+fr,k*32+fq*8))
; #define LDB(dst,b,h) _Pragma("unroll") for(int n=0;n<2;++n) _Pragma("unroll") for(int k=0;k<2;++k) \
;     dst[n][k]=*reinterpret_cast<const bf16x8*>((char*)SB(b,h)+lds_byte(wc*32+n*16+fr,k*32+fq*8))
; #define MMA(ai,bj,At_,Bt_) do{__builtin_amdgcn_s_setprio(1); \
;     _Pragma("unroll") for(int m=0;m<4;++m) _Pragma("unroll") for(int n=0;n<2;++n) _Pragma("unroll") for(int k=0;k<2;++k) \
;       acc[ai][bj][m][n]=__builtin_amdgcn_mfma_f32_16x16x32_bf16(Bt_[n][k],At_[m][k],acc[ai][bj][m][n],0,0,0); \
;     __builtin_amdgcn_s_setprio(0);}while(0)
; #define WAIT_V(n) asm volatile("s_waitcnt vmcnt(" #n ")":::"memory")
; #define WAIT_L(n) asm volatile("s_waitcnt lgkmcnt(" #n ")":::"memory")
; #define BAR __builtin_amdgcn_s_barrier()
; #define SCHED __builtin_amdgcn_sched_barrier(0)
; DEVINL void gemm8_mainloop(const u16* A, long lda, const u16* Bt, long ldb, int K, int brow, int bcol, f32x4 (&acc)[2][2][4][2], char* smem, int tid) {
;     ...
;     LDA(At,0,1); STAGE(SA(0,0),A,lda,brow,t+2);
;     BAR; WAIT_L(0); MMA(1,0,At,B0); BAR; SCHED;
;     STAGE(SB(0,1),Bt,ldb,bcol+HALF,t+2);
;     WAIT_V(6); BAR; MMA(1,1,At,B1); BAR;
;     LDB(B0,1,0); SCHED; LDA(At,1,0); STAGE(SA(0,1),A,lda,brow+HALF,t+2);
;     WAIT_L(8); BAR; WAIT_L(0); MMA(0,0,At,B0); BAR; SCHED;
;     LDB(B1,1,1); STAGE(SB(1,0),Bt,ldb,bcol,t+3);
	v_add_u32_e32 v167, s34, v154
	v_lshl_add_u64 v[168:169], v[246:247], 0, s[10:11]
	v_readfirstlane_b32 s27, v167
	s_mov_b32 m0, s27
	v_lshl_add_u64 v[178:179], v[248:249], 0, s[10:11]
	global_load_lds_dwordx4 v[168:169], off
	v_add_u32_e32 v168, 0x2000, v167
	s_nop 0
	v_readfirstlane_b32 s27, v168
	s_mov_b32 m0, s27
	s_nop 0
	global_load_lds_dwordx4 v[178:179], off
	s_waitcnt vmcnt(6)
	s_barrier
	v_mfma_f32_16x16x32_bf16 v[28:31], v[222:225], v[194:197], v[28:31]
	v_mfma_f32_16x16x32_bf16 v[24:27], v[230:233], v[194:197], v[24:27]
	v_mfma_f32_16x16x32_bf16 v[20:23], v[222:225], v[202:205], v[20:23]
	v_mfma_f32_16x16x32_bf16 v[16:19], v[230:233], v[202:205], v[16:19]
	v_mfma_f32_16x16x32_bf16 v[12:15], v[222:225], v[210:213], v[12:15]
	v_mfma_f32_16x16x32_bf16 v[8:11], v[230:233], v[210:213], v[8:11]
	v_mfma_f32_16x16x32_bf16 v[4:7], v[222:225], v[218:221], v[4:7]
	v_mfma_f32_16x16x32_bf16 v[0:3], v[230:233], v[218:221], v[0:3]
	v_mfma_f32_16x16x32_bf16 v[28:31], v[226:229], v[198:201], v[28:31]
	v_mfma_f32_16x16x32_bf16 v[24:27], v[234:237], v[198:201], v[24:27]
	v_mfma_f32_16x16x32_bf16 v[20:23], v[226:229], v[206:209], v[20:23]
	v_mfma_f32_16x16x32_bf16 v[16:19], v[234:237], v[206:209], v[16:19]
	v_mfma_f32_16x16x32_bf16 v[12:15], v[226:229], v[214:217], v[12:15]
	v_mfma_f32_16x16x32_bf16 v[8:11], v[234:237], v[214:217], v[8:11]
	v_mfma_f32_16x16x32_bf16 v[4:7], v[226:229], v[238:241], v[4:7]
	v_mfma_f32_16x16x32_bf16 v[0:3], v[234:237], v[238:241], v[0:3]
	s_barrier
	ds_read_b128 v[178:181], v157
	ds_read_b128 v[182:185], v157 offset:1024
	ds_read_b128 v[186:189], v157 offset:2048
	ds_read_b128 v[190:193], v157 offset:3072
	v_add_u32_e32 v169, 0x4000, v152
	v_add_u32_e32 v170, 0x6000, v152
	v_readfirstlane_b32 s27, v169
	v_lshl_add_u64 v[226:227], v[242:243], 0, s[12:13]
	s_mov_b32 m0, s27
	v_readfirstlane_b32 s27, v170
	ds_read_b128 v[194:197], v153 offset:32768
	ds_read_b128 v[198:201], v153 offset:33792
	ds_read_b128 v[202:205], v171 offset:32768
	ds_read_b128 v[206:209], v171 offset:33792
	ds_read_b128 v[210:213], v172 offset:32768
	ds_read_b128 v[214:217], v172 offset:33792
	ds_read_b128 v[218:221], v173 offset:32768
	ds_read_b128 v[222:225], v173 offset:33792
	global_load_lds_dwordx4 v[226:227], off
	v_lshl_add_u64 v[226:227], v[244:245], 0, s[12:13]
	s_mov_b32 m0, s27
	s_nop 0
	global_load_lds_dwordx4 v[226:227], off
	s_waitcnt lgkmcnt(8)
	s_barrier
	s_waitcnt lgkmcnt(0)
	v_mfma_f32_16x16x32_bf16 v[124:127], v[178:181], v[194:197], v[124:127]
	v_mfma_f32_16x16x32_bf16 v[120:123], v[186:189], v[194:197], v[120:123]
	v_mfma_f32_16x16x32_bf16 v[116:119], v[178:181], v[202:205], v[116:119]
	v_mfma_f32_16x16x32_bf16 v[112:115], v[186:189], v[202:205], v[112:115]
	v_mfma_f32_16x16x32_bf16 v[108:111], v[178:181], v[210:213], v[108:111]
	v_mfma_f32_16x16x32_bf16 v[104:107], v[186:189], v[210:213], v[104:107]
	v_mfma_f32_16x16x32_bf16 v[100:103], v[178:181], v[218:221], v[100:103]
	v_mfma_f32_16x16x32_bf16 v[96:99], v[186:189], v[218:221], v[96:99]
	v_mfma_f32_16x16x32_bf16 v[124:127], v[182:185], v[198:201], v[124:127]
	v_mfma_f32_16x16x32_bf16 v[120:123], v[190:193], v[198:201], v[120:123]
	v_mfma_f32_16x16x32_bf16 v[116:119], v[182:185], v[206:209], v[116:119]
	v_mfma_f32_16x16x32_bf16 v[112:115], v[190:193], v[206:209], v[112:115]
	v_mfma_f32_16x16x32_bf16 v[108:111], v[182:185], v[214:217], v[108:111]
	v_mfma_f32_16x16x32_bf16 v[104:107], v[190:193], v[214:217], v[104:107]
	v_mfma_f32_16x16x32_bf16 v[100:103], v[182:185], v[222:225], v[100:103]
	v_mfma_f32_16x16x32_bf16 v[96:99], v[190:193], v[222:225], v[96:99]
	s_barrier
	v_readfirstlane_b32 s27, v156
	v_add_u32_e32 v177, 0x2000, v156
	v_lshl_add_u64 v[250:251], v[246:247], 0, s[14:15]
	s_mov_b32 m0, s27
	v_readfirstlane_b32 s27, v177
	ds_read_b128 v[226:229], v155
	ds_read_b128 v[230:233], v155 offset:1024
	ds_read_b128 v[234:237], v155 offset:2048
	ds_read_b128 v[238:241], v155 offset:3072
	global_load_lds_dwordx4 v[250:251], off
	v_lshl_add_u64 v[250:251], v[248:249], 0, s[14:15]
	s_mov_b32 m0, s27
	s_nop 0
	global_load_lds_dwordx4 v[250:251], off
	s_barrier
	s_waitcnt lgkmcnt(0)
	v_mfma_f32_16x16x32_bf16 v[92:95], v[226:229], v[194:197], v[92:95]
	v_mfma_f32_16x16x32_bf16 v[88:91], v[234:237], v[194:197], v[88:91]
	v_mfma_f32_16x16x32_bf16 v[84:87], v[226:229], v[202:205], v[84:87]
	v_mfma_f32_16x16x32_bf16 v[80:83], v[234:237], v[202:205], v[80:83]
	v_mfma_f32_16x16x32_bf16 v[76:79], v[226:229], v[210:213], v[76:79]
	v_mfma_f32_16x16x32_bf16 v[72:75], v[234:237], v[210:213], v[72:75]
	v_mfma_f32_16x16x32_bf16 v[68:71], v[226:229], v[218:221], v[68:71]
	v_mfma_f32_16x16x32_bf16 v[64:67], v[234:237], v[218:221], v[64:67]
	v_mfma_f32_16x16x32_bf16 v[92:95], v[230:233], v[198:201], v[92:95]
	v_mfma_f32_16x16x32_bf16 v[88:91], v[238:241], v[198:201], v[88:91]
	v_mfma_f32_16x16x32_bf16 v[84:87], v[230:233], v[206:209], v[84:87]
	v_mfma_f32_16x16x32_bf16 v[80:83], v[238:241], v[206:209], v[80:83]
	v_mfma_f32_16x16x32_bf16 v[76:79], v[230:233], v[214:217], v[76:79]
	v_mfma_f32_16x16x32_bf16 v[72:75], v[238:241], v[214:217], v[72:75]
	v_mfma_f32_16x16x32_bf16 v[68:71], v[230:233], v[222:225], v[68:71]
	v_mfma_f32_16x16x32_bf16 v[64:67], v[238:241], v[222:225], v[64:67]
	v_readfirstlane_b32 s27, v158
	v_lshl_add_u64 v[242:243], v[242:243], 0, s[16:17]
	s_mov_b32 m0, s27
	v_readfirstlane_b32 s27, v159
	s_barrier
	ds_read_b128 v[194:197], v153 offset:49152
	ds_read_b128 v[198:201], v153 offset:50176
	ds_read_b128 v[202:205], v171 offset:49152
	ds_read_b128 v[206:209], v171 offset:50176
	ds_read_b128 v[210:213], v172 offset:49152
	ds_read_b128 v[214:217], v172 offset:50176
	ds_read_b128 v[218:221], v173 offset:49152
	ds_read_b128 v[222:225], v173 offset:50176
	global_load_lds_dwordx4 v[242:243], off
	v_lshl_add_u64 v[242:243], v[244:245], 0, s[16:17]
	s_mov_b32 m0, s27
	s_nop 0
	global_load_lds_dwordx4 v[242:243], off
	s_barrier
; #define STAGE(P,BASE,LD,br,kt) do{long _g=(long)(br)*(LD)+(long)(kt)*BK; \
;     _Pragma("unroll") for(int _i=0;_i<2;++_i){int _b=tid*16+_i*8192;int _r,_c;stage_rc(_b,_r,_c); \
;       __builtin_amdgcn_global_load_lds((const unsigned*)((BASE)+_g+(long)_r*(LD)+_c), \
;         (unsigned*)((char*)(P)+_b),16,0,0);}}while(0)
; #define STAGE(P,BASE,LD,br,kt) do{long _g=(long)(br)*(LD)+(long)(kt)*BK; \
;     _Pragma("unroll") for(int _i=0;_i<2;++_i){int _b=tid*16+_i*8192;int _r,_c;stage_rc(_b,_r,_c); \
;       __builtin_amdgcn_global_load_lds((const unsigned*)((BASE)+_g+(long)_r*(LD)+_c), \
;         (unsigned*)((char*)(P)+_b),16,0,0);}}while(0)
; #define LDA(dst,b,h) _Pragma("unroll") for(int m=0;m<4;++m) _Pragma("unroll") for(int k=0;k<2;++k) \
;     dst[m][k]=*reinterpret_cast<const bf16x8*>((char*)SA(b,h)+lds_byte(wr*64+m*16+fr,k*32+fq*8))
; #define LDB(dst,b,h) _Pragma("unroll") for(int n=0;n<2;++n) _Pragma("unroll") for(int k=0;k<2;++k) \
;     dst[n][k]=*reinterpret_cast<const bf16x8*>((char*)SB(b,h)+lds_byte(wc*32+n*16+fr,k*32+fq*8))
; #define MMA(ai,bj,At_,Bt_) do{__builtin_amdgcn_s_setprio(1); \
;     _Pragma("unroll") for(int m=0;m<4;++m) _Pragma("unroll") for(int n=0;n<2;++n) _Pragma("unroll") for(int k=0;k<2;++k) \
;       acc[ai][bj][m][n]=__builtin_amdgcn_mfma_f32_16x16x32_bf16(Bt_[n][k],At_[m][k],acc[ai][bj][m][n],0,0,0); \
;     __builtin_amdgcn_s_setprio(0);}while(0)
; #define WAIT_V(n) asm volatile("s_waitcnt vmcnt(" #n ")":::"memory")
; #define WAIT_L(n) asm volatile("s_waitcnt lgkmcnt(" #n ")":::"memory")
; #define BAR __builtin_amdgcn_s_barrier()
; #define SCHED __builtin_amdgcn_sched_barrier(0)
; DEVINL void gemm8_mainloop(const u16* A, long lda, const u16* Bt, long ldb, int K, int brow, int bcol, f32x4 (&acc)[2][2][4][2], char* smem, int tid) {
;     ...
;     LDB(B1,1,1); STAGE(SB(1,0),Bt,ldb,bcol,t+3);
;     BAR; WAIT_L(0); MMA(0,1,At,B1); BAR;
;     LDA(At,1,1); STAGE(SA(1,0),A,lda,brow,t+3);
;     BAR; WAIT_L(0); MMA(1,0,At,B0); BAR; SCHED;
;     STAGE(SB(1,1),Bt,ldb,bcol+HALF,t+3);
;     WAIT_V(6); BAR; MMA(1,1,At,B1); BAR;
;   }
;   { LDB(B0,0,0); LDA(At,0,0); STAGE(SA(1,1),A,lda,brow+HALF,nt-1);
;     BAR; WAIT_L(0); MMA(0,0,At,B0); BAR;
	s_waitcnt lgkmcnt(0)
	v_mfma_f32_16x16x32_bf16 v[60:63], v[178:181], v[194:197], v[60:63]
	v_mfma_f32_16x16x32_bf16 v[56:59], v[186:189], v[194:197], v[56:59]
	v_mfma_f32_16x16x32_bf16 v[52:55], v[178:181], v[202:205], v[52:55]
	v_mfma_f32_16x16x32_bf16 v[48:51], v[186:189], v[202:205], v[48:51]
	v_mfma_f32_16x16x32_bf16 v[44:47], v[178:181], v[210:213], v[44:47]
	v_mfma_f32_16x16x32_bf16 v[40:43], v[186:189], v[210:213], v[40:43]
	v_mfma_f32_16x16x32_bf16 v[36:39], v[178:181], v[218:221], v[36:39]
	v_mfma_f32_16x16x32_bf16 v[32:35], v[186:189], v[218:221], v[32:35]
	v_mfma_f32_16x16x32_bf16 v[60:63], v[182:185], v[198:201], v[60:63]
	v_mfma_f32_16x16x32_bf16 v[56:59], v[190:193], v[198:201], v[56:59]
	v_mfma_f32_16x16x32_bf16 v[52:55], v[182:185], v[206:209], v[52:55]
	v_mfma_f32_16x16x32_bf16 v[48:51], v[190:193], v[206:209], v[48:51]
	v_mfma_f32_16x16x32_bf16 v[44:47], v[182:185], v[214:217], v[44:47]
	v_mfma_f32_16x16x32_bf16 v[40:43], v[190:193], v[214:217], v[40:43]
	v_mfma_f32_16x16x32_bf16 v[36:39], v[182:185], v[222:225], v[36:39]
	v_mfma_f32_16x16x32_bf16 v[32:35], v[190:193], v[222:225], v[32:35]
	s_barrier
	v_readfirstlane_b32 s27, v161
	v_add_u32_e32 v177, 0x2000, v161
	v_lshl_add_u64 v[178:179], v[246:247], 0, s[18:19]
	s_mov_b32 m0, s27
	v_readfirstlane_b32 s27, v177
	global_load_lds_dwordx4 v[178:179], off
	v_lshl_add_u64 v[178:179], v[248:249], 0, s[18:19]
	s_mov_b32 m0, s27
	s_nop 0
	global_load_lds_dwordx4 v[178:179], off
	s_waitcnt vmcnt(6)
	s_barrier
	v_mfma_f32_16x16x32_bf16 v[28:31], v[226:229], v[194:197], v[28:31]
	v_mfma_f32_16x16x32_bf16 v[24:27], v[234:237], v[194:197], v[24:27]
	v_mfma_f32_16x16x32_bf16 v[20:23], v[226:229], v[202:205], v[20:23]
	v_mfma_f32_16x16x32_bf16 v[16:19], v[234:237], v[202:205], v[16:19]
	v_mfma_f32_16x16x32_bf16 v[12:15], v[226:229], v[210:213], v[12:15]
	v_mfma_f32_16x16x32_bf16 v[8:11], v[234:237], v[210:213], v[8:11]
	v_mfma_f32_16x16x32_bf16 v[4:7], v[226:229], v[218:221], v[4:7]
	v_mfma_f32_16x16x32_bf16 v[0:3], v[234:237], v[218:221], v[0:3]
	v_mfma_f32_16x16x32_bf16 v[28:31], v[230:233], v[198:201], v[28:31]
	v_mfma_f32_16x16x32_bf16 v[24:27], v[238:241], v[198:201], v[24:27]
	v_mfma_f32_16x16x32_bf16 v[20:23], v[230:233], v[206:209], v[20:23]
	v_mfma_f32_16x16x32_bf16 v[16:19], v[238:241], v[206:209], v[16:19]
	v_mfma_f32_16x16x32_bf16 v[12:15], v[230:233], v[214:217], v[12:15]
	v_mfma_f32_16x16x32_bf16 v[8:11], v[238:241], v[214:217], v[8:11]
	v_mfma_f32_16x16x32_bf16 v[4:7], v[230:233], v[222:225], v[4:7]
	v_mfma_f32_16x16x32_bf16 v[0:3], v[238:241], v[222:225], v[0:3]
	s_add_i32 s26, s26, 2
	v_lshl_add_u64 v[142:143], v[142:143], 0, s[20:21]
	v_lshl_add_u64 v[144:145], v[144:145], 0, s[20:21]
	v_lshl_add_u64 v[146:147], v[146:147], 0, s[20:21]
	s_cmp_lt_u32 s26, 28
	v_lshl_add_u64 v[148:149], v[148:149], 0, s[20:21]
	s_barrier
	s_cbranch_scc1 .LBB0_849
	s_or_b32 s0, s28, 0x80
	s_ashr_i32 s1, s0, 31
	s_lshl_b64 s[0:1], s[0:1], 12
	s_add_u32 s0, s58, s0
	s_addc_u32 s1, s59, s1
	v_lshl_add_u64 v[158:159], v[134:135], 1, s[0:1]
	v_lshl_add_u64 v[138:139], v[138:139], 1, v[158:159]
	v_readfirstlane_b32 s26, v174
	v_lshl_add_u64 v[138:139], v[138:139], 0, s[22:23]
	s_mov_b32 m0, s26
	ds_read_b128 v[142:145], v163
	ds_read_b128 v[146:149], v163 offset:1024
	ds_read_b128 v[178:181], v163 offset:2048
	ds_read_b128 v[182:185], v163 offset:3072
	ds_read_b128 v[186:189], v153
	ds_read_b128 v[190:193], v153 offset:1024
	ds_read_b128 v[194:197], v171
	ds_read_b128 v[198:201], v171 offset:1024
	ds_read_b128 v[202:205], v172
	ds_read_b128 v[206:209], v172 offset:1024
	ds_read_b128 v[210:213], v173
	ds_read_b128 v[214:217], v173 offset:1024
	global_load_lds_dwordx4 v[138:139], off
	v_lshl_add_u64 v[138:139], v[136:137], 1, s[0:1]
	v_lshl_add_u64 v[138:139], v[140:141], 1, v[138:139]
	v_readfirstlane_b32 s0, v175
	v_lshl_add_u64 v[138:139], v[138:139], 0, s[22:23]
	s_mov_b32 m0, s0
	s_nop 0
	global_load_lds_dwordx4 v[138:139], off
	s_barrier
	s_waitcnt lgkmcnt(0)
	v_mfma_f32_16x16x32_bf16 v[124:127], v[142:145], v[186:189], v[124:127]
	v_mfma_f32_16x16x32_bf16 v[120:123], v[178:181], v[186:189], v[120:123]
	v_mfma_f32_16x16x32_bf16 v[112:115], v[178:181], v[194:197], v[112:115]
	v_mfma_f32_16x16x32_bf16 v[104:107], v[178:181], v[202:205], v[104:107]
	v_mfma_f32_16x16x32_bf16 v[96:99], v[178:181], v[210:213], v[96:99]
	v_mfma_f32_16x16x32_bf16 v[124:127], v[146:149], v[190:193], v[124:127]
	v_mfma_f32_16x16x32_bf16 v[120:123], v[182:185], v[190:193], v[120:123]
	v_mfma_f32_16x16x32_bf16 v[116:119], v[142:145], v[194:197], v[116:119]
	v_mfma_f32_16x16x32_bf16 v[112:115], v[182:185], v[198:201], v[112:115]
	v_mfma_f32_16x16x32_bf16 v[108:111], v[142:145], v[202:205], v[108:111]
	v_mfma_f32_16x16x32_bf16 v[104:107], v[182:185], v[206:209], v[104:107]
	v_mfma_f32_16x16x32_bf16 v[100:103], v[142:145], v[210:213], v[100:103]
	v_mfma_f32_16x16x32_bf16 v[96:99], v[182:185], v[214:217], v[96:99]
	v_mfma_f32_16x16x32_bf16 v[138:141], v[146:149], v[198:201], v[116:119]
	v_mfma_f32_16x16x32_bf16 v[218:221], v[146:149], v[206:209], v[108:111]
	v_mfma_f32_16x16x32_bf16 v[222:225], v[146:149], v[214:217], v[100:103]
	s_barrier
	s_nop 1
	s_nop 0
	ds_read_b128 v[100:103], v160
	ds_read_b128 v[108:111], v160 offset:1024
	ds_read_b128 v[116:119], v160 offset:2048
	ds_read_b128 v[158:161], v160 offset:3072
	s_barrier
; #define LDA(dst,b,h) _Pragma("unroll") for(int m=0;m<4;++m) _Pragma("unroll") for(int k=0;k<2;++k) \
;     dst[m][k]=*reinterpret_cast<const bf16x8*>((char*)SA(b,h)+lds_byte(wr*64+m*16+fr,k*32+fq*8))
; #define LDB(dst,b,h) _Pragma("unroll") for(int n=0;n<2;++n) _Pragma("unroll") for(int k=0;k<2;++k) \
;     dst[n][k]=*reinterpret_cast<const bf16x8*>((char*)SB(b,h)+lds_byte(wc*32+n*16+fr,k*32+fq*8))
; #define MMA(ai,bj,At_,Bt_) do{__builtin_amdgcn_s_setprio(1); \
;     _Pragma("unroll") for(int m=0;m<4;++m) _Pragma("unroll") for(int n=0;n<2;++n) _Pragma("unroll") for(int k=0;k<2;++k) \
;       acc[ai][bj][m][n]=__builtin_amdgcn_mfma_f32_16x16x32_bf16(Bt_[n][k],At_[m][k],acc[ai][bj][m][n],0,0,0); \
;     __builtin_amdgcn_s_setprio(0);}while(0)
; #define WAIT_V(n) asm volatile("s_waitcnt vmcnt(" #n ")":::"memory")
; #define WAIT_L(n) asm volatile("s_waitcnt lgkmcnt(" #n ")":::"memory")
; #define BAR __builtin_amdgcn_s_barrier()
; DEVINL void gemm8_mainloop(const u16* A, long lda, const u16* Bt, long ldb, int K, int brow, int bcol, f32x4 (&acc)[2][2][4][2], char* smem, int tid) {
;     ...
;     BAR; WAIT_L(0); MMA(0,0,At,B0); BAR;
;     LDB(B1,0,1); BAR; WAIT_L(0); MMA(0,1,At,B1); BAR;
;     LDA(At,0,1); WAIT_V(4); BAR; WAIT_L(0); MMA(1,0,At,B0); MMA(1,1,At,B1); BAR; }
;   { LDB(B0,1,0); LDA(At,1,0); WAIT_V(2); BAR; WAIT_L(0); MMA(0,0,At,B0); BAR;
	s_waitcnt lgkmcnt(0)
	v_mfma_f32_16x16x32_bf16 v[88:91], v[116:119], v[186:189], v[88:91]
	v_mfma_f32_16x16x32_bf16 v[80:83], v[116:119], v[194:197], v[80:83]
	v_mfma_f32_16x16x32_bf16 v[72:75], v[116:119], v[202:205], v[72:75]
	v_mfma_f32_16x16x32_bf16 v[64:67], v[116:119], v[210:213], v[64:67]
	v_mfma_f32_16x16x32_bf16 v[92:95], v[100:103], v[186:189], v[92:95]
	v_mfma_f32_16x16x32_bf16 v[88:91], v[158:161], v[190:193], v[88:91]
	v_mfma_f32_16x16x32_bf16 v[84:87], v[100:103], v[194:197], v[84:87]
	v_mfma_f32_16x16x32_bf16 v[80:83], v[158:161], v[198:201], v[80:83]
	v_mfma_f32_16x16x32_bf16 v[76:79], v[100:103], v[202:205], v[76:79]
	v_mfma_f32_16x16x32_bf16 v[72:75], v[158:161], v[206:209], v[72:75]
	v_mfma_f32_16x16x32_bf16 v[68:71], v[100:103], v[210:213], v[68:71]
	v_mfma_f32_16x16x32_bf16 v[64:67], v[158:161], v[214:217], v[64:67]
	v_mfma_f32_16x16x32_bf16 v[226:229], v[108:111], v[190:193], v[92:95]
	v_mfma_f32_16x16x32_bf16 v[186:189], v[108:111], v[198:201], v[84:87]
	v_mfma_f32_16x16x32_bf16 v[190:193], v[108:111], v[206:209], v[76:79]
	v_mfma_f32_16x16x32_bf16 v[194:197], v[108:111], v[214:217], v[68:71]
	s_barrier
	s_nop 0
	s_nop 0
	ds_read_b128 v[68:71], v153 offset:16384
	ds_read_b128 v[76:79], v153 offset:17408
	ds_read_b128 v[84:87], v171 offset:16384
	ds_read_b128 v[92:95], v171 offset:17408
	ds_read_b128 v[198:201], v172 offset:16384
	ds_read_b128 v[202:205], v172 offset:17408
	ds_read_b128 v[206:209], v173 offset:16384
	ds_read_b128 v[210:213], v173 offset:17408
	s_waitcnt vmcnt(4)
	s_barrier
	s_waitcnt lgkmcnt(0)
	v_mfma_f32_16x16x32_bf16 v[60:63], v[142:145], v[68:71], v[60:63]
	v_mfma_f32_16x16x32_bf16 v[56:59], v[178:181], v[68:71], v[56:59]
	v_mfma_f32_16x16x32_bf16 v[52:55], v[142:145], v[84:87], v[52:55]
	v_mfma_f32_16x16x32_bf16 v[48:51], v[178:181], v[84:87], v[48:51]
	v_mfma_f32_16x16x32_bf16 v[36:39], v[142:145], v[206:209], v[36:39]
	v_mfma_f32_16x16x32_bf16 v[32:35], v[178:181], v[206:209], v[32:35]
	v_mfma_f32_16x16x32_bf16 v[60:63], v[146:149], v[76:79], v[60:63]
	v_mfma_f32_16x16x32_bf16 v[56:59], v[182:185], v[76:79], v[56:59]
	v_mfma_f32_16x16x32_bf16 v[52:55], v[146:149], v[92:95], v[52:55]
	v_mfma_f32_16x16x32_bf16 v[48:51], v[182:185], v[92:95], v[48:51]
	v_mfma_f32_16x16x32_bf16 v[44:47], v[142:145], v[198:201], v[44:47]
	v_mfma_f32_16x16x32_bf16 v[40:43], v[178:181], v[198:201], v[40:43]
	v_mfma_f32_16x16x32_bf16 v[36:39], v[146:149], v[210:213], v[36:39]
	v_mfma_f32_16x16x32_bf16 v[32:35], v[182:185], v[210:213], v[32:35]
	v_mfma_f32_16x16x32_bf16 v[214:217], v[146:149], v[202:205], v[44:47]
	v_mfma_f32_16x16x32_bf16 v[230:233], v[182:185], v[202:205], v[40:43]
	v_mfma_f32_16x16x32_bf16 v[20:23], v[100:103], v[84:87], v[20:23]
	v_mfma_f32_16x16x32_bf16 v[16:19], v[116:119], v[84:87], v[16:19]
	v_mfma_f32_16x16x32_bf16 v[4:7], v[100:103], v[206:209], v[4:7]
	v_mfma_f32_16x16x32_bf16 v[0:3], v[116:119], v[206:209], v[0:3]
	v_mfma_f32_16x16x32_bf16 v[28:31], v[100:103], v[68:71], v[28:31]
	v_mfma_f32_16x16x32_bf16 v[24:27], v[116:119], v[68:71], v[24:27]
	v_mfma_f32_16x16x32_bf16 v[20:23], v[108:111], v[92:95], v[20:23]
	v_mfma_f32_16x16x32_bf16 v[16:19], v[158:161], v[92:95], v[16:19]
	v_mfma_f32_16x16x32_bf16 v[12:15], v[100:103], v[198:201], v[12:15]
	v_mfma_f32_16x16x32_bf16 v[8:11], v[116:119], v[198:201], v[8:11]
	v_mfma_f32_16x16x32_bf16 v[4:7], v[108:111], v[210:213], v[4:7]
	v_mfma_f32_16x16x32_bf16 v[0:3], v[158:161], v[210:213], v[0:3]
	v_mfma_f32_16x16x32_bf16 v[142:145], v[108:111], v[76:79], v[28:31]
	v_mfma_f32_16x16x32_bf16 v[146:149], v[158:161], v[76:79], v[24:27]
	v_mfma_f32_16x16x32_bf16 v[178:181], v[108:111], v[202:205], v[12:15]
	v_mfma_f32_16x16x32_bf16 v[182:185], v[158:161], v[202:205], v[8:11]
	s_barrier
	s_nop 0
	s_nop 0
	ds_read_b128 v[8:11], v157
	ds_read_b128 v[12:15], v157 offset:1024
	ds_read_b128 v[158:161], v157 offset:2048
	ds_read_b128 v[198:201], v157 offset:3072
	ds_read_b128 v[24:27], v153 offset:32768
	ds_read_b128 v[28:31], v153 offset:33792
	ds_read_b128 v[40:43], v171 offset:32768
	ds_read_b128 v[44:47], v171 offset:33792
	ds_read_b128 v[202:205], v172 offset:32768
	ds_read_b128 v[206:209], v172 offset:33792
	ds_read_b128 v[210:213], v173 offset:32768
	ds_read_b128 v[234:237], v173 offset:33792
	s_waitcnt vmcnt(2)
	s_barrier
; #define LDA(dst,b,h) _Pragma("unroll") for(int m=0;m<4;++m) _Pragma("unroll") for(int k=0;k<2;++k) \
;     dst[m][k]=*reinterpret_cast<const bf16x8*>((char*)SA(b,h)+lds_byte(wr*64+m*16+fr,k*32+fq*8))
; #define LDB(dst,b,h) _Pragma("unroll") for(int n=0;n<2;++n) _Pragma("unroll") for(int k=0;k<2;++k) \
;     dst[n][k]=*reinterpret_cast<const bf16x8*>((char*)SB(b,h)+lds_byte(wc*32+n*16+fr,k*32+fq*8))
; #define MMA(ai,bj,At_,Bt_) do{__builtin_amdgcn_s_setprio(1); \
;     _Pragma("unroll") for(int m=0;m<4;++m) _Pragma("unroll") for(int n=0;n<2;++n) _Pragma("unroll") for(int k=0;k<2;++k) \
;       acc[ai][bj][m][n]=__builtin_amdgcn_mfma_f32_16x16x32_bf16(Bt_[n][k],At_[m][k],acc[ai][bj][m][n],0,0,0); \
;     __builtin_amdgcn_s_setprio(0);}while(0)
; #define WAIT_V(n) asm volatile("s_waitcnt vmcnt(" #n ")":::"memory")
; #define WAIT_L(n) asm volatile("s_waitcnt lgkmcnt(" #n ")":::"memory")
; #define BAR __builtin_amdgcn_s_barrier()
; DEVINL void gemm8_mainloop(const u16* A, long lda, const u16* Bt, long ldb, int K, int brow, int bcol, f32x4 (&acc)[2][2][4][2], char* smem, int tid) {
;     ...
;   { LDB(B0,1,0); LDA(At,1,0); WAIT_V(2); BAR; WAIT_L(0); MMA(0,0,At,B0); BAR;
;     LDB(B1,1,1); WAIT_V(0); BAR; WAIT_L(0); MMA(0,1,At,B1); BAR;
;     LDA(At,1,1); BAR; WAIT_L(0); MMA(1,0,At,B0); MMA(1,1,At,B1); BAR; }
;   if(wr==0)BAR;
	s_waitcnt lgkmcnt(0)
	v_mfma_f32_16x16x32_bf16 v[68:71], v[8:11], v[24:27], v[124:127]
	v_mfma_f32_16x16x32_bf16 v[124:127], v[12:15], v[28:31], v[68:71]
	v_mfma_f32_16x16x32_bf16 v[68:71], v[158:161], v[24:27], v[120:123]
	v_mfma_f32_16x16x32_bf16 v[116:119], v[198:201], v[28:31], v[68:71]
	v_mfma_f32_16x16x32_bf16 v[68:71], v[8:11], v[40:43], v[138:141]
	v_mfma_f32_16x16x32_bf16 v[108:111], v[12:15], v[44:47], v[68:71]
	v_mfma_f32_16x16x32_bf16 v[68:71], v[158:161], v[40:43], v[112:115]
	v_mfma_f32_16x16x32_bf16 v[100:103], v[198:201], v[44:47], v[68:71]
	v_mfma_f32_16x16x32_bf16 v[68:71], v[8:11], v[202:205], v[218:221]
	v_mfma_f32_16x16x32_bf16 v[92:95], v[12:15], v[206:209], v[68:71]
	v_mfma_f32_16x16x32_bf16 v[68:71], v[158:161], v[202:205], v[104:107]
	v_mfma_f32_16x16x32_bf16 v[84:87], v[198:201], v[206:209], v[68:71]
	v_mfma_f32_16x16x32_bf16 v[68:71], v[8:11], v[210:213], v[222:225]
	v_mfma_f32_16x16x32_bf16 v[76:79], v[12:15], v[234:237], v[68:71]
	v_mfma_f32_16x16x32_bf16 v[68:71], v[158:161], v[210:213], v[96:99]
	v_mfma_f32_16x16x32_bf16 v[68:71], v[198:201], v[234:237], v[68:71]
	s_barrier
	ds_read_b128 v[138:141], v155
	ds_read_b128 v[218:221], v155 offset:1024
	ds_read_b128 v[222:225], v155 offset:2048
	ds_read_b128 v[154:157], v155 offset:3072
	s_waitcnt vmcnt(0)
	s_barrier
	s_waitcnt lgkmcnt(0)
	v_mfma_f32_16x16x32_bf16 v[96:99], v[138:141], v[24:27], v[226:229]
	v_mfma_f32_16x16x32_bf16 v[24:27], v[222:225], v[24:27], v[88:91]
	v_mfma_f32_16x16x32_bf16 v[112:115], v[154:157], v[28:31], v[24:27]
	v_mfma_f32_16x16x32_bf16 v[24:27], v[138:141], v[40:43], v[186:189]
	v_mfma_f32_16x16x32_bf16 v[104:107], v[218:221], v[44:47], v[24:27]
	v_mfma_f32_16x16x32_bf16 v[24:27], v[222:225], v[40:43], v[80:83]
	v_mfma_f32_16x16x32_bf16 v[120:123], v[218:221], v[28:31], v[96:99]
	v_mfma_f32_16x16x32_bf16 v[96:99], v[154:157], v[44:47], v[24:27]
	v_mfma_f32_16x16x32_bf16 v[24:27], v[138:141], v[202:205], v[190:193]
	v_mfma_f32_16x16x32_bf16 v[88:91], v[218:221], v[206:209], v[24:27]
	v_mfma_f32_16x16x32_bf16 v[24:27], v[222:225], v[202:205], v[72:75]
	v_mfma_f32_16x16x32_bf16 v[80:83], v[154:157], v[206:209], v[24:27]
	v_mfma_f32_16x16x32_bf16 v[24:27], v[138:141], v[210:213], v[194:197]
	v_mfma_f32_16x16x32_bf16 v[72:75], v[218:221], v[234:237], v[24:27]
	v_mfma_f32_16x16x32_bf16 v[24:27], v[222:225], v[210:213], v[64:67]
	v_mfma_f32_16x16x32_bf16 v[64:67], v[154:157], v[234:237], v[24:27]
	s_barrier
	ds_read_b128 v[186:189], v153 offset:49152
	ds_read_b128 v[190:193], v153 offset:50176
	ds_read_b128 v[194:197], v171 offset:49152
	ds_read_b128 v[202:205], v171 offset:50176
	ds_read_b128 v[206:209], v172 offset:49152
	ds_read_b128 v[210:213], v172 offset:50176
	ds_read_b128 v[226:229], v173 offset:49152
	ds_read_b128 v[172:175], v173 offset:50176
	s_barrier
	s_waitcnt lgkmcnt(0)
	v_mfma_f32_16x16x32_bf16 v[24:27], v[8:11], v[186:189], v[60:63]
	v_mfma_f32_16x16x32_bf16 v[60:63], v[12:15], v[190:193], v[24:27]
	v_mfma_f32_16x16x32_bf16 v[24:27], v[158:161], v[186:189], v[56:59]
	v_mfma_f32_16x16x32_bf16 v[56:59], v[198:201], v[190:193], v[24:27]
	v_mfma_f32_16x16x32_bf16 v[24:27], v[8:11], v[194:197], v[52:55]
	v_mfma_f32_16x16x32_bf16 v[44:47], v[12:15], v[202:205], v[24:27]
	v_mfma_f32_16x16x32_bf16 v[24:27], v[158:161], v[194:197], v[48:51]
	v_mfma_f32_16x16x32_bf16 v[40:43], v[198:201], v[202:205], v[24:27]
	v_mfma_f32_16x16x32_bf16 v[24:27], v[8:11], v[206:209], v[214:217]
	v_mfma_f32_16x16x32_bf16 v[8:11], v[8:11], v[226:229], v[36:39]
	v_mfma_f32_16x16x32_bf16 v[28:31], v[12:15], v[210:213], v[24:27]
	v_mfma_f32_16x16x32_bf16 v[24:27], v[158:161], v[206:209], v[230:233]
	v_mfma_f32_16x16x32_bf16 v[12:15], v[12:15], v[172:175], v[8:11]
	v_mfma_f32_16x16x32_bf16 v[8:11], v[158:161], v[226:229], v[32:35]
	v_mfma_f32_16x16x32_bf16 v[24:27], v[198:201], v[210:213], v[24:27]
	v_mfma_f32_16x16x32_bf16 v[8:11], v[198:201], v[172:175], v[8:11]
	v_mfma_f32_16x16x32_bf16 v[32:35], v[138:141], v[186:189], v[142:145]
	v_mfma_f32_16x16x32_bf16 v[52:55], v[218:221], v[190:193], v[32:35]
	v_mfma_f32_16x16x32_bf16 v[32:35], v[222:225], v[186:189], v[146:149]
	v_mfma_f32_16x16x32_bf16 v[16:19], v[222:225], v[194:197], v[16:19]
	v_mfma_f32_16x16x32_bf16 v[48:51], v[154:157], v[190:193], v[32:35]
	v_mfma_f32_16x16x32_bf16 v[20:23], v[138:141], v[194:197], v[20:23]
	v_mfma_f32_16x16x32_bf16 v[32:35], v[154:157], v[202:205], v[16:19]
	v_mfma_f32_16x16x32_bf16 v[16:19], v[138:141], v[206:209], v[178:181]
	v_mfma_f32_16x16x32_bf16 v[36:39], v[218:221], v[202:205], v[20:23]
	v_mfma_f32_16x16x32_bf16 v[20:23], v[218:221], v[210:213], v[16:19]
	v_mfma_f32_16x16x32_bf16 v[16:19], v[222:225], v[206:209], v[182:185]
	v_mfma_f32_16x16x32_bf16 v[4:7], v[138:141], v[226:229], v[4:7]
	v_mfma_f32_16x16x32_bf16 v[0:3], v[222:225], v[226:229], v[0:3]
	v_mfma_f32_16x16x32_bf16 v[16:19], v[154:157], v[210:213], v[16:19]
	v_mfma_f32_16x16x32_bf16 v[4:7], v[218:221], v[172:175], v[4:7]
	v_mfma_f32_16x16x32_bf16 v[0:3], v[154:157], v[172:175], v[0:3]
	s_setprio 0
	s_cmpk_gt_u32 s31, 0xff
	s_barrier
	s_cbranch_scc1 .LBB0_852
	s_barrier

; #define STAGE(P,BASE,LD,br,kt) do{long _g=(long)(br)*(LD)+(long)(kt)*BK; \
;     _Pragma("unroll") for(int _i=0;_i<2;++_i){int _b=tid*16+_i*8192;int _r,_c;stage_rc(_b,_r,_c); \
;       __builtin_amdgcn_global_load_lds((const unsigned*)((BASE)+_g+(long)_r*(LD)+_c), \
;         (unsigned*)((char*)(P)+_b),16,0,0);}}while(0)
; #define STAGE(P,BASE,LD,br,kt) do{long _g=(long)(br)*(LD)+(long)(kt)*BK; \
;     _Pragma("unroll") for(int _i=0;_i<2;++_i){int _b=tid*16+_i*8192;int _r,_c;stage_rc(_b,_r,_c); \
;       __builtin_amdgcn_global_load_lds((const unsigned*)((BASE)+_g+(long)_r*(LD)+_c), \
;         (unsigned*)((char*)(P)+_b),16,0,0);}}while(0)
; #define LDA(dst,b,h) _Pragma("unroll") for(int m=0;m<4;++m) _Pragma("unroll") for(int k=0;k<2;++k) \
;     dst[m][k]=*reinterpret_cast<const bf16x8*>((char*)SA(b,h)+lds_byte(wr*64+m*16+fr,k*32+fq*8))
; #define LDB(dst,b,h) _Pragma("unroll") for(int n=0;n<2;++n) _Pragma("unroll") for(int k=0;k<2;++k) \
;     dst[n][k]=*reinterpret_cast<const bf16x8*>((char*)SB(b,h)+lds_byte(wc*32+n*16+fr,k*32+fq*8))
; #define MMA(ai,bj,At_,Bt_) do{__builtin_amdgcn_s_setprio(1); \
;     _Pragma("unroll") for(int m=0;m<4;++m) _Pragma("unroll") for(int n=0;n<2;++n) _Pragma("unroll") for(int k=0;k<2;++k) \
;       acc[ai][bj][m][n]=__builtin_amdgcn_mfma_f32_16x16x32_bf16(Bt_[n][k],At_[m][k],acc[ai][bj][m][n],0,0,0); \
;     __builtin_amdgcn_s_setprio(0);}while(0)
; #define WAIT_L(n) asm volatile("s_waitcnt lgkmcnt(" #n ")":::"memory")
; #define BAR __builtin_amdgcn_s_barrier()
; #define SCHED __builtin_amdgcn_sched_barrier(0)
; DEVINL void gemm8_mainloop(const u16* A, long lda, const u16* Bt, long ldb, int K, int brow, int bcol, f32x4 (&acc)[2][2][4][2], char* smem, int tid) {
;     ...
;   for(int t=0;t<nt-2;t+=2){
;     LDB(B0,0,0); SCHED; LDA(At,0,0); STAGE(SA(1,1),A,lda,brow+HALF,t+1);
;     WAIT_L(8); BAR; WAIT_L(0); MMA(0,0,At,B0); BAR; SCHED;
;     LDB(B1,0,1); STAGE(SB(0,0),Bt,ldb,bcol,t+2);
;     BAR; WAIT_L(0); MMA(0,1,At,B1); BAR;
;     LDA(At,0,1); STAGE(SA(0,0),A,lda,brow,t+2);
.LBB0_916:
	ds_read_b128 v[180:183], v165
	ds_read_b128 v[184:187], v165 offset:1024
	ds_read_b128 v[188:191], v165 offset:2048
	ds_read_b128 v[192:195], v165 offset:3072
	v_add_u32_e32 v177, 0xc000, v154
	v_lshl_add_u64 v[244:245], s[94:95], 0, v[146:147]
	v_readfirstlane_b32 s29, v177
	v_add_u32_e32 v178, 0xe000, v154
	v_add_u32_e32 v173, s1, v164
	v_add_u32_e32 v174, s25, v164
	v_add_u32_e32 v175, s37, v164
	v_lshl_add_u64 v[166:167], v[244:245], 0, s[4:5]
	s_mov_b32 m0, s29
	v_lshl_add_u64 v[246:247], s[94:95], 0, v[148:149]
	v_readfirstlane_b32 s29, v178
	ds_read_b128 v[168:171], v155
	ds_read_b128 v[196:199], v155 offset:1024
	ds_read_b128 v[200:203], v173
	ds_read_b128 v[204:207], v173 offset:1024
	ds_read_b128 v[208:211], v174
	ds_read_b128 v[212:215], v174 offset:1024
	ds_read_b128 v[216:219], v175
	ds_read_b128 v[220:223], v175 offset:1024
	global_load_lds_dwordx4 v[166:167], off
	v_lshl_add_u64 v[166:167], v[246:247], 0, s[4:5]
	s_mov_b32 m0, s29
	s_nop 0
	global_load_lds_dwordx4 v[166:167], off
	s_waitcnt lgkmcnt(8)
	s_barrier
	s_waitcnt lgkmcnt(0)
	v_mfma_f32_16x16x32_bf16 v[124:127], v[180:183], v[168:171], v[124:127]
	v_mfma_f32_16x16x32_bf16 v[120:123], v[188:191], v[168:171], v[120:123]
	v_mfma_f32_16x16x32_bf16 v[116:119], v[180:183], v[200:203], v[116:119]
	v_mfma_f32_16x16x32_bf16 v[112:115], v[188:191], v[200:203], v[112:115]
	v_mfma_f32_16x16x32_bf16 v[108:111], v[180:183], v[208:211], v[108:111]
	v_mfma_f32_16x16x32_bf16 v[104:107], v[188:191], v[208:211], v[104:107]
	v_mfma_f32_16x16x32_bf16 v[100:103], v[180:183], v[216:219], v[100:103]
	v_mfma_f32_16x16x32_bf16 v[96:99], v[188:191], v[216:219], v[96:99]
	v_mfma_f32_16x16x32_bf16 v[124:127], v[184:187], v[196:199], v[124:127]
	v_mfma_f32_16x16x32_bf16 v[120:123], v[192:195], v[196:199], v[120:123]
	v_mfma_f32_16x16x32_bf16 v[116:119], v[184:187], v[204:207], v[116:119]
	v_mfma_f32_16x16x32_bf16 v[112:115], v[192:195], v[204:207], v[112:115]
	v_mfma_f32_16x16x32_bf16 v[108:111], v[184:187], v[212:215], v[108:111]
	v_mfma_f32_16x16x32_bf16 v[104:107], v[192:195], v[212:215], v[104:107]
	v_mfma_f32_16x16x32_bf16 v[100:103], v[184:187], v[220:223], v[100:103]
	v_mfma_f32_16x16x32_bf16 v[96:99], v[192:195], v[220:223], v[96:99]
	s_barrier
	v_add_u32_e32 v166, s30, v157
	v_lshl_add_u64 v[248:249], s[94:95], 0, v[142:143]
	v_readfirstlane_b32 s29, v166
	v_add_u32_e32 v167, 0x2000, v166
	v_lshl_add_u64 v[240:241], v[248:249], 0, s[6:7]
	s_mov_b32 m0, s29
	v_lshl_add_u64 v[250:251], s[94:95], 0, v[144:145]
	v_readfirstlane_b32 s29, v167
	ds_read_b128 v[224:227], v162
	ds_read_b128 v[228:231], v162 offset:1024
	ds_read_b128 v[232:235], v162 offset:2048
	ds_read_b128 v[236:239], v162 offset:3072
	global_load_lds_dwordx4 v[240:241], off
	v_lshl_add_u64 v[240:241], v[250:251], 0, s[6:7]
	s_mov_b32 m0, s29
	s_nop 0
	global_load_lds_dwordx4 v[240:241], off
	s_barrier
	s_waitcnt lgkmcnt(0)
	v_mfma_f32_16x16x32_bf16 v[92:95], v[224:227], v[168:171], v[92:95]
	v_mfma_f32_16x16x32_bf16 v[88:91], v[232:235], v[168:171], v[88:91]
	v_mfma_f32_16x16x32_bf16 v[84:87], v[224:227], v[200:203], v[84:87]
	v_mfma_f32_16x16x32_bf16 v[80:83], v[232:235], v[200:203], v[80:83]
	v_mfma_f32_16x16x32_bf16 v[76:79], v[224:227], v[208:211], v[76:79]
	v_mfma_f32_16x16x32_bf16 v[72:75], v[232:235], v[208:211], v[72:75]
	v_mfma_f32_16x16x32_bf16 v[68:71], v[224:227], v[216:219], v[68:71]
	v_mfma_f32_16x16x32_bf16 v[64:67], v[232:235], v[216:219], v[64:67]
	v_mfma_f32_16x16x32_bf16 v[92:95], v[228:231], v[196:199], v[92:95]
	v_mfma_f32_16x16x32_bf16 v[88:91], v[236:239], v[196:199], v[88:91]
	v_mfma_f32_16x16x32_bf16 v[84:87], v[228:231], v[204:207], v[84:87]
	v_mfma_f32_16x16x32_bf16 v[80:83], v[236:239], v[204:207], v[80:83]
	v_mfma_f32_16x16x32_bf16 v[76:79], v[228:231], v[212:215], v[76:79]
	v_mfma_f32_16x16x32_bf16 v[72:75], v[236:239], v[212:215], v[72:75]
	v_mfma_f32_16x16x32_bf16 v[68:71], v[228:231], v[220:223], v[68:71]
	v_mfma_f32_16x16x32_bf16 v[64:67], v[236:239], v[220:223], v[64:67]
	v_readfirstlane_b32 s29, v154
	v_lshl_add_u64 v[168:169], v[244:245], 0, s[8:9]
	s_mov_b32 m0, s29
	s_barrier
	ds_read_b128 v[196:199], v155 offset:16384
	ds_read_b128 v[200:203], v155 offset:17408
	ds_read_b128 v[204:207], v173 offset:16384
	ds_read_b128 v[208:211], v173 offset:17408
	ds_read_b128 v[212:215], v174 offset:16384
	ds_read_b128 v[216:219], v174 offset:17408
	ds_read_b128 v[220:223], v175 offset:16384
	ds_read_b128 v[240:243], v175 offset:17408
	global_load_lds_dwordx4 v[168:169], off
	v_add_u32_e32 v168, 0x2000, v154
	v_lshl_add_u64 v[170:171], v[246:247], 0, s[8:9]
	v_readfirstlane_b32 s29, v168
	s_mov_b32 m0, s29
	s_nop 0
	global_load_lds_dwordx4 v[170:171], off
	s_barrier
	s_waitcnt lgkmcnt(0)
	v_mfma_f32_16x16x32_bf16 v[60:63], v[180:183], v[196:199], v[60:63]
	v_mfma_f32_16x16x32_bf16 v[56:59], v[188:191], v[196:199], v[56:59]
	v_mfma_f32_16x16x32_bf16 v[52:55], v[180:183], v[204:207], v[52:55]
	v_mfma_f32_16x16x32_bf16 v[48:51], v[188:191], v[204:207], v[48:51]
	v_mfma_f32_16x16x32_bf16 v[44:47], v[180:183], v[212:215], v[44:47]
	v_mfma_f32_16x16x32_bf16 v[40:43], v[188:191], v[212:215], v[40:43]
	v_mfma_f32_16x16x32_bf16 v[36:39], v[180:183], v[220:223], v[36:39]
	v_mfma_f32_16x16x32_bf16 v[32:35], v[188:191], v[220:223], v[32:35]
	v_mfma_f32_16x16x32_bf16 v[60:63], v[184:187], v[200:203], v[60:63]
	v_mfma_f32_16x16x32_bf16 v[56:59], v[192:195], v[200:203], v[56:59]
	v_mfma_f32_16x16x32_bf16 v[52:55], v[184:187], v[208:211], v[52:55]
	v_mfma_f32_16x16x32_bf16 v[48:51], v[192:195], v[208:211], v[48:51]
	v_mfma_f32_16x16x32_bf16 v[44:47], v[184:187], v[216:219], v[44:47]
	v_mfma_f32_16x16x32_bf16 v[40:43], v[192:195], v[216:219], v[40:43]
	v_mfma_f32_16x16x32_bf16 v[36:39], v[184:187], v[240:243], v[36:39]
	v_mfma_f32_16x16x32_bf16 v[32:35], v[192:195], v[240:243], v[32:35]
	s_barrier
; #define STAGE(P,BASE,LD,br,kt) do{long _g=(long)(br)*(LD)+(long)(kt)*BK; \
;     _Pragma("unroll") for(int _i=0;_i<2;++_i){int _b=tid*16+_i*8192;int _r,_c;stage_rc(_b,_r,_c); \
;       __builtin_amdgcn_global_load_lds((const unsigned*)((BASE)+_g+(long)_r*(LD)+_c), \
;         (unsigned*)((char*)(P)+_b),16,0,0);}}while(0)
; #define STAGE(P,BASE,LD,br,kt) do{long _g=(long)(br)*(LD)+(long)(kt)*BK; \
;     _Pragma("unroll") for(int _i=0;_i<2;++_i){int _b=tid*16+_i*8192;int _r,_c;stage_rc(_b,_r,_c); \
;       __builtin_amdgcn_global_load_lds((const unsigned*)((BASE)+_g+(long)_r*(LD)+_c), \
;         (unsigned*)((char*)(P)+_b),16,0,0);}}while(0)
; #define LDA(dst,b,h) _Pragma("unroll") for(int m=0;m<4;++m) _Pragma("unroll") for(int k=0;k<2;++k) \
;     dst[m][k]=*reinterpret_cast<const bf16x8*>((char*)SA(b,h)+lds_byte(wr*64+m*16+fr,k*32+fq*8))
; #define LDB(dst,b,h) _Pragma("unroll") for(int n=0;n<2;++n) _Pragma("unroll") for(int k=0;k<2;++k) \
;     dst[n][k]=*reinterpret_cast<const bf16x8*>((char*)SB(b,h)+lds_byte(wc*32+n*16+fr,k*32+fq*8))
; #define MMA(ai,bj,At_,Bt_) do{__builtin_amdgcn_s_setprio(1); \
;     _Pragma("unroll") for(int m=0;m<4;++m) _Pragma("unroll") for(int n=0;n<2;++n) _Pragma("unroll") for(int k=0;k<2;++k) \
;       acc[ai][bj][m][n]=__builtin_amdgcn_mfma_f32_16x16x32_bf16(Bt_[n][k],At_[m][k],acc[ai][bj][m][n],0,0,0); \
;     __builtin_amdgcn_s_setprio(0);}while(0)
; #define WAIT_V(n) asm volatile("s_waitcnt vmcnt(" #n ")":::"memory")
; #define WAIT_L(n) asm volatile("s_waitcnt lgkmcnt(" #n ")":::"memory")
; #define BAR __builtin_amdgcn_s_barrier()
; #define SCHED __builtin_amdgcn_sched_barrier(0)
; DEVINL void gemm8_mainloop(const u16* A, long lda, const u16* Bt, long ldb, int K, int brow, int bcol, f32x4 (&acc)[2][2][4][2], char* smem, int tid) {
;     ...
;     LDA(At,0,1); STAGE(SA(0,0),A,lda,brow,t+2);
;     BAR; WAIT_L(0); MMA(1,0,At,B0); BAR; SCHED;
;     STAGE(SB(0,1),Bt,ldb,bcol+HALF,t+2);
;     WAIT_V(6); BAR; MMA(1,1,At,B1); BAR;
;     LDB(B0,1,0); SCHED; LDA(At,1,0); STAGE(SA(0,1),A,lda,brow+HALF,t+2);
;     WAIT_L(8); BAR; WAIT_L(0); MMA(0,0,At,B0); BAR; SCHED;
;     LDB(B1,1,1); STAGE(SB(1,0),Bt,ldb,bcol,t+3);
	v_add_u32_e32 v169, s31, v157
	v_lshl_add_u64 v[170:171], v[248:249], 0, s[10:11]
	v_readfirstlane_b32 s29, v169
	s_mov_b32 m0, s29
	v_lshl_add_u64 v[180:181], v[250:251], 0, s[10:11]
	global_load_lds_dwordx4 v[170:171], off
	v_add_u32_e32 v170, 0x2000, v169
	s_nop 0
	v_readfirstlane_b32 s29, v170
	s_mov_b32 m0, s29
	s_nop 0
	global_load_lds_dwordx4 v[180:181], off
	s_waitcnt vmcnt(6)
	s_barrier
	v_mfma_f32_16x16x32_bf16 v[28:31], v[224:227], v[196:199], v[28:31]
	v_mfma_f32_16x16x32_bf16 v[24:27], v[232:235], v[196:199], v[24:27]
	v_mfma_f32_16x16x32_bf16 v[20:23], v[224:227], v[204:207], v[20:23]
	v_mfma_f32_16x16x32_bf16 v[16:19], v[232:235], v[204:207], v[16:19]
	v_mfma_f32_16x16x32_bf16 v[12:15], v[224:227], v[212:215], v[12:15]
	v_mfma_f32_16x16x32_bf16 v[8:11], v[232:235], v[212:215], v[8:11]
	v_mfma_f32_16x16x32_bf16 v[4:7], v[224:227], v[220:223], v[4:7]
	v_mfma_f32_16x16x32_bf16 v[0:3], v[232:235], v[220:223], v[0:3]
	v_mfma_f32_16x16x32_bf16 v[28:31], v[228:231], v[200:203], v[28:31]
	v_mfma_f32_16x16x32_bf16 v[24:27], v[236:239], v[200:203], v[24:27]
	v_mfma_f32_16x16x32_bf16 v[20:23], v[228:231], v[208:211], v[20:23]
	v_mfma_f32_16x16x32_bf16 v[16:19], v[236:239], v[208:211], v[16:19]
	v_mfma_f32_16x16x32_bf16 v[12:15], v[228:231], v[216:219], v[12:15]
	v_mfma_f32_16x16x32_bf16 v[8:11], v[236:239], v[216:219], v[8:11]
	v_mfma_f32_16x16x32_bf16 v[4:7], v[228:231], v[240:243], v[4:7]
	v_mfma_f32_16x16x32_bf16 v[0:3], v[236:239], v[240:243], v[0:3]
	s_barrier
	ds_read_b128 v[180:183], v158
	ds_read_b128 v[184:187], v158 offset:1024
	ds_read_b128 v[188:191], v158 offset:2048
	ds_read_b128 v[192:195], v158 offset:3072
	v_add_u32_e32 v171, 0x4000, v154
	v_add_u32_e32 v172, 0x6000, v154
	v_readfirstlane_b32 s29, v171
	v_lshl_add_u64 v[228:229], v[244:245], 0, s[12:13]
	s_mov_b32 m0, s29
	v_readfirstlane_b32 s29, v172
	ds_read_b128 v[196:199], v155 offset:32768
	ds_read_b128 v[200:203], v155 offset:33792
	ds_read_b128 v[204:207], v173 offset:32768
	ds_read_b128 v[208:211], v173 offset:33792
	ds_read_b128 v[212:215], v174 offset:32768
	ds_read_b128 v[216:219], v174 offset:33792
	ds_read_b128 v[220:223], v175 offset:32768
	ds_read_b128 v[224:227], v175 offset:33792
	global_load_lds_dwordx4 v[228:229], off
	v_lshl_add_u64 v[228:229], v[246:247], 0, s[12:13]
	s_mov_b32 m0, s29
	s_nop 0
	global_load_lds_dwordx4 v[228:229], off
	s_waitcnt lgkmcnt(8)
	s_barrier
	s_waitcnt lgkmcnt(0)
	v_mfma_f32_16x16x32_bf16 v[124:127], v[180:183], v[196:199], v[124:127]
	v_mfma_f32_16x16x32_bf16 v[120:123], v[188:191], v[196:199], v[120:123]
	v_mfma_f32_16x16x32_bf16 v[116:119], v[180:183], v[204:207], v[116:119]
	v_mfma_f32_16x16x32_bf16 v[112:115], v[188:191], v[204:207], v[112:115]
	v_mfma_f32_16x16x32_bf16 v[108:111], v[180:183], v[212:215], v[108:111]
	v_mfma_f32_16x16x32_bf16 v[104:107], v[188:191], v[212:215], v[104:107]
	v_mfma_f32_16x16x32_bf16 v[100:103], v[180:183], v[220:223], v[100:103]
	v_mfma_f32_16x16x32_bf16 v[96:99], v[188:191], v[220:223], v[96:99]
	v_mfma_f32_16x16x32_bf16 v[124:127], v[184:187], v[200:203], v[124:127]
	v_mfma_f32_16x16x32_bf16 v[120:123], v[192:195], v[200:203], v[120:123]
	v_mfma_f32_16x16x32_bf16 v[116:119], v[184:187], v[208:211], v[116:119]
	v_mfma_f32_16x16x32_bf16 v[112:115], v[192:195], v[208:211], v[112:115]
	v_mfma_f32_16x16x32_bf16 v[108:111], v[184:187], v[216:219], v[108:111]
	v_mfma_f32_16x16x32_bf16 v[104:107], v[192:195], v[216:219], v[104:107]
	v_mfma_f32_16x16x32_bf16 v[100:103], v[184:187], v[224:227], v[100:103]
	v_mfma_f32_16x16x32_bf16 v[96:99], v[192:195], v[224:227], v[96:99]
	s_barrier
	v_readfirstlane_b32 s29, v159
	v_add_u32_e32 v179, 0x2000, v159
	v_lshl_add_u64 v[252:253], v[248:249], 0, s[14:15]
	s_mov_b32 m0, s29
	v_readfirstlane_b32 s29, v179
	ds_read_b128 v[228:231], v156
	ds_read_b128 v[232:235], v156 offset:1024
	ds_read_b128 v[236:239], v156 offset:2048
	ds_read_b128 v[240:243], v156 offset:3072
	global_load_lds_dwordx4 v[252:253], off
	v_lshl_add_u64 v[252:253], v[250:251], 0, s[14:15]
	s_mov_b32 m0, s29
	s_nop 0
	global_load_lds_dwordx4 v[252:253], off
	s_barrier
	s_waitcnt lgkmcnt(0)
	v_mfma_f32_16x16x32_bf16 v[92:95], v[228:231], v[196:199], v[92:95]
	v_mfma_f32_16x16x32_bf16 v[88:91], v[236:239], v[196:199], v[88:91]
	v_mfma_f32_16x16x32_bf16 v[84:87], v[228:231], v[204:207], v[84:87]
	v_mfma_f32_16x16x32_bf16 v[80:83], v[236:239], v[204:207], v[80:83]
	v_mfma_f32_16x16x32_bf16 v[76:79], v[228:231], v[212:215], v[76:79]
	v_mfma_f32_16x16x32_bf16 v[72:75], v[236:239], v[212:215], v[72:75]
	v_mfma_f32_16x16x32_bf16 v[68:71], v[228:231], v[220:223], v[68:71]
	v_mfma_f32_16x16x32_bf16 v[64:67], v[236:239], v[220:223], v[64:67]
	v_mfma_f32_16x16x32_bf16 v[92:95], v[232:235], v[200:203], v[92:95]
	v_mfma_f32_16x16x32_bf16 v[88:91], v[240:243], v[200:203], v[88:91]
	v_mfma_f32_16x16x32_bf16 v[84:87], v[232:235], v[208:211], v[84:87]
	v_mfma_f32_16x16x32_bf16 v[80:83], v[240:243], v[208:211], v[80:83]
	v_mfma_f32_16x16x32_bf16 v[76:79], v[232:235], v[216:219], v[76:79]
	v_mfma_f32_16x16x32_bf16 v[72:75], v[240:243], v[216:219], v[72:75]
	v_mfma_f32_16x16x32_bf16 v[68:71], v[232:235], v[224:227], v[68:71]
	v_mfma_f32_16x16x32_bf16 v[64:67], v[240:243], v[224:227], v[64:67]
	v_readfirstlane_b32 s29, v160
	v_lshl_add_u64 v[244:245], v[244:245], 0, s[16:17]
	s_mov_b32 m0, s29
	v_readfirstlane_b32 s29, v161
	s_barrier
	ds_read_b128 v[196:199], v155 offset:49152
	ds_read_b128 v[200:203], v155 offset:50176
	ds_read_b128 v[204:207], v173 offset:49152
	ds_read_b128 v[208:211], v173 offset:50176
	ds_read_b128 v[212:215], v174 offset:49152
	ds_read_b128 v[216:219], v174 offset:50176
	ds_read_b128 v[220:223], v175 offset:49152
	ds_read_b128 v[224:227], v175 offset:50176
	global_load_lds_dwordx4 v[244:245], off
	v_lshl_add_u64 v[244:245], v[246:247], 0, s[16:17]
	s_mov_b32 m0, s29
	s_nop 0
	global_load_lds_dwordx4 v[244:245], off
	s_barrier
; #define STAGE(P,BASE,LD,br,kt) do{long _g=(long)(br)*(LD)+(long)(kt)*BK; \
;     _Pragma("unroll") for(int _i=0;_i<2;++_i){int _b=tid*16+_i*8192;int _r,_c;stage_rc(_b,_r,_c); \
;       __builtin_amdgcn_global_load_lds((const unsigned*)((BASE)+_g+(long)_r*(LD)+_c), \
;         (unsigned*)((char*)(P)+_b),16,0,0);}}while(0)
; #define STAGE(P,BASE,LD,br,kt) do{long _g=(long)(br)*(LD)+(long)(kt)*BK; \
;     _Pragma("unroll") for(int _i=0;_i<2;++_i){int _b=tid*16+_i*8192;int _r,_c;stage_rc(_b,_r,_c); \
;       __builtin_amdgcn_global_load_lds((const unsigned*)((BASE)+_g+(long)_r*(LD)+_c), \
;         (unsigned*)((char*)(P)+_b),16,0,0);}}while(0)
; #define LDA(dst,b,h) _Pragma("unroll") for(int m=0;m<4;++m) _Pragma("unroll") for(int k=0;k<2;++k) \
;     dst[m][k]=*reinterpret_cast<const bf16x8*>((char*)SA(b,h)+lds_byte(wr*64+m*16+fr,k*32+fq*8))
; #define LDB(dst,b,h) _Pragma("unroll") for(int n=0;n<2;++n) _Pragma("unroll") for(int k=0;k<2;++k) \
;     dst[n][k]=*reinterpret_cast<const bf16x8*>((char*)SB(b,h)+lds_byte(wc*32+n*16+fr,k*32+fq*8))
; #define MMA(ai,bj,At_,Bt_) do{__builtin_amdgcn_s_setprio(1); \
;     _Pragma("unroll") for(int m=0;m<4;++m) _Pragma("unroll") for(int n=0;n<2;++n) _Pragma("unroll") for(int k=0;k<2;++k) \
;       acc[ai][bj][m][n]=__builtin_amdgcn_mfma_f32_16x16x32_bf16(Bt_[n][k],At_[m][k],acc[ai][bj][m][n],0,0,0); \
;     __builtin_amdgcn_s_setprio(0);}while(0)
; #define WAIT_V(n) asm volatile("s_waitcnt vmcnt(" #n ")":::"memory")
; #define WAIT_L(n) asm volatile("s_waitcnt lgkmcnt(" #n ")":::"memory")
; #define BAR __builtin_amdgcn_s_barrier()
; #define SCHED __builtin_amdgcn_sched_barrier(0)
; DEVINL void gemm8_mainloop(const u16* A, long lda, const u16* Bt, long ldb, int K, int brow, int bcol, f32x4 (&acc)[2][2][4][2], char* smem, int tid) {
;     ...
;     LDB(B1,1,1); STAGE(SB(1,0),Bt,ldb,bcol,t+3);
;     BAR; WAIT_L(0); MMA(0,1,At,B1); BAR;
;     LDA(At,1,1); STAGE(SA(1,0),A,lda,brow,t+3);
;     BAR; WAIT_L(0); MMA(1,0,At,B0); BAR; SCHED;
;     STAGE(SB(1,1),Bt,ldb,bcol+HALF,t+3);
;     WAIT_V(6); BAR; MMA(1,1,At,B1); BAR;
;   }
;   { LDB(B0,0,0); LDA(At,0,0); STAGE(SA(1,1),A,lda,brow+HALF,nt-1);
;     BAR; WAIT_L(0); MMA(0,0,At,B0); BAR;
	s_waitcnt lgkmcnt(0)
	v_mfma_f32_16x16x32_bf16 v[60:63], v[180:183], v[196:199], v[60:63]
	v_mfma_f32_16x16x32_bf16 v[56:59], v[188:191], v[196:199], v[56:59]
	v_mfma_f32_16x16x32_bf16 v[52:55], v[180:183], v[204:207], v[52:55]
	v_mfma_f32_16x16x32_bf16 v[48:51], v[188:191], v[204:207], v[48:51]
	v_mfma_f32_16x16x32_bf16 v[44:47], v[180:183], v[212:215], v[44:47]
	v_mfma_f32_16x16x32_bf16 v[40:43], v[188:191], v[212:215], v[40:43]
	v_mfma_f32_16x16x32_bf16 v[36:39], v[180:183], v[220:223], v[36:39]
	v_mfma_f32_16x16x32_bf16 v[32:35], v[188:191], v[220:223], v[32:35]
	v_mfma_f32_16x16x32_bf16 v[60:63], v[184:187], v[200:203], v[60:63]
	v_mfma_f32_16x16x32_bf16 v[56:59], v[192:195], v[200:203], v[56:59]
	v_mfma_f32_16x16x32_bf16 v[52:55], v[184:187], v[208:211], v[52:55]
	v_mfma_f32_16x16x32_bf16 v[48:51], v[192:195], v[208:211], v[48:51]
	v_mfma_f32_16x16x32_bf16 v[44:47], v[184:187], v[216:219], v[44:47]
	v_mfma_f32_16x16x32_bf16 v[40:43], v[192:195], v[216:219], v[40:43]
	v_mfma_f32_16x16x32_bf16 v[36:39], v[184:187], v[224:227], v[36:39]
	v_mfma_f32_16x16x32_bf16 v[32:35], v[192:195], v[224:227], v[32:35]
	s_barrier
	v_readfirstlane_b32 s29, v163
	v_add_u32_e32 v179, 0x2000, v163
	v_lshl_add_u64 v[180:181], v[248:249], 0, s[18:19]
	s_mov_b32 m0, s29
	v_readfirstlane_b32 s29, v179
	global_load_lds_dwordx4 v[180:181], off
	v_lshl_add_u64 v[180:181], v[250:251], 0, s[18:19]
	s_mov_b32 m0, s29
	s_nop 0
	global_load_lds_dwordx4 v[180:181], off
	s_waitcnt vmcnt(6)
	s_barrier
	v_mfma_f32_16x16x32_bf16 v[28:31], v[228:231], v[196:199], v[28:31]
	v_mfma_f32_16x16x32_bf16 v[24:27], v[236:239], v[196:199], v[24:27]
	v_mfma_f32_16x16x32_bf16 v[20:23], v[228:231], v[204:207], v[20:23]
	v_mfma_f32_16x16x32_bf16 v[16:19], v[236:239], v[204:207], v[16:19]
	v_mfma_f32_16x16x32_bf16 v[12:15], v[228:231], v[212:215], v[12:15]
	v_mfma_f32_16x16x32_bf16 v[8:11], v[236:239], v[212:215], v[8:11]
	v_mfma_f32_16x16x32_bf16 v[4:7], v[228:231], v[220:223], v[4:7]
	v_mfma_f32_16x16x32_bf16 v[0:3], v[236:239], v[220:223], v[0:3]
	v_mfma_f32_16x16x32_bf16 v[28:31], v[232:235], v[200:203], v[28:31]
	v_mfma_f32_16x16x32_bf16 v[24:27], v[240:243], v[200:203], v[24:27]
	v_mfma_f32_16x16x32_bf16 v[20:23], v[232:235], v[208:211], v[20:23]
	v_mfma_f32_16x16x32_bf16 v[16:19], v[240:243], v[208:211], v[16:19]
	v_mfma_f32_16x16x32_bf16 v[12:15], v[232:235], v[216:219], v[12:15]
	v_mfma_f32_16x16x32_bf16 v[8:11], v[240:243], v[216:219], v[8:11]
	v_mfma_f32_16x16x32_bf16 v[4:7], v[232:235], v[224:227], v[4:7]
	v_mfma_f32_16x16x32_bf16 v[0:3], v[240:243], v[224:227], v[0:3]
	s_add_i32 s28, s28, 2
	v_lshl_add_u64 v[142:143], v[142:143], 0, s[20:21]
	v_lshl_add_u64 v[144:145], v[144:145], 0, s[20:21]
	v_lshl_add_u64 v[146:147], v[146:147], 0, s[20:21]
	s_cmp_lt_u32 s28, 28
	v_lshl_add_u64 v[148:149], v[148:149], 0, s[20:21]
	s_barrier
	s_cbranch_scc1 .LBB0_916
	s_or_b32 s28, s24, 0x80
	s_ashr_i32 s29, s28, 31
	s_lshl_b64 s[28:29], s[28:29], 12
	s_add_u32 s28, s90, s28
	s_addc_u32 s29, s91, s29
	v_lshl_add_u64 v[160:161], v[134:135], 1, s[28:29]
	v_lshl_add_u64 v[138:139], v[138:139], 1, v[160:161]
	v_readfirstlane_b32 s1, v177
	v_lshl_add_u64 v[138:139], v[138:139], 0, s[22:23]
	s_mov_b32 m0, s1
	ds_read_b128 v[142:145], v165
	ds_read_b128 v[146:149], v165 offset:1024
	ds_read_b128 v[180:183], v165 offset:2048
	ds_read_b128 v[184:187], v165 offset:3072
	ds_read_b128 v[188:191], v155
	ds_read_b128 v[192:195], v155 offset:1024
	ds_read_b128 v[196:199], v173
	ds_read_b128 v[200:203], v173 offset:1024
	ds_read_b128 v[204:207], v174
	ds_read_b128 v[208:211], v174 offset:1024
	ds_read_b128 v[212:215], v175
	ds_read_b128 v[216:219], v175 offset:1024
	global_load_lds_dwordx4 v[138:139], off
	v_lshl_add_u64 v[138:139], v[136:137], 1, s[28:29]
	v_lshl_add_u64 v[138:139], v[140:141], 1, v[138:139]
	v_readfirstlane_b32 s1, v178
	v_lshl_add_u64 v[138:139], v[138:139], 0, s[22:23]
	s_mov_b32 m0, s1
	s_nop 0
	global_load_lds_dwordx4 v[138:139], off
	s_barrier
	s_waitcnt lgkmcnt(0)
	v_mfma_f32_16x16x32_bf16 v[124:127], v[142:145], v[188:191], v[124:127]
	v_mfma_f32_16x16x32_bf16 v[120:123], v[180:183], v[188:191], v[120:123]
	v_mfma_f32_16x16x32_bf16 v[116:119], v[142:145], v[196:199], v[116:119]
	v_mfma_f32_16x16x32_bf16 v[112:115], v[180:183], v[196:199], v[112:115]
	v_mfma_f32_16x16x32_bf16 v[104:107], v[180:183], v[204:207], v[104:107]
	v_mfma_f32_16x16x32_bf16 v[96:99], v[180:183], v[212:215], v[96:99]
	v_mfma_f32_16x16x32_bf16 v[124:127], v[146:149], v[192:195], v[124:127]
	v_mfma_f32_16x16x32_bf16 v[120:123], v[184:187], v[192:195], v[120:123]
	v_mfma_f32_16x16x32_bf16 v[116:119], v[146:149], v[200:203], v[116:119]
	v_mfma_f32_16x16x32_bf16 v[112:115], v[184:187], v[200:203], v[112:115]
	v_mfma_f32_16x16x32_bf16 v[108:111], v[142:145], v[204:207], v[108:111]
	v_mfma_f32_16x16x32_bf16 v[104:107], v[184:187], v[208:211], v[104:107]
	v_mfma_f32_16x16x32_bf16 v[100:103], v[142:145], v[212:215], v[100:103]
	v_mfma_f32_16x16x32_bf16 v[96:99], v[184:187], v[216:219], v[96:99]
	v_mfma_f32_16x16x32_bf16 v[138:141], v[146:149], v[208:211], v[108:111]
	v_mfma_f32_16x16x32_bf16 v[220:223], v[146:149], v[216:219], v[100:103]
	s_barrier
	s_nop 2
	s_nop 0
	ds_read_b128 v[100:103], v162
	ds_read_b128 v[108:111], v162 offset:1024
	ds_read_b128 v[224:227], v162 offset:2048
	ds_read_b128 v[160:163], v162 offset:3072
	s_barrier
; #define LDA(dst,b,h) _Pragma("unroll") for(int m=0;m<4;++m) _Pragma("unroll") for(int k=0;k<2;++k) \
;     dst[m][k]=*reinterpret_cast<const bf16x8*>((char*)SA(b,h)+lds_byte(wr*64+m*16+fr,k*32+fq*8))
; #define LDB(dst,b,h) _Pragma("unroll") for(int n=0;n<2;++n) _Pragma("unroll") for(int k=0;k<2;++k) \
;     dst[n][k]=*reinterpret_cast<const bf16x8*>((char*)SB(b,h)+lds_byte(wc*32+n*16+fr,k*32+fq*8))
; #define MMA(ai,bj,At_,Bt_) do{__builtin_amdgcn_s_setprio(1); \
;     _Pragma("unroll") for(int m=0;m<4;++m) _Pragma("unroll") for(int n=0;n<2;++n) _Pragma("unroll") for(int k=0;k<2;++k) \
;       acc[ai][bj][m][n]=__builtin_amdgcn_mfma_f32_16x16x32_bf16(Bt_[n][k],At_[m][k],acc[ai][bj][m][n],0,0,0); \
;     __builtin_amdgcn_s_setprio(0);}while(0)
; #define WAIT_V(n) asm volatile("s_waitcnt vmcnt(" #n ")":::"memory")
; #define WAIT_L(n) asm volatile("s_waitcnt lgkmcnt(" #n ")":::"memory")
; #define BAR __builtin_amdgcn_s_barrier()
; DEVINL void gemm8_mainloop(const u16* A, long lda, const u16* Bt, long ldb, int K, int brow, int bcol, f32x4 (&acc)[2][2][4][2], char* smem, int tid) {
;     ...
;     BAR; WAIT_L(0); MMA(0,0,At,B0); BAR;
;     LDB(B1,0,1); BAR; WAIT_L(0); MMA(0,1,At,B1); BAR;
;     LDA(At,0,1); WAIT_V(4); BAR; WAIT_L(0); MMA(1,0,At,B0); MMA(1,1,At,B1); BAR; }
;   { LDB(B0,1,0); LDA(At,1,0); WAIT_V(2); BAR; WAIT_L(0); MMA(0,0,At,B0); BAR;
	s_waitcnt lgkmcnt(0)
	v_mfma_f32_16x16x32_bf16 v[88:91], v[224:227], v[188:191], v[88:91]
	v_mfma_f32_16x16x32_bf16 v[80:83], v[224:227], v[196:199], v[80:83]
	v_mfma_f32_16x16x32_bf16 v[72:75], v[224:227], v[204:207], v[72:75]
	v_mfma_f32_16x16x32_bf16 v[64:67], v[224:227], v[212:215], v[64:67]
	v_mfma_f32_16x16x32_bf16 v[92:95], v[100:103], v[188:191], v[92:95]
	v_mfma_f32_16x16x32_bf16 v[88:91], v[160:163], v[192:195], v[88:91]
	v_mfma_f32_16x16x32_bf16 v[84:87], v[100:103], v[196:199], v[84:87]
	v_mfma_f32_16x16x32_bf16 v[80:83], v[160:163], v[200:203], v[80:83]
	v_mfma_f32_16x16x32_bf16 v[76:79], v[100:103], v[204:207], v[76:79]
	v_mfma_f32_16x16x32_bf16 v[72:75], v[160:163], v[208:211], v[72:75]
	v_mfma_f32_16x16x32_bf16 v[68:71], v[100:103], v[212:215], v[68:71]
	v_mfma_f32_16x16x32_bf16 v[64:67], v[160:163], v[216:219], v[64:67]
	v_mfma_f32_16x16x32_bf16 v[228:231], v[108:111], v[192:195], v[92:95]
	v_mfma_f32_16x16x32_bf16 v[188:191], v[108:111], v[200:203], v[84:87]
	v_mfma_f32_16x16x32_bf16 v[192:195], v[108:111], v[208:211], v[76:79]
	v_mfma_f32_16x16x32_bf16 v[196:199], v[108:111], v[216:219], v[68:71]
	s_barrier
	s_nop 0
	s_nop 0
	ds_read_b128 v[68:71], v155 offset:16384
	ds_read_b128 v[76:79], v155 offset:17408
	ds_read_b128 v[84:87], v173 offset:16384
	ds_read_b128 v[92:95], v173 offset:17408
	ds_read_b128 v[200:203], v174 offset:16384
	ds_read_b128 v[204:207], v174 offset:17408
	ds_read_b128 v[208:211], v175 offset:16384
	ds_read_b128 v[212:215], v175 offset:17408
	s_waitcnt vmcnt(4)
	s_barrier
	s_waitcnt lgkmcnt(0)
	v_mfma_f32_16x16x32_bf16 v[60:63], v[142:145], v[68:71], v[60:63]
	v_mfma_f32_16x16x32_bf16 v[56:59], v[180:183], v[68:71], v[56:59]
	v_mfma_f32_16x16x32_bf16 v[48:51], v[180:183], v[84:87], v[48:51]
	v_mfma_f32_16x16x32_bf16 v[40:43], v[180:183], v[200:203], v[40:43]
	v_mfma_f32_16x16x32_bf16 v[32:35], v[180:183], v[208:211], v[32:35]
	v_mfma_f32_16x16x32_bf16 v[60:63], v[146:149], v[76:79], v[60:63]
	v_mfma_f32_16x16x32_bf16 v[56:59], v[184:187], v[76:79], v[56:59]
	v_mfma_f32_16x16x32_bf16 v[52:55], v[142:145], v[84:87], v[52:55]
	v_mfma_f32_16x16x32_bf16 v[48:51], v[184:187], v[92:95], v[48:51]
	v_mfma_f32_16x16x32_bf16 v[44:47], v[142:145], v[200:203], v[44:47]
	v_mfma_f32_16x16x32_bf16 v[40:43], v[184:187], v[204:207], v[40:43]
	v_mfma_f32_16x16x32_bf16 v[36:39], v[142:145], v[208:211], v[36:39]
	v_mfma_f32_16x16x32_bf16 v[32:35], v[184:187], v[212:215], v[32:35]
	v_mfma_f32_16x16x32_bf16 v[216:219], v[146:149], v[92:95], v[52:55]
	v_mfma_f32_16x16x32_bf16 v[232:235], v[146:149], v[204:207], v[44:47]
	v_mfma_f32_16x16x32_bf16 v[142:145], v[146:149], v[212:215], v[36:39]
	v_mfma_f32_16x16x32_bf16 v[24:27], v[224:227], v[68:71], v[24:27]
	v_mfma_f32_16x16x32_bf16 v[16:19], v[224:227], v[84:87], v[16:19]
	v_mfma_f32_16x16x32_bf16 v[4:7], v[100:103], v[208:211], v[4:7]
	v_mfma_f32_16x16x32_bf16 v[0:3], v[224:227], v[208:211], v[0:3]
	v_mfma_f32_16x16x32_bf16 v[28:31], v[100:103], v[68:71], v[28:31]
	v_mfma_f32_16x16x32_bf16 v[24:27], v[160:163], v[76:79], v[24:27]
	v_mfma_f32_16x16x32_bf16 v[20:23], v[100:103], v[84:87], v[20:23]
	v_mfma_f32_16x16x32_bf16 v[16:19], v[160:163], v[92:95], v[16:19]
	v_mfma_f32_16x16x32_bf16 v[12:15], v[100:103], v[200:203], v[12:15]
	v_mfma_f32_16x16x32_bf16 v[8:11], v[224:227], v[200:203], v[8:11]
	v_mfma_f32_16x16x32_bf16 v[4:7], v[108:111], v[212:215], v[4:7]
	v_mfma_f32_16x16x32_bf16 v[0:3], v[160:163], v[212:215], v[0:3]
	v_mfma_f32_16x16x32_bf16 v[146:149], v[108:111], v[76:79], v[28:31]
	v_mfma_f32_16x16x32_bf16 v[178:181], v[108:111], v[92:95], v[20:23]
	v_mfma_f32_16x16x32_bf16 v[182:185], v[108:111], v[204:207], v[12:15]
	v_mfma_f32_16x16x32_bf16 v[200:203], v[160:163], v[204:207], v[8:11]
	s_barrier
	s_nop 0
	s_nop 0
	ds_read_b128 v[8:11], v158
	ds_read_b128 v[12:15], v158 offset:1024
	ds_read_b128 v[160:163], v158 offset:2048
	ds_read_b128 v[204:207], v158 offset:3072
	ds_read_b128 v[20:23], v155 offset:32768
	ds_read_b128 v[28:31], v155 offset:33792
	ds_read_b128 v[36:39], v173 offset:32768
	ds_read_b128 v[44:47], v173 offset:33792
	ds_read_b128 v[52:55], v174 offset:32768
	ds_read_b128 v[208:211], v174 offset:33792
	ds_read_b128 v[212:215], v175 offset:32768
	ds_read_b128 v[224:227], v175 offset:33792
	s_waitcnt vmcnt(2)
	s_barrier
; #define LDA(dst,b,h) _Pragma("unroll") for(int m=0;m<4;++m) _Pragma("unroll") for(int k=0;k<2;++k) \
;     dst[m][k]=*reinterpret_cast<const bf16x8*>((char*)SA(b,h)+lds_byte(wr*64+m*16+fr,k*32+fq*8))
; #define LDB(dst,b,h) _Pragma("unroll") for(int n=0;n<2;++n) _Pragma("unroll") for(int k=0;k<2;++k) \
;     dst[n][k]=*reinterpret_cast<const bf16x8*>((char*)SB(b,h)+lds_byte(wc*32+n*16+fr,k*32+fq*8))
; #define MMA(ai,bj,At_,Bt_) do{__builtin_amdgcn_s_setprio(1); \
;     _Pragma("unroll") for(int m=0;m<4;++m) _Pragma("unroll") for(int n=0;n<2;++n) _Pragma("unroll") for(int k=0;k<2;++k) \
;       acc[ai][bj][m][n]=__builtin_amdgcn_mfma_f32_16x16x32_bf16(Bt_[n][k],At_[m][k],acc[ai][bj][m][n],0,0,0); \
;     __builtin_amdgcn_s_setprio(0);}while(0)
; #define WAIT_V(n) asm volatile("s_waitcnt vmcnt(" #n ")":::"memory")
; #define WAIT_L(n) asm volatile("s_waitcnt lgkmcnt(" #n ")":::"memory")
; #define BAR __builtin_amdgcn_s_barrier()
; DEVINL void gemm8_mainloop(const u16* A, long lda, const u16* Bt, long ldb, int K, int brow, int bcol, f32x4 (&acc)[2][2][4][2], char* smem, int tid) {
;     ...
;   { LDB(B0,1,0); LDA(At,1,0); WAIT_V(2); BAR; WAIT_L(0); MMA(0,0,At,B0); BAR;
;     LDB(B1,1,1); WAIT_V(0); BAR; WAIT_L(0); MMA(0,1,At,B1); BAR;
;     LDA(At,1,1); BAR; WAIT_L(0); MMA(1,0,At,B0); MMA(1,1,At,B1); BAR; }
;   if(wr==0)BAR;
	s_waitcnt lgkmcnt(0)
	v_mfma_f32_16x16x32_bf16 v[68:71], v[8:11], v[20:23], v[124:127]
	v_mfma_f32_16x16x32_bf16 v[124:127], v[12:15], v[28:31], v[68:71]
	v_mfma_f32_16x16x32_bf16 v[68:71], v[160:163], v[20:23], v[120:123]
	v_mfma_f32_16x16x32_bf16 v[120:123], v[204:207], v[28:31], v[68:71]
	v_mfma_f32_16x16x32_bf16 v[68:71], v[8:11], v[36:39], v[116:119]
	v_mfma_f32_16x16x32_bf16 v[108:111], v[12:15], v[44:47], v[68:71]
	v_mfma_f32_16x16x32_bf16 v[68:71], v[160:163], v[36:39], v[112:115]
	v_mfma_f32_16x16x32_bf16 v[100:103], v[204:207], v[44:47], v[68:71]
	v_mfma_f32_16x16x32_bf16 v[68:71], v[8:11], v[52:55], v[138:141]
	v_mfma_f32_16x16x32_bf16 v[92:95], v[12:15], v[208:211], v[68:71]
	v_mfma_f32_16x16x32_bf16 v[68:71], v[160:163], v[52:55], v[104:107]
	v_mfma_f32_16x16x32_bf16 v[84:87], v[204:207], v[208:211], v[68:71]
	v_mfma_f32_16x16x32_bf16 v[68:71], v[8:11], v[212:215], v[220:223]
	v_mfma_f32_16x16x32_bf16 v[76:79], v[12:15], v[224:227], v[68:71]
	v_mfma_f32_16x16x32_bf16 v[68:71], v[160:163], v[212:215], v[96:99]
	v_mfma_f32_16x16x32_bf16 v[68:71], v[204:207], v[224:227], v[68:71]
	s_barrier
	ds_read_b128 v[138:141], v156
	ds_read_b128 v[220:223], v156 offset:1024
	ds_read_b128 v[236:239], v156 offset:2048
	ds_read_b128 v[156:159], v156 offset:3072
	s_waitcnt vmcnt(0)
	s_barrier
	s_waitcnt lgkmcnt(0)
	v_mfma_f32_16x16x32_bf16 v[96:99], v[138:141], v[20:23], v[228:231]
	v_mfma_f32_16x16x32_bf16 v[20:23], v[236:239], v[20:23], v[88:91]
	v_mfma_f32_16x16x32_bf16 v[112:115], v[156:159], v[28:31], v[20:23]
	v_mfma_f32_16x16x32_bf16 v[20:23], v[138:141], v[36:39], v[188:191]
	v_mfma_f32_16x16x32_bf16 v[104:107], v[220:223], v[44:47], v[20:23]
	v_mfma_f32_16x16x32_bf16 v[20:23], v[236:239], v[36:39], v[80:83]
	v_mfma_f32_16x16x32_bf16 v[116:119], v[220:223], v[28:31], v[96:99]
	v_mfma_f32_16x16x32_bf16 v[96:99], v[156:159], v[44:47], v[20:23]
	v_mfma_f32_16x16x32_bf16 v[20:23], v[138:141], v[52:55], v[192:195]
	v_mfma_f32_16x16x32_bf16 v[88:91], v[220:223], v[208:211], v[20:23]
	v_mfma_f32_16x16x32_bf16 v[20:23], v[236:239], v[52:55], v[72:75]
	v_mfma_f32_16x16x32_bf16 v[80:83], v[156:159], v[208:211], v[20:23]
	v_mfma_f32_16x16x32_bf16 v[20:23], v[138:141], v[212:215], v[196:199]
	v_mfma_f32_16x16x32_bf16 v[72:75], v[220:223], v[224:227], v[20:23]
	v_mfma_f32_16x16x32_bf16 v[20:23], v[236:239], v[212:215], v[64:67]
	v_mfma_f32_16x16x32_bf16 v[64:67], v[156:159], v[224:227], v[20:23]
	s_barrier
	ds_read_b128 v[186:189], v155 offset:49152
	ds_read_b128 v[190:193], v155 offset:50176
	ds_read_b128 v[194:197], v173 offset:49152
	ds_read_b128 v[208:211], v173 offset:50176
	ds_read_b128 v[212:215], v174 offset:49152
	ds_read_b128 v[224:227], v174 offset:50176
	ds_read_b128 v[228:231], v175 offset:49152
	ds_read_b128 v[240:243], v175 offset:50176
	s_barrier
	s_waitcnt lgkmcnt(0)
	v_mfma_f32_16x16x32_bf16 v[20:23], v[8:11], v[186:189], v[60:63]
	v_mfma_f32_16x16x32_bf16 v[60:63], v[12:15], v[190:193], v[20:23]
	v_mfma_f32_16x16x32_bf16 v[20:23], v[160:163], v[186:189], v[56:59]
	v_mfma_f32_16x16x32_bf16 v[52:55], v[204:207], v[190:193], v[20:23]
	v_mfma_f32_16x16x32_bf16 v[20:23], v[8:11], v[194:197], v[216:219]
	v_mfma_f32_16x16x32_bf16 v[44:47], v[12:15], v[208:211], v[20:23]
	v_mfma_f32_16x16x32_bf16 v[20:23], v[160:163], v[194:197], v[48:51]
	v_mfma_f32_16x16x32_bf16 v[36:39], v[204:207], v[208:211], v[20:23]
	v_mfma_f32_16x16x32_bf16 v[20:23], v[8:11], v[212:215], v[232:235]
	v_mfma_f32_16x16x32_bf16 v[8:11], v[8:11], v[228:231], v[142:145]
	v_mfma_f32_16x16x32_bf16 v[28:31], v[12:15], v[224:227], v[20:23]
	v_mfma_f32_16x16x32_bf16 v[20:23], v[160:163], v[212:215], v[40:43]
	v_mfma_f32_16x16x32_bf16 v[12:15], v[12:15], v[240:243], v[8:11]
	v_mfma_f32_16x16x32_bf16 v[8:11], v[160:163], v[228:231], v[32:35]
	v_mfma_f32_16x16x32_bf16 v[20:23], v[204:207], v[224:227], v[20:23]
	v_mfma_f32_16x16x32_bf16 v[8:11], v[204:207], v[240:243], v[8:11]
	v_mfma_f32_16x16x32_bf16 v[32:35], v[138:141], v[186:189], v[146:149]
	v_mfma_f32_16x16x32_bf16 v[24:27], v[236:239], v[186:189], v[24:27]
	v_mfma_f32_16x16x32_bf16 v[16:19], v[236:239], v[194:197], v[16:19]
	v_mfma_f32_16x16x32_bf16 v[56:59], v[220:223], v[190:193], v[32:35]
	v_mfma_f32_16x16x32_bf16 v[48:51], v[156:159], v[190:193], v[24:27]
	v_mfma_f32_16x16x32_bf16 v[24:27], v[138:141], v[194:197], v[178:181]
	v_mfma_f32_16x16x32_bf16 v[32:35], v[156:159], v[208:211], v[16:19]
	v_mfma_f32_16x16x32_bf16 v[16:19], v[138:141], v[212:215], v[182:185]
	v_mfma_f32_16x16x32_bf16 v[40:43], v[220:223], v[208:211], v[24:27]
	v_mfma_f32_16x16x32_bf16 v[24:27], v[220:223], v[224:227], v[16:19]
	v_mfma_f32_16x16x32_bf16 v[16:19], v[236:239], v[212:215], v[200:203]
	v_mfma_f32_16x16x32_bf16 v[4:7], v[138:141], v[228:231], v[4:7]
	v_mfma_f32_16x16x32_bf16 v[0:3], v[236:239], v[228:231], v[0:3]
	v_mfma_f32_16x16x32_bf16 v[16:19], v[156:159], v[224:227], v[16:19]
	v_mfma_f32_16x16x32_bf16 v[4:7], v[220:223], v[240:243], v[4:7]
	v_mfma_f32_16x16x32_bf16 v[0:3], v[156:159], v[240:243], v[0:3]
	s_setprio 0
	s_cmpk_gt_u32 s0, 0xff
	s_barrier
	s_cbranch_scc1 .LBB0_919
	s_barrier

; #define STAGE(P,BASE,LD,br,kt) do{long _g=(long)(br)*(LD)+(long)(kt)*BK; \
;     _Pragma("unroll") for(int _i=0;_i<2;++_i){int _b=tid*16+_i*8192;int _r,_c;stage_rc(_b,_r,_c); \
;       __builtin_amdgcn_global_load_lds((const unsigned*)((BASE)+_g+(long)_r*(LD)+_c), \
;         (unsigned*)((char*)(P)+_b),16,0,0);}}while(0)
; #define STAGE(P,BASE,LD,br,kt) do{long _g=(long)(br)*(LD)+(long)(kt)*BK; \
;     _Pragma("unroll") for(int _i=0;_i<2;++_i){int _b=tid*16+_i*8192;int _r,_c;stage_rc(_b,_r,_c); \
;       __builtin_amdgcn_global_load_lds((const unsigned*)((BASE)+_g+(long)_r*(LD)+_c), \
;         (unsigned*)((char*)(P)+_b),16,0,0);}}while(0)
; #define LDA(dst,b,h) _Pragma("unroll") for(int m=0;m<4;++m) _Pragma("unroll") for(int k=0;k<2;++k) \
;     dst[m][k]=*reinterpret_cast<const bf16x8*>((char*)SA(b,h)+lds_byte(wr*64+m*16+fr,k*32+fq*8))
; #define LDB(dst,b,h) _Pragma("unroll") for(int n=0;n<2;++n) _Pragma("unroll") for(int k=0;k<2;++k) \
;     dst[n][k]=*reinterpret_cast<const bf16x8*>((char*)SB(b,h)+lds_byte(wc*32+n*16+fr,k*32+fq*8))
; #define MMA(ai,bj,At_,Bt_) do{__builtin_amdgcn_s_setprio(1); \
;     _Pragma("unroll") for(int m=0;m<4;++m) _Pragma("unroll") for(int n=0;n<2;++n) _Pragma("unroll") for(int k=0;k<2;++k) \
;       acc[ai][bj][m][n]=__builtin_amdgcn_mfma_f32_16x16x32_bf16(Bt_[n][k],At_[m][k],acc[ai][bj][m][n],0,0,0); \
;     __builtin_amdgcn_s_setprio(0);}while(0)
; #define WAIT_L(n) asm volatile("s_waitcnt lgkmcnt(" #n ")":::"memory")
; #define BAR __builtin_amdgcn_s_barrier()
; #define SCHED __builtin_amdgcn_sched_barrier(0)
; DEVINL void gemm8_mainloop(const u16* A, long lda, const u16* Bt, long ldb, int K, int brow, int bcol, f32x4 (&acc)[2][2][4][2], char* smem, int tid) {
;     ...
;   for(int t=0;t<nt-2;t+=2){
;     LDB(B0,0,0); SCHED; LDA(At,0,0); STAGE(SA(1,1),A,lda,brow+HALF,t+1);
;     WAIT_L(8); BAR; WAIT_L(0); MMA(0,0,At,B0); BAR; SCHED;
;     LDB(B1,0,1); STAGE(SB(0,0),Bt,ldb,bcol,t+2);
;     BAR; WAIT_L(0); MMA(0,1,At,B1); BAR;
;     LDA(At,0,1); STAGE(SA(0,0),A,lda,brow,t+2);
.LBB0_965:
	ds_read_b128 v[178:181], v163
	ds_read_b128 v[182:185], v163 offset:1024
	ds_read_b128 v[186:189], v163 offset:2048
	ds_read_b128 v[190:193], v163 offset:3072
	v_add_u32_e32 v174, 0xc000, v152
	v_lshl_add_u64 v[242:243], s[94:95], 0, v[146:147]
	v_readfirstlane_b32 s25, v174
	v_add_u32_e32 v175, 0xe000, v152
	v_add_u32_e32 v171, s0, v162
	v_add_u32_e32 v172, s1, v162
	v_add_u32_e32 v173, s27, v162
	v_lshl_add_u64 v[164:165], v[242:243], 0, s[4:5]
	s_mov_b32 m0, s25
	v_lshl_add_u64 v[244:245], s[94:95], 0, v[148:149]
	v_readfirstlane_b32 s25, v175
	ds_read_b128 v[166:169], v153
	ds_read_b128 v[194:197], v153 offset:1024
	ds_read_b128 v[198:201], v171
	ds_read_b128 v[202:205], v171 offset:1024
	ds_read_b128 v[206:209], v172
	ds_read_b128 v[210:213], v172 offset:1024
	ds_read_b128 v[214:217], v173
	ds_read_b128 v[218:221], v173 offset:1024
	global_load_lds_dwordx4 v[164:165], off
	v_lshl_add_u64 v[164:165], v[244:245], 0, s[4:5]
	s_mov_b32 m0, s25
	s_nop 0
	global_load_lds_dwordx4 v[164:165], off
	s_waitcnt lgkmcnt(8)
	s_barrier
	s_waitcnt lgkmcnt(0)
	v_mfma_f32_16x16x32_bf16 v[124:127], v[178:181], v[166:169], v[124:127]
	v_mfma_f32_16x16x32_bf16 v[120:123], v[186:189], v[166:169], v[120:123]
	v_mfma_f32_16x16x32_bf16 v[116:119], v[178:181], v[198:201], v[116:119]
	v_mfma_f32_16x16x32_bf16 v[112:115], v[186:189], v[198:201], v[112:115]
	v_mfma_f32_16x16x32_bf16 v[108:111], v[178:181], v[206:209], v[108:111]
	v_mfma_f32_16x16x32_bf16 v[104:107], v[186:189], v[206:209], v[104:107]
	v_mfma_f32_16x16x32_bf16 v[100:103], v[178:181], v[214:217], v[100:103]
	v_mfma_f32_16x16x32_bf16 v[96:99], v[186:189], v[214:217], v[96:99]
	v_mfma_f32_16x16x32_bf16 v[124:127], v[182:185], v[194:197], v[124:127]
	v_mfma_f32_16x16x32_bf16 v[120:123], v[190:193], v[194:197], v[120:123]
	v_mfma_f32_16x16x32_bf16 v[116:119], v[182:185], v[202:205], v[116:119]
	v_mfma_f32_16x16x32_bf16 v[112:115], v[190:193], v[202:205], v[112:115]
	v_mfma_f32_16x16x32_bf16 v[108:111], v[182:185], v[210:213], v[108:111]
	v_mfma_f32_16x16x32_bf16 v[104:107], v[190:193], v[210:213], v[104:107]
	v_mfma_f32_16x16x32_bf16 v[100:103], v[182:185], v[218:221], v[100:103]
	v_mfma_f32_16x16x32_bf16 v[96:99], v[190:193], v[218:221], v[96:99]
	s_barrier
	v_add_u32_e32 v164, s30, v154
	v_lshl_add_u64 v[246:247], s[94:95], 0, v[142:143]
	v_readfirstlane_b32 s25, v164
	v_add_u32_e32 v165, 0x2000, v164
	v_lshl_add_u64 v[238:239], v[246:247], 0, s[6:7]
	s_mov_b32 m0, s25
	v_lshl_add_u64 v[248:249], s[94:95], 0, v[144:145]
	v_readfirstlane_b32 s25, v165
	ds_read_b128 v[222:225], v160
	ds_read_b128 v[226:229], v160 offset:1024
	ds_read_b128 v[230:233], v160 offset:2048
	ds_read_b128 v[234:237], v160 offset:3072
	global_load_lds_dwordx4 v[238:239], off
	v_lshl_add_u64 v[238:239], v[248:249], 0, s[6:7]
	s_mov_b32 m0, s25
	s_nop 0
	global_load_lds_dwordx4 v[238:239], off
	s_barrier
	s_waitcnt lgkmcnt(0)
	v_mfma_f32_16x16x32_bf16 v[92:95], v[222:225], v[166:169], v[92:95]
	v_mfma_f32_16x16x32_bf16 v[88:91], v[230:233], v[166:169], v[88:91]
	v_mfma_f32_16x16x32_bf16 v[84:87], v[222:225], v[198:201], v[84:87]
	v_mfma_f32_16x16x32_bf16 v[80:83], v[230:233], v[198:201], v[80:83]
	v_mfma_f32_16x16x32_bf16 v[76:79], v[222:225], v[206:209], v[76:79]
	v_mfma_f32_16x16x32_bf16 v[72:75], v[230:233], v[206:209], v[72:75]
	v_mfma_f32_16x16x32_bf16 v[68:71], v[222:225], v[214:217], v[68:71]
	v_mfma_f32_16x16x32_bf16 v[64:67], v[230:233], v[214:217], v[64:67]
	v_mfma_f32_16x16x32_bf16 v[92:95], v[226:229], v[194:197], v[92:95]
	v_mfma_f32_16x16x32_bf16 v[88:91], v[234:237], v[194:197], v[88:91]
	v_mfma_f32_16x16x32_bf16 v[84:87], v[226:229], v[202:205], v[84:87]
	v_mfma_f32_16x16x32_bf16 v[80:83], v[234:237], v[202:205], v[80:83]
	v_mfma_f32_16x16x32_bf16 v[76:79], v[226:229], v[210:213], v[76:79]
	v_mfma_f32_16x16x32_bf16 v[72:75], v[234:237], v[210:213], v[72:75]
	v_mfma_f32_16x16x32_bf16 v[68:71], v[226:229], v[218:221], v[68:71]
	v_mfma_f32_16x16x32_bf16 v[64:67], v[234:237], v[218:221], v[64:67]
	v_readfirstlane_b32 s25, v152
	v_lshl_add_u64 v[166:167], v[242:243], 0, s[8:9]
	s_mov_b32 m0, s25
	s_barrier
	ds_read_b128 v[194:197], v153 offset:16384
	ds_read_b128 v[198:201], v153 offset:17408
	ds_read_b128 v[202:205], v171 offset:16384
	ds_read_b128 v[206:209], v171 offset:17408
	ds_read_b128 v[210:213], v172 offset:16384
	ds_read_b128 v[214:217], v172 offset:17408
	ds_read_b128 v[218:221], v173 offset:16384
	ds_read_b128 v[238:241], v173 offset:17408
	global_load_lds_dwordx4 v[166:167], off
	v_add_u32_e32 v166, 0x2000, v152
	v_lshl_add_u64 v[168:169], v[244:245], 0, s[8:9]
	v_readfirstlane_b32 s25, v166
	s_mov_b32 m0, s25
	s_nop 0
	global_load_lds_dwordx4 v[168:169], off
	s_barrier
	s_waitcnt lgkmcnt(0)
	v_mfma_f32_16x16x32_bf16 v[60:63], v[178:181], v[194:197], v[60:63]
	v_mfma_f32_16x16x32_bf16 v[56:59], v[186:189], v[194:197], v[56:59]
	v_mfma_f32_16x16x32_bf16 v[52:55], v[178:181], v[202:205], v[52:55]
	v_mfma_f32_16x16x32_bf16 v[48:51], v[186:189], v[202:205], v[48:51]
	v_mfma_f32_16x16x32_bf16 v[44:47], v[178:181], v[210:213], v[44:47]
	v_mfma_f32_16x16x32_bf16 v[40:43], v[186:189], v[210:213], v[40:43]
	v_mfma_f32_16x16x32_bf16 v[36:39], v[178:181], v[218:221], v[36:39]
	v_mfma_f32_16x16x32_bf16 v[32:35], v[186:189], v[218:221], v[32:35]
	v_mfma_f32_16x16x32_bf16 v[60:63], v[182:185], v[198:201], v[60:63]
	v_mfma_f32_16x16x32_bf16 v[56:59], v[190:193], v[198:201], v[56:59]
	v_mfma_f32_16x16x32_bf16 v[52:55], v[182:185], v[206:209], v[52:55]
	v_mfma_f32_16x16x32_bf16 v[48:51], v[190:193], v[206:209], v[48:51]
	v_mfma_f32_16x16x32_bf16 v[44:47], v[182:185], v[214:217], v[44:47]
	v_mfma_f32_16x16x32_bf16 v[40:43], v[190:193], v[214:217], v[40:43]
	v_mfma_f32_16x16x32_bf16 v[36:39], v[182:185], v[238:241], v[36:39]
	v_mfma_f32_16x16x32_bf16 v[32:35], v[190:193], v[238:241], v[32:35]
	s_barrier
; #define STAGE(P,BASE,LD,br,kt) do{long _g=(long)(br)*(LD)+(long)(kt)*BK; \
;     _Pragma("unroll") for(int _i=0;_i<2;++_i){int _b=tid*16+_i*8192;int _r,_c;stage_rc(_b,_r,_c); \
;       __builtin_amdgcn_global_load_lds((const unsigned*)((BASE)+_g+(long)_r*(LD)+_c), \
;         (unsigned*)((char*)(P)+_b),16,0,0);}}while(0)
; #define STAGE(P,BASE,LD,br,kt) do{long _g=(long)(br)*(LD)+(long)(kt)*BK; \
;     _Pragma("unroll") for(int _i=0;_i<2;++_i){int _b=tid*16+_i*8192;int _r,_c;stage_rc(_b,_r,_c); \
;       __builtin_amdgcn_global_load_lds((const unsigned*)((BASE)+_g+(long)_r*(LD)+_c), \
;         (unsigned*)((char*)(P)+_b),16,0,0);}}while(0)
; #define LDA(dst,b,h) _Pragma("unroll") for(int m=0;m<4;++m) _Pragma("unroll") for(int k=0;k<2;++k) \
;     dst[m][k]=*reinterpret_cast<const bf16x8*>((char*)SA(b,h)+lds_byte(wr*64+m*16+fr,k*32+fq*8))
; #define LDB(dst,b,h) _Pragma("unroll") for(int n=0;n<2;++n) _Pragma("unroll") for(int k=0;k<2;++k) \
;     dst[n][k]=*reinterpret_cast<const bf16x8*>((char*)SB(b,h)+lds_byte(wc*32+n*16+fr,k*32+fq*8))
; #define MMA(ai,bj,At_,Bt_) do{__builtin_amdgcn_s_setprio(1); \
;     _Pragma("unroll") for(int m=0;m<4;++m) _Pragma("unroll") for(int n=0;n<2;++n) _Pragma("unroll") for(int k=0;k<2;++k) \
;       acc[ai][bj][m][n]=__builtin_amdgcn_mfma_f32_16x16x32_bf16(Bt_[n][k],At_[m][k],acc[ai][bj][m][n],0,0,0); \
;     __builtin_amdgcn_s_setprio(0);}while(0)
; #define WAIT_V(n) asm volatile("s_waitcnt vmcnt(" #n ")":::"memory")
; #define WAIT_L(n) asm volatile("s_waitcnt lgkmcnt(" #n ")":::"memory")
; #define BAR __builtin_amdgcn_s_barrier()
; #define SCHED __builtin_amdgcn_sched_barrier(0)
; DEVINL void gemm8_mainloop(const u16* A, long lda, const u16* Bt, long ldb, int K, int brow, int bcol, f32x4 (&acc)[2][2][4][2], char* smem, int tid) {
;     ...
;     LDA(At,0,1); STAGE(SA(0,0),A,lda,brow,t+2);
;     BAR; WAIT_L(0); MMA(1,0,At,B0); BAR; SCHED;
;     STAGE(SB(0,1),Bt,ldb,bcol+HALF,t+2);
;     WAIT_V(6); BAR; MMA(1,1,At,B1); BAR;
;     LDB(B0,1,0); SCHED; LDA(At,1,0); STAGE(SA(0,1),A,lda,brow+HALF,t+2);
;     WAIT_L(8); BAR; WAIT_L(0); MMA(0,0,At,B0); BAR; SCHED;
;     LDB(B1,1,1); STAGE(SB(1,0),Bt,ldb,bcol,t+3);
	v_add_u32_e32 v167, s31, v154
	v_lshl_add_u64 v[168:169], v[246:247], 0, s[10:11]
	v_readfirstlane_b32 s25, v167
	s_mov_b32 m0, s25
	v_lshl_add_u64 v[178:179], v[248:249], 0, s[10:11]
	global_load_lds_dwordx4 v[168:169], off
	v_add_u32_e32 v168, 0x2000, v167
	s_nop 0
	v_readfirstlane_b32 s25, v168
	s_mov_b32 m0, s25
	s_nop 0
	global_load_lds_dwordx4 v[178:179], off
	s_waitcnt vmcnt(6)
	s_barrier
	v_mfma_f32_16x16x32_bf16 v[28:31], v[222:225], v[194:197], v[28:31]
	v_mfma_f32_16x16x32_bf16 v[24:27], v[230:233], v[194:197], v[24:27]
	v_mfma_f32_16x16x32_bf16 v[20:23], v[222:225], v[202:205], v[20:23]
	v_mfma_f32_16x16x32_bf16 v[16:19], v[230:233], v[202:205], v[16:19]
	v_mfma_f32_16x16x32_bf16 v[12:15], v[222:225], v[210:213], v[12:15]
	v_mfma_f32_16x16x32_bf16 v[8:11], v[230:233], v[210:213], v[8:11]
	v_mfma_f32_16x16x32_bf16 v[4:7], v[222:225], v[218:221], v[4:7]
	v_mfma_f32_16x16x32_bf16 v[0:3], v[230:233], v[218:221], v[0:3]
	v_mfma_f32_16x16x32_bf16 v[28:31], v[226:229], v[198:201], v[28:31]
	v_mfma_f32_16x16x32_bf16 v[24:27], v[234:237], v[198:201], v[24:27]
	v_mfma_f32_16x16x32_bf16 v[20:23], v[226:229], v[206:209], v[20:23]
	v_mfma_f32_16x16x32_bf16 v[16:19], v[234:237], v[206:209], v[16:19]
	v_mfma_f32_16x16x32_bf16 v[12:15], v[226:229], v[214:217], v[12:15]
	v_mfma_f32_16x16x32_bf16 v[8:11], v[234:237], v[214:217], v[8:11]
	v_mfma_f32_16x16x32_bf16 v[4:7], v[226:229], v[238:241], v[4:7]
	v_mfma_f32_16x16x32_bf16 v[0:3], v[234:237], v[238:241], v[0:3]
	s_barrier
	ds_read_b128 v[178:181], v157
	ds_read_b128 v[182:185], v157 offset:1024
	ds_read_b128 v[186:189], v157 offset:2048
	ds_read_b128 v[190:193], v157 offset:3072
	v_add_u32_e32 v169, 0x4000, v152
	v_add_u32_e32 v170, 0x6000, v152
	v_readfirstlane_b32 s25, v169
	v_lshl_add_u64 v[226:227], v[242:243], 0, s[12:13]
	s_mov_b32 m0, s25
	v_readfirstlane_b32 s25, v170
	ds_read_b128 v[194:197], v153 offset:32768
	ds_read_b128 v[198:201], v153 offset:33792
	ds_read_b128 v[202:205], v171 offset:32768
	ds_read_b128 v[206:209], v171 offset:33792
	ds_read_b128 v[210:213], v172 offset:32768
	ds_read_b128 v[214:217], v172 offset:33792
	ds_read_b128 v[218:221], v173 offset:32768
	ds_read_b128 v[222:225], v173 offset:33792
	global_load_lds_dwordx4 v[226:227], off
	v_lshl_add_u64 v[226:227], v[244:245], 0, s[12:13]
	s_mov_b32 m0, s25
	s_nop 0
	global_load_lds_dwordx4 v[226:227], off
	s_waitcnt lgkmcnt(8)
	s_barrier
	s_waitcnt lgkmcnt(0)
	v_mfma_f32_16x16x32_bf16 v[124:127], v[178:181], v[194:197], v[124:127]
	v_mfma_f32_16x16x32_bf16 v[120:123], v[186:189], v[194:197], v[120:123]
	v_mfma_f32_16x16x32_bf16 v[116:119], v[178:181], v[202:205], v[116:119]
	v_mfma_f32_16x16x32_bf16 v[112:115], v[186:189], v[202:205], v[112:115]
	v_mfma_f32_16x16x32_bf16 v[108:111], v[178:181], v[210:213], v[108:111]
	v_mfma_f32_16x16x32_bf16 v[104:107], v[186:189], v[210:213], v[104:107]
	v_mfma_f32_16x16x32_bf16 v[100:103], v[178:181], v[218:221], v[100:103]
	v_mfma_f32_16x16x32_bf16 v[96:99], v[186:189], v[218:221], v[96:99]
	v_mfma_f32_16x16x32_bf16 v[124:127], v[182:185], v[198:201], v[124:127]
	v_mfma_f32_16x16x32_bf16 v[120:123], v[190:193], v[198:201], v[120:123]
	v_mfma_f32_16x16x32_bf16 v[116:119], v[182:185], v[206:209], v[116:119]
	v_mfma_f32_16x16x32_bf16 v[112:115], v[190:193], v[206:209], v[112:115]
	v_mfma_f32_16x16x32_bf16 v[108:111], v[182:185], v[214:217], v[108:111]
	v_mfma_f32_16x16x32_bf16 v[104:107], v[190:193], v[214:217], v[104:107]
	v_mfma_f32_16x16x32_bf16 v[100:103], v[182:185], v[222:225], v[100:103]
	v_mfma_f32_16x16x32_bf16 v[96:99], v[190:193], v[222:225], v[96:99]
	s_barrier
	v_readfirstlane_b32 s25, v156
	v_add_u32_e32 v177, 0x2000, v156
	v_lshl_add_u64 v[250:251], v[246:247], 0, s[14:15]
	s_mov_b32 m0, s25
	v_readfirstlane_b32 s25, v177
	ds_read_b128 v[226:229], v155
	ds_read_b128 v[230:233], v155 offset:1024
	ds_read_b128 v[234:237], v155 offset:2048
	ds_read_b128 v[238:241], v155 offset:3072
	global_load_lds_dwordx4 v[250:251], off
	v_lshl_add_u64 v[250:251], v[248:249], 0, s[14:15]
	s_mov_b32 m0, s25
	s_nop 0
	global_load_lds_dwordx4 v[250:251], off
	s_barrier
	s_waitcnt lgkmcnt(0)
	v_mfma_f32_16x16x32_bf16 v[92:95], v[226:229], v[194:197], v[92:95]
	v_mfma_f32_16x16x32_bf16 v[88:91], v[234:237], v[194:197], v[88:91]
	v_mfma_f32_16x16x32_bf16 v[84:87], v[226:229], v[202:205], v[84:87]
	v_mfma_f32_16x16x32_bf16 v[80:83], v[234:237], v[202:205], v[80:83]
	v_mfma_f32_16x16x32_bf16 v[76:79], v[226:229], v[210:213], v[76:79]
	v_mfma_f32_16x16x32_bf16 v[72:75], v[234:237], v[210:213], v[72:75]
	v_mfma_f32_16x16x32_bf16 v[68:71], v[226:229], v[218:221], v[68:71]
	v_mfma_f32_16x16x32_bf16 v[64:67], v[234:237], v[218:221], v[64:67]
	v_mfma_f32_16x16x32_bf16 v[92:95], v[230:233], v[198:201], v[92:95]
	v_mfma_f32_16x16x32_bf16 v[88:91], v[238:241], v[198:201], v[88:91]
	v_mfma_f32_16x16x32_bf16 v[84:87], v[230:233], v[206:209], v[84:87]
	v_mfma_f32_16x16x32_bf16 v[80:83], v[238:241], v[206:209], v[80:83]
	v_mfma_f32_16x16x32_bf16 v[76:79], v[230:233], v[214:217], v[76:79]
	v_mfma_f32_16x16x32_bf16 v[72:75], v[238:241], v[214:217], v[72:75]
	v_mfma_f32_16x16x32_bf16 v[68:71], v[230:233], v[222:225], v[68:71]
	v_mfma_f32_16x16x32_bf16 v[64:67], v[238:241], v[222:225], v[64:67]
	v_readfirstlane_b32 s25, v158
	v_lshl_add_u64 v[242:243], v[242:243], 0, s[16:17]
	s_mov_b32 m0, s25
	v_readfirstlane_b32 s25, v159
	s_barrier
	ds_read_b128 v[194:197], v153 offset:49152
	ds_read_b128 v[198:201], v153 offset:50176
	ds_read_b128 v[202:205], v171 offset:49152
	ds_read_b128 v[206:209], v171 offset:50176
	ds_read_b128 v[210:213], v172 offset:49152
	ds_read_b128 v[214:217], v172 offset:50176
	ds_read_b128 v[218:221], v173 offset:49152
	ds_read_b128 v[222:225], v173 offset:50176
	global_load_lds_dwordx4 v[242:243], off
	v_lshl_add_u64 v[242:243], v[244:245], 0, s[16:17]
	s_mov_b32 m0, s25
	s_nop 0
	global_load_lds_dwordx4 v[242:243], off
	s_barrier
; #define STAGE(P,BASE,LD,br,kt) do{long _g=(long)(br)*(LD)+(long)(kt)*BK; \
;     _Pragma("unroll") for(int _i=0;_i<2;++_i){int _b=tid*16+_i*8192;int _r,_c;stage_rc(_b,_r,_c); \
;       __builtin_amdgcn_global_load_lds((const unsigned*)((BASE)+_g+(long)_r*(LD)+_c), \
;         (unsigned*)((char*)(P)+_b),16,0,0);}}while(0)
; #define STAGE(P,BASE,LD,br,kt) do{long _g=(long)(br)*(LD)+(long)(kt)*BK; \
;     _Pragma("unroll") for(int _i=0;_i<2;++_i){int _b=tid*16+_i*8192;int _r,_c;stage_rc(_b,_r,_c); \
;       __builtin_amdgcn_global_load_lds((const unsigned*)((BASE)+_g+(long)_r*(LD)+_c), \
;         (unsigned*)((char*)(P)+_b),16,0,0);}}while(0)
; #define LDA(dst,b,h) _Pragma("unroll") for(int m=0;m<4;++m) _Pragma("unroll") for(int k=0;k<2;++k) \
;     dst[m][k]=*reinterpret_cast<const bf16x8*>((char*)SA(b,h)+lds_byte(wr*64+m*16+fr,k*32+fq*8))
; #define LDB(dst,b,h) _Pragma("unroll") for(int n=0;n<2;++n) _Pragma("unroll") for(int k=0;k<2;++k) \
;     dst[n][k]=*reinterpret_cast<const bf16x8*>((char*)SB(b,h)+lds_byte(wc*32+n*16+fr,k*32+fq*8))
; #define MMA(ai,bj,At_,Bt_) do{__builtin_amdgcn_s_setprio(1); \
;     _Pragma("unroll") for(int m=0;m<4;++m) _Pragma("unroll") for(int n=0;n<2;++n) _Pragma("unroll") for(int k=0;k<2;++k) \
;       acc[ai][bj][m][n]=__builtin_amdgcn_mfma_f32_16x16x32_bf16(Bt_[n][k],At_[m][k],acc[ai][bj][m][n],0,0,0); \
;     __builtin_amdgcn_s_setprio(0);}while(0)
; #define WAIT_V(n) asm volatile("s_waitcnt vmcnt(" #n ")":::"memory")
; #define WAIT_L(n) asm volatile("s_waitcnt lgkmcnt(" #n ")":::"memory")
; #define BAR __builtin_amdgcn_s_barrier()
; #define SCHED __builtin_amdgcn_sched_barrier(0)
; DEVINL void gemm8_mainloop(const u16* A, long lda, const u16* Bt, long ldb, int K, int brow, int bcol, f32x4 (&acc)[2][2][4][2], char* smem, int tid) {
;     ...
;     LDB(B1,1,1); STAGE(SB(1,0),Bt,ldb,bcol,t+3);
;     BAR; WAIT_L(0); MMA(0,1,At,B1); BAR;
;     LDA(At,1,1); STAGE(SA(1,0),A,lda,brow,t+3);
;     BAR; WAIT_L(0); MMA(1,0,At,B0); BAR; SCHED;
;     STAGE(SB(1,1),Bt,ldb,bcol+HALF,t+3);
;     WAIT_V(6); BAR; MMA(1,1,At,B1); BAR;
;   }
;   { LDB(B0,0,0); LDA(At,0,0); STAGE(SA(1,1),A,lda,brow+HALF,nt-1);
;     BAR; WAIT_L(0); MMA(0,0,At,B0); BAR;
	s_waitcnt lgkmcnt(0)
	v_mfma_f32_16x16x32_bf16 v[60:63], v[178:181], v[194:197], v[60:63]
	v_mfma_f32_16x16x32_bf16 v[56:59], v[186:189], v[194:197], v[56:59]
	v_mfma_f32_16x16x32_bf16 v[52:55], v[178:181], v[202:205], v[52:55]
	v_mfma_f32_16x16x32_bf16 v[48:51], v[186:189], v[202:205], v[48:51]
	v_mfma_f32_16x16x32_bf16 v[44:47], v[178:181], v[210:213], v[44:47]
	v_mfma_f32_16x16x32_bf16 v[40:43], v[186:189], v[210:213], v[40:43]
	v_mfma_f32_16x16x32_bf16 v[36:39], v[178:181], v[218:221], v[36:39]
	v_mfma_f32_16x16x32_bf16 v[32:35], v[186:189], v[218:221], v[32:35]
	v_mfma_f32_16x16x32_bf16 v[60:63], v[182:185], v[198:201], v[60:63]
	v_mfma_f32_16x16x32_bf16 v[56:59], v[190:193], v[198:201], v[56:59]
	v_mfma_f32_16x16x32_bf16 v[52:55], v[182:185], v[206:209], v[52:55]
	v_mfma_f32_16x16x32_bf16 v[48:51], v[190:193], v[206:209], v[48:51]
	v_mfma_f32_16x16x32_bf16 v[44:47], v[182:185], v[214:217], v[44:47]
	v_mfma_f32_16x16x32_bf16 v[40:43], v[190:193], v[214:217], v[40:43]
	v_mfma_f32_16x16x32_bf16 v[36:39], v[182:185], v[222:225], v[36:39]
	v_mfma_f32_16x16x32_bf16 v[32:35], v[190:193], v[222:225], v[32:35]
	s_barrier
	v_readfirstlane_b32 s25, v161
	v_add_u32_e32 v177, 0x2000, v161
	v_lshl_add_u64 v[178:179], v[246:247], 0, s[18:19]
	s_mov_b32 m0, s25
	v_readfirstlane_b32 s25, v177
	global_load_lds_dwordx4 v[178:179], off
	v_lshl_add_u64 v[178:179], v[248:249], 0, s[18:19]
	s_mov_b32 m0, s25
	s_nop 0
	global_load_lds_dwordx4 v[178:179], off
	s_waitcnt vmcnt(6)
	s_barrier
	v_mfma_f32_16x16x32_bf16 v[28:31], v[226:229], v[194:197], v[28:31]
	v_mfma_f32_16x16x32_bf16 v[24:27], v[234:237], v[194:197], v[24:27]
	v_mfma_f32_16x16x32_bf16 v[20:23], v[226:229], v[202:205], v[20:23]
	v_mfma_f32_16x16x32_bf16 v[16:19], v[234:237], v[202:205], v[16:19]
	v_mfma_f32_16x16x32_bf16 v[12:15], v[226:229], v[210:213], v[12:15]
	v_mfma_f32_16x16x32_bf16 v[8:11], v[234:237], v[210:213], v[8:11]
	v_mfma_f32_16x16x32_bf16 v[4:7], v[226:229], v[218:221], v[4:7]
	v_mfma_f32_16x16x32_bf16 v[0:3], v[234:237], v[218:221], v[0:3]
	v_mfma_f32_16x16x32_bf16 v[28:31], v[230:233], v[198:201], v[28:31]
	v_mfma_f32_16x16x32_bf16 v[24:27], v[238:241], v[198:201], v[24:27]
	v_mfma_f32_16x16x32_bf16 v[20:23], v[230:233], v[206:209], v[20:23]
	v_mfma_f32_16x16x32_bf16 v[16:19], v[238:241], v[206:209], v[16:19]
	v_mfma_f32_16x16x32_bf16 v[12:15], v[230:233], v[214:217], v[12:15]
	v_mfma_f32_16x16x32_bf16 v[8:11], v[238:241], v[214:217], v[8:11]
	v_mfma_f32_16x16x32_bf16 v[4:7], v[230:233], v[222:225], v[4:7]
	v_mfma_f32_16x16x32_bf16 v[0:3], v[238:241], v[222:225], v[0:3]
	s_add_i32 s24, s24, 2
	v_lshl_add_u64 v[142:143], v[142:143], 0, s[20:21]
	v_lshl_add_u64 v[144:145], v[144:145], 0, s[20:21]
	v_lshl_add_u64 v[146:147], v[146:147], 0, s[20:21]
	s_cmpk_lt_u32 s24, 0x7c
	v_lshl_add_u64 v[148:149], v[148:149], 0, s[20:21]
	s_barrier
	s_cbranch_scc1 .LBB0_965
	s_or_b32 s0, s26, 0x80
	s_ashr_i32 s1, s0, 31
	s_lshl_b64 s[0:1], s[0:1], 14
	s_add_u32 s0, s62, s0
	s_addc_u32 s1, s63, s1
	s_add_u32 s0, s0, 0x3f80
	s_addc_u32 s1, s1, 0
	v_lshl_add_u64 v[158:159], v[134:135], 1, s[0:1]
	v_readfirstlane_b32 s24, v174
	v_lshl_add_u64 v[138:139], v[138:139], 1, v[158:159]
	s_mov_b32 m0, s24
	ds_read_b128 v[142:145], v163
	ds_read_b128 v[146:149], v163 offset:1024
	ds_read_b128 v[178:181], v163 offset:2048
	ds_read_b128 v[182:185], v163 offset:3072
	ds_read_b128 v[186:189], v153
	ds_read_b128 v[190:193], v153 offset:1024
	ds_read_b128 v[194:197], v171
	ds_read_b128 v[198:201], v171 offset:1024
	ds_read_b128 v[202:205], v172
	ds_read_b128 v[206:209], v172 offset:1024
	ds_read_b128 v[210:213], v173
	ds_read_b128 v[214:217], v173 offset:1024
	global_load_lds_dwordx4 v[138:139], off
	v_lshl_add_u64 v[138:139], v[136:137], 1, s[0:1]
	v_readfirstlane_b32 s0, v175
	v_lshl_add_u64 v[138:139], v[140:141], 1, v[138:139]
	s_mov_b32 m0, s0
	s_nop 0
	global_load_lds_dwordx4 v[138:139], off
	s_barrier
	s_waitcnt lgkmcnt(0)
	v_mfma_f32_16x16x32_bf16 v[124:127], v[142:145], v[186:189], v[124:127]
	v_mfma_f32_16x16x32_bf16 v[120:123], v[178:181], v[186:189], v[120:123]
	v_mfma_f32_16x16x32_bf16 v[116:119], v[142:145], v[194:197], v[116:119]
	v_mfma_f32_16x16x32_bf16 v[112:115], v[178:181], v[194:197], v[112:115]
	v_mfma_f32_16x16x32_bf16 v[100:103], v[142:145], v[210:213], v[100:103]
	v_mfma_f32_16x16x32_bf16 v[96:99], v[178:181], v[210:213], v[96:99]
	v_mfma_f32_16x16x32_bf16 v[124:127], v[146:149], v[190:193], v[124:127]
	v_mfma_f32_16x16x32_bf16 v[120:123], v[182:185], v[190:193], v[120:123]
	v_mfma_f32_16x16x32_bf16 v[116:119], v[146:149], v[198:201], v[116:119]
	v_mfma_f32_16x16x32_bf16 v[112:115], v[182:185], v[198:201], v[112:115]
	v_mfma_f32_16x16x32_bf16 v[108:111], v[142:145], v[202:205], v[108:111]
	v_mfma_f32_16x16x32_bf16 v[104:107], v[178:181], v[202:205], v[104:107]
	v_mfma_f32_16x16x32_bf16 v[100:103], v[146:149], v[214:217], v[100:103]
	v_mfma_f32_16x16x32_bf16 v[96:99], v[182:185], v[214:217], v[96:99]
	v_mfma_f32_16x16x32_bf16 v[138:141], v[146:149], v[206:209], v[108:111]
	v_mfma_f32_16x16x32_bf16 v[218:221], v[182:185], v[206:209], v[104:107]
	s_barrier
	s_nop 1
	s_nop 0
	ds_read_b128 v[104:107], v160
	ds_read_b128 v[108:111], v160 offset:1024
	ds_read_b128 v[222:225], v160 offset:2048
	ds_read_b128 v[158:161], v160 offset:3072
	s_barrier
; #define LDA(dst,b,h) _Pragma("unroll") for(int m=0;m<4;++m) _Pragma("unroll") for(int k=0;k<2;++k) \
;     dst[m][k]=*reinterpret_cast<const bf16x8*>((char*)SA(b,h)+lds_byte(wr*64+m*16+fr,k*32+fq*8))
; #define LDB(dst,b,h) _Pragma("unroll") for(int n=0;n<2;++n) _Pragma("unroll") for(int k=0;k<2;++k) \
;     dst[n][k]=*reinterpret_cast<const bf16x8*>((char*)SB(b,h)+lds_byte(wc*32+n*16+fr,k*32+fq*8))
; #define MMA(ai,bj,At_,Bt_) do{__builtin_amdgcn_s_setprio(1); \
;     _Pragma("unroll") for(int m=0;m<4;++m) _Pragma("unroll") for(int n=0;n<2;++n) _Pragma("unroll") for(int k=0;k<2;++k) \
;       acc[ai][bj][m][n]=__builtin_amdgcn_mfma_f32_16x16x32_bf16(Bt_[n][k],At_[m][k],acc[ai][bj][m][n],0,0,0); \
;     __builtin_amdgcn_s_setprio(0);}while(0)
; #define WAIT_V(n) asm volatile("s_waitcnt vmcnt(" #n ")":::"memory")
; #define WAIT_L(n) asm volatile("s_waitcnt lgkmcnt(" #n ")":::"memory")
; #define BAR __builtin_amdgcn_s_barrier()
; DEVINL void gemm8_mainloop(const u16* A, long lda, const u16* Bt, long ldb, int K, int brow, int bcol, f32x4 (&acc)[2][2][4][2], char* smem, int tid) {
;     ...
;     BAR; WAIT_L(0); MMA(0,0,At,B0); BAR;
;     LDB(B1,0,1); BAR; WAIT_L(0); MMA(0,1,At,B1); BAR;
;     LDA(At,0,1); WAIT_V(4); BAR; WAIT_L(0); MMA(1,0,At,B0); MMA(1,1,At,B1); BAR; }
;   { LDB(B0,1,0); LDA(At,1,0); WAIT_V(2); BAR; WAIT_L(0); MMA(0,0,At,B0); BAR;
	s_waitcnt lgkmcnt(0)
	v_mfma_f32_16x16x32_bf16 v[84:87], v[104:107], v[194:197], v[84:87]
	v_mfma_f32_16x16x32_bf16 v[80:83], v[222:225], v[194:197], v[80:83]
	v_mfma_f32_16x16x32_bf16 v[68:71], v[104:107], v[210:213], v[68:71]
	v_mfma_f32_16x16x32_bf16 v[92:95], v[104:107], v[186:189], v[92:95]
	v_mfma_f32_16x16x32_bf16 v[88:91], v[222:225], v[186:189], v[88:91]
	v_mfma_f32_16x16x32_bf16 v[84:87], v[108:111], v[198:201], v[84:87]
	v_mfma_f32_16x16x32_bf16 v[80:83], v[158:161], v[198:201], v[80:83]
	v_mfma_f32_16x16x32_bf16 v[76:79], v[104:107], v[202:205], v[76:79]
	v_mfma_f32_16x16x32_bf16 v[72:75], v[222:225], v[202:205], v[72:75]
	v_mfma_f32_16x16x32_bf16 v[68:71], v[108:111], v[214:217], v[68:71]
	v_mfma_f32_16x16x32_bf16 v[64:67], v[222:225], v[210:213], v[64:67]
	v_mfma_f32_16x16x32_bf16 v[226:229], v[108:111], v[190:193], v[92:95]
	v_mfma_f32_16x16x32_bf16 v[186:189], v[158:161], v[190:193], v[88:91]
	v_mfma_f32_16x16x32_bf16 v[190:193], v[108:111], v[206:209], v[76:79]
	v_mfma_f32_16x16x32_bf16 v[194:197], v[158:161], v[206:209], v[72:75]
	v_mfma_f32_16x16x32_bf16 v[198:201], v[158:161], v[214:217], v[64:67]
	s_barrier
	s_nop 0
	s_nop 0
	ds_read_b128 v[64:67], v153 offset:16384
	ds_read_b128 v[72:75], v153 offset:17408
	ds_read_b128 v[76:79], v171 offset:16384
	ds_read_b128 v[88:91], v171 offset:17408
	ds_read_b128 v[92:95], v172 offset:16384
	ds_read_b128 v[202:205], v172 offset:17408
	ds_read_b128 v[206:209], v173 offset:16384
	ds_read_b128 v[210:213], v173 offset:17408
	s_waitcnt vmcnt(4)
	s_barrier
	s_waitcnt lgkmcnt(0)
	v_mfma_f32_16x16x32_bf16 v[60:63], v[142:145], v[64:67], v[60:63]
	v_mfma_f32_16x16x32_bf16 v[56:59], v[178:181], v[64:67], v[56:59]
	v_mfma_f32_16x16x32_bf16 v[52:55], v[142:145], v[76:79], v[52:55]
	v_mfma_f32_16x16x32_bf16 v[48:51], v[178:181], v[76:79], v[48:51]
	v_mfma_f32_16x16x32_bf16 v[36:39], v[142:145], v[206:209], v[36:39]
	v_mfma_f32_16x16x32_bf16 v[32:35], v[178:181], v[206:209], v[32:35]
	v_mfma_f32_16x16x32_bf16 v[60:63], v[146:149], v[72:75], v[60:63]
	v_mfma_f32_16x16x32_bf16 v[56:59], v[182:185], v[72:75], v[56:59]
	v_mfma_f32_16x16x32_bf16 v[52:55], v[146:149], v[88:91], v[52:55]
	v_mfma_f32_16x16x32_bf16 v[48:51], v[182:185], v[88:91], v[48:51]
	v_mfma_f32_16x16x32_bf16 v[44:47], v[142:145], v[92:95], v[44:47]
	v_mfma_f32_16x16x32_bf16 v[40:43], v[178:181], v[92:95], v[40:43]
	v_mfma_f32_16x16x32_bf16 v[36:39], v[146:149], v[210:213], v[36:39]
	v_mfma_f32_16x16x32_bf16 v[32:35], v[182:185], v[210:213], v[32:35]
	v_mfma_f32_16x16x32_bf16 v[214:217], v[146:149], v[202:205], v[44:47]
	v_mfma_f32_16x16x32_bf16 v[230:233], v[182:185], v[202:205], v[40:43]
	v_mfma_f32_16x16x32_bf16 v[20:23], v[104:107], v[76:79], v[20:23]
	v_mfma_f32_16x16x32_bf16 v[16:19], v[222:225], v[76:79], v[16:19]
	v_mfma_f32_16x16x32_bf16 v[4:7], v[104:107], v[206:209], v[4:7]
	v_mfma_f32_16x16x32_bf16 v[0:3], v[222:225], v[206:209], v[0:3]
	v_mfma_f32_16x16x32_bf16 v[28:31], v[104:107], v[64:67], v[28:31]
	v_mfma_f32_16x16x32_bf16 v[24:27], v[222:225], v[64:67], v[24:27]
	v_mfma_f32_16x16x32_bf16 v[20:23], v[108:111], v[88:91], v[20:23]
	v_mfma_f32_16x16x32_bf16 v[16:19], v[158:161], v[88:91], v[16:19]
	v_mfma_f32_16x16x32_bf16 v[12:15], v[104:107], v[92:95], v[12:15]
	v_mfma_f32_16x16x32_bf16 v[8:11], v[222:225], v[92:95], v[8:11]
	v_mfma_f32_16x16x32_bf16 v[4:7], v[108:111], v[210:213], v[4:7]
	v_mfma_f32_16x16x32_bf16 v[0:3], v[158:161], v[210:213], v[0:3]
	v_mfma_f32_16x16x32_bf16 v[142:145], v[108:111], v[72:75], v[28:31]
	v_mfma_f32_16x16x32_bf16 v[146:149], v[158:161], v[72:75], v[24:27]
	v_mfma_f32_16x16x32_bf16 v[178:181], v[108:111], v[202:205], v[12:15]
	v_mfma_f32_16x16x32_bf16 v[182:185], v[158:161], v[202:205], v[8:11]
	s_barrier
	s_nop 0
	s_nop 0
	ds_read_b128 v[8:11], v157
	ds_read_b128 v[12:15], v157 offset:1024
	ds_read_b128 v[158:161], v157 offset:2048
	ds_read_b128 v[202:205], v157 offset:3072
	ds_read_b128 v[24:27], v153 offset:32768
	ds_read_b128 v[28:31], v153 offset:33792
	ds_read_b128 v[40:43], v171 offset:32768
	ds_read_b128 v[44:47], v171 offset:33792
	ds_read_b128 v[64:67], v172 offset:32768
	ds_read_b128 v[206:209], v172 offset:33792
	ds_read_b128 v[210:213], v173 offset:32768
	ds_read_b128 v[222:225], v173 offset:33792
	s_waitcnt vmcnt(2)
	s_barrier
; #define LDA(dst,b,h) _Pragma("unroll") for(int m=0;m<4;++m) _Pragma("unroll") for(int k=0;k<2;++k) \
;     dst[m][k]=*reinterpret_cast<const bf16x8*>((char*)SA(b,h)+lds_byte(wr*64+m*16+fr,k*32+fq*8))
; #define LDB(dst,b,h) _Pragma("unroll") for(int n=0;n<2;++n) _Pragma("unroll") for(int k=0;k<2;++k) \
;     dst[n][k]=*reinterpret_cast<const bf16x8*>((char*)SB(b,h)+lds_byte(wc*32+n*16+fr,k*32+fq*8))
; #define MMA(ai,bj,At_,Bt_) do{__builtin_amdgcn_s_setprio(1); \
;     _Pragma("unroll") for(int m=0;m<4;++m) _Pragma("unroll") for(int n=0;n<2;++n) _Pragma("unroll") for(int k=0;k<2;++k) \
;       acc[ai][bj][m][n]=__builtin_amdgcn_mfma_f32_16x16x32_bf16(Bt_[n][k],At_[m][k],acc[ai][bj][m][n],0,0,0); \
;     __builtin_amdgcn_s_setprio(0);}while(0)
; #define WAIT_V(n) asm volatile("s_waitcnt vmcnt(" #n ")":::"memory")
; #define WAIT_L(n) asm volatile("s_waitcnt lgkmcnt(" #n ")":::"memory")
; #define BAR __builtin_amdgcn_s_barrier()
; DEVINL void gemm8_mainloop(const u16* A, long lda, const u16* Bt, long ldb, int K, int brow, int bcol, f32x4 (&acc)[2][2][4][2], char* smem, int tid) {
;     ...
;   { LDB(B0,1,0); LDA(At,1,0); WAIT_V(2); BAR; WAIT_L(0); MMA(0,0,At,B0); BAR;
;     LDB(B1,1,1); WAIT_V(0); BAR; WAIT_L(0); MMA(0,1,At,B1); BAR;
;     LDA(At,1,1); BAR; WAIT_L(0); MMA(1,0,At,B0); MMA(1,1,At,B1); BAR; }
;   if(wr==0)BAR;
	s_waitcnt lgkmcnt(0)
	v_mfma_f32_16x16x32_bf16 v[72:75], v[8:11], v[24:27], v[124:127]
	v_mfma_f32_16x16x32_bf16 v[124:127], v[12:15], v[28:31], v[72:75]
	v_mfma_f32_16x16x32_bf16 v[72:75], v[158:161], v[24:27], v[120:123]
	v_mfma_f32_16x16x32_bf16 v[120:123], v[202:205], v[28:31], v[72:75]
	v_mfma_f32_16x16x32_bf16 v[72:75], v[8:11], v[40:43], v[116:119]
	v_mfma_f32_16x16x32_bf16 v[108:111], v[12:15], v[44:47], v[72:75]
	v_mfma_f32_16x16x32_bf16 v[72:75], v[158:161], v[40:43], v[112:115]
	v_mfma_f32_16x16x32_bf16 v[104:107], v[202:205], v[44:47], v[72:75]
	v_mfma_f32_16x16x32_bf16 v[72:75], v[8:11], v[64:67], v[138:141]
	v_mfma_f32_16x16x32_bf16 v[92:95], v[12:15], v[206:209], v[72:75]
	v_mfma_f32_16x16x32_bf16 v[72:75], v[158:161], v[64:67], v[218:221]
	v_mfma_f32_16x16x32_bf16 v[88:91], v[202:205], v[206:209], v[72:75]
	v_mfma_f32_16x16x32_bf16 v[72:75], v[8:11], v[210:213], v[100:103]
	v_mfma_f32_16x16x32_bf16 v[76:79], v[12:15], v[222:225], v[72:75]
	v_mfma_f32_16x16x32_bf16 v[72:75], v[158:161], v[210:213], v[96:99]
	v_mfma_f32_16x16x32_bf16 v[72:75], v[202:205], v[222:225], v[72:75]
	s_barrier
	ds_read_b128 v[138:141], v155
	ds_read_b128 v[218:221], v155 offset:1024
	ds_read_b128 v[234:237], v155 offset:2048
	ds_read_b128 v[154:157], v155 offset:3072
	s_waitcnt vmcnt(0)
	s_barrier
	s_waitcnt lgkmcnt(0)
	v_mfma_f32_16x16x32_bf16 v[96:99], v[138:141], v[24:27], v[226:229]
	v_mfma_f32_16x16x32_bf16 v[24:27], v[234:237], v[24:27], v[186:189]
	v_mfma_f32_16x16x32_bf16 v[116:119], v[154:157], v[28:31], v[24:27]
	v_mfma_f32_16x16x32_bf16 v[24:27], v[138:141], v[40:43], v[84:87]
	v_mfma_f32_16x16x32_bf16 v[112:115], v[218:221], v[28:31], v[96:99]
	v_mfma_f32_16x16x32_bf16 v[96:99], v[218:221], v[44:47], v[24:27]
	v_mfma_f32_16x16x32_bf16 v[24:27], v[234:237], v[40:43], v[80:83]
	v_mfma_f32_16x16x32_bf16 v[100:103], v[154:157], v[44:47], v[24:27]
	v_mfma_f32_16x16x32_bf16 v[24:27], v[138:141], v[64:67], v[190:193]
	v_mfma_f32_16x16x32_bf16 v[80:83], v[218:221], v[206:209], v[24:27]
	v_mfma_f32_16x16x32_bf16 v[24:27], v[234:237], v[64:67], v[194:197]
	v_mfma_f32_16x16x32_bf16 v[84:87], v[154:157], v[206:209], v[24:27]
	v_mfma_f32_16x16x32_bf16 v[24:27], v[138:141], v[210:213], v[68:71]
	v_mfma_f32_16x16x32_bf16 v[64:67], v[218:221], v[222:225], v[24:27]
	v_mfma_f32_16x16x32_bf16 v[24:27], v[234:237], v[210:213], v[198:201]
	v_mfma_f32_16x16x32_bf16 v[68:71], v[154:157], v[222:225], v[24:27]
	s_barrier
	ds_read_b128 v[186:189], v153 offset:49152
	ds_read_b128 v[190:193], v153 offset:50176
	ds_read_b128 v[194:197], v171 offset:49152
	ds_read_b128 v[198:201], v171 offset:50176
	ds_read_b128 v[206:209], v172 offset:49152
	ds_read_b128 v[210:213], v172 offset:50176
	ds_read_b128 v[222:225], v173 offset:49152
	ds_read_b128 v[172:175], v173 offset:50176
	s_barrier
	s_waitcnt lgkmcnt(0)
	v_mfma_f32_16x16x32_bf16 v[24:27], v[8:11], v[186:189], v[60:63]
	v_mfma_f32_16x16x32_bf16 v[60:63], v[12:15], v[190:193], v[24:27]
	v_mfma_f32_16x16x32_bf16 v[24:27], v[158:161], v[186:189], v[56:59]
	v_mfma_f32_16x16x32_bf16 v[56:59], v[202:205], v[190:193], v[24:27]
	v_mfma_f32_16x16x32_bf16 v[24:27], v[8:11], v[194:197], v[52:55]
	v_mfma_f32_16x16x32_bf16 v[44:47], v[12:15], v[198:201], v[24:27]
	v_mfma_f32_16x16x32_bf16 v[24:27], v[158:161], v[194:197], v[48:51]
	v_mfma_f32_16x16x32_bf16 v[40:43], v[202:205], v[198:201], v[24:27]
	v_mfma_f32_16x16x32_bf16 v[24:27], v[8:11], v[206:209], v[214:217]
	v_mfma_f32_16x16x32_bf16 v[8:11], v[8:11], v[222:225], v[36:39]
	v_mfma_f32_16x16x32_bf16 v[28:31], v[12:15], v[210:213], v[24:27]
	v_mfma_f32_16x16x32_bf16 v[24:27], v[158:161], v[206:209], v[230:233]
	v_mfma_f32_16x16x32_bf16 v[12:15], v[12:15], v[172:175], v[8:11]
	v_mfma_f32_16x16x32_bf16 v[8:11], v[158:161], v[222:225], v[32:35]
	v_mfma_f32_16x16x32_bf16 v[24:27], v[202:205], v[210:213], v[24:27]
	v_mfma_f32_16x16x32_bf16 v[8:11], v[202:205], v[172:175], v[8:11]
	v_mfma_f32_16x16x32_bf16 v[32:35], v[138:141], v[186:189], v[142:145]
	v_mfma_f32_16x16x32_bf16 v[48:51], v[218:221], v[190:193], v[32:35]
	v_mfma_f32_16x16x32_bf16 v[32:35], v[234:237], v[186:189], v[146:149]
	v_mfma_f32_16x16x32_bf16 v[20:23], v[138:141], v[194:197], v[20:23]
	v_mfma_f32_16x16x32_bf16 v[16:19], v[234:237], v[194:197], v[16:19]
	v_mfma_f32_16x16x32_bf16 v[52:55], v[154:157], v[190:193], v[32:35]
	v_mfma_f32_16x16x32_bf16 v[32:35], v[218:221], v[198:201], v[20:23]
	v_mfma_f32_16x16x32_bf16 v[36:39], v[154:157], v[198:201], v[16:19]
	v_mfma_f32_16x16x32_bf16 v[16:19], v[138:141], v[206:209], v[178:181]
	v_mfma_f32_16x16x32_bf16 v[20:23], v[234:237], v[206:209], v[182:185]
	v_mfma_f32_16x16x32_bf16 v[4:7], v[138:141], v[222:225], v[4:7]
	v_mfma_f32_16x16x32_bf16 v[0:3], v[234:237], v[222:225], v[0:3]
	v_mfma_f32_16x16x32_bf16 v[16:19], v[218:221], v[210:213], v[16:19]
	v_mfma_f32_16x16x32_bf16 v[20:23], v[154:157], v[210:213], v[20:23]
	v_mfma_f32_16x16x32_bf16 v[4:7], v[218:221], v[172:175], v[4:7]
	v_mfma_f32_16x16x32_bf16 v[0:3], v[154:157], v[172:175], v[0:3]
	s_setprio 0
	s_cmpk_gt_u32 s29, 0xff
	s_barrier
	s_cbranch_scc1 .LBB0_968
	s_barrier

; #define STAGE(P,BASE,LD,br,kt) do{long _g=(long)(br)*(LD)+(long)(kt)*BK; \
;     _Pragma("unroll") for(int _i=0;_i<2;++_i){int _b=tid*16+_i*8192;int _r,_c;stage_rc(_b,_r,_c); \
;       __builtin_amdgcn_global_load_lds((const unsigned*)((BASE)+_g+(long)_r*(LD)+_c), \
;         (unsigned*)((char*)(P)+_b),16,0,0);}}while(0)
; #define STAGE(P,BASE,LD,br,kt) do{long _g=(long)(br)*(LD)+(long)(kt)*BK; \
;     _Pragma("unroll") for(int _i=0;_i<2;++_i){int _b=tid*16+_i*8192;int _r,_c;stage_rc(_b,_r,_c); \
;       __builtin_amdgcn_global_load_lds((const unsigned*)((BASE)+_g+(long)_r*(LD)+_c), \
;         (unsigned*)((char*)(P)+_b),16,0,0);}}while(0)
; #define LDA(dst,b,h) _Pragma("unroll") for(int m=0;m<4;++m) _Pragma("unroll") for(int k=0;k<2;++k) \
;     dst[m][k]=*reinterpret_cast<const bf16x8*>((char*)SA(b,h)+lds_byte(wr*64+m*16+fr,k*32+fq*8))
; #define LDB(dst,b,h) _Pragma("unroll") for(int n=0;n<2;++n) _Pragma("unroll") for(int k=0;k<2;++k) \
;     dst[n][k]=*reinterpret_cast<const bf16x8*>((char*)SB(b,h)+lds_byte(wc*32+n*16+fr,k*32+fq*8))
; #define MMA(ai,bj,At_,Bt_) do{__builtin_amdgcn_s_setprio(1); \
;     _Pragma("unroll") for(int m=0;m<4;++m) _Pragma("unroll") for(int n=0;n<2;++n) _Pragma("unroll") for(int k=0;k<2;++k) \
;       acc[ai][bj][m][n]=__builtin_amdgcn_mfma_f32_16x16x32_bf16(Bt_[n][k],At_[m][k],acc[ai][bj][m][n],0,0,0); \
;     __builtin_amdgcn_s_setprio(0);}while(0)
; #define WAIT_L(n) asm volatile("s_waitcnt lgkmcnt(" #n ")":::"memory")
; #define BAR __builtin_amdgcn_s_barrier()
; #define SCHED __builtin_amdgcn_sched_barrier(0)
; DEVINL void gemm8_mainloop(const u16* A, long lda, const u16* Bt, long ldb, int K, int brow, int bcol, f32x4 (&acc)[2][2][4][2], char* smem, int tid) {
;     ...
;   for(int t=0;t<nt-2;t+=2){
;     LDB(B0,0,0); SCHED; LDA(At,0,0); STAGE(SA(1,1),A,lda,brow+HALF,t+1);
;     WAIT_L(8); BAR; WAIT_L(0); MMA(0,0,At,B0); BAR; SCHED;
;     LDB(B1,0,1); STAGE(SB(0,0),Bt,ldb,bcol,t+2);
;     BAR; WAIT_L(0); MMA(0,1,At,B1); BAR;
;     LDA(At,0,1); STAGE(SA(0,0),A,lda,brow,t+2);
.LBB0_1292:
	ds_read_b128 v[170:173], v161
	ds_read_b128 v[180:183], v161 offset:1024
	ds_read_b128 v[184:187], v161 offset:2048
	ds_read_b128 v[188:191], v161 offset:3072
	v_add_u32_e32 v178, 0xc000, v128
	v_lshl_add_u64 v[244:245], s[94:95], 0, v[148:149]
	v_readfirstlane_b32 s5, v178
	v_add_u32_e32 v179, 0xe000, v128
	v_add_u32_e32 v174, s1, v160
	v_add_u32_e32 v175, s37, v160
	v_add_u32_e32 v177, s40, v160
	v_lshl_add_u64 v[162:163], v[244:245], 0, s[8:9]
	s_mov_b32 m0, s5
	v_lshl_add_u64 v[246:247], s[94:95], 0, v[150:151]
	v_readfirstlane_b32 s5, v179
	ds_read_b128 v[192:195], v131
	ds_read_b128 v[196:199], v131 offset:1024
	ds_read_b128 v[200:203], v174
	ds_read_b128 v[204:207], v174 offset:1024
	ds_read_b128 v[208:211], v175
	ds_read_b128 v[212:215], v175 offset:1024
	ds_read_b128 v[216:219], v177
	ds_read_b128 v[220:223], v177 offset:1024
	global_load_lds_dwordx4 v[162:163], off
	v_lshl_add_u64 v[162:163], v[246:247], 0, s[8:9]
	s_mov_b32 m0, s5
	s_nop 0
	global_load_lds_dwordx4 v[162:163], off
	s_waitcnt lgkmcnt(8)
	s_barrier
	s_waitcnt lgkmcnt(0)
	v_mfma_f32_16x16x32_bf16 v[124:127], v[170:173], v[192:195], v[124:127]
	v_mfma_f32_16x16x32_bf16 v[120:123], v[184:187], v[192:195], v[120:123]
	v_mfma_f32_16x16x32_bf16 v[116:119], v[170:173], v[200:203], v[116:119]
	v_mfma_f32_16x16x32_bf16 v[112:115], v[184:187], v[200:203], v[112:115]
	v_mfma_f32_16x16x32_bf16 v[108:111], v[170:173], v[208:211], v[108:111]
	v_mfma_f32_16x16x32_bf16 v[104:107], v[184:187], v[208:211], v[104:107]
	v_mfma_f32_16x16x32_bf16 v[100:103], v[170:173], v[216:219], v[100:103]
	v_mfma_f32_16x16x32_bf16 v[96:99], v[184:187], v[216:219], v[96:99]
	v_mfma_f32_16x16x32_bf16 v[124:127], v[180:183], v[196:199], v[124:127]
	v_mfma_f32_16x16x32_bf16 v[120:123], v[188:191], v[196:199], v[120:123]
	v_mfma_f32_16x16x32_bf16 v[116:119], v[180:183], v[204:207], v[116:119]
	v_mfma_f32_16x16x32_bf16 v[112:115], v[188:191], v[204:207], v[112:115]
	v_mfma_f32_16x16x32_bf16 v[108:111], v[180:183], v[212:215], v[108:111]
	v_mfma_f32_16x16x32_bf16 v[104:107], v[188:191], v[212:215], v[104:107]
	v_mfma_f32_16x16x32_bf16 v[100:103], v[180:183], v[220:223], v[100:103]
	v_mfma_f32_16x16x32_bf16 v[96:99], v[188:191], v[220:223], v[96:99]
	s_barrier
	v_add_u32_e32 v162, s27, v153
	v_lshl_add_u64 v[248:249], s[94:95], 0, v[144:145]
	v_readfirstlane_b32 s5, v162
	v_add_u32_e32 v163, 0x2000, v162
	v_lshl_add_u64 v[240:241], v[248:249], 0, s[10:11]
	s_mov_b32 m0, s5
	v_lshl_add_u64 v[250:251], s[94:95], 0, v[146:147]
	v_readfirstlane_b32 s5, v163
	ds_read_b128 v[224:227], v158
	ds_read_b128 v[228:231], v158 offset:1024
	ds_read_b128 v[232:235], v158 offset:2048
	ds_read_b128 v[236:239], v158 offset:3072
	global_load_lds_dwordx4 v[240:241], off
	v_lshl_add_u64 v[240:241], v[250:251], 0, s[10:11]
	s_mov_b32 m0, s5
	s_nop 0
	global_load_lds_dwordx4 v[240:241], off
	s_barrier
	s_waitcnt lgkmcnt(0)
	v_mfma_f32_16x16x32_bf16 v[92:95], v[224:227], v[192:195], v[92:95]
	v_mfma_f32_16x16x32_bf16 v[88:91], v[232:235], v[192:195], v[88:91]
	v_mfma_f32_16x16x32_bf16 v[84:87], v[224:227], v[200:203], v[84:87]
	v_mfma_f32_16x16x32_bf16 v[80:83], v[232:235], v[200:203], v[80:83]
	v_mfma_f32_16x16x32_bf16 v[76:79], v[224:227], v[208:211], v[76:79]
	v_mfma_f32_16x16x32_bf16 v[72:75], v[232:235], v[208:211], v[72:75]
	v_mfma_f32_16x16x32_bf16 v[68:71], v[224:227], v[216:219], v[68:71]
	v_mfma_f32_16x16x32_bf16 v[64:67], v[232:235], v[216:219], v[64:67]
	v_mfma_f32_16x16x32_bf16 v[92:95], v[228:231], v[196:199], v[92:95]
	v_mfma_f32_16x16x32_bf16 v[88:91], v[236:239], v[196:199], v[88:91]
	v_mfma_f32_16x16x32_bf16 v[84:87], v[228:231], v[204:207], v[84:87]
	v_mfma_f32_16x16x32_bf16 v[80:83], v[236:239], v[204:207], v[80:83]
	v_mfma_f32_16x16x32_bf16 v[76:79], v[228:231], v[212:215], v[76:79]
	v_mfma_f32_16x16x32_bf16 v[72:75], v[236:239], v[212:215], v[72:75]
	v_mfma_f32_16x16x32_bf16 v[68:71], v[228:231], v[220:223], v[68:71]
	v_mfma_f32_16x16x32_bf16 v[64:67], v[236:239], v[220:223], v[64:67]
	v_readfirstlane_b32 s5, v128
	v_add_u32_e32 v169, 0x2000, v128
	v_lshl_add_u64 v[240:241], v[244:245], 0, s[12:13]
	s_mov_b32 m0, s5
	v_readfirstlane_b32 s5, v169
	s_barrier
	ds_read_b128 v[192:195], v131 offset:16384
	ds_read_b128 v[196:199], v131 offset:17408
	ds_read_b128 v[200:203], v174 offset:16384
	ds_read_b128 v[204:207], v174 offset:17408
	ds_read_b128 v[208:211], v175 offset:16384
	ds_read_b128 v[212:215], v175 offset:17408
	ds_read_b128 v[216:219], v177 offset:16384
	ds_read_b128 v[220:223], v177 offset:17408
	global_load_lds_dwordx4 v[240:241], off
	v_lshl_add_u64 v[240:241], v[246:247], 0, s[12:13]
	s_mov_b32 m0, s5
	s_nop 0
	global_load_lds_dwordx4 v[240:241], off
	s_barrier
	s_waitcnt lgkmcnt(0)
	v_mfma_f32_16x16x32_bf16 v[60:63], v[170:173], v[192:195], v[60:63]
	v_mfma_f32_16x16x32_bf16 v[56:59], v[184:187], v[192:195], v[56:59]
	v_mfma_f32_16x16x32_bf16 v[52:55], v[170:173], v[200:203], v[52:55]
	v_mfma_f32_16x16x32_bf16 v[48:51], v[184:187], v[200:203], v[48:51]
	v_mfma_f32_16x16x32_bf16 v[44:47], v[170:173], v[208:211], v[44:47]
	v_mfma_f32_16x16x32_bf16 v[40:43], v[184:187], v[208:211], v[40:43]
	v_mfma_f32_16x16x32_bf16 v[36:39], v[170:173], v[216:219], v[36:39]
	v_mfma_f32_16x16x32_bf16 v[32:35], v[184:187], v[216:219], v[32:35]
	v_mfma_f32_16x16x32_bf16 v[60:63], v[180:183], v[196:199], v[60:63]
	v_mfma_f32_16x16x32_bf16 v[56:59], v[188:191], v[196:199], v[56:59]
	v_mfma_f32_16x16x32_bf16 v[52:55], v[180:183], v[204:207], v[52:55]
	v_mfma_f32_16x16x32_bf16 v[48:51], v[188:191], v[204:207], v[48:51]
	v_mfma_f32_16x16x32_bf16 v[44:47], v[180:183], v[212:215], v[44:47]
	v_mfma_f32_16x16x32_bf16 v[40:43], v[188:191], v[212:215], v[40:43]
	v_mfma_f32_16x16x32_bf16 v[36:39], v[180:183], v[220:223], v[36:39]
	v_mfma_f32_16x16x32_bf16 v[32:35], v[188:191], v[220:223], v[32:35]
	s_barrier
; #define STAGE(P,BASE,LD,br,kt) do{long _g=(long)(br)*(LD)+(long)(kt)*BK; \
;     _Pragma("unroll") for(int _i=0;_i<2;++_i){int _b=tid*16+_i*8192;int _r,_c;stage_rc(_b,_r,_c); \
;       __builtin_amdgcn_global_load_lds((const unsigned*)((BASE)+_g+(long)_r*(LD)+_c), \
;         (unsigned*)((char*)(P)+_b),16,0,0);}}while(0)
; #define STAGE(P,BASE,LD,br,kt) do{long _g=(long)(br)*(LD)+(long)(kt)*BK; \
;     _Pragma("unroll") for(int _i=0;_i<2;++_i){int _b=tid*16+_i*8192;int _r,_c;stage_rc(_b,_r,_c); \
;       __builtin_amdgcn_global_load_lds((const unsigned*)((BASE)+_g+(long)_r*(LD)+_c), \
;         (unsigned*)((char*)(P)+_b),16,0,0);}}while(0)
; #define LDA(dst,b,h) _Pragma("unroll") for(int m=0;m<4;++m) _Pragma("unroll") for(int k=0;k<2;++k) \
;     dst[m][k]=*reinterpret_cast<const bf16x8*>((char*)SA(b,h)+lds_byte(wr*64+m*16+fr,k*32+fq*8))
; #define LDB(dst,b,h) _Pragma("unroll") for(int n=0;n<2;++n) _Pragma("unroll") for(int k=0;k<2;++k) \
;     dst[n][k]=*reinterpret_cast<const bf16x8*>((char*)SB(b,h)+lds_byte(wc*32+n*16+fr,k*32+fq*8))
; #define MMA(ai,bj,At_,Bt_) do{__builtin_amdgcn_s_setprio(1); \
;     _Pragma("unroll") for(int m=0;m<4;++m) _Pragma("unroll") for(int n=0;n<2;++n) _Pragma("unroll") for(int k=0;k<2;++k) \
;       acc[ai][bj][m][n]=__builtin_amdgcn_mfma_f32_16x16x32_bf16(Bt_[n][k],At_[m][k],acc[ai][bj][m][n],0,0,0); \
;     __builtin_amdgcn_s_setprio(0);}while(0)
; #define WAIT_V(n) asm volatile("s_waitcnt vmcnt(" #n ")":::"memory")
; #define WAIT_L(n) asm volatile("s_waitcnt lgkmcnt(" #n ")":::"memory")
; #define BAR __builtin_amdgcn_s_barrier()
; #define SCHED __builtin_amdgcn_sched_barrier(0)
; DEVINL void gemm8_mainloop(const u16* A, long lda, const u16* Bt, long ldb, int K, int brow, int bcol, f32x4 (&acc)[2][2][4][2], char* smem, int tid) {
;     ...
;     LDA(At,0,1); STAGE(SA(0,0),A,lda,brow,t+2);
;     BAR; WAIT_L(0); MMA(1,0,At,B0); BAR; SCHED;
;     STAGE(SB(0,1),Bt,ldb,bcol+HALF,t+2);
;     WAIT_V(6); BAR; MMA(1,1,At,B1); BAR;
;     LDB(B0,1,0); SCHED; LDA(At,1,0); STAGE(SA(0,1),A,lda,brow+HALF,t+2);
;     WAIT_L(8); BAR; WAIT_L(0); MMA(0,0,At,B0); BAR; SCHED;
;     LDB(B1,1,1); STAGE(SB(1,0),Bt,ldb,bcol,t+3);
	v_add_u32_e32 v170, s29, v153
	v_add_u32_e32 v171, 0x2000, v170
	v_readfirstlane_b32 s5, v170
	v_lshl_add_u64 v[172:173], v[248:249], 0, s[14:15]
	s_mov_b32 m0, s5
	v_readfirstlane_b32 s5, v171
	global_load_lds_dwordx4 v[172:173], off
	v_lshl_add_u64 v[172:173], v[250:251], 0, s[14:15]
	s_mov_b32 m0, s5
	s_nop 0
	global_load_lds_dwordx4 v[172:173], off
	s_waitcnt vmcnt(6)
	s_barrier
	v_mfma_f32_16x16x32_bf16 v[28:31], v[224:227], v[192:195], v[28:31]
	v_mfma_f32_16x16x32_bf16 v[24:27], v[232:235], v[192:195], v[24:27]
	v_mfma_f32_16x16x32_bf16 v[20:23], v[224:227], v[200:203], v[20:23]
	v_mfma_f32_16x16x32_bf16 v[16:19], v[232:235], v[200:203], v[16:19]
	v_mfma_f32_16x16x32_bf16 v[12:15], v[224:227], v[208:211], v[12:15]
	v_mfma_f32_16x16x32_bf16 v[8:11], v[232:235], v[208:211], v[8:11]
	v_mfma_f32_16x16x32_bf16 v[4:7], v[224:227], v[216:219], v[4:7]
	v_mfma_f32_16x16x32_bf16 v[0:3], v[232:235], v[216:219], v[0:3]
	v_mfma_f32_16x16x32_bf16 v[28:31], v[228:231], v[196:199], v[28:31]
	v_mfma_f32_16x16x32_bf16 v[24:27], v[236:239], v[196:199], v[24:27]
	v_mfma_f32_16x16x32_bf16 v[20:23], v[228:231], v[204:207], v[20:23]
	v_mfma_f32_16x16x32_bf16 v[16:19], v[236:239], v[204:207], v[16:19]
	v_mfma_f32_16x16x32_bf16 v[12:15], v[228:231], v[212:215], v[12:15]
	v_mfma_f32_16x16x32_bf16 v[8:11], v[236:239], v[212:215], v[8:11]
	v_mfma_f32_16x16x32_bf16 v[4:7], v[228:231], v[220:223], v[4:7]
	v_mfma_f32_16x16x32_bf16 v[0:3], v[236:239], v[220:223], v[0:3]
	s_barrier
	ds_read_b128 v[180:183], v154
	ds_read_b128 v[184:187], v154 offset:1024
	ds_read_b128 v[188:191], v154 offset:2048
	ds_read_b128 v[192:195], v154 offset:3072
	v_add_u32_e32 v172, 0x4000, v128
	v_add_u32_e32 v173, 0x6000, v128
	v_readfirstlane_b32 s5, v172
	v_lshl_add_u64 v[228:229], v[244:245], 0, s[16:17]
	s_mov_b32 m0, s5
	v_readfirstlane_b32 s5, v173
	ds_read_b128 v[196:199], v131 offset:32768
	ds_read_b128 v[200:203], v131 offset:33792
	ds_read_b128 v[204:207], v174 offset:32768
	ds_read_b128 v[208:211], v174 offset:33792
	ds_read_b128 v[212:215], v175 offset:32768
	ds_read_b128 v[216:219], v175 offset:33792
	ds_read_b128 v[220:223], v177 offset:32768
	ds_read_b128 v[224:227], v177 offset:33792
	global_load_lds_dwordx4 v[228:229], off
	v_lshl_add_u64 v[228:229], v[246:247], 0, s[16:17]
	s_mov_b32 m0, s5
	s_nop 0
	global_load_lds_dwordx4 v[228:229], off
	s_waitcnt lgkmcnt(8)
	s_barrier
	s_waitcnt lgkmcnt(0)
	v_mfma_f32_16x16x32_bf16 v[124:127], v[180:183], v[196:199], v[124:127]
	v_mfma_f32_16x16x32_bf16 v[120:123], v[188:191], v[196:199], v[120:123]
	v_mfma_f32_16x16x32_bf16 v[116:119], v[180:183], v[204:207], v[116:119]
	v_mfma_f32_16x16x32_bf16 v[112:115], v[188:191], v[204:207], v[112:115]
	v_mfma_f32_16x16x32_bf16 v[108:111], v[180:183], v[212:215], v[108:111]
	v_mfma_f32_16x16x32_bf16 v[104:107], v[188:191], v[212:215], v[104:107]
	v_mfma_f32_16x16x32_bf16 v[100:103], v[180:183], v[220:223], v[100:103]
	v_mfma_f32_16x16x32_bf16 v[96:99], v[188:191], v[220:223], v[96:99]
	v_mfma_f32_16x16x32_bf16 v[124:127], v[184:187], v[200:203], v[124:127]
	v_mfma_f32_16x16x32_bf16 v[120:123], v[192:195], v[200:203], v[120:123]
	v_mfma_f32_16x16x32_bf16 v[116:119], v[184:187], v[208:211], v[116:119]
	v_mfma_f32_16x16x32_bf16 v[112:115], v[192:195], v[208:211], v[112:115]
	v_mfma_f32_16x16x32_bf16 v[108:111], v[184:187], v[216:219], v[108:111]
	v_mfma_f32_16x16x32_bf16 v[104:107], v[192:195], v[216:219], v[104:107]
	v_mfma_f32_16x16x32_bf16 v[100:103], v[184:187], v[224:227], v[100:103]
	v_mfma_f32_16x16x32_bf16 v[96:99], v[192:195], v[224:227], v[96:99]
	s_barrier
	v_readfirstlane_b32 s5, v155
	v_add_u32_e32 v165, 0x2000, v155
	v_lshl_add_u64 v[252:253], v[248:249], 0, s[18:19]
	s_mov_b32 m0, s5
	v_readfirstlane_b32 s5, v165
	ds_read_b128 v[228:231], v152
	ds_read_b128 v[232:235], v152 offset:1024
	ds_read_b128 v[236:239], v152 offset:2048
	ds_read_b128 v[240:243], v152 offset:3072
	global_load_lds_dwordx4 v[252:253], off
	v_lshl_add_u64 v[252:253], v[250:251], 0, s[18:19]
	s_mov_b32 m0, s5
	s_nop 0
	global_load_lds_dwordx4 v[252:253], off
	s_barrier
	s_waitcnt lgkmcnt(0)
	v_mfma_f32_16x16x32_bf16 v[92:95], v[228:231], v[196:199], v[92:95]
	v_mfma_f32_16x16x32_bf16 v[88:91], v[236:239], v[196:199], v[88:91]
	v_mfma_f32_16x16x32_bf16 v[84:87], v[228:231], v[204:207], v[84:87]
	v_mfma_f32_16x16x32_bf16 v[80:83], v[236:239], v[204:207], v[80:83]
	v_mfma_f32_16x16x32_bf16 v[76:79], v[228:231], v[212:215], v[76:79]
	v_mfma_f32_16x16x32_bf16 v[72:75], v[236:239], v[212:215], v[72:75]
	v_mfma_f32_16x16x32_bf16 v[68:71], v[228:231], v[220:223], v[68:71]
	v_mfma_f32_16x16x32_bf16 v[64:67], v[236:239], v[220:223], v[64:67]
	v_mfma_f32_16x16x32_bf16 v[92:95], v[232:235], v[200:203], v[92:95]
	v_mfma_f32_16x16x32_bf16 v[88:91], v[240:243], v[200:203], v[88:91]
	v_mfma_f32_16x16x32_bf16 v[84:87], v[232:235], v[208:211], v[84:87]
	v_mfma_f32_16x16x32_bf16 v[80:83], v[240:243], v[208:211], v[80:83]
	v_mfma_f32_16x16x32_bf16 v[76:79], v[232:235], v[216:219], v[76:79]
	v_mfma_f32_16x16x32_bf16 v[72:75], v[240:243], v[216:219], v[72:75]
	v_mfma_f32_16x16x32_bf16 v[68:71], v[232:235], v[224:227], v[68:71]
	v_mfma_f32_16x16x32_bf16 v[64:67], v[240:243], v[224:227], v[64:67]
	v_readfirstlane_b32 s5, v156
	v_lshl_add_u64 v[244:245], v[244:245], 0, s[20:21]
	s_mov_b32 m0, s5
	v_readfirstlane_b32 s5, v157
	s_barrier
	ds_read_b128 v[196:199], v131 offset:49152
	ds_read_b128 v[200:203], v131 offset:50176
	ds_read_b128 v[204:207], v174 offset:49152
	ds_read_b128 v[208:211], v174 offset:50176
	ds_read_b128 v[212:215], v175 offset:49152
	ds_read_b128 v[216:219], v175 offset:50176
	ds_read_b128 v[220:223], v177 offset:49152
	ds_read_b128 v[224:227], v177 offset:50176
	global_load_lds_dwordx4 v[244:245], off
	v_lshl_add_u64 v[244:245], v[246:247], 0, s[20:21]
	s_mov_b32 m0, s5
	s_nop 0
	global_load_lds_dwordx4 v[244:245], off
	s_barrier
; #define STAGE(P,BASE,LD,br,kt) do{long _g=(long)(br)*(LD)+(long)(kt)*BK; \
;     _Pragma("unroll") for(int _i=0;_i<2;++_i){int _b=tid*16+_i*8192;int _r,_c;stage_rc(_b,_r,_c); \
;       __builtin_amdgcn_global_load_lds((const unsigned*)((BASE)+_g+(long)_r*(LD)+_c), \
;         (unsigned*)((char*)(P)+_b),16,0,0);}}while(0)
; #define STAGE(P,BASE,LD,br,kt) do{long _g=(long)(br)*(LD)+(long)(kt)*BK; \
;     _Pragma("unroll") for(int _i=0;_i<2;++_i){int _b=tid*16+_i*8192;int _r,_c;stage_rc(_b,_r,_c); \
;       __builtin_amdgcn_global_load_lds((const unsigned*)((BASE)+_g+(long)_r*(LD)+_c), \
;         (unsigned*)((char*)(P)+_b),16,0,0);}}while(0)
; #define LDA(dst,b,h) _Pragma("unroll") for(int m=0;m<4;++m) _Pragma("unroll") for(int k=0;k<2;++k) \
;     dst[m][k]=*reinterpret_cast<const bf16x8*>((char*)SA(b,h)+lds_byte(wr*64+m*16+fr,k*32+fq*8))
; #define LDB(dst,b,h) _Pragma("unroll") for(int n=0;n<2;++n) _Pragma("unroll") for(int k=0;k<2;++k) \
;     dst[n][k]=*reinterpret_cast<const bf16x8*>((char*)SB(b,h)+lds_byte(wc*32+n*16+fr,k*32+fq*8))
; #define MMA(ai,bj,At_,Bt_) do{__builtin_amdgcn_s_setprio(1); \
;     _Pragma("unroll") for(int m=0;m<4;++m) _Pragma("unroll") for(int n=0;n<2;++n) _Pragma("unroll") for(int k=0;k<2;++k) \
;       acc[ai][bj][m][n]=__builtin_amdgcn_mfma_f32_16x16x32_bf16(Bt_[n][k],At_[m][k],acc[ai][bj][m][n],0,0,0); \
;     __builtin_amdgcn_s_setprio(0);}while(0)
; #define WAIT_V(n) asm volatile("s_waitcnt vmcnt(" #n ")":::"memory")
; #define WAIT_L(n) asm volatile("s_waitcnt lgkmcnt(" #n ")":::"memory")
; #define BAR __builtin_amdgcn_s_barrier()
; #define SCHED __builtin_amdgcn_sched_barrier(0)
; DEVINL void gemm8_mainloop(const u16* A, long lda, const u16* Bt, long ldb, int K, int brow, int bcol, f32x4 (&acc)[2][2][4][2], char* smem, int tid) {
;     ...
;     LDB(B1,1,1); STAGE(SB(1,0),Bt,ldb,bcol,t+3);
;     BAR; WAIT_L(0); MMA(0,1,At,B1); BAR;
;     LDA(At,1,1); STAGE(SA(1,0),A,lda,brow,t+3);
;     BAR; WAIT_L(0); MMA(1,0,At,B0); BAR; SCHED;
;     STAGE(SB(1,1),Bt,ldb,bcol+HALF,t+3);
;     WAIT_V(6); BAR; MMA(1,1,At,B1); BAR;
;   }
;   { LDB(B0,0,0); LDA(At,0,0); STAGE(SA(1,1),A,lda,brow+HALF,nt-1);
;     BAR; WAIT_L(0); MMA(0,0,At,B0); BAR;
	s_waitcnt lgkmcnt(0)
	v_mfma_f32_16x16x32_bf16 v[60:63], v[180:183], v[196:199], v[60:63]
	v_mfma_f32_16x16x32_bf16 v[56:59], v[188:191], v[196:199], v[56:59]
	v_mfma_f32_16x16x32_bf16 v[52:55], v[180:183], v[204:207], v[52:55]
	v_mfma_f32_16x16x32_bf16 v[48:51], v[188:191], v[204:207], v[48:51]
	v_mfma_f32_16x16x32_bf16 v[44:47], v[180:183], v[212:215], v[44:47]
	v_mfma_f32_16x16x32_bf16 v[40:43], v[188:191], v[212:215], v[40:43]
	v_mfma_f32_16x16x32_bf16 v[36:39], v[180:183], v[220:223], v[36:39]
	v_mfma_f32_16x16x32_bf16 v[32:35], v[188:191], v[220:223], v[32:35]
	v_mfma_f32_16x16x32_bf16 v[60:63], v[184:187], v[200:203], v[60:63]
	v_mfma_f32_16x16x32_bf16 v[56:59], v[192:195], v[200:203], v[56:59]
	v_mfma_f32_16x16x32_bf16 v[52:55], v[184:187], v[208:211], v[52:55]
	v_mfma_f32_16x16x32_bf16 v[48:51], v[192:195], v[208:211], v[48:51]
	v_mfma_f32_16x16x32_bf16 v[44:47], v[184:187], v[216:219], v[44:47]
	v_mfma_f32_16x16x32_bf16 v[40:43], v[192:195], v[216:219], v[40:43]
	v_mfma_f32_16x16x32_bf16 v[36:39], v[184:187], v[224:227], v[36:39]
	v_mfma_f32_16x16x32_bf16 v[32:35], v[192:195], v[224:227], v[32:35]
	s_barrier
	v_readfirstlane_b32 s5, v159
	v_add_u32_e32 v165, 0x2000, v159
	v_lshl_add_u64 v[180:181], v[248:249], 0, s[22:23]
	s_mov_b32 m0, s5
	v_readfirstlane_b32 s5, v165
	global_load_lds_dwordx4 v[180:181], off
	v_lshl_add_u64 v[180:181], v[250:251], 0, s[22:23]
	s_mov_b32 m0, s5
	s_nop 0
	global_load_lds_dwordx4 v[180:181], off
	s_waitcnt vmcnt(6)
	s_barrier
	v_mfma_f32_16x16x32_bf16 v[28:31], v[228:231], v[196:199], v[28:31]
	v_mfma_f32_16x16x32_bf16 v[24:27], v[236:239], v[196:199], v[24:27]
	v_mfma_f32_16x16x32_bf16 v[20:23], v[228:231], v[204:207], v[20:23]
	v_mfma_f32_16x16x32_bf16 v[16:19], v[236:239], v[204:207], v[16:19]
	v_mfma_f32_16x16x32_bf16 v[12:15], v[228:231], v[212:215], v[12:15]
	v_mfma_f32_16x16x32_bf16 v[8:11], v[236:239], v[212:215], v[8:11]
	v_mfma_f32_16x16x32_bf16 v[4:7], v[228:231], v[220:223], v[4:7]
	v_mfma_f32_16x16x32_bf16 v[0:3], v[236:239], v[220:223], v[0:3]
	v_mfma_f32_16x16x32_bf16 v[28:31], v[232:235], v[200:203], v[28:31]
	v_mfma_f32_16x16x32_bf16 v[24:27], v[240:243], v[200:203], v[24:27]
	v_mfma_f32_16x16x32_bf16 v[20:23], v[232:235], v[208:211], v[20:23]
	v_mfma_f32_16x16x32_bf16 v[16:19], v[240:243], v[208:211], v[16:19]
	v_mfma_f32_16x16x32_bf16 v[12:15], v[232:235], v[216:219], v[12:15]
	v_mfma_f32_16x16x32_bf16 v[8:11], v[240:243], v[216:219], v[8:11]
	v_mfma_f32_16x16x32_bf16 v[4:7], v[232:235], v[224:227], v[4:7]
	v_mfma_f32_16x16x32_bf16 v[0:3], v[240:243], v[224:227], v[0:3]
	s_add_i32 s4, s4, 2
	v_lshl_add_u64 v[144:145], v[144:145], 0, s[10:11]
	v_lshl_add_u64 v[146:147], v[146:147], 0, s[10:11]
	v_lshl_add_u64 v[148:149], v[148:149], 0, s[10:11]
	s_cmp_lt_u32 s4, 28
	v_lshl_add_u64 v[150:151], v[150:151], 0, s[10:11]
	s_barrier
	s_cbranch_scc1 .LBB0_1292
	s_or_b32 s4, s36, 0x80
	s_ashr_i32 s5, s4, 31
	s_lshl_b64 s[4:5], s[4:5], 12
	s_add_u32 s4, s90, s4
	s_addc_u32 s5, s91, s5
	v_lshl_add_u64 v[156:157], v[136:137], 1, s[4:5]
	v_lshl_add_u64 v[140:141], v[140:141], 1, v[156:157]
	v_readfirstlane_b32 s1, v178
	v_lshl_add_u64 v[140:141], v[140:141], 0, s[24:25]
	s_mov_b32 m0, s1
	ds_read_b128 v[144:147], v161
	ds_read_b128 v[148:151], v161 offset:1024
	ds_read_b128 v[180:183], v161 offset:2048
	ds_read_b128 v[184:187], v161 offset:3072
	ds_read_b128 v[188:191], v131
	ds_read_b128 v[192:195], v131 offset:1024
	ds_read_b128 v[196:199], v174
	ds_read_b128 v[200:203], v174 offset:1024
	ds_read_b128 v[204:207], v175
	ds_read_b128 v[208:211], v175 offset:1024
	ds_read_b128 v[212:215], v177
	ds_read_b128 v[216:219], v177 offset:1024
	global_load_lds_dwordx4 v[140:141], off
	v_lshl_add_u64 v[140:141], v[138:139], 1, s[4:5]
	v_lshl_add_u64 v[140:141], v[142:143], 1, v[140:141]
	v_readfirstlane_b32 s1, v179
	v_lshl_add_u64 v[140:141], v[140:141], 0, s[24:25]
	s_mov_b32 m0, s1
	s_nop 0
	global_load_lds_dwordx4 v[140:141], off
	s_barrier
	s_waitcnt lgkmcnt(0)
	v_mfma_f32_16x16x32_bf16 v[124:127], v[144:147], v[188:191], v[124:127]
	v_mfma_f32_16x16x32_bf16 v[120:123], v[180:183], v[188:191], v[120:123]
	v_mfma_f32_16x16x32_bf16 v[108:111], v[144:147], v[204:207], v[108:111]
	v_mfma_f32_16x16x32_bf16 v[104:107], v[180:183], v[204:207], v[104:107]
	v_mfma_f32_16x16x32_bf16 v[124:127], v[148:151], v[192:195], v[124:127]
	v_mfma_f32_16x16x32_bf16 v[120:123], v[184:187], v[192:195], v[120:123]
	v_mfma_f32_16x16x32_bf16 v[116:119], v[144:147], v[196:199], v[116:119]
	v_mfma_f32_16x16x32_bf16 v[112:115], v[180:183], v[196:199], v[112:115]
	v_mfma_f32_16x16x32_bf16 v[108:111], v[148:151], v[208:211], v[108:111]
	v_mfma_f32_16x16x32_bf16 v[104:107], v[184:187], v[208:211], v[104:107]
	v_mfma_f32_16x16x32_bf16 v[100:103], v[144:147], v[212:215], v[100:103]
	v_mfma_f32_16x16x32_bf16 v[96:99], v[180:183], v[212:215], v[96:99]
	v_mfma_f32_16x16x32_bf16 v[140:143], v[148:151], v[200:203], v[116:119]
	v_mfma_f32_16x16x32_bf16 v[220:223], v[184:187], v[200:203], v[112:115]
	v_mfma_f32_16x16x32_bf16 v[224:227], v[148:151], v[216:219], v[100:103]
	v_mfma_f32_16x16x32_bf16 v[228:231], v[184:187], v[216:219], v[96:99]
	s_barrier
	s_nop 1
	s_nop 0
	ds_read_b128 v[96:99], v158
	ds_read_b128 v[100:103], v158 offset:1024
	ds_read_b128 v[112:115], v158 offset:2048
	ds_read_b128 v[116:119], v158 offset:3072
	s_barrier
; #define LDA(dst,b,h) _Pragma("unroll") for(int m=0;m<4;++m) _Pragma("unroll") for(int k=0;k<2;++k) \
;     dst[m][k]=*reinterpret_cast<const bf16x8*>((char*)SA(b,h)+lds_byte(wr*64+m*16+fr,k*32+fq*8))
; #define LDB(dst,b,h) _Pragma("unroll") for(int n=0;n<2;++n) _Pragma("unroll") for(int k=0;k<2;++k) \
;     dst[n][k]=*reinterpret_cast<const bf16x8*>((char*)SB(b,h)+lds_byte(wc*32+n*16+fr,k*32+fq*8))
; #define MMA(ai,bj,At_,Bt_) do{__builtin_amdgcn_s_setprio(1); \
;     _Pragma("unroll") for(int m=0;m<4;++m) _Pragma("unroll") for(int n=0;n<2;++n) _Pragma("unroll") for(int k=0;k<2;++k) \
;       acc[ai][bj][m][n]=__builtin_amdgcn_mfma_f32_16x16x32_bf16(Bt_[n][k],At_[m][k],acc[ai][bj][m][n],0,0,0); \
;     __builtin_amdgcn_s_setprio(0);}while(0)
; #define WAIT_V(n) asm volatile("s_waitcnt vmcnt(" #n ")":::"memory")
; #define WAIT_L(n) asm volatile("s_waitcnt lgkmcnt(" #n ")":::"memory")
; #define BAR __builtin_amdgcn_s_barrier()
; DEVINL void gemm8_mainloop(const u16* A, long lda, const u16* Bt, long ldb, int K, int brow, int bcol, f32x4 (&acc)[2][2][4][2], char* smem, int tid) {
;     ...
;     BAR; WAIT_L(0); MMA(0,0,At,B0); BAR;
;     LDB(B1,0,1); BAR; WAIT_L(0); MMA(0,1,At,B1); BAR;
;     LDA(At,0,1); WAIT_V(4); BAR; WAIT_L(0); MMA(1,0,At,B0); MMA(1,1,At,B1); BAR; }
;   { LDB(B0,1,0); LDA(At,1,0); WAIT_V(2); BAR; WAIT_L(0); MMA(0,0,At,B0); BAR;
	s_waitcnt lgkmcnt(0)
	v_mfma_f32_16x16x32_bf16 v[92:95], v[96:99], v[188:191], v[92:95]
	v_mfma_f32_16x16x32_bf16 v[88:91], v[112:115], v[188:191], v[88:91]
	v_mfma_f32_16x16x32_bf16 v[76:79], v[96:99], v[204:207], v[76:79]
	v_mfma_f32_16x16x32_bf16 v[72:75], v[112:115], v[204:207], v[72:75]
	v_mfma_f32_16x16x32_bf16 v[92:95], v[100:103], v[192:195], v[92:95]
	v_mfma_f32_16x16x32_bf16 v[88:91], v[116:119], v[192:195], v[88:91]
	v_mfma_f32_16x16x32_bf16 v[84:87], v[96:99], v[196:199], v[84:87]
	v_mfma_f32_16x16x32_bf16 v[80:83], v[112:115], v[196:199], v[80:83]
	v_mfma_f32_16x16x32_bf16 v[76:79], v[100:103], v[208:211], v[76:79]
	v_mfma_f32_16x16x32_bf16 v[72:75], v[116:119], v[208:211], v[72:75]
	v_mfma_f32_16x16x32_bf16 v[68:71], v[96:99], v[212:215], v[68:71]
	v_mfma_f32_16x16x32_bf16 v[64:67], v[112:115], v[212:215], v[64:67]
	v_mfma_f32_16x16x32_bf16 v[156:159], v[100:103], v[200:203], v[84:87]
	v_mfma_f32_16x16x32_bf16 v[188:191], v[116:119], v[200:203], v[80:83]
	v_mfma_f32_16x16x32_bf16 v[192:195], v[100:103], v[216:219], v[68:71]
	v_mfma_f32_16x16x32_bf16 v[196:199], v[116:119], v[216:219], v[64:67]
	s_barrier
	s_nop 1
	s_nop 0
	ds_read_b128 v[64:67], v131 offset:16384
	ds_read_b128 v[68:71], v131 offset:17408
	ds_read_b128 v[80:83], v174 offset:16384
	ds_read_b128 v[84:87], v174 offset:17408
	ds_read_b128 v[200:203], v175 offset:16384
	ds_read_b128 v[204:207], v175 offset:17408
	ds_read_b128 v[208:211], v177 offset:16384
	ds_read_b128 v[212:215], v177 offset:17408
	s_waitcnt vmcnt(4)
	s_barrier
	s_waitcnt lgkmcnt(0)
	v_mfma_f32_16x16x32_bf16 v[60:63], v[144:147], v[64:67], v[60:63]
	v_mfma_f32_16x16x32_bf16 v[52:55], v[144:147], v[80:83], v[52:55]
	v_mfma_f32_16x16x32_bf16 v[44:47], v[144:147], v[200:203], v[44:47]
	v_mfma_f32_16x16x32_bf16 v[40:43], v[180:183], v[200:203], v[40:43]
	v_mfma_f32_16x16x32_bf16 v[60:63], v[148:151], v[68:71], v[60:63]
	v_mfma_f32_16x16x32_bf16 v[56:59], v[180:183], v[64:67], v[56:59]
	v_mfma_f32_16x16x32_bf16 v[52:55], v[148:151], v[84:87], v[52:55]
	v_mfma_f32_16x16x32_bf16 v[48:51], v[180:183], v[80:83], v[48:51]
	v_mfma_f32_16x16x32_bf16 v[44:47], v[148:151], v[204:207], v[44:47]
	v_mfma_f32_16x16x32_bf16 v[40:43], v[184:187], v[204:207], v[40:43]
	v_mfma_f32_16x16x32_bf16 v[36:39], v[144:147], v[208:211], v[36:39]
	v_mfma_f32_16x16x32_bf16 v[32:35], v[180:183], v[208:211], v[32:35]
	v_mfma_f32_16x16x32_bf16 v[216:219], v[184:187], v[68:71], v[56:59]
	v_mfma_f32_16x16x32_bf16 v[232:235], v[184:187], v[84:87], v[48:51]
	v_mfma_f32_16x16x32_bf16 v[144:147], v[148:151], v[212:215], v[36:39]
	v_mfma_f32_16x16x32_bf16 v[148:151], v[184:187], v[212:215], v[32:35]
	v_mfma_f32_16x16x32_bf16 v[28:31], v[96:99], v[64:67], v[28:31]
	v_mfma_f32_16x16x32_bf16 v[20:23], v[96:99], v[80:83], v[20:23]
	v_mfma_f32_16x16x32_bf16 v[12:15], v[96:99], v[200:203], v[12:15]
	v_mfma_f32_16x16x32_bf16 v[4:7], v[96:99], v[208:211], v[4:7]
	v_mfma_f32_16x16x32_bf16 v[28:31], v[100:103], v[68:71], v[28:31]
	v_mfma_f32_16x16x32_bf16 v[24:27], v[112:115], v[64:67], v[24:27]
	v_mfma_f32_16x16x32_bf16 v[20:23], v[100:103], v[84:87], v[20:23]
	v_mfma_f32_16x16x32_bf16 v[16:19], v[112:115], v[80:83], v[16:19]
	v_mfma_f32_16x16x32_bf16 v[12:15], v[100:103], v[204:207], v[12:15]
	v_mfma_f32_16x16x32_bf16 v[8:11], v[112:115], v[200:203], v[8:11]
	v_mfma_f32_16x16x32_bf16 v[4:7], v[100:103], v[212:215], v[4:7]
	v_mfma_f32_16x16x32_bf16 v[0:3], v[112:115], v[208:211], v[0:3]
	v_mfma_f32_16x16x32_bf16 v[178:181], v[116:119], v[68:71], v[24:27]
	v_mfma_f32_16x16x32_bf16 v[182:185], v[116:119], v[84:87], v[16:19]
	v_mfma_f32_16x16x32_bf16 v[200:203], v[116:119], v[204:207], v[8:11]
	v_mfma_f32_16x16x32_bf16 v[204:207], v[116:119], v[212:215], v[0:3]
	s_barrier
	s_nop 1
	s_nop 0
	ds_read_b128 v[0:3], v154
	ds_read_b128 v[8:11], v154 offset:1024
	ds_read_b128 v[208:211], v154 offset:2048
	ds_read_b128 v[212:215], v154 offset:3072
	ds_read_b128 v[16:19], v131 offset:32768
	ds_read_b128 v[24:27], v131 offset:33792
	ds_read_b128 v[32:35], v174 offset:32768
	ds_read_b128 v[36:39], v174 offset:33792
	ds_read_b128 v[48:51], v175 offset:32768
	ds_read_b128 v[56:59], v175 offset:33792
	ds_read_b128 v[236:239], v177 offset:32768
	ds_read_b128 v[240:243], v177 offset:33792
	s_waitcnt vmcnt(2)
	s_barrier
; #define LDA(dst,b,h) _Pragma("unroll") for(int m=0;m<4;++m) _Pragma("unroll") for(int k=0;k<2;++k) \
;     dst[m][k]=*reinterpret_cast<const bf16x8*>((char*)SA(b,h)+lds_byte(wr*64+m*16+fr,k*32+fq*8))
; #define LDB(dst,b,h) _Pragma("unroll") for(int n=0;n<2;++n) _Pragma("unroll") for(int k=0;k<2;++k) \
;     dst[n][k]=*reinterpret_cast<const bf16x8*>((char*)SB(b,h)+lds_byte(wc*32+n*16+fr,k*32+fq*8))
; #define MMA(ai,bj,At_,Bt_) do{__builtin_amdgcn_s_setprio(1); \
;     _Pragma("unroll") for(int m=0;m<4;++m) _Pragma("unroll") for(int n=0;n<2;++n) _Pragma("unroll") for(int k=0;k<2;++k) \
;       acc[ai][bj][m][n]=__builtin_amdgcn_mfma_f32_16x16x32_bf16(Bt_[n][k],At_[m][k],acc[ai][bj][m][n],0,0,0); \
;     __builtin_amdgcn_s_setprio(0);}while(0)
; #define WAIT_V(n) asm volatile("s_waitcnt vmcnt(" #n ")":::"memory")
; #define WAIT_L(n) asm volatile("s_waitcnt lgkmcnt(" #n ")":::"memory")
; #define BAR __builtin_amdgcn_s_barrier()
; DEVINL void gemm8_mainloop(const u16* A, long lda, const u16* Bt, long ldb, int K, int brow, int bcol, f32x4 (&acc)[2][2][4][2], char* smem, int tid) {
;     ...
;   { LDB(B0,1,0); LDA(At,1,0); WAIT_V(2); BAR; WAIT_L(0); MMA(0,0,At,B0); BAR;
;     LDB(B1,1,1); WAIT_V(0); BAR; WAIT_L(0); MMA(0,1,At,B1); BAR;
;     LDA(At,1,1); BAR; WAIT_L(0); MMA(1,0,At,B0); MMA(1,1,At,B1); BAR; }
;   if(wr==0)BAR;
	s_waitcnt lgkmcnt(0)
	v_mfma_f32_16x16x32_bf16 v[64:67], v[0:3], v[16:19], v[124:127]
	v_mfma_f32_16x16x32_bf16 v[116:119], v[8:11], v[24:27], v[64:67]
	v_mfma_f32_16x16x32_bf16 v[64:67], v[208:211], v[16:19], v[120:123]
	v_mfma_f32_16x16x32_bf16 v[112:115], v[212:215], v[24:27], v[64:67]
	v_mfma_f32_16x16x32_bf16 v[64:67], v[0:3], v[32:35], v[140:143]
	v_mfma_f32_16x16x32_bf16 v[100:103], v[8:11], v[36:39], v[64:67]
	v_mfma_f32_16x16x32_bf16 v[64:67], v[208:211], v[32:35], v[220:223]
	v_mfma_f32_16x16x32_bf16 v[96:99], v[212:215], v[36:39], v[64:67]
	v_mfma_f32_16x16x32_bf16 v[64:67], v[0:3], v[48:51], v[108:111]
	v_mfma_f32_16x16x32_bf16 v[84:87], v[8:11], v[56:59], v[64:67]
	v_mfma_f32_16x16x32_bf16 v[64:67], v[208:211], v[48:51], v[104:107]
	v_mfma_f32_16x16x32_bf16 v[80:83], v[212:215], v[56:59], v[64:67]
	v_mfma_f32_16x16x32_bf16 v[64:67], v[0:3], v[236:239], v[224:227]
	v_mfma_f32_16x16x32_bf16 v[68:71], v[8:11], v[240:243], v[64:67]
	v_mfma_f32_16x16x32_bf16 v[64:67], v[208:211], v[236:239], v[228:231]
	v_mfma_f32_16x16x32_bf16 v[64:67], v[212:215], v[240:243], v[64:67]
	s_barrier
	ds_read_b128 v[140:143], v152
	ds_read_b128 v[220:223], v152 offset:1024
	ds_read_b128 v[224:227], v152 offset:2048
	ds_read_b128 v[152:155], v152 offset:3072
	s_waitcnt vmcnt(0)
	s_barrier
	s_waitcnt lgkmcnt(0)
	v_mfma_f32_16x16x32_bf16 v[92:95], v[140:143], v[16:19], v[92:95]
	v_mfma_f32_16x16x32_bf16 v[16:19], v[224:227], v[16:19], v[88:91]
	v_mfma_f32_16x16x32_bf16 v[120:123], v[152:155], v[24:27], v[16:19]
	v_mfma_f32_16x16x32_bf16 v[16:19], v[140:143], v[32:35], v[156:159]
	v_mfma_f32_16x16x32_bf16 v[104:107], v[220:223], v[36:39], v[16:19]
	v_mfma_f32_16x16x32_bf16 v[16:19], v[224:227], v[32:35], v[188:191]
	v_mfma_f32_16x16x32_bf16 v[108:111], v[152:155], v[36:39], v[16:19]
	v_mfma_f32_16x16x32_bf16 v[16:19], v[140:143], v[48:51], v[76:79]
	v_mfma_f32_16x16x32_bf16 v[124:127], v[220:223], v[24:27], v[92:95]
	v_mfma_f32_16x16x32_bf16 v[92:95], v[220:223], v[56:59], v[16:19]
	v_mfma_f32_16x16x32_bf16 v[16:19], v[224:227], v[48:51], v[72:75]
	v_mfma_f32_16x16x32_bf16 v[88:91], v[152:155], v[56:59], v[16:19]
	v_mfma_f32_16x16x32_bf16 v[16:19], v[140:143], v[236:239], v[192:195]
	v_mfma_f32_16x16x32_bf16 v[72:75], v[220:223], v[240:243], v[16:19]
	v_mfma_f32_16x16x32_bf16 v[16:19], v[224:227], v[236:239], v[196:199]
	v_mfma_f32_16x16x32_bf16 v[76:79], v[152:155], v[240:243], v[16:19]
	s_barrier
	ds_read_b128 v[156:159], v131 offset:49152
	ds_read_b128 v[186:189], v131 offset:50176
	ds_read_b128 v[190:193], v174 offset:49152
	ds_read_b128 v[194:197], v174 offset:50176
	ds_read_b128 v[228:231], v175 offset:49152
	ds_read_b128 v[236:239], v175 offset:50176
	ds_read_b128 v[240:243], v177 offset:49152
	ds_read_b128 v[244:247], v177 offset:50176
	s_barrier
	s_waitcnt lgkmcnt(0)
	v_mfma_f32_16x16x32_bf16 v[16:19], v[0:3], v[156:159], v[60:63]
	v_mfma_f32_16x16x32_bf16 v[56:59], v[8:11], v[186:189], v[16:19]
	v_mfma_f32_16x16x32_bf16 v[16:19], v[208:211], v[156:159], v[216:219]
	v_mfma_f32_16x16x32_bf16 v[48:51], v[212:215], v[186:189], v[16:19]
	v_mfma_f32_16x16x32_bf16 v[16:19], v[0:3], v[190:193], v[52:55]
	v_mfma_f32_16x16x32_bf16 v[36:39], v[8:11], v[194:197], v[16:19]
	v_mfma_f32_16x16x32_bf16 v[16:19], v[208:211], v[190:193], v[232:235]
	v_mfma_f32_16x16x32_bf16 v[32:35], v[212:215], v[194:197], v[16:19]
	v_mfma_f32_16x16x32_bf16 v[16:19], v[0:3], v[228:231], v[44:47]
	v_mfma_f32_16x16x32_bf16 v[0:3], v[0:3], v[240:243], v[144:147]
	v_mfma_f32_16x16x32_bf16 v[24:27], v[8:11], v[236:239], v[16:19]
	v_mfma_f32_16x16x32_bf16 v[16:19], v[208:211], v[228:231], v[40:43]
	v_mfma_f32_16x16x32_bf16 v[8:11], v[8:11], v[244:247], v[0:3]
	v_mfma_f32_16x16x32_bf16 v[0:3], v[208:211], v[240:243], v[148:151]
	v_mfma_f32_16x16x32_bf16 v[16:19], v[212:215], v[236:239], v[16:19]
	v_mfma_f32_16x16x32_bf16 v[0:3], v[212:215], v[244:247], v[0:3]
	v_mfma_f32_16x16x32_bf16 v[28:31], v[140:143], v[156:159], v[28:31]
	v_mfma_f32_16x16x32_bf16 v[60:63], v[220:223], v[186:189], v[28:31]
	v_mfma_f32_16x16x32_bf16 v[28:31], v[224:227], v[156:159], v[178:181]
	v_mfma_f32_16x16x32_bf16 v[20:23], v[140:143], v[190:193], v[20:23]
	v_mfma_f32_16x16x32_bf16 v[12:15], v[140:143], v[228:231], v[12:15]
	v_mfma_f32_16x16x32_bf16 v[52:55], v[152:155], v[186:189], v[28:31]
	v_mfma_f32_16x16x32_bf16 v[40:43], v[220:223], v[194:197], v[20:23]
	v_mfma_f32_16x16x32_bf16 v[20:23], v[224:227], v[190:193], v[182:185]
	v_mfma_f32_16x16x32_bf16 v[28:31], v[220:223], v[236:239], v[12:15]
	v_mfma_f32_16x16x32_bf16 v[12:15], v[224:227], v[228:231], v[200:203]
	v_mfma_f32_16x16x32_bf16 v[4:7], v[140:143], v[240:243], v[4:7]
	v_mfma_f32_16x16x32_bf16 v[44:47], v[152:155], v[194:197], v[20:23]
	v_mfma_f32_16x16x32_bf16 v[20:23], v[152:155], v[236:239], v[12:15]
	v_mfma_f32_16x16x32_bf16 v[12:15], v[220:223], v[244:247], v[4:7]
	v_mfma_f32_16x16x32_bf16 v[4:7], v[224:227], v[240:243], v[204:207]
	v_mfma_f32_16x16x32_bf16 v[4:7], v[152:155], v[244:247], v[4:7]
	s_setprio 0
	s_cmpk_gt_u32 s0, 0xff
	s_barrier
	s_cbranch_scc1 .LBB0_1295
	s_barrier

; #define STAGE(P,BASE,LD,br,kt) do{long _g=(long)(br)*(LD)+(long)(kt)*BK; \
;     _Pragma("unroll") for(int _i=0;_i<2;++_i){int _b=tid*16+_i*8192;int _r,_c;stage_rc(_b,_r,_c); \
;       __builtin_amdgcn_global_load_lds((const unsigned*)((BASE)+_g+(long)_r*(LD)+_c), \
;         (unsigned*)((char*)(P)+_b),16,0,0);}}while(0)
; #define STAGE(P,BASE,LD,br,kt) do{long _g=(long)(br)*(LD)+(long)(kt)*BK; \
;     _Pragma("unroll") for(int _i=0;_i<2;++_i){int _b=tid*16+_i*8192;int _r,_c;stage_rc(_b,_r,_c); \
;       __builtin_amdgcn_global_load_lds((const unsigned*)((BASE)+_g+(long)_r*(LD)+_c), \
;         (unsigned*)((char*)(P)+_b),16,0,0);}}while(0)
; #define LDA(dst,b,h) _Pragma("unroll") for(int m=0;m<4;++m) _Pragma("unroll") for(int k=0;k<2;++k) \
;     dst[m][k]=*reinterpret_cast<const bf16x8*>((char*)SA(b,h)+lds_byte(wr*64+m*16+fr,k*32+fq*8))
; #define LDB(dst,b,h) _Pragma("unroll") for(int n=0;n<2;++n) _Pragma("unroll") for(int k=0;k<2;++k) \
;     dst[n][k]=*reinterpret_cast<const bf16x8*>((char*)SB(b,h)+lds_byte(wc*32+n*16+fr,k*32+fq*8))
; #define MMA(ai,bj,At_,Bt_) do{__builtin_amdgcn_s_setprio(1); \
;     _Pragma("unroll") for(int m=0;m<4;++m) _Pragma("unroll") for(int n=0;n<2;++n) _Pragma("unroll") for(int k=0;k<2;++k) \
;       acc[ai][bj][m][n]=__builtin_amdgcn_mfma_f32_16x16x32_bf16(Bt_[n][k],At_[m][k],acc[ai][bj][m][n],0,0,0); \
;     __builtin_amdgcn_s_setprio(0);}while(0)
; #define WAIT_L(n) asm volatile("s_waitcnt lgkmcnt(" #n ")":::"memory")
; #define BAR __builtin_amdgcn_s_barrier()
; #define SCHED __builtin_amdgcn_sched_barrier(0)
; DEVINL void gemm8_mainloop(const u16* A, long lda, const u16* Bt, long ldb, int K, int brow, int bcol, f32x4 (&acc)[2][2][4][2], char* smem, int tid) {
;     ...
;   for(int t=0;t<nt-2;t+=2){
;     LDB(B0,0,0); SCHED; LDA(At,0,0); STAGE(SA(1,1),A,lda,brow+HALF,t+1);
;     WAIT_L(8); BAR; WAIT_L(0); MMA(0,0,At,B0); BAR; SCHED;
;     LDB(B1,0,1); STAGE(SB(0,0),Bt,ldb,bcol,t+2);
;     BAR; WAIT_L(0); MMA(0,1,At,B1); BAR;
;     LDA(At,0,1); STAGE(SA(0,0),A,lda,brow,t+2);
.LBB0_1871:
	ds_read_b128 v[178:181], v163
	ds_read_b128 v[182:185], v163 offset:1024
	ds_read_b128 v[186:189], v163 offset:2048
	ds_read_b128 v[190:193], v163 offset:3072
	v_add_u32_e32 v174, 0xc000, v152
	v_lshl_add_u64 v[242:243], s[94:95], 0, v[146:147]
	v_readfirstlane_b32 s27, v174
	v_add_u32_e32 v175, 0xe000, v152
	v_add_u32_e32 v171, s25, v162
	v_add_u32_e32 v172, s37, v162
	v_add_u32_e32 v173, s38, v162
	v_lshl_add_u64 v[164:165], v[242:243], 0, s[2:3]
	s_mov_b32 m0, s27
	v_lshl_add_u64 v[244:245], s[94:95], 0, v[148:149]
	v_readfirstlane_b32 s27, v175
	ds_read_b128 v[166:169], v153
	ds_read_b128 v[194:197], v153 offset:1024
	ds_read_b128 v[198:201], v171
	ds_read_b128 v[202:205], v171 offset:1024
	ds_read_b128 v[206:209], v172
	ds_read_b128 v[210:213], v172 offset:1024
	ds_read_b128 v[214:217], v173
	ds_read_b128 v[218:221], v173 offset:1024
	global_load_lds_dwordx4 v[164:165], off
	v_lshl_add_u64 v[164:165], v[244:245], 0, s[2:3]
	s_mov_b32 m0, s27
	s_nop 0
	global_load_lds_dwordx4 v[164:165], off
	s_waitcnt lgkmcnt(8)
	s_barrier
	s_waitcnt lgkmcnt(0)
	v_mfma_f32_16x16x32_bf16 v[124:127], v[178:181], v[166:169], v[124:127]
	v_mfma_f32_16x16x32_bf16 v[120:123], v[186:189], v[166:169], v[120:123]
	v_mfma_f32_16x16x32_bf16 v[116:119], v[178:181], v[198:201], v[116:119]
	v_mfma_f32_16x16x32_bf16 v[112:115], v[186:189], v[198:201], v[112:115]
	v_mfma_f32_16x16x32_bf16 v[108:111], v[178:181], v[206:209], v[108:111]
	v_mfma_f32_16x16x32_bf16 v[104:107], v[186:189], v[206:209], v[104:107]
	v_mfma_f32_16x16x32_bf16 v[100:103], v[178:181], v[214:217], v[100:103]
	v_mfma_f32_16x16x32_bf16 v[96:99], v[186:189], v[214:217], v[96:99]
	v_mfma_f32_16x16x32_bf16 v[124:127], v[182:185], v[194:197], v[124:127]
	v_mfma_f32_16x16x32_bf16 v[120:123], v[190:193], v[194:197], v[120:123]
	v_mfma_f32_16x16x32_bf16 v[116:119], v[182:185], v[202:205], v[116:119]
	v_mfma_f32_16x16x32_bf16 v[112:115], v[190:193], v[202:205], v[112:115]
	v_mfma_f32_16x16x32_bf16 v[108:111], v[182:185], v[210:213], v[108:111]
	v_mfma_f32_16x16x32_bf16 v[104:107], v[190:193], v[210:213], v[104:107]
	v_mfma_f32_16x16x32_bf16 v[100:103], v[182:185], v[218:221], v[100:103]
	v_mfma_f32_16x16x32_bf16 v[96:99], v[190:193], v[218:221], v[96:99]
	s_barrier
	v_add_u32_e32 v164, s30, v154
	v_lshl_add_u64 v[246:247], s[94:95], 0, v[142:143]
	v_readfirstlane_b32 s27, v164
	v_add_u32_e32 v165, 0x2000, v164
	v_lshl_add_u64 v[238:239], v[246:247], 0, s[4:5]
	s_mov_b32 m0, s27
	v_lshl_add_u64 v[248:249], s[94:95], 0, v[144:145]
	v_readfirstlane_b32 s27, v165
	ds_read_b128 v[222:225], v160
	ds_read_b128 v[226:229], v160 offset:1024
	ds_read_b128 v[230:233], v160 offset:2048
	ds_read_b128 v[234:237], v160 offset:3072
	global_load_lds_dwordx4 v[238:239], off
	v_lshl_add_u64 v[238:239], v[248:249], 0, s[4:5]
	s_mov_b32 m0, s27
	s_nop 0
	global_load_lds_dwordx4 v[238:239], off
	s_barrier
	s_waitcnt lgkmcnt(0)
	v_mfma_f32_16x16x32_bf16 v[92:95], v[222:225], v[166:169], v[92:95]
	v_mfma_f32_16x16x32_bf16 v[88:91], v[230:233], v[166:169], v[88:91]
	v_mfma_f32_16x16x32_bf16 v[84:87], v[222:225], v[198:201], v[84:87]
	v_mfma_f32_16x16x32_bf16 v[80:83], v[230:233], v[198:201], v[80:83]
	v_mfma_f32_16x16x32_bf16 v[76:79], v[222:225], v[206:209], v[76:79]
	v_mfma_f32_16x16x32_bf16 v[72:75], v[230:233], v[206:209], v[72:75]
	v_mfma_f32_16x16x32_bf16 v[68:71], v[222:225], v[214:217], v[68:71]
	v_mfma_f32_16x16x32_bf16 v[64:67], v[230:233], v[214:217], v[64:67]
	v_mfma_f32_16x16x32_bf16 v[92:95], v[226:229], v[194:197], v[92:95]
	v_mfma_f32_16x16x32_bf16 v[88:91], v[234:237], v[194:197], v[88:91]
	v_mfma_f32_16x16x32_bf16 v[84:87], v[226:229], v[202:205], v[84:87]
	v_mfma_f32_16x16x32_bf16 v[80:83], v[234:237], v[202:205], v[80:83]
	v_mfma_f32_16x16x32_bf16 v[76:79], v[226:229], v[210:213], v[76:79]
	v_mfma_f32_16x16x32_bf16 v[72:75], v[234:237], v[210:213], v[72:75]
	v_mfma_f32_16x16x32_bf16 v[68:71], v[226:229], v[218:221], v[68:71]
	v_mfma_f32_16x16x32_bf16 v[64:67], v[234:237], v[218:221], v[64:67]
	v_readfirstlane_b32 s27, v152
	v_lshl_add_u64 v[166:167], v[242:243], 0, s[6:7]
	s_mov_b32 m0, s27
	s_barrier
	ds_read_b128 v[194:197], v153 offset:16384
	ds_read_b128 v[198:201], v153 offset:17408
	ds_read_b128 v[202:205], v171 offset:16384
	ds_read_b128 v[206:209], v171 offset:17408
	ds_read_b128 v[210:213], v172 offset:16384
	ds_read_b128 v[214:217], v172 offset:17408
	ds_read_b128 v[218:221], v173 offset:16384
	ds_read_b128 v[238:241], v173 offset:17408
	global_load_lds_dwordx4 v[166:167], off
	v_add_u32_e32 v166, 0x2000, v152
	v_lshl_add_u64 v[168:169], v[244:245], 0, s[6:7]
	v_readfirstlane_b32 s27, v166
	s_mov_b32 m0, s27
	s_nop 0
	global_load_lds_dwordx4 v[168:169], off
	s_barrier
	s_waitcnt lgkmcnt(0)
	v_mfma_f32_16x16x32_bf16 v[60:63], v[178:181], v[194:197], v[60:63]
	v_mfma_f32_16x16x32_bf16 v[56:59], v[186:189], v[194:197], v[56:59]
	v_mfma_f32_16x16x32_bf16 v[52:55], v[178:181], v[202:205], v[52:55]
	v_mfma_f32_16x16x32_bf16 v[48:51], v[186:189], v[202:205], v[48:51]
	v_mfma_f32_16x16x32_bf16 v[44:47], v[178:181], v[210:213], v[44:47]
	v_mfma_f32_16x16x32_bf16 v[40:43], v[186:189], v[210:213], v[40:43]
	v_mfma_f32_16x16x32_bf16 v[36:39], v[178:181], v[218:221], v[36:39]
	v_mfma_f32_16x16x32_bf16 v[32:35], v[186:189], v[218:221], v[32:35]
	v_mfma_f32_16x16x32_bf16 v[60:63], v[182:185], v[198:201], v[60:63]
	v_mfma_f32_16x16x32_bf16 v[56:59], v[190:193], v[198:201], v[56:59]
	v_mfma_f32_16x16x32_bf16 v[52:55], v[182:185], v[206:209], v[52:55]
	v_mfma_f32_16x16x32_bf16 v[48:51], v[190:193], v[206:209], v[48:51]
	v_mfma_f32_16x16x32_bf16 v[44:47], v[182:185], v[214:217], v[44:47]
	v_mfma_f32_16x16x32_bf16 v[40:43], v[190:193], v[214:217], v[40:43]
	v_mfma_f32_16x16x32_bf16 v[36:39], v[182:185], v[238:241], v[36:39]
	v_mfma_f32_16x16x32_bf16 v[32:35], v[190:193], v[238:241], v[32:35]
	s_barrier
; #define STAGE(P,BASE,LD,br,kt) do{long _g=(long)(br)*(LD)+(long)(kt)*BK; \
;     _Pragma("unroll") for(int _i=0;_i<2;++_i){int _b=tid*16+_i*8192;int _r,_c;stage_rc(_b,_r,_c); \
;       __builtin_amdgcn_global_load_lds((const unsigned*)((BASE)+_g+(long)_r*(LD)+_c), \
;         (unsigned*)((char*)(P)+_b),16,0,0);}}while(0)
; #define STAGE(P,BASE,LD,br,kt) do{long _g=(long)(br)*(LD)+(long)(kt)*BK; \
;     _Pragma("unroll") for(int _i=0;_i<2;++_i){int _b=tid*16+_i*8192;int _r,_c;stage_rc(_b,_r,_c); \
;       __builtin_amdgcn_global_load_lds((const unsigned*)((BASE)+_g+(long)_r*(LD)+_c), \
;         (unsigned*)((char*)(P)+_b),16,0,0);}}while(0)
; #define LDA(dst,b,h) _Pragma("unroll") for(int m=0;m<4;++m) _Pragma("unroll") for(int k=0;k<2;++k) \
;     dst[m][k]=*reinterpret_cast<const bf16x8*>((char*)SA(b,h)+lds_byte(wr*64+m*16+fr,k*32+fq*8))
; #define LDB(dst,b,h) _Pragma("unroll") for(int n=0;n<2;++n) _Pragma("unroll") for(int k=0;k<2;++k) \
;     dst[n][k]=*reinterpret_cast<const bf16x8*>((char*)SB(b,h)+lds_byte(wc*32+n*16+fr,k*32+fq*8))
; #define MMA(ai,bj,At_,Bt_) do{__builtin_amdgcn_s_setprio(1); \
;     _Pragma("unroll") for(int m=0;m<4;++m) _Pragma("unroll") for(int n=0;n<2;++n) _Pragma("unroll") for(int k=0;k<2;++k) \
;       acc[ai][bj][m][n]=__builtin_amdgcn_mfma_f32_16x16x32_bf16(Bt_[n][k],At_[m][k],acc[ai][bj][m][n],0,0,0); \
;     __builtin_amdgcn_s_setprio(0);}while(0)
; #define WAIT_V(n) asm volatile("s_waitcnt vmcnt(" #n ")":::"memory")
; #define WAIT_L(n) asm volatile("s_waitcnt lgkmcnt(" #n ")":::"memory")
; #define BAR __builtin_amdgcn_s_barrier()
; #define SCHED __builtin_amdgcn_sched_barrier(0)
; DEVINL void gemm8_mainloop(const u16* A, long lda, const u16* Bt, long ldb, int K, int brow, int bcol, f32x4 (&acc)[2][2][4][2], char* smem, int tid) {
;     ...
;     LDA(At,0,1); STAGE(SA(0,0),A,lda,brow,t+2);
;     BAR; WAIT_L(0); MMA(1,0,At,B0); BAR; SCHED;
;     STAGE(SB(0,1),Bt,ldb,bcol+HALF,t+2);
;     WAIT_V(6); BAR; MMA(1,1,At,B1); BAR;
;     LDB(B0,1,0); SCHED; LDA(At,1,0); STAGE(SA(0,1),A,lda,brow+HALF,t+2);
;     WAIT_L(8); BAR; WAIT_L(0); MMA(0,0,At,B0); BAR; SCHED;
;     LDB(B1,1,1); STAGE(SB(1,0),Bt,ldb,bcol,t+3);
	v_add_u32_e32 v167, s31, v154
	v_lshl_add_u64 v[168:169], v[246:247], 0, s[8:9]
	v_readfirstlane_b32 s27, v167
	s_mov_b32 m0, s27
	v_lshl_add_u64 v[178:179], v[248:249], 0, s[8:9]
	global_load_lds_dwordx4 v[168:169], off
	v_add_u32_e32 v168, 0x2000, v167
	s_nop 0
	v_readfirstlane_b32 s27, v168
	s_mov_b32 m0, s27
	s_nop 0
	global_load_lds_dwordx4 v[178:179], off
	s_waitcnt vmcnt(6)
	s_barrier
	v_mfma_f32_16x16x32_bf16 v[28:31], v[222:225], v[194:197], v[28:31]
	v_mfma_f32_16x16x32_bf16 v[24:27], v[230:233], v[194:197], v[24:27]
	v_mfma_f32_16x16x32_bf16 v[20:23], v[222:225], v[202:205], v[20:23]
	v_mfma_f32_16x16x32_bf16 v[16:19], v[230:233], v[202:205], v[16:19]
	v_mfma_f32_16x16x32_bf16 v[12:15], v[222:225], v[210:213], v[12:15]
	v_mfma_f32_16x16x32_bf16 v[8:11], v[230:233], v[210:213], v[8:11]
	v_mfma_f32_16x16x32_bf16 v[4:7], v[222:225], v[218:221], v[4:7]
	v_mfma_f32_16x16x32_bf16 v[0:3], v[230:233], v[218:221], v[0:3]
	v_mfma_f32_16x16x32_bf16 v[28:31], v[226:229], v[198:201], v[28:31]
	v_mfma_f32_16x16x32_bf16 v[24:27], v[234:237], v[198:201], v[24:27]
	v_mfma_f32_16x16x32_bf16 v[20:23], v[226:229], v[206:209], v[20:23]
	v_mfma_f32_16x16x32_bf16 v[16:19], v[234:237], v[206:209], v[16:19]
	v_mfma_f32_16x16x32_bf16 v[12:15], v[226:229], v[214:217], v[12:15]
	v_mfma_f32_16x16x32_bf16 v[8:11], v[234:237], v[214:217], v[8:11]
	v_mfma_f32_16x16x32_bf16 v[4:7], v[226:229], v[238:241], v[4:7]
	v_mfma_f32_16x16x32_bf16 v[0:3], v[234:237], v[238:241], v[0:3]
	s_barrier
	ds_read_b128 v[178:181], v156
	ds_read_b128 v[182:185], v156 offset:1024
	ds_read_b128 v[186:189], v156 offset:2048
	ds_read_b128 v[190:193], v156 offset:3072
	v_add_u32_e32 v169, 0x4000, v152
	v_add_u32_e32 v170, 0x6000, v152
	v_readfirstlane_b32 s27, v169
	v_lshl_add_u64 v[226:227], v[242:243], 0, s[10:11]
	s_mov_b32 m0, s27
	v_readfirstlane_b32 s27, v170
	ds_read_b128 v[194:197], v153 offset:32768
	ds_read_b128 v[198:201], v153 offset:33792
	ds_read_b128 v[202:205], v171 offset:32768
	ds_read_b128 v[206:209], v171 offset:33792
	ds_read_b128 v[210:213], v172 offset:32768
	ds_read_b128 v[214:217], v172 offset:33792
	ds_read_b128 v[218:221], v173 offset:32768
	ds_read_b128 v[222:225], v173 offset:33792
	global_load_lds_dwordx4 v[226:227], off
	v_lshl_add_u64 v[226:227], v[244:245], 0, s[10:11]
	s_mov_b32 m0, s27
	s_nop 0
	global_load_lds_dwordx4 v[226:227], off
	s_waitcnt lgkmcnt(8)
	s_barrier
	s_waitcnt lgkmcnt(0)
	v_mfma_f32_16x16x32_bf16 v[124:127], v[178:181], v[194:197], v[124:127]
	v_mfma_f32_16x16x32_bf16 v[120:123], v[186:189], v[194:197], v[120:123]
	v_mfma_f32_16x16x32_bf16 v[116:119], v[178:181], v[202:205], v[116:119]
	v_mfma_f32_16x16x32_bf16 v[112:115], v[186:189], v[202:205], v[112:115]
	v_mfma_f32_16x16x32_bf16 v[108:111], v[178:181], v[210:213], v[108:111]
	v_mfma_f32_16x16x32_bf16 v[104:107], v[186:189], v[210:213], v[104:107]
	v_mfma_f32_16x16x32_bf16 v[100:103], v[178:181], v[218:221], v[100:103]
	v_mfma_f32_16x16x32_bf16 v[96:99], v[186:189], v[218:221], v[96:99]
	v_mfma_f32_16x16x32_bf16 v[124:127], v[182:185], v[198:201], v[124:127]
	v_mfma_f32_16x16x32_bf16 v[120:123], v[190:193], v[198:201], v[120:123]
	v_mfma_f32_16x16x32_bf16 v[116:119], v[182:185], v[206:209], v[116:119]
	v_mfma_f32_16x16x32_bf16 v[112:115], v[190:193], v[206:209], v[112:115]
	v_mfma_f32_16x16x32_bf16 v[108:111], v[182:185], v[214:217], v[108:111]
	v_mfma_f32_16x16x32_bf16 v[104:107], v[190:193], v[214:217], v[104:107]
	v_mfma_f32_16x16x32_bf16 v[100:103], v[182:185], v[222:225], v[100:103]
	v_mfma_f32_16x16x32_bf16 v[96:99], v[190:193], v[222:225], v[96:99]
	s_barrier
	v_readfirstlane_b32 s27, v157
	v_add_u32_e32 v177, 0x2000, v157
	v_lshl_add_u64 v[250:251], v[246:247], 0, s[12:13]
	s_mov_b32 m0, s27
	v_readfirstlane_b32 s27, v177
	ds_read_b128 v[226:229], v155
	ds_read_b128 v[230:233], v155 offset:1024
	ds_read_b128 v[234:237], v155 offset:2048
	ds_read_b128 v[238:241], v155 offset:3072
	global_load_lds_dwordx4 v[250:251], off
	v_lshl_add_u64 v[250:251], v[248:249], 0, s[12:13]
	s_mov_b32 m0, s27
	s_nop 0
	global_load_lds_dwordx4 v[250:251], off
	s_barrier
	s_waitcnt lgkmcnt(0)
	v_mfma_f32_16x16x32_bf16 v[92:95], v[226:229], v[194:197], v[92:95]
	v_mfma_f32_16x16x32_bf16 v[88:91], v[234:237], v[194:197], v[88:91]
	v_mfma_f32_16x16x32_bf16 v[84:87], v[226:229], v[202:205], v[84:87]
	v_mfma_f32_16x16x32_bf16 v[80:83], v[234:237], v[202:205], v[80:83]
	v_mfma_f32_16x16x32_bf16 v[76:79], v[226:229], v[210:213], v[76:79]
	v_mfma_f32_16x16x32_bf16 v[72:75], v[234:237], v[210:213], v[72:75]
	v_mfma_f32_16x16x32_bf16 v[68:71], v[226:229], v[218:221], v[68:71]
	v_mfma_f32_16x16x32_bf16 v[64:67], v[234:237], v[218:221], v[64:67]
	v_mfma_f32_16x16x32_bf16 v[92:95], v[230:233], v[198:201], v[92:95]
	v_mfma_f32_16x16x32_bf16 v[88:91], v[238:241], v[198:201], v[88:91]
	v_mfma_f32_16x16x32_bf16 v[84:87], v[230:233], v[206:209], v[84:87]
	v_mfma_f32_16x16x32_bf16 v[80:83], v[238:241], v[206:209], v[80:83]
	v_mfma_f32_16x16x32_bf16 v[76:79], v[230:233], v[214:217], v[76:79]
	v_mfma_f32_16x16x32_bf16 v[72:75], v[238:241], v[214:217], v[72:75]
	v_mfma_f32_16x16x32_bf16 v[68:71], v[230:233], v[222:225], v[68:71]
	v_mfma_f32_16x16x32_bf16 v[64:67], v[238:241], v[222:225], v[64:67]
	v_readfirstlane_b32 s27, v158
	v_lshl_add_u64 v[242:243], v[242:243], 0, s[14:15]
	s_mov_b32 m0, s27
	v_readfirstlane_b32 s27, v159
	s_barrier
	ds_read_b128 v[194:197], v153 offset:49152
	ds_read_b128 v[198:201], v153 offset:50176
	ds_read_b128 v[202:205], v171 offset:49152
	ds_read_b128 v[206:209], v171 offset:50176
	ds_read_b128 v[210:213], v172 offset:49152
	ds_read_b128 v[214:217], v172 offset:50176
	ds_read_b128 v[218:221], v173 offset:49152
	ds_read_b128 v[222:225], v173 offset:50176
	global_load_lds_dwordx4 v[242:243], off
	v_lshl_add_u64 v[242:243], v[244:245], 0, s[14:15]
	s_mov_b32 m0, s27
	s_nop 0
	global_load_lds_dwordx4 v[242:243], off
	s_barrier
; #define STAGE(P,BASE,LD,br,kt) do{long _g=(long)(br)*(LD)+(long)(kt)*BK; \
;     _Pragma("unroll") for(int _i=0;_i<2;++_i){int _b=tid*16+_i*8192;int _r,_c;stage_rc(_b,_r,_c); \
;       __builtin_amdgcn_global_load_lds((const unsigned*)((BASE)+_g+(long)_r*(LD)+_c), \
;         (unsigned*)((char*)(P)+_b),16,0,0);}}while(0)
; #define STAGE(P,BASE,LD,br,kt) do{long _g=(long)(br)*(LD)+(long)(kt)*BK; \
;     _Pragma("unroll") for(int _i=0;_i<2;++_i){int _b=tid*16+_i*8192;int _r,_c;stage_rc(_b,_r,_c); \
;       __builtin_amdgcn_global_load_lds((const unsigned*)((BASE)+_g+(long)_r*(LD)+_c), \
;         (unsigned*)((char*)(P)+_b),16,0,0);}}while(0)
; #define LDA(dst,b,h) _Pragma("unroll") for(int m=0;m<4;++m) _Pragma("unroll") for(int k=0;k<2;++k) \
;     dst[m][k]=*reinterpret_cast<const bf16x8*>((char*)SA(b,h)+lds_byte(wr*64+m*16+fr,k*32+fq*8))
; #define LDB(dst,b,h) _Pragma("unroll") for(int n=0;n<2;++n) _Pragma("unroll") for(int k=0;k<2;++k) \
;     dst[n][k]=*reinterpret_cast<const bf16x8*>((char*)SB(b,h)+lds_byte(wc*32+n*16+fr,k*32+fq*8))
; #define MMA(ai,bj,At_,Bt_) do{__builtin_amdgcn_s_setprio(1); \
;     _Pragma("unroll") for(int m=0;m<4;++m) _Pragma("unroll") for(int n=0;n<2;++n) _Pragma("unroll") for(int k=0;k<2;++k) \
;       acc[ai][bj][m][n]=__builtin_amdgcn_mfma_f32_16x16x32_bf16(Bt_[n][k],At_[m][k],acc[ai][bj][m][n],0,0,0); \
;     __builtin_amdgcn_s_setprio(0);}while(0)
; #define WAIT_V(n) asm volatile("s_waitcnt vmcnt(" #n ")":::"memory")
; #define WAIT_L(n) asm volatile("s_waitcnt lgkmcnt(" #n ")":::"memory")
; #define BAR __builtin_amdgcn_s_barrier()
; #define SCHED __builtin_amdgcn_sched_barrier(0)
; DEVINL void gemm8_mainloop(const u16* A, long lda, const u16* Bt, long ldb, int K, int brow, int bcol, f32x4 (&acc)[2][2][4][2], char* smem, int tid) {
;     ...
;     BAR; WAIT_L(0); MMA(1,0,At,B0); BAR; SCHED;
;     STAGE(SB(1,1),Bt,ldb,bcol+HALF,t+3);
;     WAIT_V(6); BAR; MMA(1,1,At,B1); BAR;
;   }
;   { LDB(B0,0,0); LDA(At,0,0); STAGE(SA(1,1),A,lda,brow+HALF,nt-1);
;     BAR; WAIT_L(0); MMA(0,0,At,B0); BAR;
;     LDB(B1,0,1); BAR; WAIT_L(0); MMA(0,1,At,B1); BAR;
	s_waitcnt lgkmcnt(0)
	v_mfma_f32_16x16x32_bf16 v[60:63], v[178:181], v[194:197], v[60:63]
	v_mfma_f32_16x16x32_bf16 v[56:59], v[186:189], v[194:197], v[56:59]
	v_mfma_f32_16x16x32_bf16 v[52:55], v[178:181], v[202:205], v[52:55]
	v_mfma_f32_16x16x32_bf16 v[48:51], v[186:189], v[202:205], v[48:51]
	v_mfma_f32_16x16x32_bf16 v[44:47], v[178:181], v[210:213], v[44:47]
	v_mfma_f32_16x16x32_bf16 v[40:43], v[186:189], v[210:213], v[40:43]
	v_mfma_f32_16x16x32_bf16 v[36:39], v[178:181], v[218:221], v[36:39]
	v_mfma_f32_16x16x32_bf16 v[32:35], v[186:189], v[218:221], v[32:35]
	v_mfma_f32_16x16x32_bf16 v[60:63], v[182:185], v[198:201], v[60:63]
	v_mfma_f32_16x16x32_bf16 v[56:59], v[190:193], v[198:201], v[56:59]
	v_mfma_f32_16x16x32_bf16 v[52:55], v[182:185], v[206:209], v[52:55]
	v_mfma_f32_16x16x32_bf16 v[48:51], v[190:193], v[206:209], v[48:51]
	v_mfma_f32_16x16x32_bf16 v[44:47], v[182:185], v[214:217], v[44:47]
	v_mfma_f32_16x16x32_bf16 v[40:43], v[190:193], v[214:217], v[40:43]
	v_mfma_f32_16x16x32_bf16 v[36:39], v[182:185], v[222:225], v[36:39]
	v_mfma_f32_16x16x32_bf16 v[32:35], v[190:193], v[222:225], v[32:35]
	s_barrier
	v_readfirstlane_b32 s27, v161
	v_add_u32_e32 v177, 0x2000, v161
	v_lshl_add_u64 v[178:179], v[246:247], 0, s[16:17]
	s_mov_b32 m0, s27
	v_readfirstlane_b32 s27, v177
	global_load_lds_dwordx4 v[178:179], off
	v_lshl_add_u64 v[178:179], v[248:249], 0, s[16:17]
	s_mov_b32 m0, s27
	s_nop 0
	global_load_lds_dwordx4 v[178:179], off
	s_waitcnt vmcnt(6)
	s_barrier
	v_mfma_f32_16x16x32_bf16 v[28:31], v[226:229], v[194:197], v[28:31]
	v_mfma_f32_16x16x32_bf16 v[24:27], v[234:237], v[194:197], v[24:27]
	v_mfma_f32_16x16x32_bf16 v[20:23], v[226:229], v[202:205], v[20:23]
	v_mfma_f32_16x16x32_bf16 v[16:19], v[234:237], v[202:205], v[16:19]
	v_mfma_f32_16x16x32_bf16 v[12:15], v[226:229], v[210:213], v[12:15]
	v_mfma_f32_16x16x32_bf16 v[8:11], v[234:237], v[210:213], v[8:11]
	v_mfma_f32_16x16x32_bf16 v[4:7], v[226:229], v[218:221], v[4:7]
	v_mfma_f32_16x16x32_bf16 v[0:3], v[234:237], v[218:221], v[0:3]
	v_mfma_f32_16x16x32_bf16 v[28:31], v[230:233], v[198:201], v[28:31]
	v_mfma_f32_16x16x32_bf16 v[24:27], v[238:241], v[198:201], v[24:27]
	v_mfma_f32_16x16x32_bf16 v[20:23], v[230:233], v[206:209], v[20:23]
	v_mfma_f32_16x16x32_bf16 v[16:19], v[238:241], v[206:209], v[16:19]
	v_mfma_f32_16x16x32_bf16 v[12:15], v[230:233], v[214:217], v[12:15]
	v_mfma_f32_16x16x32_bf16 v[8:11], v[238:241], v[214:217], v[8:11]
	v_mfma_f32_16x16x32_bf16 v[4:7], v[230:233], v[222:225], v[4:7]
	v_mfma_f32_16x16x32_bf16 v[0:3], v[238:241], v[222:225], v[0:3]
	s_add_i32 s26, s26, 2
	v_lshl_add_u64 v[142:143], v[142:143], 0, s[18:19]
	v_lshl_add_u64 v[144:145], v[144:145], 0, s[18:19]
	v_lshl_add_u64 v[146:147], v[146:147], 0, s[18:19]
	s_cmp_lt_u32 s26, 28
	v_lshl_add_u64 v[148:149], v[148:149], 0, s[18:19]
	s_barrier
	s_cbranch_scc1 .LBB0_1871
	s_or_b32 s26, s24, 0x80
	s_ashr_i32 s27, s26, 31
	s_lshl_b64 s[26:27], s[26:27], 12
	s_add_u32 s26, s47, s26
	s_addc_u32 s27, s48, s27
	v_lshl_add_u64 v[158:159], v[134:135], 1, s[26:27]
	v_lshl_add_u64 v[138:139], v[138:139], 1, v[158:159]
	v_readfirstlane_b32 s25, v174
	v_lshl_add_u64 v[138:139], v[138:139], 0, s[20:21]
	s_mov_b32 m0, s25
	ds_read_b128 v[142:145], v163
	ds_read_b128 v[146:149], v163 offset:1024
	ds_read_b128 v[178:181], v163 offset:2048
	ds_read_b128 v[182:185], v163 offset:3072
	ds_read_b128 v[186:189], v153
	ds_read_b128 v[190:193], v153 offset:1024
	ds_read_b128 v[194:197], v171
	ds_read_b128 v[198:201], v171 offset:1024
	ds_read_b128 v[202:205], v172
	ds_read_b128 v[206:209], v172 offset:1024
	ds_read_b128 v[210:213], v173
	ds_read_b128 v[214:217], v173 offset:1024
	global_load_lds_dwordx4 v[138:139], off
	v_lshl_add_u64 v[138:139], v[136:137], 1, s[26:27]
	v_lshl_add_u64 v[138:139], v[140:141], 1, v[138:139]
	v_readfirstlane_b32 s25, v175
	v_lshl_add_u64 v[138:139], v[138:139], 0, s[20:21]
	s_mov_b32 m0, s25
	s_nop 0
	global_load_lds_dwordx4 v[138:139], off
	s_barrier
	s_waitcnt lgkmcnt(0)
	v_mfma_f32_16x16x32_bf16 v[124:127], v[142:145], v[186:189], v[124:127]
	v_mfma_f32_16x16x32_bf16 v[120:123], v[178:181], v[186:189], v[120:123]
	v_mfma_f32_16x16x32_bf16 v[116:119], v[142:145], v[194:197], v[116:119]
	v_mfma_f32_16x16x32_bf16 v[112:115], v[178:181], v[194:197], v[112:115]
	v_mfma_f32_16x16x32_bf16 v[100:103], v[142:145], v[210:213], v[100:103]
	v_mfma_f32_16x16x32_bf16 v[96:99], v[178:181], v[210:213], v[96:99]
	v_mfma_f32_16x16x32_bf16 v[124:127], v[146:149], v[190:193], v[124:127]
	v_mfma_f32_16x16x32_bf16 v[120:123], v[182:185], v[190:193], v[120:123]
	v_mfma_f32_16x16x32_bf16 v[116:119], v[146:149], v[198:201], v[116:119]
	v_mfma_f32_16x16x32_bf16 v[112:115], v[182:185], v[198:201], v[112:115]
	v_mfma_f32_16x16x32_bf16 v[108:111], v[142:145], v[202:205], v[108:111]
	v_mfma_f32_16x16x32_bf16 v[104:107], v[178:181], v[202:205], v[104:107]
	v_mfma_f32_16x16x32_bf16 v[100:103], v[146:149], v[214:217], v[100:103]
	v_mfma_f32_16x16x32_bf16 v[96:99], v[182:185], v[214:217], v[96:99]
	v_mfma_f32_16x16x32_bf16 v[138:141], v[146:149], v[206:209], v[108:111]
	v_mfma_f32_16x16x32_bf16 v[218:221], v[182:185], v[206:209], v[104:107]
	s_barrier
	s_nop 1
	s_nop 0
	ds_read_b128 v[104:107], v160
	ds_read_b128 v[108:111], v160 offset:1024
	ds_read_b128 v[222:225], v160 offset:2048
	ds_read_b128 v[158:161], v160 offset:3072
	s_barrier
; #define LDA(dst,b,h) _Pragma("unroll") for(int m=0;m<4;++m) _Pragma("unroll") for(int k=0;k<2;++k) \
;     dst[m][k]=*reinterpret_cast<const bf16x8*>((char*)SA(b,h)+lds_byte(wr*64+m*16+fr,k*32+fq*8))
; #define LDB(dst,b,h) _Pragma("unroll") for(int n=0;n<2;++n) _Pragma("unroll") for(int k=0;k<2;++k) \
;     dst[n][k]=*reinterpret_cast<const bf16x8*>((char*)SB(b,h)+lds_byte(wc*32+n*16+fr,k*32+fq*8))
; #define MMA(ai,bj,At_,Bt_) do{__builtin_amdgcn_s_setprio(1); \
;     _Pragma("unroll") for(int m=0;m<4;++m) _Pragma("unroll") for(int n=0;n<2;++n) _Pragma("unroll") for(int k=0;k<2;++k) \
;       acc[ai][bj][m][n]=__builtin_amdgcn_mfma_f32_16x16x32_bf16(Bt_[n][k],At_[m][k],acc[ai][bj][m][n],0,0,0); \
;     __builtin_amdgcn_s_setprio(0);}while(0)
; #define WAIT_V(n) asm volatile("s_waitcnt vmcnt(" #n ")":::"memory")
; #define WAIT_L(n) asm volatile("s_waitcnt lgkmcnt(" #n ")":::"memory")
; #define BAR __builtin_amdgcn_s_barrier()
; DEVINL void gemm8_mainloop(const u16* A, long lda, const u16* Bt, long ldb, int K, int brow, int bcol, f32x4 (&acc)[2][2][4][2], char* smem, int tid) {
;     ...
;     LDB(B1,0,1); BAR; WAIT_L(0); MMA(0,1,At,B1); BAR;
;     LDA(At,0,1); WAIT_V(4); BAR; WAIT_L(0); MMA(1,0,At,B0); MMA(1,1,At,B1); BAR; }
;   { LDB(B0,1,0); LDA(At,1,0); WAIT_V(2); BAR; WAIT_L(0); MMA(0,0,At,B0); BAR;
	s_waitcnt lgkmcnt(0)
	v_mfma_f32_16x16x32_bf16 v[84:87], v[104:107], v[194:197], v[84:87]
	v_mfma_f32_16x16x32_bf16 v[80:83], v[222:225], v[194:197], v[80:83]
	v_mfma_f32_16x16x32_bf16 v[68:71], v[104:107], v[210:213], v[68:71]
	v_mfma_f32_16x16x32_bf16 v[92:95], v[104:107], v[186:189], v[92:95]
	v_mfma_f32_16x16x32_bf16 v[88:91], v[222:225], v[186:189], v[88:91]
	v_mfma_f32_16x16x32_bf16 v[84:87], v[108:111], v[198:201], v[84:87]
	v_mfma_f32_16x16x32_bf16 v[80:83], v[158:161], v[198:201], v[80:83]
	v_mfma_f32_16x16x32_bf16 v[76:79], v[104:107], v[202:205], v[76:79]
	v_mfma_f32_16x16x32_bf16 v[72:75], v[222:225], v[202:205], v[72:75]
	v_mfma_f32_16x16x32_bf16 v[68:71], v[108:111], v[214:217], v[68:71]
	v_mfma_f32_16x16x32_bf16 v[64:67], v[222:225], v[210:213], v[64:67]
	v_mfma_f32_16x16x32_bf16 v[226:229], v[108:111], v[190:193], v[92:95]
	v_mfma_f32_16x16x32_bf16 v[186:189], v[158:161], v[190:193], v[88:91]
	v_mfma_f32_16x16x32_bf16 v[190:193], v[108:111], v[206:209], v[76:79]
	v_mfma_f32_16x16x32_bf16 v[194:197], v[158:161], v[206:209], v[72:75]
	v_mfma_f32_16x16x32_bf16 v[198:201], v[158:161], v[214:217], v[64:67]
	s_barrier
	s_nop 0
	s_nop 0
	ds_read_b128 v[64:67], v153 offset:16384
	ds_read_b128 v[72:75], v153 offset:17408
	ds_read_b128 v[76:79], v171 offset:16384
	ds_read_b128 v[88:91], v171 offset:17408
	ds_read_b128 v[92:95], v172 offset:16384
	ds_read_b128 v[202:205], v172 offset:17408
	ds_read_b128 v[206:209], v173 offset:16384
	ds_read_b128 v[210:213], v173 offset:17408
	s_waitcnt vmcnt(4)
	s_barrier
	s_waitcnt lgkmcnt(0)
	v_mfma_f32_16x16x32_bf16 v[60:63], v[142:145], v[64:67], v[60:63]
	v_mfma_f32_16x16x32_bf16 v[56:59], v[178:181], v[64:67], v[56:59]
	v_mfma_f32_16x16x32_bf16 v[52:55], v[142:145], v[76:79], v[52:55]
	v_mfma_f32_16x16x32_bf16 v[48:51], v[178:181], v[76:79], v[48:51]
	v_mfma_f32_16x16x32_bf16 v[36:39], v[142:145], v[206:209], v[36:39]
	v_mfma_f32_16x16x32_bf16 v[32:35], v[178:181], v[206:209], v[32:35]
	v_mfma_f32_16x16x32_bf16 v[60:63], v[146:149], v[72:75], v[60:63]
	v_mfma_f32_16x16x32_bf16 v[56:59], v[182:185], v[72:75], v[56:59]
	v_mfma_f32_16x16x32_bf16 v[52:55], v[146:149], v[88:91], v[52:55]
	v_mfma_f32_16x16x32_bf16 v[48:51], v[182:185], v[88:91], v[48:51]
	v_mfma_f32_16x16x32_bf16 v[44:47], v[142:145], v[92:95], v[44:47]
	v_mfma_f32_16x16x32_bf16 v[40:43], v[178:181], v[92:95], v[40:43]
	v_mfma_f32_16x16x32_bf16 v[36:39], v[146:149], v[210:213], v[36:39]
	v_mfma_f32_16x16x32_bf16 v[32:35], v[182:185], v[210:213], v[32:35]
	v_mfma_f32_16x16x32_bf16 v[214:217], v[146:149], v[202:205], v[44:47]
	v_mfma_f32_16x16x32_bf16 v[230:233], v[182:185], v[202:205], v[40:43]
	v_mfma_f32_16x16x32_bf16 v[20:23], v[104:107], v[76:79], v[20:23]
	v_mfma_f32_16x16x32_bf16 v[16:19], v[222:225], v[76:79], v[16:19]
	v_mfma_f32_16x16x32_bf16 v[4:7], v[104:107], v[206:209], v[4:7]
	v_mfma_f32_16x16x32_bf16 v[28:31], v[104:107], v[64:67], v[28:31]
	v_mfma_f32_16x16x32_bf16 v[24:27], v[222:225], v[64:67], v[24:27]
	v_mfma_f32_16x16x32_bf16 v[20:23], v[108:111], v[88:91], v[20:23]
	v_mfma_f32_16x16x32_bf16 v[16:19], v[158:161], v[88:91], v[16:19]
	v_mfma_f32_16x16x32_bf16 v[12:15], v[104:107], v[92:95], v[12:15]
	v_mfma_f32_16x16x32_bf16 v[8:11], v[222:225], v[92:95], v[8:11]
	v_mfma_f32_16x16x32_bf16 v[4:7], v[108:111], v[210:213], v[4:7]
	v_mfma_f32_16x16x32_bf16 v[0:3], v[222:225], v[206:209], v[0:3]
	v_mfma_f32_16x16x32_bf16 v[142:145], v[108:111], v[72:75], v[28:31]
	v_mfma_f32_16x16x32_bf16 v[146:149], v[158:161], v[72:75], v[24:27]
	v_mfma_f32_16x16x32_bf16 v[178:181], v[108:111], v[202:205], v[12:15]
	v_mfma_f32_16x16x32_bf16 v[182:185], v[158:161], v[202:205], v[8:11]
	v_mfma_f32_16x16x32_bf16 v[158:161], v[158:161], v[210:213], v[0:3]
	s_barrier
	s_nop 0
	s_nop 0
	ds_read_b128 v[0:3], v156
	ds_read_b128 v[8:11], v156 offset:1024
	ds_read_b128 v[202:205], v156 offset:2048
	ds_read_b128 v[206:209], v156 offset:3072
	ds_read_b128 v[12:15], v153 offset:32768
	ds_read_b128 v[24:27], v153 offset:33792
	ds_read_b128 v[28:31], v171 offset:32768
	ds_read_b128 v[40:43], v171 offset:33792
	ds_read_b128 v[44:47], v172 offset:32768
	ds_read_b128 v[64:67], v172 offset:33792
	ds_read_b128 v[210:213], v173 offset:32768
	ds_read_b128 v[222:225], v173 offset:33792
	s_waitcnt vmcnt(2)
	s_barrier
; #define LDA(dst,b,h) _Pragma("unroll") for(int m=0;m<4;++m) _Pragma("unroll") for(int k=0;k<2;++k) \
;     dst[m][k]=*reinterpret_cast<const bf16x8*>((char*)SA(b,h)+lds_byte(wr*64+m*16+fr,k*32+fq*8))
; #define LDB(dst,b,h) _Pragma("unroll") for(int n=0;n<2;++n) _Pragma("unroll") for(int k=0;k<2;++k) \
;     dst[n][k]=*reinterpret_cast<const bf16x8*>((char*)SB(b,h)+lds_byte(wc*32+n*16+fr,k*32+fq*8))
; #define MMA(ai,bj,At_,Bt_) do{__builtin_amdgcn_s_setprio(1); \
;     _Pragma("unroll") for(int m=0;m<4;++m) _Pragma("unroll") for(int n=0;n<2;++n) _Pragma("unroll") for(int k=0;k<2;++k) \
;       acc[ai][bj][m][n]=__builtin_amdgcn_mfma_f32_16x16x32_bf16(Bt_[n][k],At_[m][k],acc[ai][bj][m][n],0,0,0); \
;     __builtin_amdgcn_s_setprio(0);}while(0)
; #define WAIT_V(n) asm volatile("s_waitcnt vmcnt(" #n ")":::"memory")
; #define WAIT_L(n) asm volatile("s_waitcnt lgkmcnt(" #n ")":::"memory")
; #define BAR __builtin_amdgcn_s_barrier()
; DEVINL void gemm8_mainloop(const u16* A, long lda, const u16* Bt, long ldb, int K, int brow, int bcol, f32x4 (&acc)[2][2][4][2], char* smem, int tid) {
;     ...
;   { LDB(B0,1,0); LDA(At,1,0); WAIT_V(2); BAR; WAIT_L(0); MMA(0,0,At,B0); BAR;
;     LDB(B1,1,1); WAIT_V(0); BAR; WAIT_L(0); MMA(0,1,At,B1); BAR;
;     LDA(At,1,1); BAR; WAIT_L(0); MMA(1,0,At,B0); MMA(1,1,At,B1); BAR; }
;   if(wr==0)BAR;
;   __syncthreads();
	s_waitcnt lgkmcnt(0)
	v_mfma_f32_16x16x32_bf16 v[72:75], v[0:3], v[12:15], v[124:127]
	v_mfma_f32_16x16x32_bf16 v[124:127], v[8:11], v[24:27], v[72:75]
	v_mfma_f32_16x16x32_bf16 v[72:75], v[202:205], v[12:15], v[120:123]
	v_mfma_f32_16x16x32_bf16 v[120:123], v[206:209], v[24:27], v[72:75]
	v_mfma_f32_16x16x32_bf16 v[72:75], v[0:3], v[28:31], v[116:119]
	v_mfma_f32_16x16x32_bf16 v[108:111], v[8:11], v[40:43], v[72:75]
	v_mfma_f32_16x16x32_bf16 v[72:75], v[202:205], v[28:31], v[112:115]
	v_mfma_f32_16x16x32_bf16 v[104:107], v[206:209], v[40:43], v[72:75]
	v_mfma_f32_16x16x32_bf16 v[72:75], v[0:3], v[44:47], v[138:141]
	v_mfma_f32_16x16x32_bf16 v[92:95], v[8:11], v[64:67], v[72:75]
	v_mfma_f32_16x16x32_bf16 v[72:75], v[202:205], v[44:47], v[218:221]
	v_mfma_f32_16x16x32_bf16 v[88:91], v[206:209], v[64:67], v[72:75]
	v_mfma_f32_16x16x32_bf16 v[72:75], v[0:3], v[210:213], v[100:103]
	v_mfma_f32_16x16x32_bf16 v[76:79], v[8:11], v[222:225], v[72:75]
	v_mfma_f32_16x16x32_bf16 v[72:75], v[202:205], v[210:213], v[96:99]
	v_mfma_f32_16x16x32_bf16 v[72:75], v[206:209], v[222:225], v[72:75]
	s_barrier
	ds_read_b128 v[138:141], v155
	ds_read_b128 v[218:221], v155 offset:1024
	ds_read_b128 v[234:237], v155 offset:2048
	ds_read_b128 v[154:157], v155 offset:3072
	s_waitcnt vmcnt(0)
	s_barrier
	s_waitcnt lgkmcnt(0)
	v_mfma_f32_16x16x32_bf16 v[96:99], v[138:141], v[12:15], v[226:229]
	v_mfma_f32_16x16x32_bf16 v[12:15], v[234:237], v[12:15], v[186:189]
	v_mfma_f32_16x16x32_bf16 v[116:119], v[154:157], v[24:27], v[12:15]
	v_mfma_f32_16x16x32_bf16 v[12:15], v[138:141], v[28:31], v[84:87]
	v_mfma_f32_16x16x32_bf16 v[112:115], v[218:221], v[24:27], v[96:99]
	v_mfma_f32_16x16x32_bf16 v[96:99], v[218:221], v[40:43], v[12:15]
	v_mfma_f32_16x16x32_bf16 v[12:15], v[234:237], v[28:31], v[80:83]
	v_mfma_f32_16x16x32_bf16 v[100:103], v[154:157], v[40:43], v[12:15]
	v_mfma_f32_16x16x32_bf16 v[12:15], v[138:141], v[44:47], v[190:193]
	v_mfma_f32_16x16x32_bf16 v[80:83], v[218:221], v[64:67], v[12:15]
	v_mfma_f32_16x16x32_bf16 v[12:15], v[234:237], v[44:47], v[194:197]
	v_mfma_f32_16x16x32_bf16 v[84:87], v[154:157], v[64:67], v[12:15]
	v_mfma_f32_16x16x32_bf16 v[12:15], v[138:141], v[210:213], v[68:71]
	v_mfma_f32_16x16x32_bf16 v[64:67], v[218:221], v[222:225], v[12:15]
	v_mfma_f32_16x16x32_bf16 v[12:15], v[234:237], v[210:213], v[198:201]
	v_mfma_f32_16x16x32_bf16 v[68:71], v[154:157], v[222:225], v[12:15]
	s_barrier
	ds_read_b128 v[186:189], v153 offset:49152
	ds_read_b128 v[190:193], v153 offset:50176
	ds_read_b128 v[194:197], v171 offset:49152
	ds_read_b128 v[198:201], v171 offset:50176
	ds_read_b128 v[210:213], v172 offset:49152
	ds_read_b128 v[222:225], v172 offset:50176
	ds_read_b128 v[226:229], v173 offset:49152
	ds_read_b128 v[172:175], v173 offset:50176
	s_barrier
	s_waitcnt lgkmcnt(0)
	v_mfma_f32_16x16x32_bf16 v[12:15], v[0:3], v[186:189], v[60:63]
	v_mfma_f32_16x16x32_bf16 v[60:63], v[8:11], v[190:193], v[12:15]
	v_mfma_f32_16x16x32_bf16 v[12:15], v[202:205], v[186:189], v[56:59]
	v_mfma_f32_16x16x32_bf16 v[56:59], v[206:209], v[190:193], v[12:15]
	v_mfma_f32_16x16x32_bf16 v[12:15], v[0:3], v[194:197], v[52:55]
	v_mfma_f32_16x16x32_bf16 v[44:47], v[8:11], v[198:201], v[12:15]
	v_mfma_f32_16x16x32_bf16 v[12:15], v[202:205], v[194:197], v[48:51]
	v_mfma_f32_16x16x32_bf16 v[40:43], v[206:209], v[198:201], v[12:15]
	v_mfma_f32_16x16x32_bf16 v[12:15], v[0:3], v[210:213], v[214:217]
	v_mfma_f32_16x16x32_bf16 v[28:31], v[8:11], v[222:225], v[12:15]
	v_mfma_f32_16x16x32_bf16 v[12:15], v[202:205], v[210:213], v[230:233]
	v_mfma_f32_16x16x32_bf16 v[0:3], v[0:3], v[226:229], v[36:39]
	v_mfma_f32_16x16x32_bf16 v[24:27], v[206:209], v[222:225], v[12:15]
	v_mfma_f32_16x16x32_bf16 v[12:15], v[8:11], v[172:175], v[0:3]
	v_mfma_f32_16x16x32_bf16 v[0:3], v[202:205], v[226:229], v[32:35]
	v_mfma_f32_16x16x32_bf16 v[8:11], v[206:209], v[172:175], v[0:3]
	v_mfma_f32_16x16x32_bf16 v[0:3], v[138:141], v[186:189], v[142:145]
	v_mfma_f32_16x16x32_bf16 v[48:51], v[218:221], v[190:193], v[0:3]
	v_mfma_f32_16x16x32_bf16 v[0:3], v[234:237], v[186:189], v[146:149]
	v_mfma_f32_16x16x32_bf16 v[52:55], v[154:157], v[190:193], v[0:3]
	v_mfma_f32_16x16x32_bf16 v[0:3], v[138:141], v[194:197], v[20:23]
	v_mfma_f32_16x16x32_bf16 v[32:35], v[218:221], v[198:201], v[0:3]
	v_mfma_f32_16x16x32_bf16 v[0:3], v[234:237], v[194:197], v[16:19]
	v_mfma_f32_16x16x32_bf16 v[36:39], v[154:157], v[198:201], v[0:3]
	v_mfma_f32_16x16x32_bf16 v[0:3], v[138:141], v[210:213], v[178:181]
	v_mfma_f32_16x16x32_bf16 v[16:19], v[218:221], v[222:225], v[0:3]
	v_mfma_f32_16x16x32_bf16 v[0:3], v[234:237], v[210:213], v[182:185]
	v_mfma_f32_16x16x32_bf16 v[20:23], v[154:157], v[222:225], v[0:3]
	v_mfma_f32_16x16x32_bf16 v[0:3], v[138:141], v[226:229], v[4:7]
	v_mfma_f32_16x16x32_bf16 v[4:7], v[234:237], v[226:229], v[158:161]
	v_mfma_f32_16x16x32_bf16 v[0:3], v[218:221], v[172:175], v[0:3]
	v_mfma_f32_16x16x32_bf16 v[4:7], v[154:157], v[172:175], v[4:7]
	s_setprio 0
	s_cmpk_gt_u32 s29, 0xff
	s_barrier
	s_cbranch_scc1 .LBB0_1874
	s_barrier

; #define STAGE(P,BASE,LD,br,kt) do{long _g=(long)(br)*(LD)+(long)(kt)*BK; \
;     _Pragma("unroll") for(int _i=0;_i<2;++_i){int _b=tid*16+_i*8192;int _r,_c;stage_rc(_b,_r,_c); \
;       __builtin_amdgcn_global_load_lds((const unsigned*)((BASE)+_g+(long)_r*(LD)+_c), \
;         (unsigned*)((char*)(P)+_b),16,0,0);}}while(0)
; #define STAGE(P,BASE,LD,br,kt) do{long _g=(long)(br)*(LD)+(long)(kt)*BK; \
;     _Pragma("unroll") for(int _i=0;_i<2;++_i){int _b=tid*16+_i*8192;int _r,_c;stage_rc(_b,_r,_c); \
;       __builtin_amdgcn_global_load_lds((const unsigned*)((BASE)+_g+(long)_r*(LD)+_c), \
;         (unsigned*)((char*)(P)+_b),16,0,0);}}while(0)
; #define LDA(dst,b,h) _Pragma("unroll") for(int m=0;m<4;++m) _Pragma("unroll") for(int k=0;k<2;++k) \
;     dst[m][k]=*reinterpret_cast<const bf16x8*>((char*)SA(b,h)+lds_byte(wr*64+m*16+fr,k*32+fq*8))
; #define LDB(dst,b,h) _Pragma("unroll") for(int n=0;n<2;++n) _Pragma("unroll") for(int k=0;k<2;++k) \
;     dst[n][k]=*reinterpret_cast<const bf16x8*>((char*)SB(b,h)+lds_byte(wc*32+n*16+fr,k*32+fq*8))
; #define MMA(ai,bj,At_,Bt_) do{__builtin_amdgcn_s_setprio(1); \
;     _Pragma("unroll") for(int m=0;m<4;++m) _Pragma("unroll") for(int n=0;n<2;++n) _Pragma("unroll") for(int k=0;k<2;++k) \
;       acc[ai][bj][m][n]=__builtin_amdgcn_mfma_f32_16x16x32_bf16(Bt_[n][k],At_[m][k],acc[ai][bj][m][n],0,0,0); \
;     __builtin_amdgcn_s_setprio(0);}while(0)
; #define WAIT_L(n) asm volatile("s_waitcnt lgkmcnt(" #n ")":::"memory")
; #define BAR __builtin_amdgcn_s_barrier()
; #define SCHED __builtin_amdgcn_sched_barrier(0)
; DEVINL void gemm8_mainloop(const u16* A, long lda, const u16* Bt, long ldb, int K, int brow, int bcol, f32x4 (&acc)[2][2][4][2], char* smem, int tid) {
;     ...
;     LDB(B0,0,0); SCHED; LDA(At,0,0); STAGE(SA(1,1),A,lda,brow+HALF,t+1);
;     WAIT_L(8); BAR; WAIT_L(0); MMA(0,0,At,B0); BAR; SCHED;
;     LDB(B1,0,1); STAGE(SB(0,0),Bt,ldb,bcol,t+2);
;     BAR; WAIT_L(0); MMA(0,1,At,B1); BAR;
;     LDA(At,0,1); STAGE(SA(0,0),A,lda,brow,t+2);
;     BAR; WAIT_L(0); MMA(1,0,At,B0); BAR; SCHED;
.LBB0_1938:
	ds_read_b128 v[180:183], v165
	ds_read_b128 v[184:187], v165 offset:1024
	ds_read_b128 v[188:191], v165 offset:2048
	ds_read_b128 v[192:195], v165 offset:3072
	v_add_u32_e32 v177, 0xc000, v154
	v_lshl_add_u64 v[244:245], s[94:95], 0, v[146:147]
	v_readfirstlane_b32 s27, v177
	v_add_u32_e32 v178, 0xe000, v154
	v_add_u32_e32 v173, s23, v164
	v_add_u32_e32 v174, s38, v164
	v_add_u32_e32 v175, s39, v164
	v_lshl_add_u64 v[166:167], v[244:245], 0, s[2:3]
	s_mov_b32 m0, s27
	v_lshl_add_u64 v[246:247], s[94:95], 0, v[148:149]
	v_readfirstlane_b32 s27, v178
	ds_read_b128 v[168:171], v155
	ds_read_b128 v[196:199], v155 offset:1024
	ds_read_b128 v[200:203], v173
	ds_read_b128 v[204:207], v173 offset:1024
	ds_read_b128 v[208:211], v174
	ds_read_b128 v[212:215], v174 offset:1024
	ds_read_b128 v[216:219], v175
	ds_read_b128 v[220:223], v175 offset:1024
	global_load_lds_dwordx4 v[166:167], off
	v_lshl_add_u64 v[166:167], v[246:247], 0, s[2:3]
	s_mov_b32 m0, s27
	s_nop 0
	global_load_lds_dwordx4 v[166:167], off
	s_waitcnt lgkmcnt(8)
	s_barrier
	s_waitcnt lgkmcnt(0)
	v_mfma_f32_16x16x32_bf16 v[124:127], v[180:183], v[168:171], v[124:127]
	v_mfma_f32_16x16x32_bf16 v[120:123], v[188:191], v[168:171], v[120:123]
	v_mfma_f32_16x16x32_bf16 v[116:119], v[180:183], v[200:203], v[116:119]
	v_mfma_f32_16x16x32_bf16 v[112:115], v[188:191], v[200:203], v[112:115]
	v_mfma_f32_16x16x32_bf16 v[108:111], v[180:183], v[208:211], v[108:111]
	v_mfma_f32_16x16x32_bf16 v[104:107], v[188:191], v[208:211], v[104:107]
	v_mfma_f32_16x16x32_bf16 v[100:103], v[180:183], v[216:219], v[100:103]
	v_mfma_f32_16x16x32_bf16 v[96:99], v[188:191], v[216:219], v[96:99]
	v_mfma_f32_16x16x32_bf16 v[124:127], v[184:187], v[196:199], v[124:127]
	v_mfma_f32_16x16x32_bf16 v[120:123], v[192:195], v[196:199], v[120:123]
	v_mfma_f32_16x16x32_bf16 v[116:119], v[184:187], v[204:207], v[116:119]
	v_mfma_f32_16x16x32_bf16 v[112:115], v[192:195], v[204:207], v[112:115]
	v_mfma_f32_16x16x32_bf16 v[108:111], v[184:187], v[212:215], v[108:111]
	v_mfma_f32_16x16x32_bf16 v[104:107], v[192:195], v[212:215], v[104:107]
	v_mfma_f32_16x16x32_bf16 v[100:103], v[184:187], v[220:223], v[100:103]
	v_mfma_f32_16x16x32_bf16 v[96:99], v[192:195], v[220:223], v[96:99]
	s_barrier
	v_add_u32_e32 v166, s28, v157
	v_lshl_add_u64 v[248:249], s[94:95], 0, v[142:143]
	v_readfirstlane_b32 s27, v166
	v_add_u32_e32 v167, 0x2000, v166
	v_lshl_add_u64 v[240:241], v[248:249], 0, s[4:5]
	s_mov_b32 m0, s27
	v_lshl_add_u64 v[250:251], s[94:95], 0, v[144:145]
	v_readfirstlane_b32 s27, v167
	ds_read_b128 v[224:227], v161
	ds_read_b128 v[228:231], v161 offset:1024
	ds_read_b128 v[232:235], v161 offset:2048
	ds_read_b128 v[236:239], v161 offset:3072
	global_load_lds_dwordx4 v[240:241], off
	v_lshl_add_u64 v[240:241], v[250:251], 0, s[4:5]
	s_mov_b32 m0, s27
	s_nop 0
	global_load_lds_dwordx4 v[240:241], off
	s_barrier
	s_waitcnt lgkmcnt(0)
	v_mfma_f32_16x16x32_bf16 v[92:95], v[224:227], v[168:171], v[92:95]
	v_mfma_f32_16x16x32_bf16 v[88:91], v[232:235], v[168:171], v[88:91]
	v_mfma_f32_16x16x32_bf16 v[84:87], v[224:227], v[200:203], v[84:87]
	v_mfma_f32_16x16x32_bf16 v[80:83], v[232:235], v[200:203], v[80:83]
	v_mfma_f32_16x16x32_bf16 v[76:79], v[224:227], v[208:211], v[76:79]
	v_mfma_f32_16x16x32_bf16 v[72:75], v[232:235], v[208:211], v[72:75]
	v_mfma_f32_16x16x32_bf16 v[68:71], v[224:227], v[216:219], v[68:71]
	v_mfma_f32_16x16x32_bf16 v[64:67], v[232:235], v[216:219], v[64:67]
	v_mfma_f32_16x16x32_bf16 v[92:95], v[228:231], v[196:199], v[92:95]
	v_mfma_f32_16x16x32_bf16 v[88:91], v[236:239], v[196:199], v[88:91]
	v_mfma_f32_16x16x32_bf16 v[84:87], v[228:231], v[204:207], v[84:87]
	v_mfma_f32_16x16x32_bf16 v[80:83], v[236:239], v[204:207], v[80:83]
	v_mfma_f32_16x16x32_bf16 v[76:79], v[228:231], v[212:215], v[76:79]
	v_mfma_f32_16x16x32_bf16 v[72:75], v[236:239], v[212:215], v[72:75]
	v_mfma_f32_16x16x32_bf16 v[68:71], v[228:231], v[220:223], v[68:71]
	v_mfma_f32_16x16x32_bf16 v[64:67], v[236:239], v[220:223], v[64:67]
	v_readfirstlane_b32 s27, v154
	v_lshl_add_u64 v[168:169], v[244:245], 0, s[6:7]
	s_mov_b32 m0, s27
	s_barrier
	ds_read_b128 v[196:199], v155 offset:16384
	ds_read_b128 v[200:203], v155 offset:17408
	ds_read_b128 v[204:207], v173 offset:16384
	ds_read_b128 v[208:211], v173 offset:17408
	ds_read_b128 v[212:215], v174 offset:16384
	ds_read_b128 v[216:219], v174 offset:17408
	ds_read_b128 v[220:223], v175 offset:16384
	ds_read_b128 v[240:243], v175 offset:17408
	global_load_lds_dwordx4 v[168:169], off
	v_add_u32_e32 v168, 0x2000, v154
	v_lshl_add_u64 v[170:171], v[246:247], 0, s[6:7]
	v_readfirstlane_b32 s27, v168
	s_mov_b32 m0, s27
	s_nop 0
	global_load_lds_dwordx4 v[170:171], off
	s_barrier
	s_waitcnt lgkmcnt(0)
	v_mfma_f32_16x16x32_bf16 v[60:63], v[180:183], v[196:199], v[60:63]
	v_mfma_f32_16x16x32_bf16 v[56:59], v[188:191], v[196:199], v[56:59]
	v_mfma_f32_16x16x32_bf16 v[52:55], v[180:183], v[204:207], v[52:55]
	v_mfma_f32_16x16x32_bf16 v[48:51], v[188:191], v[204:207], v[48:51]
	v_mfma_f32_16x16x32_bf16 v[44:47], v[180:183], v[212:215], v[44:47]
	v_mfma_f32_16x16x32_bf16 v[40:43], v[188:191], v[212:215], v[40:43]
	v_mfma_f32_16x16x32_bf16 v[36:39], v[180:183], v[220:223], v[36:39]
	v_mfma_f32_16x16x32_bf16 v[32:35], v[188:191], v[220:223], v[32:35]
	v_mfma_f32_16x16x32_bf16 v[60:63], v[184:187], v[200:203], v[60:63]
	v_mfma_f32_16x16x32_bf16 v[56:59], v[192:195], v[200:203], v[56:59]
	v_mfma_f32_16x16x32_bf16 v[52:55], v[184:187], v[208:211], v[52:55]
	v_mfma_f32_16x16x32_bf16 v[48:51], v[192:195], v[208:211], v[48:51]
	v_mfma_f32_16x16x32_bf16 v[44:47], v[184:187], v[216:219], v[44:47]
	v_mfma_f32_16x16x32_bf16 v[40:43], v[192:195], v[216:219], v[40:43]
	v_mfma_f32_16x16x32_bf16 v[36:39], v[184:187], v[240:243], v[36:39]
	v_mfma_f32_16x16x32_bf16 v[32:35], v[192:195], v[240:243], v[32:35]
	s_barrier
; #define STAGE(P,BASE,LD,br,kt) do{long _g=(long)(br)*(LD)+(long)(kt)*BK; \
;     _Pragma("unroll") for(int _i=0;_i<2;++_i){int _b=tid*16+_i*8192;int _r,_c;stage_rc(_b,_r,_c); \
;       __builtin_amdgcn_global_load_lds((const unsigned*)((BASE)+_g+(long)_r*(LD)+_c), \
;         (unsigned*)((char*)(P)+_b),16,0,0);}}while(0)
; #define STAGE(P,BASE,LD,br,kt) do{long _g=(long)(br)*(LD)+(long)(kt)*BK; \
;     _Pragma("unroll") for(int _i=0;_i<2;++_i){int _b=tid*16+_i*8192;int _r,_c;stage_rc(_b,_r,_c); \
;       __builtin_amdgcn_global_load_lds((const unsigned*)((BASE)+_g+(long)_r*(LD)+_c), \
;         (unsigned*)((char*)(P)+_b),16,0,0);}}while(0)
; #define LDA(dst,b,h) _Pragma("unroll") for(int m=0;m<4;++m) _Pragma("unroll") for(int k=0;k<2;++k) \
;     dst[m][k]=*reinterpret_cast<const bf16x8*>((char*)SA(b,h)+lds_byte(wr*64+m*16+fr,k*32+fq*8))
; #define LDB(dst,b,h) _Pragma("unroll") for(int n=0;n<2;++n) _Pragma("unroll") for(int k=0;k<2;++k) \
;     dst[n][k]=*reinterpret_cast<const bf16x8*>((char*)SB(b,h)+lds_byte(wc*32+n*16+fr,k*32+fq*8))
; #define MMA(ai,bj,At_,Bt_) do{__builtin_amdgcn_s_setprio(1); \
;     _Pragma("unroll") for(int m=0;m<4;++m) _Pragma("unroll") for(int n=0;n<2;++n) _Pragma("unroll") for(int k=0;k<2;++k) \
;       acc[ai][bj][m][n]=__builtin_amdgcn_mfma_f32_16x16x32_bf16(Bt_[n][k],At_[m][k],acc[ai][bj][m][n],0,0,0); \
;     __builtin_amdgcn_s_setprio(0);}while(0)
; #define WAIT_V(n) asm volatile("s_waitcnt vmcnt(" #n ")":::"memory")
; #define WAIT_L(n) asm volatile("s_waitcnt lgkmcnt(" #n ")":::"memory")
; #define BAR __builtin_amdgcn_s_barrier()
; #define SCHED __builtin_amdgcn_sched_barrier(0)
; DEVINL void gemm8_mainloop(const u16* A, long lda, const u16* Bt, long ldb, int K, int brow, int bcol, f32x4 (&acc)[2][2][4][2], char* smem, int tid) {
;     ...
;     STAGE(SB(0,1),Bt,ldb,bcol+HALF,t+2);
;     WAIT_V(6); BAR; MMA(1,1,At,B1); BAR;
;     LDB(B0,1,0); SCHED; LDA(At,1,0); STAGE(SA(0,1),A,lda,brow+HALF,t+2);
;     WAIT_L(8); BAR; WAIT_L(0); MMA(0,0,At,B0); BAR; SCHED;
;     LDB(B1,1,1); STAGE(SB(1,0),Bt,ldb,bcol,t+3);
;     BAR; WAIT_L(0); MMA(0,1,At,B1); BAR;
;     LDA(At,1,1); STAGE(SA(1,0),A,lda,brow,t+3);
	v_add_u32_e32 v169, s29, v157
	v_lshl_add_u64 v[170:171], v[248:249], 0, s[8:9]
	v_readfirstlane_b32 s27, v169
	s_mov_b32 m0, s27
	v_lshl_add_u64 v[180:181], v[250:251], 0, s[8:9]
	global_load_lds_dwordx4 v[170:171], off
	v_add_u32_e32 v170, 0x2000, v169
	s_nop 0
	v_readfirstlane_b32 s27, v170
	s_mov_b32 m0, s27
	s_nop 0
	global_load_lds_dwordx4 v[180:181], off
	s_waitcnt vmcnt(6)
	s_barrier
	v_mfma_f32_16x16x32_bf16 v[28:31], v[224:227], v[196:199], v[28:31]
	v_mfma_f32_16x16x32_bf16 v[24:27], v[232:235], v[196:199], v[24:27]
	v_mfma_f32_16x16x32_bf16 v[20:23], v[224:227], v[204:207], v[20:23]
	v_mfma_f32_16x16x32_bf16 v[16:19], v[232:235], v[204:207], v[16:19]
	v_mfma_f32_16x16x32_bf16 v[12:15], v[224:227], v[212:215], v[12:15]
	v_mfma_f32_16x16x32_bf16 v[8:11], v[232:235], v[212:215], v[8:11]
	v_mfma_f32_16x16x32_bf16 v[4:7], v[224:227], v[220:223], v[4:7]
	v_mfma_f32_16x16x32_bf16 v[0:3], v[232:235], v[220:223], v[0:3]
	v_mfma_f32_16x16x32_bf16 v[28:31], v[228:231], v[200:203], v[28:31]
	v_mfma_f32_16x16x32_bf16 v[24:27], v[236:239], v[200:203], v[24:27]
	v_mfma_f32_16x16x32_bf16 v[20:23], v[228:231], v[208:211], v[20:23]
	v_mfma_f32_16x16x32_bf16 v[16:19], v[236:239], v[208:211], v[16:19]
	v_mfma_f32_16x16x32_bf16 v[12:15], v[228:231], v[216:219], v[12:15]
	v_mfma_f32_16x16x32_bf16 v[8:11], v[236:239], v[216:219], v[8:11]
	v_mfma_f32_16x16x32_bf16 v[4:7], v[228:231], v[240:243], v[4:7]
	v_mfma_f32_16x16x32_bf16 v[0:3], v[236:239], v[240:243], v[0:3]
	s_barrier
	ds_read_b128 v[180:183], v158
	ds_read_b128 v[184:187], v158 offset:1024
	ds_read_b128 v[188:191], v158 offset:2048
	ds_read_b128 v[192:195], v158 offset:3072
	v_add_u32_e32 v171, 0x4000, v154
	v_add_u32_e32 v172, 0x6000, v154
	v_readfirstlane_b32 s27, v171
	v_lshl_add_u64 v[228:229], v[244:245], 0, s[10:11]
	s_mov_b32 m0, s27
	v_readfirstlane_b32 s27, v172
	ds_read_b128 v[196:199], v155 offset:32768
	ds_read_b128 v[200:203], v155 offset:33792
	ds_read_b128 v[204:207], v173 offset:32768
	ds_read_b128 v[208:211], v173 offset:33792
	ds_read_b128 v[212:215], v174 offset:32768
	ds_read_b128 v[216:219], v174 offset:33792
	ds_read_b128 v[220:223], v175 offset:32768
	ds_read_b128 v[224:227], v175 offset:33792
	global_load_lds_dwordx4 v[228:229], off
	v_lshl_add_u64 v[228:229], v[246:247], 0, s[10:11]
	s_mov_b32 m0, s27
	s_nop 0
	global_load_lds_dwordx4 v[228:229], off
	s_waitcnt lgkmcnt(8)
	s_barrier
	s_waitcnt lgkmcnt(0)
	v_mfma_f32_16x16x32_bf16 v[124:127], v[180:183], v[196:199], v[124:127]
	v_mfma_f32_16x16x32_bf16 v[120:123], v[188:191], v[196:199], v[120:123]
	v_mfma_f32_16x16x32_bf16 v[116:119], v[180:183], v[204:207], v[116:119]
	v_mfma_f32_16x16x32_bf16 v[112:115], v[188:191], v[204:207], v[112:115]
	v_mfma_f32_16x16x32_bf16 v[108:111], v[180:183], v[212:215], v[108:111]
	v_mfma_f32_16x16x32_bf16 v[104:107], v[188:191], v[212:215], v[104:107]
	v_mfma_f32_16x16x32_bf16 v[100:103], v[180:183], v[220:223], v[100:103]
	v_mfma_f32_16x16x32_bf16 v[96:99], v[188:191], v[220:223], v[96:99]
	v_mfma_f32_16x16x32_bf16 v[124:127], v[184:187], v[200:203], v[124:127]
	v_mfma_f32_16x16x32_bf16 v[120:123], v[192:195], v[200:203], v[120:123]
	v_mfma_f32_16x16x32_bf16 v[116:119], v[184:187], v[208:211], v[116:119]
	v_mfma_f32_16x16x32_bf16 v[112:115], v[192:195], v[208:211], v[112:115]
	v_mfma_f32_16x16x32_bf16 v[108:111], v[184:187], v[216:219], v[108:111]
	v_mfma_f32_16x16x32_bf16 v[104:107], v[192:195], v[216:219], v[104:107]
	v_mfma_f32_16x16x32_bf16 v[100:103], v[184:187], v[224:227], v[100:103]
	v_mfma_f32_16x16x32_bf16 v[96:99], v[192:195], v[224:227], v[96:99]
	s_barrier
	v_readfirstlane_b32 s27, v159
	v_add_u32_e32 v179, 0x2000, v159
	v_lshl_add_u64 v[252:253], v[248:249], 0, s[12:13]
	s_mov_b32 m0, s27
	v_readfirstlane_b32 s27, v179
	ds_read_b128 v[228:231], v156
	ds_read_b128 v[232:235], v156 offset:1024
	ds_read_b128 v[236:239], v156 offset:2048
	ds_read_b128 v[240:243], v156 offset:3072
	global_load_lds_dwordx4 v[252:253], off
	v_lshl_add_u64 v[252:253], v[250:251], 0, s[12:13]
	s_mov_b32 m0, s27
	s_nop 0
	global_load_lds_dwordx4 v[252:253], off
	s_barrier
	s_waitcnt lgkmcnt(0)
	v_mfma_f32_16x16x32_bf16 v[92:95], v[228:231], v[196:199], v[92:95]
	v_mfma_f32_16x16x32_bf16 v[88:91], v[236:239], v[196:199], v[88:91]
	v_mfma_f32_16x16x32_bf16 v[84:87], v[228:231], v[204:207], v[84:87]
	v_mfma_f32_16x16x32_bf16 v[80:83], v[236:239], v[204:207], v[80:83]
	v_mfma_f32_16x16x32_bf16 v[76:79], v[228:231], v[212:215], v[76:79]
	v_mfma_f32_16x16x32_bf16 v[72:75], v[236:239], v[212:215], v[72:75]
	v_mfma_f32_16x16x32_bf16 v[68:71], v[228:231], v[220:223], v[68:71]
	v_mfma_f32_16x16x32_bf16 v[64:67], v[236:239], v[220:223], v[64:67]
	v_mfma_f32_16x16x32_bf16 v[92:95], v[232:235], v[200:203], v[92:95]
	v_mfma_f32_16x16x32_bf16 v[88:91], v[240:243], v[200:203], v[88:91]
	v_mfma_f32_16x16x32_bf16 v[84:87], v[232:235], v[208:211], v[84:87]
	v_mfma_f32_16x16x32_bf16 v[80:83], v[240:243], v[208:211], v[80:83]
	v_mfma_f32_16x16x32_bf16 v[76:79], v[232:235], v[216:219], v[76:79]
	v_mfma_f32_16x16x32_bf16 v[72:75], v[240:243], v[216:219], v[72:75]
	v_mfma_f32_16x16x32_bf16 v[68:71], v[232:235], v[224:227], v[68:71]
	v_mfma_f32_16x16x32_bf16 v[64:67], v[240:243], v[224:227], v[64:67]
	v_readfirstlane_b32 s27, v160
	v_lshl_add_u64 v[244:245], v[244:245], 0, s[14:15]
	s_mov_b32 m0, s27
	v_readfirstlane_b32 s27, v162
	s_barrier
	ds_read_b128 v[196:199], v155 offset:49152
	ds_read_b128 v[200:203], v155 offset:50176
	ds_read_b128 v[204:207], v173 offset:49152
	ds_read_b128 v[208:211], v173 offset:50176
	ds_read_b128 v[212:215], v174 offset:49152
	ds_read_b128 v[216:219], v174 offset:50176
	ds_read_b128 v[220:223], v175 offset:49152
	ds_read_b128 v[224:227], v175 offset:50176
	global_load_lds_dwordx4 v[244:245], off
	v_lshl_add_u64 v[244:245], v[246:247], 0, s[14:15]
	s_mov_b32 m0, s27
	s_nop 0
	global_load_lds_dwordx4 v[244:245], off
	s_barrier
; #define STAGE(P,BASE,LD,br,kt) do{long _g=(long)(br)*(LD)+(long)(kt)*BK; \
;     _Pragma("unroll") for(int _i=0;_i<2;++_i){int _b=tid*16+_i*8192;int _r,_c;stage_rc(_b,_r,_c); \
;       __builtin_amdgcn_global_load_lds((const unsigned*)((BASE)+_g+(long)_r*(LD)+_c), \
;         (unsigned*)((char*)(P)+_b),16,0,0);}}while(0)
; #define STAGE(P,BASE,LD,br,kt) do{long _g=(long)(br)*(LD)+(long)(kt)*BK; \
;     _Pragma("unroll") for(int _i=0;_i<2;++_i){int _b=tid*16+_i*8192;int _r,_c;stage_rc(_b,_r,_c); \
;       __builtin_amdgcn_global_load_lds((const unsigned*)((BASE)+_g+(long)_r*(LD)+_c), \
;         (unsigned*)((char*)(P)+_b),16,0,0);}}while(0)
; #define LDA(dst,b,h) _Pragma("unroll") for(int m=0;m<4;++m) _Pragma("unroll") for(int k=0;k<2;++k) \
;     dst[m][k]=*reinterpret_cast<const bf16x8*>((char*)SA(b,h)+lds_byte(wr*64+m*16+fr,k*32+fq*8))
; #define LDB(dst,b,h) _Pragma("unroll") for(int n=0;n<2;++n) _Pragma("unroll") for(int k=0;k<2;++k) \
;     dst[n][k]=*reinterpret_cast<const bf16x8*>((char*)SB(b,h)+lds_byte(wc*32+n*16+fr,k*32+fq*8))
; #define MMA(ai,bj,At_,Bt_) do{__builtin_amdgcn_s_setprio(1); \
;     _Pragma("unroll") for(int m=0;m<4;++m) _Pragma("unroll") for(int n=0;n<2;++n) _Pragma("unroll") for(int k=0;k<2;++k) \
;       acc[ai][bj][m][n]=__builtin_amdgcn_mfma_f32_16x16x32_bf16(Bt_[n][k],At_[m][k],acc[ai][bj][m][n],0,0,0); \
;     __builtin_amdgcn_s_setprio(0);}while(0)
; #define WAIT_V(n) asm volatile("s_waitcnt vmcnt(" #n ")":::"memory")
; #define WAIT_L(n) asm volatile("s_waitcnt lgkmcnt(" #n ")":::"memory")
; #define BAR __builtin_amdgcn_s_barrier()
; #define SCHED __builtin_amdgcn_sched_barrier(0)
; DEVINL void gemm8_mainloop(const u16* A, long lda, const u16* Bt, long ldb, int K, int brow, int bcol, f32x4 (&acc)[2][2][4][2], char* smem, int tid) {
;     ...
;     BAR; WAIT_L(0); MMA(1,0,At,B0); BAR; SCHED;
;     STAGE(SB(1,1),Bt,ldb,bcol+HALF,t+3);
;     WAIT_V(6); BAR; MMA(1,1,At,B1); BAR;
;   }
;   { LDB(B0,0,0); LDA(At,0,0); STAGE(SA(1,1),A,lda,brow+HALF,nt-1);
;     BAR; WAIT_L(0); MMA(0,0,At,B0); BAR;
;     LDB(B1,0,1); BAR; WAIT_L(0); MMA(0,1,At,B1); BAR;
	s_waitcnt lgkmcnt(0)
	v_mfma_f32_16x16x32_bf16 v[60:63], v[180:183], v[196:199], v[60:63]
	v_mfma_f32_16x16x32_bf16 v[56:59], v[188:191], v[196:199], v[56:59]
	v_mfma_f32_16x16x32_bf16 v[52:55], v[180:183], v[204:207], v[52:55]
	v_mfma_f32_16x16x32_bf16 v[48:51], v[188:191], v[204:207], v[48:51]
	v_mfma_f32_16x16x32_bf16 v[44:47], v[180:183], v[212:215], v[44:47]
	v_mfma_f32_16x16x32_bf16 v[40:43], v[188:191], v[212:215], v[40:43]
	v_mfma_f32_16x16x32_bf16 v[36:39], v[180:183], v[220:223], v[36:39]
	v_mfma_f32_16x16x32_bf16 v[32:35], v[188:191], v[220:223], v[32:35]
	v_mfma_f32_16x16x32_bf16 v[60:63], v[184:187], v[200:203], v[60:63]
	v_mfma_f32_16x16x32_bf16 v[56:59], v[192:195], v[200:203], v[56:59]
	v_mfma_f32_16x16x32_bf16 v[52:55], v[184:187], v[208:211], v[52:55]
	v_mfma_f32_16x16x32_bf16 v[48:51], v[192:195], v[208:211], v[48:51]
	v_mfma_f32_16x16x32_bf16 v[44:47], v[184:187], v[216:219], v[44:47]
	v_mfma_f32_16x16x32_bf16 v[40:43], v[192:195], v[216:219], v[40:43]
	v_mfma_f32_16x16x32_bf16 v[36:39], v[184:187], v[224:227], v[36:39]
	v_mfma_f32_16x16x32_bf16 v[32:35], v[192:195], v[224:227], v[32:35]
	s_barrier
	v_readfirstlane_b32 s27, v163
	v_add_u32_e32 v179, 0x2000, v163
	v_lshl_add_u64 v[180:181], v[248:249], 0, s[16:17]
	s_mov_b32 m0, s27
	v_readfirstlane_b32 s27, v179
	global_load_lds_dwordx4 v[180:181], off
	v_lshl_add_u64 v[180:181], v[250:251], 0, s[16:17]
	s_mov_b32 m0, s27
	s_nop 0
	global_load_lds_dwordx4 v[180:181], off
	s_waitcnt vmcnt(6)
	s_barrier
	v_mfma_f32_16x16x32_bf16 v[28:31], v[228:231], v[196:199], v[28:31]
	v_mfma_f32_16x16x32_bf16 v[24:27], v[236:239], v[196:199], v[24:27]
	v_mfma_f32_16x16x32_bf16 v[20:23], v[228:231], v[204:207], v[20:23]
	v_mfma_f32_16x16x32_bf16 v[16:19], v[236:239], v[204:207], v[16:19]
	v_mfma_f32_16x16x32_bf16 v[12:15], v[228:231], v[212:215], v[12:15]
	v_mfma_f32_16x16x32_bf16 v[8:11], v[236:239], v[212:215], v[8:11]
	v_mfma_f32_16x16x32_bf16 v[4:7], v[228:231], v[220:223], v[4:7]
	v_mfma_f32_16x16x32_bf16 v[0:3], v[236:239], v[220:223], v[0:3]
	v_mfma_f32_16x16x32_bf16 v[28:31], v[232:235], v[200:203], v[28:31]
	v_mfma_f32_16x16x32_bf16 v[24:27], v[240:243], v[200:203], v[24:27]
	v_mfma_f32_16x16x32_bf16 v[20:23], v[232:235], v[208:211], v[20:23]
	v_mfma_f32_16x16x32_bf16 v[16:19], v[240:243], v[208:211], v[16:19]
	v_mfma_f32_16x16x32_bf16 v[12:15], v[232:235], v[216:219], v[12:15]
	v_mfma_f32_16x16x32_bf16 v[8:11], v[240:243], v[216:219], v[8:11]
	v_mfma_f32_16x16x32_bf16 v[4:7], v[232:235], v[224:227], v[4:7]
	v_mfma_f32_16x16x32_bf16 v[0:3], v[240:243], v[224:227], v[0:3]
	s_add_i32 s26, s26, 2
	v_lshl_add_u64 v[142:143], v[142:143], 0, s[18:19]
	v_lshl_add_u64 v[144:145], v[144:145], 0, s[18:19]
	v_lshl_add_u64 v[146:147], v[146:147], 0, s[18:19]
	s_cmp_lt_u32 s26, 28
	v_lshl_add_u64 v[148:149], v[148:149], 0, s[18:19]
	s_barrier
	s_cbranch_scc1 .LBB0_1938
	s_or_b32 s26, s22, 0x80
	s_ashr_i32 s27, s26, 31
	s_lshl_b64 s[26:27], s[26:27], 12
	s_add_u32 s26, s90, s26
	s_addc_u32 s27, s91, s27
	v_lshl_add_u64 v[216:217], v[134:135], 1, s[26:27]
	v_lshl_add_u64 v[138:139], v[138:139], 1, v[216:217]
	v_readfirstlane_b32 s23, v177
	v_lshl_add_u64 v[138:139], v[138:139], 0, s[20:21]
	s_mov_b32 m0, s23
	ds_read_b128 v[142:145], v165
	ds_read_b128 v[146:149], v165 offset:1024
	ds_read_b128 v[180:183], v165 offset:2048
	ds_read_b128 v[162:165], v165 offset:3072
	ds_read_b128 v[184:187], v155
	ds_read_b128 v[188:191], v155 offset:1024
	ds_read_b128 v[192:195], v173
	ds_read_b128 v[196:199], v173 offset:1024
	ds_read_b128 v[200:203], v174
	ds_read_b128 v[204:207], v174 offset:1024
	ds_read_b128 v[208:211], v175
	ds_read_b128 v[212:215], v175 offset:1024
	global_load_lds_dwordx4 v[138:139], off
	v_lshl_add_u64 v[138:139], v[136:137], 1, s[26:27]
	v_lshl_add_u64 v[138:139], v[140:141], 1, v[138:139]
	v_readfirstlane_b32 s23, v178
	v_lshl_add_u64 v[138:139], v[138:139], 0, s[20:21]
	s_mov_b32 m0, s23
	s_nop 0
	global_load_lds_dwordx4 v[138:139], off
	s_barrier
	s_waitcnt lgkmcnt(0)
	v_mfma_f32_16x16x32_bf16 v[124:127], v[142:145], v[184:187], v[124:127]
	v_mfma_f32_16x16x32_bf16 v[120:123], v[180:183], v[184:187], v[120:123]
	v_mfma_f32_16x16x32_bf16 v[116:119], v[142:145], v[192:195], v[116:119]
	v_mfma_f32_16x16x32_bf16 v[112:115], v[180:183], v[192:195], v[112:115]
	v_mfma_f32_16x16x32_bf16 v[104:107], v[180:183], v[200:203], v[104:107]
	v_mfma_f32_16x16x32_bf16 v[96:99], v[180:183], v[208:211], v[96:99]
	v_mfma_f32_16x16x32_bf16 v[124:127], v[146:149], v[188:191], v[124:127]
	v_mfma_f32_16x16x32_bf16 v[120:123], v[162:165], v[188:191], v[120:123]
	v_mfma_f32_16x16x32_bf16 v[116:119], v[146:149], v[196:199], v[116:119]
	v_mfma_f32_16x16x32_bf16 v[112:115], v[162:165], v[196:199], v[112:115]
	v_mfma_f32_16x16x32_bf16 v[108:111], v[142:145], v[200:203], v[108:111]
	v_mfma_f32_16x16x32_bf16 v[104:107], v[162:165], v[204:207], v[104:107]
	v_mfma_f32_16x16x32_bf16 v[100:103], v[142:145], v[208:211], v[100:103]
	v_mfma_f32_16x16x32_bf16 v[96:99], v[162:165], v[212:215], v[96:99]
	v_mfma_f32_16x16x32_bf16 v[138:141], v[146:149], v[204:207], v[108:111]
	v_mfma_f32_16x16x32_bf16 v[216:219], v[146:149], v[212:215], v[100:103]
	s_barrier
	s_nop 2
	s_nop 0
	ds_read_b128 v[100:103], v161
	ds_read_b128 v[108:111], v161 offset:1024
	ds_read_b128 v[220:223], v161 offset:2048
	ds_read_b128 v[224:227], v161 offset:3072
	s_barrier
; #define LDA(dst,b,h) _Pragma("unroll") for(int m=0;m<4;++m) _Pragma("unroll") for(int k=0;k<2;++k) \
;     dst[m][k]=*reinterpret_cast<const bf16x8*>((char*)SA(b,h)+lds_byte(wr*64+m*16+fr,k*32+fq*8))
; #define LDB(dst,b,h) _Pragma("unroll") for(int n=0;n<2;++n) _Pragma("unroll") for(int k=0;k<2;++k) \
;     dst[n][k]=*reinterpret_cast<const bf16x8*>((char*)SB(b,h)+lds_byte(wc*32+n*16+fr,k*32+fq*8))
; #define MMA(ai,bj,At_,Bt_) do{__builtin_amdgcn_s_setprio(1); \
;     _Pragma("unroll") for(int m=0;m<4;++m) _Pragma("unroll") for(int n=0;n<2;++n) _Pragma("unroll") for(int k=0;k<2;++k) \
;       acc[ai][bj][m][n]=__builtin_amdgcn_mfma_f32_16x16x32_bf16(Bt_[n][k],At_[m][k],acc[ai][bj][m][n],0,0,0); \
;     __builtin_amdgcn_s_setprio(0);}while(0)
; #define WAIT_V(n) asm volatile("s_waitcnt vmcnt(" #n ")":::"memory")
; #define WAIT_L(n) asm volatile("s_waitcnt lgkmcnt(" #n ")":::"memory")
; #define BAR __builtin_amdgcn_s_barrier()
; DEVINL void gemm8_mainloop(const u16* A, long lda, const u16* Bt, long ldb, int K, int brow, int bcol, f32x4 (&acc)[2][2][4][2], char* smem, int tid) {
;     ...
;     LDB(B1,0,1); BAR; WAIT_L(0); MMA(0,1,At,B1); BAR;
;     LDA(At,0,1); WAIT_V(4); BAR; WAIT_L(0); MMA(1,0,At,B0); MMA(1,1,At,B1); BAR; }
;   { LDB(B0,1,0); LDA(At,1,0); WAIT_V(2); BAR; WAIT_L(0); MMA(0,0,At,B0); BAR;
	s_waitcnt lgkmcnt(0)
	v_mfma_f32_16x16x32_bf16 v[88:91], v[220:223], v[184:187], v[88:91]
	v_mfma_f32_16x16x32_bf16 v[80:83], v[220:223], v[192:195], v[80:83]
	v_mfma_f32_16x16x32_bf16 v[72:75], v[220:223], v[200:203], v[72:75]
	v_mfma_f32_16x16x32_bf16 v[64:67], v[220:223], v[208:211], v[64:67]
	v_mfma_f32_16x16x32_bf16 v[92:95], v[100:103], v[184:187], v[92:95]
	v_mfma_f32_16x16x32_bf16 v[88:91], v[224:227], v[188:191], v[88:91]
	v_mfma_f32_16x16x32_bf16 v[84:87], v[100:103], v[192:195], v[84:87]
	v_mfma_f32_16x16x32_bf16 v[80:83], v[224:227], v[196:199], v[80:83]
	v_mfma_f32_16x16x32_bf16 v[76:79], v[100:103], v[200:203], v[76:79]
	v_mfma_f32_16x16x32_bf16 v[72:75], v[224:227], v[204:207], v[72:75]
	v_mfma_f32_16x16x32_bf16 v[68:71], v[100:103], v[208:211], v[68:71]
	v_mfma_f32_16x16x32_bf16 v[64:67], v[224:227], v[212:215], v[64:67]
	v_mfma_f32_16x16x32_bf16 v[228:231], v[108:111], v[188:191], v[92:95]
	v_mfma_f32_16x16x32_bf16 v[184:187], v[108:111], v[196:199], v[84:87]
	v_mfma_f32_16x16x32_bf16 v[188:191], v[108:111], v[204:207], v[76:79]
	v_mfma_f32_16x16x32_bf16 v[192:195], v[108:111], v[212:215], v[68:71]
	s_barrier
	s_nop 0
	s_nop 0
	ds_read_b128 v[68:71], v155 offset:16384
	ds_read_b128 v[76:79], v155 offset:17408
	ds_read_b128 v[84:87], v173 offset:16384
	ds_read_b128 v[92:95], v173 offset:17408
	ds_read_b128 v[196:199], v174 offset:16384
	ds_read_b128 v[200:203], v174 offset:17408
	ds_read_b128 v[204:207], v175 offset:16384
	ds_read_b128 v[208:211], v175 offset:17408
	s_waitcnt vmcnt(4)
	s_barrier
	s_waitcnt lgkmcnt(0)
	v_mfma_f32_16x16x32_bf16 v[60:63], v[142:145], v[68:71], v[60:63]
	v_mfma_f32_16x16x32_bf16 v[56:59], v[180:183], v[68:71], v[56:59]
	v_mfma_f32_16x16x32_bf16 v[48:51], v[180:183], v[84:87], v[48:51]
	v_mfma_f32_16x16x32_bf16 v[40:43], v[180:183], v[196:199], v[40:43]
	v_mfma_f32_16x16x32_bf16 v[32:35], v[180:183], v[204:207], v[32:35]
	v_mfma_f32_16x16x32_bf16 v[60:63], v[146:149], v[76:79], v[60:63]
	v_mfma_f32_16x16x32_bf16 v[56:59], v[162:165], v[76:79], v[56:59]
	v_mfma_f32_16x16x32_bf16 v[52:55], v[142:145], v[84:87], v[52:55]
	v_mfma_f32_16x16x32_bf16 v[48:51], v[162:165], v[92:95], v[48:51]
	v_mfma_f32_16x16x32_bf16 v[44:47], v[142:145], v[196:199], v[44:47]
	v_mfma_f32_16x16x32_bf16 v[40:43], v[162:165], v[200:203], v[40:43]
	v_mfma_f32_16x16x32_bf16 v[36:39], v[142:145], v[204:207], v[36:39]
	v_mfma_f32_16x16x32_bf16 v[32:35], v[162:165], v[208:211], v[32:35]
	v_mfma_f32_16x16x32_bf16 v[212:215], v[146:149], v[92:95], v[52:55]
	v_mfma_f32_16x16x32_bf16 v[232:235], v[146:149], v[200:203], v[44:47]
	v_mfma_f32_16x16x32_bf16 v[142:145], v[146:149], v[208:211], v[36:39]
	v_mfma_f32_16x16x32_bf16 v[24:27], v[220:223], v[68:71], v[24:27]
	v_mfma_f32_16x16x32_bf16 v[16:19], v[220:223], v[84:87], v[16:19]
	v_mfma_f32_16x16x32_bf16 v[4:7], v[100:103], v[204:207], v[4:7]
	v_mfma_f32_16x16x32_bf16 v[0:3], v[220:223], v[204:207], v[0:3]
	v_mfma_f32_16x16x32_bf16 v[28:31], v[100:103], v[68:71], v[28:31]
	v_mfma_f32_16x16x32_bf16 v[24:27], v[224:227], v[76:79], v[24:27]
	v_mfma_f32_16x16x32_bf16 v[20:23], v[100:103], v[84:87], v[20:23]
	v_mfma_f32_16x16x32_bf16 v[16:19], v[224:227], v[92:95], v[16:19]
	v_mfma_f32_16x16x32_bf16 v[12:15], v[100:103], v[196:199], v[12:15]
	v_mfma_f32_16x16x32_bf16 v[8:11], v[220:223], v[196:199], v[8:11]
	v_mfma_f32_16x16x32_bf16 v[4:7], v[108:111], v[208:211], v[4:7]
	v_mfma_f32_16x16x32_bf16 v[0:3], v[224:227], v[208:211], v[0:3]
	v_mfma_f32_16x16x32_bf16 v[146:149], v[108:111], v[76:79], v[28:31]
	v_mfma_f32_16x16x32_bf16 v[160:163], v[108:111], v[92:95], v[20:23]
	v_mfma_f32_16x16x32_bf16 v[178:181], v[108:111], v[200:203], v[12:15]
	v_mfma_f32_16x16x32_bf16 v[196:199], v[224:227], v[200:203], v[8:11]
	s_barrier
	s_nop 0
	s_nop 0
	ds_read_b128 v[8:11], v158
	ds_read_b128 v[12:15], v158 offset:1024
	ds_read_b128 v[200:203], v158 offset:2048
	ds_read_b128 v[204:207], v158 offset:3072
	ds_read_b128 v[20:23], v155 offset:32768
	ds_read_b128 v[28:31], v155 offset:33792
	ds_read_b128 v[36:39], v173 offset:32768
	ds_read_b128 v[44:47], v173 offset:33792
	ds_read_b128 v[52:55], v174 offset:32768
	ds_read_b128 v[208:211], v174 offset:33792
	ds_read_b128 v[220:223], v175 offset:32768
	ds_read_b128 v[224:227], v175 offset:33792
	s_waitcnt vmcnt(2)
	s_barrier
; #define LDA(dst,b,h) _Pragma("unroll") for(int m=0;m<4;++m) _Pragma("unroll") for(int k=0;k<2;++k) \
;     dst[m][k]=*reinterpret_cast<const bf16x8*>((char*)SA(b,h)+lds_byte(wr*64+m*16+fr,k*32+fq*8))
; #define LDB(dst,b,h) _Pragma("unroll") for(int n=0;n<2;++n) _Pragma("unroll") for(int k=0;k<2;++k) \
;     dst[n][k]=*reinterpret_cast<const bf16x8*>((char*)SB(b,h)+lds_byte(wc*32+n*16+fr,k*32+fq*8))
; #define MMA(ai,bj,At_,Bt_) do{__builtin_amdgcn_s_setprio(1); \
;     _Pragma("unroll") for(int m=0;m<4;++m) _Pragma("unroll") for(int n=0;n<2;++n) _Pragma("unroll") for(int k=0;k<2;++k) \
;       acc[ai][bj][m][n]=__builtin_amdgcn_mfma_f32_16x16x32_bf16(Bt_[n][k],At_[m][k],acc[ai][bj][m][n],0,0,0); \
;     __builtin_amdgcn_s_setprio(0);}while(0)
; #define WAIT_V(n) asm volatile("s_waitcnt vmcnt(" #n ")":::"memory")
; #define WAIT_L(n) asm volatile("s_waitcnt lgkmcnt(" #n ")":::"memory")
; #define BAR __builtin_amdgcn_s_barrier()
; DEVINL void gemm8_mainloop(const u16* A, long lda, const u16* Bt, long ldb, int K, int brow, int bcol, f32x4 (&acc)[2][2][4][2], char* smem, int tid) {
;     ...
;   { LDB(B0,1,0); LDA(At,1,0); WAIT_V(2); BAR; WAIT_L(0); MMA(0,0,At,B0); BAR;
;     LDB(B1,1,1); WAIT_V(0); BAR; WAIT_L(0); MMA(0,1,At,B1); BAR;
;     LDA(At,1,1); BAR; WAIT_L(0); MMA(1,0,At,B0); MMA(1,1,At,B1); BAR; }
;   if(wr==0)BAR;
;   __syncthreads();
	s_waitcnt lgkmcnt(0)
	v_mfma_f32_16x16x32_bf16 v[68:71], v[8:11], v[20:23], v[124:127]
	v_mfma_f32_16x16x32_bf16 v[124:127], v[12:15], v[28:31], v[68:71]
	v_mfma_f32_16x16x32_bf16 v[68:71], v[200:203], v[20:23], v[120:123]
	v_mfma_f32_16x16x32_bf16 v[120:123], v[204:207], v[28:31], v[68:71]
	v_mfma_f32_16x16x32_bf16 v[68:71], v[8:11], v[36:39], v[116:119]
	v_mfma_f32_16x16x32_bf16 v[108:111], v[12:15], v[44:47], v[68:71]
	v_mfma_f32_16x16x32_bf16 v[68:71], v[200:203], v[36:39], v[112:115]
	v_mfma_f32_16x16x32_bf16 v[100:103], v[204:207], v[44:47], v[68:71]
	v_mfma_f32_16x16x32_bf16 v[68:71], v[8:11], v[52:55], v[138:141]
	v_mfma_f32_16x16x32_bf16 v[92:95], v[12:15], v[208:211], v[68:71]
	v_mfma_f32_16x16x32_bf16 v[68:71], v[200:203], v[52:55], v[104:107]
	v_mfma_f32_16x16x32_bf16 v[84:87], v[204:207], v[208:211], v[68:71]
	v_mfma_f32_16x16x32_bf16 v[68:71], v[8:11], v[220:223], v[216:219]
	v_mfma_f32_16x16x32_bf16 v[76:79], v[12:15], v[224:227], v[68:71]
	v_mfma_f32_16x16x32_bf16 v[68:71], v[200:203], v[220:223], v[96:99]
	v_mfma_f32_16x16x32_bf16 v[68:71], v[204:207], v[224:227], v[68:71]
	s_barrier
	ds_read_b128 v[138:141], v156
	ds_read_b128 v[216:219], v156 offset:1024
	ds_read_b128 v[236:239], v156 offset:2048
	ds_read_b128 v[156:159], v156 offset:3072
	s_waitcnt vmcnt(0)
	s_barrier
	s_waitcnt lgkmcnt(0)
	v_mfma_f32_16x16x32_bf16 v[96:99], v[138:141], v[20:23], v[228:231]
	v_mfma_f32_16x16x32_bf16 v[20:23], v[236:239], v[20:23], v[88:91]
	v_mfma_f32_16x16x32_bf16 v[112:115], v[156:159], v[28:31], v[20:23]
	v_mfma_f32_16x16x32_bf16 v[20:23], v[138:141], v[36:39], v[184:187]
	v_mfma_f32_16x16x32_bf16 v[104:107], v[216:219], v[44:47], v[20:23]
	v_mfma_f32_16x16x32_bf16 v[20:23], v[236:239], v[36:39], v[80:83]
	v_mfma_f32_16x16x32_bf16 v[116:119], v[216:219], v[28:31], v[96:99]
	v_mfma_f32_16x16x32_bf16 v[96:99], v[156:159], v[44:47], v[20:23]
	v_mfma_f32_16x16x32_bf16 v[20:23], v[138:141], v[52:55], v[188:191]
	v_mfma_f32_16x16x32_bf16 v[88:91], v[216:219], v[208:211], v[20:23]
	v_mfma_f32_16x16x32_bf16 v[20:23], v[236:239], v[52:55], v[72:75]
	v_mfma_f32_16x16x32_bf16 v[80:83], v[156:159], v[208:211], v[20:23]
	v_mfma_f32_16x16x32_bf16 v[20:23], v[138:141], v[220:223], v[192:195]
	v_mfma_f32_16x16x32_bf16 v[72:75], v[216:219], v[224:227], v[20:23]
	v_mfma_f32_16x16x32_bf16 v[20:23], v[236:239], v[220:223], v[64:67]
	v_mfma_f32_16x16x32_bf16 v[64:67], v[156:159], v[224:227], v[20:23]
	s_barrier
	ds_read_b128 v[182:185], v155 offset:49152
	ds_read_b128 v[186:189], v155 offset:50176
	ds_read_b128 v[190:193], v173 offset:49152
	ds_read_b128 v[208:211], v173 offset:50176
	ds_read_b128 v[220:223], v174 offset:49152
	ds_read_b128 v[224:227], v174 offset:50176
	ds_read_b128 v[228:231], v175 offset:49152
	ds_read_b128 v[240:243], v175 offset:50176
	s_barrier
	s_waitcnt lgkmcnt(0)
	v_mfma_f32_16x16x32_bf16 v[20:23], v[8:11], v[182:185], v[60:63]
	v_mfma_f32_16x16x32_bf16 v[60:63], v[12:15], v[186:189], v[20:23]
	v_mfma_f32_16x16x32_bf16 v[20:23], v[200:203], v[182:185], v[56:59]
	v_mfma_f32_16x16x32_bf16 v[52:55], v[204:207], v[186:189], v[20:23]
	v_mfma_f32_16x16x32_bf16 v[20:23], v[8:11], v[190:193], v[212:215]
	v_mfma_f32_16x16x32_bf16 v[44:47], v[12:15], v[208:211], v[20:23]
	v_mfma_f32_16x16x32_bf16 v[20:23], v[200:203], v[190:193], v[48:51]
	v_mfma_f32_16x16x32_bf16 v[36:39], v[204:207], v[208:211], v[20:23]
	v_mfma_f32_16x16x32_bf16 v[20:23], v[8:11], v[220:223], v[232:235]
	v_mfma_f32_16x16x32_bf16 v[8:11], v[8:11], v[228:231], v[142:145]
	v_mfma_f32_16x16x32_bf16 v[28:31], v[12:15], v[224:227], v[20:23]
	v_mfma_f32_16x16x32_bf16 v[20:23], v[200:203], v[220:223], v[40:43]
	v_mfma_f32_16x16x32_bf16 v[12:15], v[12:15], v[240:243], v[8:11]
	v_mfma_f32_16x16x32_bf16 v[8:11], v[200:203], v[228:231], v[32:35]
	v_mfma_f32_16x16x32_bf16 v[20:23], v[204:207], v[224:227], v[20:23]
	v_mfma_f32_16x16x32_bf16 v[8:11], v[204:207], v[240:243], v[8:11]
	v_mfma_f32_16x16x32_bf16 v[32:35], v[138:141], v[182:185], v[146:149]
	v_mfma_f32_16x16x32_bf16 v[24:27], v[236:239], v[182:185], v[24:27]
	v_mfma_f32_16x16x32_bf16 v[16:19], v[236:239], v[190:193], v[16:19]
	v_mfma_f32_16x16x32_bf16 v[56:59], v[216:219], v[186:189], v[32:35]
	v_mfma_f32_16x16x32_bf16 v[48:51], v[156:159], v[186:189], v[24:27]
	v_mfma_f32_16x16x32_bf16 v[24:27], v[138:141], v[190:193], v[160:163]
	v_mfma_f32_16x16x32_bf16 v[32:35], v[156:159], v[208:211], v[16:19]
	v_mfma_f32_16x16x32_bf16 v[16:19], v[138:141], v[220:223], v[178:181]
	v_mfma_f32_16x16x32_bf16 v[40:43], v[216:219], v[208:211], v[24:27]
	v_mfma_f32_16x16x32_bf16 v[24:27], v[216:219], v[224:227], v[16:19]
	v_mfma_f32_16x16x32_bf16 v[16:19], v[236:239], v[220:223], v[196:199]
	v_mfma_f32_16x16x32_bf16 v[4:7], v[138:141], v[228:231], v[4:7]
	v_mfma_f32_16x16x32_bf16 v[0:3], v[236:239], v[228:231], v[0:3]
	v_mfma_f32_16x16x32_bf16 v[16:19], v[156:159], v[224:227], v[16:19]
	v_mfma_f32_16x16x32_bf16 v[4:7], v[216:219], v[240:243], v[4:7]
	v_mfma_f32_16x16x32_bf16 v[0:3], v[156:159], v[240:243], v[0:3]
	s_setprio 0
	s_cmpk_gt_u32 s37, 0xff
	s_barrier
	s_cbranch_scc1 .LBB0_1941
	s_barrier

; #define STAGE(P,BASE,LD,br,kt) do{long _g=(long)(br)*(LD)+(long)(kt)*BK; \
;     _Pragma("unroll") for(int _i=0;_i<2;++_i){int _b=tid*16+_i*8192;int _r,_c;stage_rc(_b,_r,_c); \
;       __builtin_amdgcn_global_load_lds((const unsigned*)((BASE)+_g+(long)_r*(LD)+_c), \
;         (unsigned*)((char*)(P)+_b),16,0,0);}}while(0)
; #define STAGE(P,BASE,LD,br,kt) do{long _g=(long)(br)*(LD)+(long)(kt)*BK; \
;     _Pragma("unroll") for(int _i=0;_i<2;++_i){int _b=tid*16+_i*8192;int _r,_c;stage_rc(_b,_r,_c); \
;       __builtin_amdgcn_global_load_lds((const unsigned*)((BASE)+_g+(long)_r*(LD)+_c), \
;         (unsigned*)((char*)(P)+_b),16,0,0);}}while(0)
; #define LDA(dst,b,h) _Pragma("unroll") for(int m=0;m<4;++m) _Pragma("unroll") for(int k=0;k<2;++k) \
;     dst[m][k]=*reinterpret_cast<const bf16x8*>((char*)SA(b,h)+lds_byte(wr*64+m*16+fr,k*32+fq*8))
; #define LDB(dst,b,h) _Pragma("unroll") for(int n=0;n<2;++n) _Pragma("unroll") for(int k=0;k<2;++k) \
;     dst[n][k]=*reinterpret_cast<const bf16x8*>((char*)SB(b,h)+lds_byte(wc*32+n*16+fr,k*32+fq*8))
; #define MMA(ai,bj,At_,Bt_) do{__builtin_amdgcn_s_setprio(1); \
;     _Pragma("unroll") for(int m=0;m<4;++m) _Pragma("unroll") for(int n=0;n<2;++n) _Pragma("unroll") for(int k=0;k<2;++k) \
;       acc[ai][bj][m][n]=__builtin_amdgcn_mfma_f32_16x16x32_bf16(Bt_[n][k],At_[m][k],acc[ai][bj][m][n],0,0,0); \
;     __builtin_amdgcn_s_setprio(0);}while(0)
; #define WAIT_L(n) asm volatile("s_waitcnt lgkmcnt(" #n ")":::"memory")
; #define BAR __builtin_amdgcn_s_barrier()
; #define SCHED __builtin_amdgcn_sched_barrier(0)
; DEVINL void gemm8_mainloop(const u16* A, long lda, const u16* Bt, long ldb, int K, int brow, int bcol, f32x4 (&acc)[2][2][4][2], char* smem, int tid) {
;     ...
;     LDB(B0,0,0); SCHED; LDA(At,0,0); STAGE(SA(1,1),A,lda,brow+HALF,t+1);
;     WAIT_L(8); BAR; WAIT_L(0); MMA(0,0,At,B0); BAR; SCHED;
;     LDB(B1,0,1); STAGE(SB(0,0),Bt,ldb,bcol,t+2);
;     BAR; WAIT_L(0); MMA(0,1,At,B1); BAR;
;     LDA(At,0,1); STAGE(SA(0,0),A,lda,brow,t+2);
;     BAR; WAIT_L(0); MMA(1,0,At,B0); BAR; SCHED;
.LBB0_1987:
	ds_read_b128 v[178:181], v163
	ds_read_b128 v[182:185], v163 offset:1024
	ds_read_b128 v[186:189], v163 offset:2048
	ds_read_b128 v[190:193], v163 offset:3072
	v_add_u32_e32 v174, 0xc000, v152
	v_lshl_add_u64 v[242:243], s[94:95], 0, v[146:147]
	v_readfirstlane_b32 s25, v174
	v_add_u32_e32 v175, 0xe000, v152
	v_add_u32_e32 v171, s23, v162
	v_add_u32_e32 v172, s34, v162
	v_add_u32_e32 v173, s35, v162
	v_lshl_add_u64 v[164:165], v[242:243], 0, s[2:3]
	s_mov_b32 m0, s25
	v_lshl_add_u64 v[244:245], s[94:95], 0, v[148:149]
	v_readfirstlane_b32 s25, v175
	ds_read_b128 v[166:169], v153
	ds_read_b128 v[194:197], v153 offset:1024
	ds_read_b128 v[198:201], v171
	ds_read_b128 v[202:205], v171 offset:1024
	ds_read_b128 v[206:209], v172
	ds_read_b128 v[210:213], v172 offset:1024
	ds_read_b128 v[214:217], v173
	ds_read_b128 v[218:221], v173 offset:1024
	global_load_lds_dwordx4 v[164:165], off
	v_lshl_add_u64 v[164:165], v[244:245], 0, s[2:3]
	s_mov_b32 m0, s25
	s_nop 0
	global_load_lds_dwordx4 v[164:165], off
	s_waitcnt lgkmcnt(8)
	s_barrier
	s_waitcnt lgkmcnt(0)
	v_mfma_f32_16x16x32_bf16 v[124:127], v[178:181], v[166:169], v[124:127]
	v_mfma_f32_16x16x32_bf16 v[120:123], v[186:189], v[166:169], v[120:123]
	v_mfma_f32_16x16x32_bf16 v[116:119], v[178:181], v[198:201], v[116:119]
	v_mfma_f32_16x16x32_bf16 v[112:115], v[186:189], v[198:201], v[112:115]
	v_mfma_f32_16x16x32_bf16 v[108:111], v[178:181], v[206:209], v[108:111]
	v_mfma_f32_16x16x32_bf16 v[104:107], v[186:189], v[206:209], v[104:107]
	v_mfma_f32_16x16x32_bf16 v[100:103], v[178:181], v[214:217], v[100:103]
	v_mfma_f32_16x16x32_bf16 v[96:99], v[186:189], v[214:217], v[96:99]
	v_mfma_f32_16x16x32_bf16 v[124:127], v[182:185], v[194:197], v[124:127]
	v_mfma_f32_16x16x32_bf16 v[120:123], v[190:193], v[194:197], v[120:123]
	v_mfma_f32_16x16x32_bf16 v[116:119], v[182:185], v[202:205], v[116:119]
	v_mfma_f32_16x16x32_bf16 v[112:115], v[190:193], v[202:205], v[112:115]
	v_mfma_f32_16x16x32_bf16 v[108:111], v[182:185], v[210:213], v[108:111]
	v_mfma_f32_16x16x32_bf16 v[104:107], v[190:193], v[210:213], v[104:107]
	v_mfma_f32_16x16x32_bf16 v[100:103], v[182:185], v[218:221], v[100:103]
	v_mfma_f32_16x16x32_bf16 v[96:99], v[190:193], v[218:221], v[96:99]
	s_barrier
	v_add_u32_e32 v164, s28, v154
	v_lshl_add_u64 v[246:247], s[94:95], 0, v[142:143]
	v_readfirstlane_b32 s25, v164
	v_add_u32_e32 v165, 0x2000, v164
	v_lshl_add_u64 v[238:239], v[246:247], 0, s[4:5]
	s_mov_b32 m0, s25
	v_lshl_add_u64 v[248:249], s[94:95], 0, v[144:145]
	v_readfirstlane_b32 s25, v165
	ds_read_b128 v[222:225], v160
	ds_read_b128 v[226:229], v160 offset:1024
	ds_read_b128 v[230:233], v160 offset:2048
	ds_read_b128 v[234:237], v160 offset:3072
	global_load_lds_dwordx4 v[238:239], off
	v_lshl_add_u64 v[238:239], v[248:249], 0, s[4:5]
	s_mov_b32 m0, s25
	s_nop 0
	global_load_lds_dwordx4 v[238:239], off
	s_barrier
	s_waitcnt lgkmcnt(0)
	v_mfma_f32_16x16x32_bf16 v[92:95], v[222:225], v[166:169], v[92:95]
	v_mfma_f32_16x16x32_bf16 v[88:91], v[230:233], v[166:169], v[88:91]
	v_mfma_f32_16x16x32_bf16 v[84:87], v[222:225], v[198:201], v[84:87]
	v_mfma_f32_16x16x32_bf16 v[80:83], v[230:233], v[198:201], v[80:83]
	v_mfma_f32_16x16x32_bf16 v[76:79], v[222:225], v[206:209], v[76:79]
	v_mfma_f32_16x16x32_bf16 v[72:75], v[230:233], v[206:209], v[72:75]
	v_mfma_f32_16x16x32_bf16 v[68:71], v[222:225], v[214:217], v[68:71]
	v_mfma_f32_16x16x32_bf16 v[64:67], v[230:233], v[214:217], v[64:67]
	v_mfma_f32_16x16x32_bf16 v[92:95], v[226:229], v[194:197], v[92:95]
	v_mfma_f32_16x16x32_bf16 v[88:91], v[234:237], v[194:197], v[88:91]
	v_mfma_f32_16x16x32_bf16 v[84:87], v[226:229], v[202:205], v[84:87]
	v_mfma_f32_16x16x32_bf16 v[80:83], v[234:237], v[202:205], v[80:83]
	v_mfma_f32_16x16x32_bf16 v[76:79], v[226:229], v[210:213], v[76:79]
	v_mfma_f32_16x16x32_bf16 v[72:75], v[234:237], v[210:213], v[72:75]
	v_mfma_f32_16x16x32_bf16 v[68:71], v[226:229], v[218:221], v[68:71]
	v_mfma_f32_16x16x32_bf16 v[64:67], v[234:237], v[218:221], v[64:67]
	v_readfirstlane_b32 s25, v152
	v_lshl_add_u64 v[166:167], v[242:243], 0, s[6:7]
	s_mov_b32 m0, s25
	s_barrier
	ds_read_b128 v[194:197], v153 offset:16384
	ds_read_b128 v[198:201], v153 offset:17408
	ds_read_b128 v[202:205], v171 offset:16384
	ds_read_b128 v[206:209], v171 offset:17408
	ds_read_b128 v[210:213], v172 offset:16384
	ds_read_b128 v[214:217], v172 offset:17408
	ds_read_b128 v[218:221], v173 offset:16384
	ds_read_b128 v[238:241], v173 offset:17408
	global_load_lds_dwordx4 v[166:167], off
	v_add_u32_e32 v166, 0x2000, v152
	v_lshl_add_u64 v[168:169], v[244:245], 0, s[6:7]
	v_readfirstlane_b32 s25, v166
	s_mov_b32 m0, s25
	s_nop 0
	global_load_lds_dwordx4 v[168:169], off
	s_barrier
	s_waitcnt lgkmcnt(0)
	v_mfma_f32_16x16x32_bf16 v[60:63], v[178:181], v[194:197], v[60:63]
	v_mfma_f32_16x16x32_bf16 v[56:59], v[186:189], v[194:197], v[56:59]
	v_mfma_f32_16x16x32_bf16 v[52:55], v[178:181], v[202:205], v[52:55]
	v_mfma_f32_16x16x32_bf16 v[48:51], v[186:189], v[202:205], v[48:51]
	v_mfma_f32_16x16x32_bf16 v[44:47], v[178:181], v[210:213], v[44:47]
	v_mfma_f32_16x16x32_bf16 v[40:43], v[186:189], v[210:213], v[40:43]
	v_mfma_f32_16x16x32_bf16 v[36:39], v[178:181], v[218:221], v[36:39]
	v_mfma_f32_16x16x32_bf16 v[32:35], v[186:189], v[218:221], v[32:35]
	v_mfma_f32_16x16x32_bf16 v[60:63], v[182:185], v[198:201], v[60:63]
	v_mfma_f32_16x16x32_bf16 v[56:59], v[190:193], v[198:201], v[56:59]
	v_mfma_f32_16x16x32_bf16 v[52:55], v[182:185], v[206:209], v[52:55]
	v_mfma_f32_16x16x32_bf16 v[48:51], v[190:193], v[206:209], v[48:51]
	v_mfma_f32_16x16x32_bf16 v[44:47], v[182:185], v[214:217], v[44:47]
	v_mfma_f32_16x16x32_bf16 v[40:43], v[190:193], v[214:217], v[40:43]
	v_mfma_f32_16x16x32_bf16 v[36:39], v[182:185], v[238:241], v[36:39]
	v_mfma_f32_16x16x32_bf16 v[32:35], v[190:193], v[238:241], v[32:35]
	s_barrier
; #define STAGE(P,BASE,LD,br,kt) do{long _g=(long)(br)*(LD)+(long)(kt)*BK; \
;     _Pragma("unroll") for(int _i=0;_i<2;++_i){int _b=tid*16+_i*8192;int _r,_c;stage_rc(_b,_r,_c); \
;       __builtin_amdgcn_global_load_lds((const unsigned*)((BASE)+_g+(long)_r*(LD)+_c), \
;         (unsigned*)((char*)(P)+_b),16,0,0);}}while(0)
; #define STAGE(P,BASE,LD,br,kt) do{long _g=(long)(br)*(LD)+(long)(kt)*BK; \
;     _Pragma("unroll") for(int _i=0;_i<2;++_i){int _b=tid*16+_i*8192;int _r,_c;stage_rc(_b,_r,_c); \
;       __builtin_amdgcn_global_load_lds((const unsigned*)((BASE)+_g+(long)_r*(LD)+_c), \
;         (unsigned*)((char*)(P)+_b),16,0,0);}}while(0)
; #define LDA(dst,b,h) _Pragma("unroll") for(int m=0;m<4;++m) _Pragma("unroll") for(int k=0;k<2;++k) \
;     dst[m][k]=*reinterpret_cast<const bf16x8*>((char*)SA(b,h)+lds_byte(wr*64+m*16+fr,k*32+fq*8))
; #define LDB(dst,b,h) _Pragma("unroll") for(int n=0;n<2;++n) _Pragma("unroll") for(int k=0;k<2;++k) \
;     dst[n][k]=*reinterpret_cast<const bf16x8*>((char*)SB(b,h)+lds_byte(wc*32+n*16+fr,k*32+fq*8))
; #define MMA(ai,bj,At_,Bt_) do{__builtin_amdgcn_s_setprio(1); \
;     _Pragma("unroll") for(int m=0;m<4;++m) _Pragma("unroll") for(int n=0;n<2;++n) _Pragma("unroll") for(int k=0;k<2;++k) \
;       acc[ai][bj][m][n]=__builtin_amdgcn_mfma_f32_16x16x32_bf16(Bt_[n][k],At_[m][k],acc[ai][bj][m][n],0,0,0); \
;     __builtin_amdgcn_s_setprio(0);}while(0)
; #define WAIT_V(n) asm volatile("s_waitcnt vmcnt(" #n ")":::"memory")
; #define WAIT_L(n) asm volatile("s_waitcnt lgkmcnt(" #n ")":::"memory")
; #define BAR __builtin_amdgcn_s_barrier()
; #define SCHED __builtin_amdgcn_sched_barrier(0)
; DEVINL void gemm8_mainloop(const u16* A, long lda, const u16* Bt, long ldb, int K, int brow, int bcol, f32x4 (&acc)[2][2][4][2], char* smem, int tid) {
;     ...
;     STAGE(SB(0,1),Bt,ldb,bcol+HALF,t+2);
;     WAIT_V(6); BAR; MMA(1,1,At,B1); BAR;
;     LDB(B0,1,0); SCHED; LDA(At,1,0); STAGE(SA(0,1),A,lda,brow+HALF,t+2);
;     WAIT_L(8); BAR; WAIT_L(0); MMA(0,0,At,B0); BAR; SCHED;
;     LDB(B1,1,1); STAGE(SB(1,0),Bt,ldb,bcol,t+3);
;     BAR; WAIT_L(0); MMA(0,1,At,B1); BAR;
;     LDA(At,1,1); STAGE(SA(1,0),A,lda,brow,t+3);
	v_add_u32_e32 v167, s29, v154
	v_lshl_add_u64 v[168:169], v[246:247], 0, s[8:9]
	v_readfirstlane_b32 s25, v167
	s_mov_b32 m0, s25
	v_lshl_add_u64 v[178:179], v[248:249], 0, s[8:9]
	global_load_lds_dwordx4 v[168:169], off
	v_add_u32_e32 v168, 0x2000, v167
	s_nop 0
	v_readfirstlane_b32 s25, v168
	s_mov_b32 m0, s25
	s_nop 0
	global_load_lds_dwordx4 v[178:179], off
	s_waitcnt vmcnt(6)
	s_barrier
	v_mfma_f32_16x16x32_bf16 v[28:31], v[222:225], v[194:197], v[28:31]
	v_mfma_f32_16x16x32_bf16 v[24:27], v[230:233], v[194:197], v[24:27]
	v_mfma_f32_16x16x32_bf16 v[20:23], v[222:225], v[202:205], v[20:23]
	v_mfma_f32_16x16x32_bf16 v[16:19], v[230:233], v[202:205], v[16:19]
	v_mfma_f32_16x16x32_bf16 v[12:15], v[222:225], v[210:213], v[12:15]
	v_mfma_f32_16x16x32_bf16 v[8:11], v[230:233], v[210:213], v[8:11]
	v_mfma_f32_16x16x32_bf16 v[4:7], v[222:225], v[218:221], v[4:7]
	v_mfma_f32_16x16x32_bf16 v[0:3], v[230:233], v[218:221], v[0:3]
	v_mfma_f32_16x16x32_bf16 v[28:31], v[226:229], v[198:201], v[28:31]
	v_mfma_f32_16x16x32_bf16 v[24:27], v[234:237], v[198:201], v[24:27]
	v_mfma_f32_16x16x32_bf16 v[20:23], v[226:229], v[206:209], v[20:23]
	v_mfma_f32_16x16x32_bf16 v[16:19], v[234:237], v[206:209], v[16:19]
	v_mfma_f32_16x16x32_bf16 v[12:15], v[226:229], v[214:217], v[12:15]
	v_mfma_f32_16x16x32_bf16 v[8:11], v[234:237], v[214:217], v[8:11]
	v_mfma_f32_16x16x32_bf16 v[4:7], v[226:229], v[238:241], v[4:7]
	v_mfma_f32_16x16x32_bf16 v[0:3], v[234:237], v[238:241], v[0:3]
	s_barrier
	ds_read_b128 v[178:181], v156
	ds_read_b128 v[182:185], v156 offset:1024
	ds_read_b128 v[186:189], v156 offset:2048
	ds_read_b128 v[190:193], v156 offset:3072
	v_add_u32_e32 v169, 0x4000, v152
	v_add_u32_e32 v170, 0x6000, v152
	v_readfirstlane_b32 s25, v169
	v_lshl_add_u64 v[226:227], v[242:243], 0, s[10:11]
	s_mov_b32 m0, s25
	v_readfirstlane_b32 s25, v170
	ds_read_b128 v[194:197], v153 offset:32768
	ds_read_b128 v[198:201], v153 offset:33792
	ds_read_b128 v[202:205], v171 offset:32768
	ds_read_b128 v[206:209], v171 offset:33792
	ds_read_b128 v[210:213], v172 offset:32768
	ds_read_b128 v[214:217], v172 offset:33792
	ds_read_b128 v[218:221], v173 offset:32768
	ds_read_b128 v[222:225], v173 offset:33792
	global_load_lds_dwordx4 v[226:227], off
	v_lshl_add_u64 v[226:227], v[244:245], 0, s[10:11]
	s_mov_b32 m0, s25
	s_nop 0
	global_load_lds_dwordx4 v[226:227], off
	s_waitcnt lgkmcnt(8)
	s_barrier
	s_waitcnt lgkmcnt(0)
	v_mfma_f32_16x16x32_bf16 v[124:127], v[178:181], v[194:197], v[124:127]
	v_mfma_f32_16x16x32_bf16 v[120:123], v[186:189], v[194:197], v[120:123]
	v_mfma_f32_16x16x32_bf16 v[116:119], v[178:181], v[202:205], v[116:119]
	v_mfma_f32_16x16x32_bf16 v[112:115], v[186:189], v[202:205], v[112:115]
	v_mfma_f32_16x16x32_bf16 v[108:111], v[178:181], v[210:213], v[108:111]
	v_mfma_f32_16x16x32_bf16 v[104:107], v[186:189], v[210:213], v[104:107]
	v_mfma_f32_16x16x32_bf16 v[100:103], v[178:181], v[218:221], v[100:103]
	v_mfma_f32_16x16x32_bf16 v[96:99], v[186:189], v[218:221], v[96:99]
	v_mfma_f32_16x16x32_bf16 v[124:127], v[182:185], v[198:201], v[124:127]
	v_mfma_f32_16x16x32_bf16 v[120:123], v[190:193], v[198:201], v[120:123]
	v_mfma_f32_16x16x32_bf16 v[116:119], v[182:185], v[206:209], v[116:119]
	v_mfma_f32_16x16x32_bf16 v[112:115], v[190:193], v[206:209], v[112:115]
	v_mfma_f32_16x16x32_bf16 v[108:111], v[182:185], v[214:217], v[108:111]
	v_mfma_f32_16x16x32_bf16 v[104:107], v[190:193], v[214:217], v[104:107]
	v_mfma_f32_16x16x32_bf16 v[100:103], v[182:185], v[222:225], v[100:103]
	v_mfma_f32_16x16x32_bf16 v[96:99], v[190:193], v[222:225], v[96:99]
	s_barrier
	v_readfirstlane_b32 s25, v157
	v_add_u32_e32 v177, 0x2000, v157
	v_lshl_add_u64 v[250:251], v[246:247], 0, s[12:13]
	s_mov_b32 m0, s25
	v_readfirstlane_b32 s25, v177
	ds_read_b128 v[226:229], v155
	ds_read_b128 v[230:233], v155 offset:1024
	ds_read_b128 v[234:237], v155 offset:2048
	ds_read_b128 v[238:241], v155 offset:3072
	global_load_lds_dwordx4 v[250:251], off
	v_lshl_add_u64 v[250:251], v[248:249], 0, s[12:13]
	s_mov_b32 m0, s25
	s_nop 0
	global_load_lds_dwordx4 v[250:251], off
	s_barrier
	s_waitcnt lgkmcnt(0)
	v_mfma_f32_16x16x32_bf16 v[92:95], v[226:229], v[194:197], v[92:95]
	v_mfma_f32_16x16x32_bf16 v[88:91], v[234:237], v[194:197], v[88:91]
	v_mfma_f32_16x16x32_bf16 v[84:87], v[226:229], v[202:205], v[84:87]
	v_mfma_f32_16x16x32_bf16 v[80:83], v[234:237], v[202:205], v[80:83]
	v_mfma_f32_16x16x32_bf16 v[76:79], v[226:229], v[210:213], v[76:79]
	v_mfma_f32_16x16x32_bf16 v[72:75], v[234:237], v[210:213], v[72:75]
	v_mfma_f32_16x16x32_bf16 v[68:71], v[226:229], v[218:221], v[68:71]
	v_mfma_f32_16x16x32_bf16 v[64:67], v[234:237], v[218:221], v[64:67]
	v_mfma_f32_16x16x32_bf16 v[92:95], v[230:233], v[198:201], v[92:95]
	v_mfma_f32_16x16x32_bf16 v[88:91], v[238:241], v[198:201], v[88:91]
	v_mfma_f32_16x16x32_bf16 v[84:87], v[230:233], v[206:209], v[84:87]
	v_mfma_f32_16x16x32_bf16 v[80:83], v[238:241], v[206:209], v[80:83]
	v_mfma_f32_16x16x32_bf16 v[76:79], v[230:233], v[214:217], v[76:79]
	v_mfma_f32_16x16x32_bf16 v[72:75], v[238:241], v[214:217], v[72:75]
	v_mfma_f32_16x16x32_bf16 v[68:71], v[230:233], v[222:225], v[68:71]
	v_mfma_f32_16x16x32_bf16 v[64:67], v[238:241], v[222:225], v[64:67]
	v_readfirstlane_b32 s25, v158
	v_lshl_add_u64 v[242:243], v[242:243], 0, s[14:15]
	s_mov_b32 m0, s25
	v_readfirstlane_b32 s25, v159
	s_barrier
	ds_read_b128 v[194:197], v153 offset:49152
	ds_read_b128 v[198:201], v153 offset:50176
	ds_read_b128 v[202:205], v171 offset:49152
	ds_read_b128 v[206:209], v171 offset:50176
	ds_read_b128 v[210:213], v172 offset:49152
	ds_read_b128 v[214:217], v172 offset:50176
	ds_read_b128 v[218:221], v173 offset:49152
	ds_read_b128 v[222:225], v173 offset:50176
	global_load_lds_dwordx4 v[242:243], off
	v_lshl_add_u64 v[242:243], v[244:245], 0, s[14:15]
	s_mov_b32 m0, s25
	s_nop 0
	global_load_lds_dwordx4 v[242:243], off
	s_barrier
; #define STAGE(P,BASE,LD,br,kt) do{long _g=(long)(br)*(LD)+(long)(kt)*BK; \
;     _Pragma("unroll") for(int _i=0;_i<2;++_i){int _b=tid*16+_i*8192;int _r,_c;stage_rc(_b,_r,_c); \
;       __builtin_amdgcn_global_load_lds((const unsigned*)((BASE)+_g+(long)_r*(LD)+_c), \
;         (unsigned*)((char*)(P)+_b),16,0,0);}}while(0)
; #define STAGE(P,BASE,LD,br,kt) do{long _g=(long)(br)*(LD)+(long)(kt)*BK; \
;     _Pragma("unroll") for(int _i=0;_i<2;++_i){int _b=tid*16+_i*8192;int _r,_c;stage_rc(_b,_r,_c); \
;       __builtin_amdgcn_global_load_lds((const unsigned*)((BASE)+_g+(long)_r*(LD)+_c), \
;         (unsigned*)((char*)(P)+_b),16,0,0);}}while(0)
; #define LDA(dst,b,h) _Pragma("unroll") for(int m=0;m<4;++m) _Pragma("unroll") for(int k=0;k<2;++k) \
;     dst[m][k]=*reinterpret_cast<const bf16x8*>((char*)SA(b,h)+lds_byte(wr*64+m*16+fr,k*32+fq*8))
; #define LDB(dst,b,h) _Pragma("unroll") for(int n=0;n<2;++n) _Pragma("unroll") for(int k=0;k<2;++k) \
;     dst[n][k]=*reinterpret_cast<const bf16x8*>((char*)SB(b,h)+lds_byte(wc*32+n*16+fr,k*32+fq*8))
; #define MMA(ai,bj,At_,Bt_) do{__builtin_amdgcn_s_setprio(1); \
;     _Pragma("unroll") for(int m=0;m<4;++m) _Pragma("unroll") for(int n=0;n<2;++n) _Pragma("unroll") for(int k=0;k<2;++k) \
;       acc[ai][bj][m][n]=__builtin_amdgcn_mfma_f32_16x16x32_bf16(Bt_[n][k],At_[m][k],acc[ai][bj][m][n],0,0,0); \
;     __builtin_amdgcn_s_setprio(0);}while(0)
; #define WAIT_V(n) asm volatile("s_waitcnt vmcnt(" #n ")":::"memory")
; #define WAIT_L(n) asm volatile("s_waitcnt lgkmcnt(" #n ")":::"memory")
; #define BAR __builtin_amdgcn_s_barrier()
; #define SCHED __builtin_amdgcn_sched_barrier(0)
; DEVINL void gemm8_mainloop(const u16* A, long lda, const u16* Bt, long ldb, int K, int brow, int bcol, f32x4 (&acc)[2][2][4][2], char* smem, int tid) {
;     ...
;     BAR; WAIT_L(0); MMA(1,0,At,B0); BAR; SCHED;
;     STAGE(SB(1,1),Bt,ldb,bcol+HALF,t+3);
;     WAIT_V(6); BAR; MMA(1,1,At,B1); BAR;
;   }
;   { LDB(B0,0,0); LDA(At,0,0); STAGE(SA(1,1),A,lda,brow+HALF,nt-1);
;     BAR; WAIT_L(0); MMA(0,0,At,B0); BAR;
;     LDB(B1,0,1); BAR; WAIT_L(0); MMA(0,1,At,B1); BAR;
	s_waitcnt lgkmcnt(0)
	v_mfma_f32_16x16x32_bf16 v[60:63], v[178:181], v[194:197], v[60:63]
	v_mfma_f32_16x16x32_bf16 v[56:59], v[186:189], v[194:197], v[56:59]
	v_mfma_f32_16x16x32_bf16 v[52:55], v[178:181], v[202:205], v[52:55]
	v_mfma_f32_16x16x32_bf16 v[48:51], v[186:189], v[202:205], v[48:51]
	v_mfma_f32_16x16x32_bf16 v[44:47], v[178:181], v[210:213], v[44:47]
	v_mfma_f32_16x16x32_bf16 v[40:43], v[186:189], v[210:213], v[40:43]
	v_mfma_f32_16x16x32_bf16 v[36:39], v[178:181], v[218:221], v[36:39]
	v_mfma_f32_16x16x32_bf16 v[32:35], v[186:189], v[218:221], v[32:35]
	v_mfma_f32_16x16x32_bf16 v[60:63], v[182:185], v[198:201], v[60:63]
	v_mfma_f32_16x16x32_bf16 v[56:59], v[190:193], v[198:201], v[56:59]
	v_mfma_f32_16x16x32_bf16 v[52:55], v[182:185], v[206:209], v[52:55]
	v_mfma_f32_16x16x32_bf16 v[48:51], v[190:193], v[206:209], v[48:51]
	v_mfma_f32_16x16x32_bf16 v[44:47], v[182:185], v[214:217], v[44:47]
	v_mfma_f32_16x16x32_bf16 v[40:43], v[190:193], v[214:217], v[40:43]
	v_mfma_f32_16x16x32_bf16 v[36:39], v[182:185], v[222:225], v[36:39]
	v_mfma_f32_16x16x32_bf16 v[32:35], v[190:193], v[222:225], v[32:35]
	s_barrier
	v_readfirstlane_b32 s25, v161
	v_add_u32_e32 v177, 0x2000, v161
	v_lshl_add_u64 v[178:179], v[246:247], 0, s[16:17]
	s_mov_b32 m0, s25
	v_readfirstlane_b32 s25, v177
	global_load_lds_dwordx4 v[178:179], off
	v_lshl_add_u64 v[178:179], v[248:249], 0, s[16:17]
	s_mov_b32 m0, s25
	s_nop 0
	global_load_lds_dwordx4 v[178:179], off
	s_waitcnt vmcnt(6)
	s_barrier
	v_mfma_f32_16x16x32_bf16 v[28:31], v[226:229], v[194:197], v[28:31]
	v_mfma_f32_16x16x32_bf16 v[24:27], v[234:237], v[194:197], v[24:27]
	v_mfma_f32_16x16x32_bf16 v[20:23], v[226:229], v[202:205], v[20:23]
	v_mfma_f32_16x16x32_bf16 v[16:19], v[234:237], v[202:205], v[16:19]
	v_mfma_f32_16x16x32_bf16 v[12:15], v[226:229], v[210:213], v[12:15]
	v_mfma_f32_16x16x32_bf16 v[8:11], v[234:237], v[210:213], v[8:11]
	v_mfma_f32_16x16x32_bf16 v[4:7], v[226:229], v[218:221], v[4:7]
	v_mfma_f32_16x16x32_bf16 v[0:3], v[234:237], v[218:221], v[0:3]
	v_mfma_f32_16x16x32_bf16 v[28:31], v[230:233], v[198:201], v[28:31]
	v_mfma_f32_16x16x32_bf16 v[24:27], v[238:241], v[198:201], v[24:27]
	v_mfma_f32_16x16x32_bf16 v[20:23], v[230:233], v[206:209], v[20:23]
	v_mfma_f32_16x16x32_bf16 v[16:19], v[238:241], v[206:209], v[16:19]
	v_mfma_f32_16x16x32_bf16 v[12:15], v[230:233], v[214:217], v[12:15]
	v_mfma_f32_16x16x32_bf16 v[8:11], v[238:241], v[214:217], v[8:11]
	v_mfma_f32_16x16x32_bf16 v[4:7], v[230:233], v[222:225], v[4:7]
	v_mfma_f32_16x16x32_bf16 v[0:3], v[238:241], v[222:225], v[0:3]
	s_add_i32 s24, s24, 2
	v_lshl_add_u64 v[142:143], v[142:143], 0, s[18:19]
	v_lshl_add_u64 v[144:145], v[144:145], 0, s[18:19]
	v_lshl_add_u64 v[146:147], v[146:147], 0, s[18:19]
	s_cmpk_lt_u32 s24, 0x7c
	v_lshl_add_u64 v[148:149], v[148:149], 0, s[18:19]
	s_barrier
	s_cbranch_scc1 .LBB0_1987
	s_or_b32 s24, s22, 0x80
	s_ashr_i32 s25, s24, 31
	s_lshl_b64 s[24:25], s[24:25], 14
	s_add_u32 s23, s62, s24
	s_addc_u32 s25, s63, s25
	s_add_u32 s24, s23, 0x3f80
	s_addc_u32 s25, s25, 0
	v_lshl_add_u64 v[158:159], v[134:135], 1, s[24:25]
	v_readfirstlane_b32 s23, v174
	v_lshl_add_u64 v[138:139], v[138:139], 1, v[158:159]
	s_mov_b32 m0, s23
	ds_read_b128 v[142:145], v163
	ds_read_b128 v[146:149], v163 offset:1024
	ds_read_b128 v[178:181], v163 offset:2048
	ds_read_b128 v[182:185], v163 offset:3072
	ds_read_b128 v[186:189], v153
	ds_read_b128 v[190:193], v153 offset:1024
	ds_read_b128 v[194:197], v171
	ds_read_b128 v[198:201], v171 offset:1024
	ds_read_b128 v[202:205], v172
	ds_read_b128 v[206:209], v172 offset:1024
	ds_read_b128 v[210:213], v173
	ds_read_b128 v[214:217], v173 offset:1024
	global_load_lds_dwordx4 v[138:139], off
	v_lshl_add_u64 v[138:139], v[136:137], 1, s[24:25]
	v_readfirstlane_b32 s23, v175
	v_lshl_add_u64 v[138:139], v[140:141], 1, v[138:139]
	s_mov_b32 m0, s23
	s_nop 0
	global_load_lds_dwordx4 v[138:139], off
	s_barrier
	s_waitcnt lgkmcnt(0)
	v_mfma_f32_16x16x32_bf16 v[124:127], v[142:145], v[186:189], v[124:127]
	v_mfma_f32_16x16x32_bf16 v[120:123], v[178:181], v[186:189], v[120:123]
	v_mfma_f32_16x16x32_bf16 v[116:119], v[142:145], v[194:197], v[116:119]
	v_mfma_f32_16x16x32_bf16 v[112:115], v[178:181], v[194:197], v[112:115]
	v_mfma_f32_16x16x32_bf16 v[100:103], v[142:145], v[210:213], v[100:103]
	v_mfma_f32_16x16x32_bf16 v[96:99], v[178:181], v[210:213], v[96:99]
	v_mfma_f32_16x16x32_bf16 v[124:127], v[146:149], v[190:193], v[124:127]
	v_mfma_f32_16x16x32_bf16 v[120:123], v[182:185], v[190:193], v[120:123]
	v_mfma_f32_16x16x32_bf16 v[116:119], v[146:149], v[198:201], v[116:119]
	v_mfma_f32_16x16x32_bf16 v[112:115], v[182:185], v[198:201], v[112:115]
	v_mfma_f32_16x16x32_bf16 v[108:111], v[142:145], v[202:205], v[108:111]
	v_mfma_f32_16x16x32_bf16 v[104:107], v[178:181], v[202:205], v[104:107]
	v_mfma_f32_16x16x32_bf16 v[100:103], v[146:149], v[214:217], v[100:103]
	v_mfma_f32_16x16x32_bf16 v[96:99], v[182:185], v[214:217], v[96:99]
	v_mfma_f32_16x16x32_bf16 v[138:141], v[146:149], v[206:209], v[108:111]
	v_mfma_f32_16x16x32_bf16 v[218:221], v[182:185], v[206:209], v[104:107]
	s_barrier
	s_nop 1
	s_nop 0
	ds_read_b128 v[104:107], v160
	ds_read_b128 v[108:111], v160 offset:1024
	ds_read_b128 v[222:225], v160 offset:2048
	ds_read_b128 v[158:161], v160 offset:3072
	s_barrier
; #define LDA(dst,b,h) _Pragma("unroll") for(int m=0;m<4;++m) _Pragma("unroll") for(int k=0;k<2;++k) \
;     dst[m][k]=*reinterpret_cast<const bf16x8*>((char*)SA(b,h)+lds_byte(wr*64+m*16+fr,k*32+fq*8))
; #define LDB(dst,b,h) _Pragma("unroll") for(int n=0;n<2;++n) _Pragma("unroll") for(int k=0;k<2;++k) \
;     dst[n][k]=*reinterpret_cast<const bf16x8*>((char*)SB(b,h)+lds_byte(wc*32+n*16+fr,k*32+fq*8))
; #define MMA(ai,bj,At_,Bt_) do{__builtin_amdgcn_s_setprio(1); \
;     _Pragma("unroll") for(int m=0;m<4;++m) _Pragma("unroll") for(int n=0;n<2;++n) _Pragma("unroll") for(int k=0;k<2;++k) \
;       acc[ai][bj][m][n]=__builtin_amdgcn_mfma_f32_16x16x32_bf16(Bt_[n][k],At_[m][k],acc[ai][bj][m][n],0,0,0); \
;     __builtin_amdgcn_s_setprio(0);}while(0)
; #define WAIT_V(n) asm volatile("s_waitcnt vmcnt(" #n ")":::"memory")
; #define WAIT_L(n) asm volatile("s_waitcnt lgkmcnt(" #n ")":::"memory")
; #define BAR __builtin_amdgcn_s_barrier()
; DEVINL void gemm8_mainloop(const u16* A, long lda, const u16* Bt, long ldb, int K, int brow, int bcol, f32x4 (&acc)[2][2][4][2], char* smem, int tid) {
;     ...
;     LDB(B1,0,1); BAR; WAIT_L(0); MMA(0,1,At,B1); BAR;
;     LDA(At,0,1); WAIT_V(4); BAR; WAIT_L(0); MMA(1,0,At,B0); MMA(1,1,At,B1); BAR; }
;   { LDB(B0,1,0); LDA(At,1,0); WAIT_V(2); BAR; WAIT_L(0); MMA(0,0,At,B0); BAR;
	s_waitcnt lgkmcnt(0)
	v_mfma_f32_16x16x32_bf16 v[84:87], v[104:107], v[194:197], v[84:87]
	v_mfma_f32_16x16x32_bf16 v[80:83], v[222:225], v[194:197], v[80:83]
	v_mfma_f32_16x16x32_bf16 v[68:71], v[104:107], v[210:213], v[68:71]
	v_mfma_f32_16x16x32_bf16 v[92:95], v[104:107], v[186:189], v[92:95]
	v_mfma_f32_16x16x32_bf16 v[88:91], v[222:225], v[186:189], v[88:91]
	v_mfma_f32_16x16x32_bf16 v[84:87], v[108:111], v[198:201], v[84:87]
	v_mfma_f32_16x16x32_bf16 v[80:83], v[158:161], v[198:201], v[80:83]
	v_mfma_f32_16x16x32_bf16 v[76:79], v[104:107], v[202:205], v[76:79]
	v_mfma_f32_16x16x32_bf16 v[72:75], v[222:225], v[202:205], v[72:75]
	v_mfma_f32_16x16x32_bf16 v[68:71], v[108:111], v[214:217], v[68:71]
	v_mfma_f32_16x16x32_bf16 v[64:67], v[222:225], v[210:213], v[64:67]
	v_mfma_f32_16x16x32_bf16 v[226:229], v[108:111], v[190:193], v[92:95]
	v_mfma_f32_16x16x32_bf16 v[186:189], v[158:161], v[190:193], v[88:91]
	v_mfma_f32_16x16x32_bf16 v[190:193], v[108:111], v[206:209], v[76:79]
	v_mfma_f32_16x16x32_bf16 v[194:197], v[158:161], v[206:209], v[72:75]
	v_mfma_f32_16x16x32_bf16 v[198:201], v[158:161], v[214:217], v[64:67]
	s_barrier
	s_nop 0
	s_nop 0
	ds_read_b128 v[64:67], v153 offset:16384
	ds_read_b128 v[72:75], v153 offset:17408
	ds_read_b128 v[76:79], v171 offset:16384
	ds_read_b128 v[88:91], v171 offset:17408
	ds_read_b128 v[92:95], v172 offset:16384
	ds_read_b128 v[202:205], v172 offset:17408
	ds_read_b128 v[206:209], v173 offset:16384
	ds_read_b128 v[210:213], v173 offset:17408
	s_waitcnt vmcnt(4)
	s_barrier
	s_waitcnt lgkmcnt(0)
	v_mfma_f32_16x16x32_bf16 v[60:63], v[142:145], v[64:67], v[60:63]
	v_mfma_f32_16x16x32_bf16 v[56:59], v[178:181], v[64:67], v[56:59]
	v_mfma_f32_16x16x32_bf16 v[52:55], v[142:145], v[76:79], v[52:55]
	v_mfma_f32_16x16x32_bf16 v[48:51], v[178:181], v[76:79], v[48:51]
	v_mfma_f32_16x16x32_bf16 v[36:39], v[142:145], v[206:209], v[36:39]
	v_mfma_f32_16x16x32_bf16 v[32:35], v[178:181], v[206:209], v[32:35]
	v_mfma_f32_16x16x32_bf16 v[60:63], v[146:149], v[72:75], v[60:63]
	v_mfma_f32_16x16x32_bf16 v[56:59], v[182:185], v[72:75], v[56:59]
	v_mfma_f32_16x16x32_bf16 v[52:55], v[146:149], v[88:91], v[52:55]
	v_mfma_f32_16x16x32_bf16 v[48:51], v[182:185], v[88:91], v[48:51]
	v_mfma_f32_16x16x32_bf16 v[44:47], v[142:145], v[92:95], v[44:47]
	v_mfma_f32_16x16x32_bf16 v[40:43], v[178:181], v[92:95], v[40:43]
	v_mfma_f32_16x16x32_bf16 v[36:39], v[146:149], v[210:213], v[36:39]
	v_mfma_f32_16x16x32_bf16 v[32:35], v[182:185], v[210:213], v[32:35]
	v_mfma_f32_16x16x32_bf16 v[214:217], v[146:149], v[202:205], v[44:47]
	v_mfma_f32_16x16x32_bf16 v[230:233], v[182:185], v[202:205], v[40:43]
	v_mfma_f32_16x16x32_bf16 v[20:23], v[104:107], v[76:79], v[20:23]
	v_mfma_f32_16x16x32_bf16 v[16:19], v[222:225], v[76:79], v[16:19]
	v_mfma_f32_16x16x32_bf16 v[4:7], v[104:107], v[206:209], v[4:7]
	v_mfma_f32_16x16x32_bf16 v[28:31], v[104:107], v[64:67], v[28:31]
	v_mfma_f32_16x16x32_bf16 v[24:27], v[222:225], v[64:67], v[24:27]
	v_mfma_f32_16x16x32_bf16 v[20:23], v[108:111], v[88:91], v[20:23]
	v_mfma_f32_16x16x32_bf16 v[16:19], v[158:161], v[88:91], v[16:19]
	v_mfma_f32_16x16x32_bf16 v[12:15], v[104:107], v[92:95], v[12:15]
	v_mfma_f32_16x16x32_bf16 v[8:11], v[222:225], v[92:95], v[8:11]
	v_mfma_f32_16x16x32_bf16 v[4:7], v[108:111], v[210:213], v[4:7]
	v_mfma_f32_16x16x32_bf16 v[0:3], v[222:225], v[206:209], v[0:3]
	v_mfma_f32_16x16x32_bf16 v[142:145], v[108:111], v[72:75], v[28:31]
	v_mfma_f32_16x16x32_bf16 v[146:149], v[158:161], v[72:75], v[24:27]
	v_mfma_f32_16x16x32_bf16 v[178:181], v[108:111], v[202:205], v[12:15]
	v_mfma_f32_16x16x32_bf16 v[182:185], v[158:161], v[202:205], v[8:11]
	v_mfma_f32_16x16x32_bf16 v[158:161], v[158:161], v[210:213], v[0:3]
	s_barrier
	s_nop 0
	s_nop 0
	ds_read_b128 v[0:3], v156
	ds_read_b128 v[8:11], v156 offset:1024
	ds_read_b128 v[202:205], v156 offset:2048
	ds_read_b128 v[206:209], v156 offset:3072
	ds_read_b128 v[12:15], v153 offset:32768
	ds_read_b128 v[24:27], v153 offset:33792
	ds_read_b128 v[28:31], v171 offset:32768
	ds_read_b128 v[40:43], v171 offset:33792
	ds_read_b128 v[44:47], v172 offset:32768
	ds_read_b128 v[64:67], v172 offset:33792
	ds_read_b128 v[210:213], v173 offset:32768
	ds_read_b128 v[222:225], v173 offset:33792
	s_waitcnt vmcnt(2)
	s_barrier
; #define LDA(dst,b,h) _Pragma("unroll") for(int m=0;m<4;++m) _Pragma("unroll") for(int k=0;k<2;++k) \
;     dst[m][k]=*reinterpret_cast<const bf16x8*>((char*)SA(b,h)+lds_byte(wr*64+m*16+fr,k*32+fq*8))
; #define LDB(dst,b,h) _Pragma("unroll") for(int n=0;n<2;++n) _Pragma("unroll") for(int k=0;k<2;++k) \
;     dst[n][k]=*reinterpret_cast<const bf16x8*>((char*)SB(b,h)+lds_byte(wc*32+n*16+fr,k*32+fq*8))
; #define MMA(ai,bj,At_,Bt_) do{__builtin_amdgcn_s_setprio(1); \
;     _Pragma("unroll") for(int m=0;m<4;++m) _Pragma("unroll") for(int n=0;n<2;++n) _Pragma("unroll") for(int k=0;k<2;++k) \
;       acc[ai][bj][m][n]=__builtin_amdgcn_mfma_f32_16x16x32_bf16(Bt_[n][k],At_[m][k],acc[ai][bj][m][n],0,0,0); \
;     __builtin_amdgcn_s_setprio(0);}while(0)
; #define WAIT_V(n) asm volatile("s_waitcnt vmcnt(" #n ")":::"memory")
; #define WAIT_L(n) asm volatile("s_waitcnt lgkmcnt(" #n ")":::"memory")
; #define BAR __builtin_amdgcn_s_barrier()
; DEVINL void gemm8_mainloop(const u16* A, long lda, const u16* Bt, long ldb, int K, int brow, int bcol, f32x4 (&acc)[2][2][4][2], char* smem, int tid) {
;     ...
;   { LDB(B0,1,0); LDA(At,1,0); WAIT_V(2); BAR; WAIT_L(0); MMA(0,0,At,B0); BAR;
;     LDB(B1,1,1); WAIT_V(0); BAR; WAIT_L(0); MMA(0,1,At,B1); BAR;
;     LDA(At,1,1); BAR; WAIT_L(0); MMA(1,0,At,B0); MMA(1,1,At,B1); BAR; }
;   if(wr==0)BAR;
;   __syncthreads();
	s_waitcnt lgkmcnt(0)
	v_mfma_f32_16x16x32_bf16 v[72:75], v[0:3], v[12:15], v[124:127]
	v_mfma_f32_16x16x32_bf16 v[124:127], v[8:11], v[24:27], v[72:75]
	v_mfma_f32_16x16x32_bf16 v[72:75], v[202:205], v[12:15], v[120:123]
	v_mfma_f32_16x16x32_bf16 v[120:123], v[206:209], v[24:27], v[72:75]
	v_mfma_f32_16x16x32_bf16 v[72:75], v[0:3], v[28:31], v[116:119]
	v_mfma_f32_16x16x32_bf16 v[108:111], v[8:11], v[40:43], v[72:75]
	v_mfma_f32_16x16x32_bf16 v[72:75], v[202:205], v[28:31], v[112:115]
	v_mfma_f32_16x16x32_bf16 v[104:107], v[206:209], v[40:43], v[72:75]
	v_mfma_f32_16x16x32_bf16 v[72:75], v[0:3], v[44:47], v[138:141]
	v_mfma_f32_16x16x32_bf16 v[92:95], v[8:11], v[64:67], v[72:75]
	v_mfma_f32_16x16x32_bf16 v[72:75], v[202:205], v[44:47], v[218:221]
	v_mfma_f32_16x16x32_bf16 v[88:91], v[206:209], v[64:67], v[72:75]
	v_mfma_f32_16x16x32_bf16 v[72:75], v[0:3], v[210:213], v[100:103]
	v_mfma_f32_16x16x32_bf16 v[76:79], v[8:11], v[222:225], v[72:75]
	v_mfma_f32_16x16x32_bf16 v[72:75], v[202:205], v[210:213], v[96:99]
	v_mfma_f32_16x16x32_bf16 v[72:75], v[206:209], v[222:225], v[72:75]
	s_barrier
	ds_read_b128 v[138:141], v155
	ds_read_b128 v[218:221], v155 offset:1024
	ds_read_b128 v[234:237], v155 offset:2048
	ds_read_b128 v[154:157], v155 offset:3072
	s_waitcnt vmcnt(0)
	s_barrier
	s_waitcnt lgkmcnt(0)
	v_mfma_f32_16x16x32_bf16 v[96:99], v[138:141], v[12:15], v[226:229]
	v_mfma_f32_16x16x32_bf16 v[12:15], v[234:237], v[12:15], v[186:189]
	v_mfma_f32_16x16x32_bf16 v[116:119], v[154:157], v[24:27], v[12:15]
	v_mfma_f32_16x16x32_bf16 v[12:15], v[138:141], v[28:31], v[84:87]
	v_mfma_f32_16x16x32_bf16 v[112:115], v[218:221], v[24:27], v[96:99]
	v_mfma_f32_16x16x32_bf16 v[96:99], v[218:221], v[40:43], v[12:15]
	v_mfma_f32_16x16x32_bf16 v[12:15], v[234:237], v[28:31], v[80:83]
	v_mfma_f32_16x16x32_bf16 v[100:103], v[154:157], v[40:43], v[12:15]
	v_mfma_f32_16x16x32_bf16 v[12:15], v[138:141], v[44:47], v[190:193]
	v_mfma_f32_16x16x32_bf16 v[80:83], v[218:221], v[64:67], v[12:15]
	v_mfma_f32_16x16x32_bf16 v[12:15], v[234:237], v[44:47], v[194:197]
	v_mfma_f32_16x16x32_bf16 v[84:87], v[154:157], v[64:67], v[12:15]
	v_mfma_f32_16x16x32_bf16 v[12:15], v[138:141], v[210:213], v[68:71]
	v_mfma_f32_16x16x32_bf16 v[64:67], v[218:221], v[222:225], v[12:15]
	v_mfma_f32_16x16x32_bf16 v[12:15], v[234:237], v[210:213], v[198:201]
	v_mfma_f32_16x16x32_bf16 v[68:71], v[154:157], v[222:225], v[12:15]
	s_barrier
	ds_read_b128 v[186:189], v153 offset:49152
	ds_read_b128 v[190:193], v153 offset:50176
	ds_read_b128 v[194:197], v171 offset:49152
	ds_read_b128 v[198:201], v171 offset:50176
	ds_read_b128 v[210:213], v172 offset:49152
	ds_read_b128 v[222:225], v172 offset:50176
	ds_read_b128 v[226:229], v173 offset:49152
	ds_read_b128 v[172:175], v173 offset:50176
	s_barrier
	s_waitcnt lgkmcnt(0)
	v_mfma_f32_16x16x32_bf16 v[12:15], v[0:3], v[186:189], v[60:63]
	v_mfma_f32_16x16x32_bf16 v[60:63], v[8:11], v[190:193], v[12:15]
	v_mfma_f32_16x16x32_bf16 v[12:15], v[202:205], v[186:189], v[56:59]
	v_mfma_f32_16x16x32_bf16 v[56:59], v[206:209], v[190:193], v[12:15]
	v_mfma_f32_16x16x32_bf16 v[12:15], v[0:3], v[194:197], v[52:55]
	v_mfma_f32_16x16x32_bf16 v[44:47], v[8:11], v[198:201], v[12:15]
	v_mfma_f32_16x16x32_bf16 v[12:15], v[202:205], v[194:197], v[48:51]
	v_mfma_f32_16x16x32_bf16 v[40:43], v[206:209], v[198:201], v[12:15]
	v_mfma_f32_16x16x32_bf16 v[12:15], v[0:3], v[210:213], v[214:217]
	v_mfma_f32_16x16x32_bf16 v[28:31], v[8:11], v[222:225], v[12:15]
	v_mfma_f32_16x16x32_bf16 v[12:15], v[202:205], v[210:213], v[230:233]
	v_mfma_f32_16x16x32_bf16 v[0:3], v[0:3], v[226:229], v[36:39]
	v_mfma_f32_16x16x32_bf16 v[24:27], v[206:209], v[222:225], v[12:15]
	v_mfma_f32_16x16x32_bf16 v[12:15], v[8:11], v[172:175], v[0:3]
	v_mfma_f32_16x16x32_bf16 v[0:3], v[202:205], v[226:229], v[32:35]
	v_mfma_f32_16x16x32_bf16 v[8:11], v[206:209], v[172:175], v[0:3]
	v_mfma_f32_16x16x32_bf16 v[0:3], v[138:141], v[186:189], v[142:145]
	v_mfma_f32_16x16x32_bf16 v[48:51], v[218:221], v[190:193], v[0:3]
	v_mfma_f32_16x16x32_bf16 v[0:3], v[234:237], v[186:189], v[146:149]
	v_mfma_f32_16x16x32_bf16 v[52:55], v[154:157], v[190:193], v[0:3]
	v_mfma_f32_16x16x32_bf16 v[0:3], v[138:141], v[194:197], v[20:23]
	v_mfma_f32_16x16x32_bf16 v[32:35], v[218:221], v[198:201], v[0:3]
	v_mfma_f32_16x16x32_bf16 v[0:3], v[234:237], v[194:197], v[16:19]
	v_mfma_f32_16x16x32_bf16 v[36:39], v[154:157], v[198:201], v[0:3]
	v_mfma_f32_16x16x32_bf16 v[0:3], v[138:141], v[210:213], v[178:181]
	v_mfma_f32_16x16x32_bf16 v[16:19], v[218:221], v[222:225], v[0:3]
	v_mfma_f32_16x16x32_bf16 v[0:3], v[234:237], v[210:213], v[182:185]
	v_mfma_f32_16x16x32_bf16 v[20:23], v[154:157], v[222:225], v[0:3]
	v_mfma_f32_16x16x32_bf16 v[0:3], v[138:141], v[226:229], v[4:7]
	v_mfma_f32_16x16x32_bf16 v[4:7], v[234:237], v[226:229], v[158:161]
	v_mfma_f32_16x16x32_bf16 v[0:3], v[218:221], v[172:175], v[0:3]
	v_mfma_f32_16x16x32_bf16 v[4:7], v[154:157], v[172:175], v[4:7]
	s_setprio 0
	s_cmpk_gt_u32 s27, 0xff
	s_barrier
	s_cbranch_scc1 .LBB0_1990
	s_barrier
